# baseline (speedup 1.0000x reference)
; #define PG8_STAGE(bufoff, gbase, voff) do { _Pragma("unroll") for (int _i = 0; _i < 2; ++_i) \
;         __builtin_amdgcn_global_load_lds((const unsigned*)((const char*)(gbase) + (voff)[_i]), (LAS unsigned*)(lds + (bufoff) + ldsw + _i * 8192), 16, 0, 0); } while (0)
; #define PG8_LDA(dst, b, h) do { _Pragma("unroll") for (int m = 0; m < 4; ++m) _Pragma("unroll") for (int k = 0; k < 2; ++k) dst[m][k] = *(const LAS bf16x8*)(lds + PG8_SA(b, h) + aoff + m * 2048 + k * 1024); } while (0)
; #define PG8_LDB(dst, b, h) do { _Pragma("unroll") for (int n = 0; n < 2; ++n) _Pragma("unroll") for (int k = 0; k < 2; ++k) dst[n][k] = *(const LAS bf16x8*)(lds + PG8_SB(b, h) + boff + n * 2048 + k * 1024); } while (0)
; #define PG8_MMA(ai, bj, At, Bt) do { __builtin_amdgcn_s_setprio(1); _Pragma("unroll") for (int m = 0; m < 4; ++m) _Pragma("unroll") for (int n = 0; n < 2; ++n) _Pragma("unroll") for (int k = 0; k < 2; ++k) \
;         acc[ai][bj][m][n] = __builtin_amdgcn_mfma_f32_16x16x32_bf16(Bt[n][k], At[m][k], acc[ai][bj][m][n], 0, 0, 0); __builtin_amdgcn_s_setprio(0); } while (0)
; #define PG8_WAIT_V(n) asm volatile("s_waitcnt vmcnt(" #n ")" ::: "memory")
; #define PG8_WAIT_L(n) asm volatile("s_waitcnt lgkmcnt(" #n ")" ::: "memory")
; #define PG8_BAR __builtin_amdgcn_s_barrier()
; #define PG8_SCHED __builtin_amdgcn_sched_barrier(0)
; template <class Epi, class Sched>
; __device__ __forceinline__ void gemm_phase(LAS unsigned char* lds, const Gemm g, const Sched& S, const Epi& E) {
;     ...
;             PG8_LDB(B0, 0, 0); PG8_SCHED; PG8_LDA(At, 0, 0); PG8_STAGE(PG8_SA(1, 1), a1 + hstep, voffA);
;             PG8_WAIT_L(8); PG8_BAR; PG8_WAIT_L(0); PG8_MMA(0, 0, At, B0); PG8_BAR; PG8_SCHED;
;             PG8_LDB(B1, 0, 1); PG8_STAGE(PG8_SB(0, 0), b2, voffB);
;             PG8_BAR; PG8_WAIT_L(0); PG8_MMA(0, 1, At, B1); PG8_BAR;
;             PG8_LDA(At, 0, 1); PG8_STAGE(PG8_SA(0, 0), a2, voffA);
;             PG8_BAR; PG8_WAIT_L(0); PG8_MMA(1, 0, At, B0); PG8_BAR; PG8_SCHED;
;             PG8_STAGE(PG8_SB(0, 1), b2 + hstep, voffB);
;             PG8_WAIT_V(6); PG8_BAR; PG8_MMA(1, 1, At, B1); PG8_BAR;
.LBB0_135:
	ds_read_b128 v[154:157], v150
	ds_read_b128 v[158:161], v150 offset:1024
	ds_read_b128 v[162:165], v150 offset:2048
	ds_read_b128 v[170:173], v150 offset:3072
	s_add_u32 s36, s28, 0x4000
	s_addc_u32 s37, s29, 0
	s_cmp_eq_u32 s63, 28
	s_cselect_b32 s40, s33, s36
	s_cselect_b32 s41, s13, s37
	s_cselect_b32 s36, s60, s61
	s_cselect_b32 s37, s11, s62
	s_add_u32 s38, s40, 0x8000
	s_addc_u32 s39, s41, 0
	v_lshl_add_u64 v[166:167], s[28:29], 0, v[138:139]
	s_add_i32 m0, s48, 0xc000
	ds_read_b128 v[174:177], v151
	ds_read_b128 v[178:181], v151 offset:1024
	ds_read_b128 v[182:185], v151 offset:2048
	ds_read_b128 v[186:189], v151 offset:3072
	ds_read_b128 v[190:193], v151 offset:4096
	ds_read_b128 v[194:197], v151 offset:5120
	ds_read_b128 v[198:201], v151 offset:6144
	ds_read_b128 v[206:209], v151 offset:7168
	global_load_lds_dwordx4 v[166:167], off
	v_lshl_add_u64 v[166:167], s[28:29], 0, v[140:141]
	s_add_i32 m0, s48, 0xe000
	s_nop 0
	global_load_lds_dwordx4 v[166:167], off
	s_waitcnt lgkmcnt(8)
	s_barrier
	s_waitcnt lgkmcnt(0)
	v_mfma_f32_16x16x32_bf16 v[124:127], v[154:157], v[174:177], v[124:127]
	v_mfma_f32_16x16x32_bf16 v[120:123], v[162:165], v[174:177], v[120:123]
	v_mfma_f32_16x16x32_bf16 v[108:111], v[154:157], v[182:185], v[108:111]
	v_mfma_f32_16x16x32_bf16 v[104:107], v[162:165], v[182:185], v[104:107]
	v_mfma_f32_16x16x32_bf16 v[92:95], v[154:157], v[190:193], v[92:95]
	v_mfma_f32_16x16x32_bf16 v[88:91], v[162:165], v[190:193], v[88:91]
	v_mfma_f32_16x16x32_bf16 v[76:79], v[154:157], v[198:201], v[76:79]
	v_mfma_f32_16x16x32_bf16 v[72:75], v[162:165], v[198:201], v[72:75]
	v_mfma_f32_16x16x32_bf16 v[124:127], v[158:161], v[178:181], v[124:127]
	v_mfma_f32_16x16x32_bf16 v[120:123], v[170:173], v[178:181], v[120:123]
	v_mfma_f32_16x16x32_bf16 v[108:111], v[158:161], v[186:189], v[108:111]
	v_mfma_f32_16x16x32_bf16 v[104:107], v[170:173], v[186:189], v[104:107]
	v_mfma_f32_16x16x32_bf16 v[92:95], v[158:161], v[194:197], v[92:95]
	v_mfma_f32_16x16x32_bf16 v[88:91], v[170:173], v[194:197], v[88:91]
	v_mfma_f32_16x16x32_bf16 v[76:79], v[158:161], v[206:209], v[76:79]
	v_mfma_f32_16x16x32_bf16 v[72:75], v[170:173], v[206:209], v[72:75]
	s_barrier
	s_add_i32 s64, s57, s46
	v_lshl_add_u64 v[166:167], s[36:37], 0, v[132:133]
	s_mov_b32 m0, s64
	ds_read_b128 v[210:213], v152
	ds_read_b128 v[214:217], v152 offset:1024
	ds_read_b128 v[218:221], v152 offset:2048
	ds_read_b128 v[222:225], v152 offset:3072
	global_load_lds_dwordx4 v[166:167], off
	v_lshl_add_u64 v[166:167], s[36:37], 0, v[128:129]
	s_add_i32 m0, s64, 0x2000
	s_nop 0
	global_load_lds_dwordx4 v[166:167], off
	s_barrier
	s_waitcnt lgkmcnt(0)
	v_mfma_f32_16x16x32_bf16 v[116:119], v[210:213], v[174:177], v[116:119]
	v_mfma_f32_16x16x32_bf16 v[112:115], v[218:221], v[174:177], v[112:115]
	v_mfma_f32_16x16x32_bf16 v[100:103], v[210:213], v[182:185], v[100:103]
	v_mfma_f32_16x16x32_bf16 v[96:99], v[218:221], v[182:185], v[96:99]
	v_mfma_f32_16x16x32_bf16 v[84:87], v[210:213], v[190:193], v[84:87]
	v_mfma_f32_16x16x32_bf16 v[80:83], v[218:221], v[190:193], v[80:83]
	v_mfma_f32_16x16x32_bf16 v[68:71], v[210:213], v[198:201], v[68:71]
	v_mfma_f32_16x16x32_bf16 v[64:67], v[218:221], v[198:201], v[64:67]
	v_mfma_f32_16x16x32_bf16 v[116:119], v[214:217], v[178:181], v[116:119]
	v_mfma_f32_16x16x32_bf16 v[112:115], v[222:225], v[178:181], v[112:115]
	v_mfma_f32_16x16x32_bf16 v[100:103], v[214:217], v[186:189], v[100:103]
	v_mfma_f32_16x16x32_bf16 v[96:99], v[222:225], v[186:189], v[96:99]
	v_mfma_f32_16x16x32_bf16 v[84:87], v[214:217], v[194:197], v[84:87]
	v_mfma_f32_16x16x32_bf16 v[80:83], v[222:225], v[194:197], v[80:83]
	v_mfma_f32_16x16x32_bf16 v[68:71], v[214:217], v[206:209], v[68:71]
	v_mfma_f32_16x16x32_bf16 v[64:67], v[222:225], v[206:209], v[64:67]
	s_mov_b32 m0, s48
	v_lshl_add_u64 v[166:167], s[40:41], 0, v[134:135]
	s_barrier
	ds_read_b128 v[174:177], v151 offset:16384
	ds_read_b128 v[178:181], v151 offset:17408
	ds_read_b128 v[182:185], v151 offset:18432
	ds_read_b128 v[186:189], v151 offset:19456
	ds_read_b128 v[190:193], v151 offset:20480
	ds_read_b128 v[194:197], v151 offset:21504
	ds_read_b128 v[198:201], v151 offset:22528
	ds_read_b128 v[206:209], v151 offset:23552
	global_load_lds_dwordx4 v[166:167], off
	v_lshl_add_u64 v[166:167], s[40:41], 0, v[130:131]
	s_mov_b32 m0, s49
	s_nop 0
	global_load_lds_dwordx4 v[166:167], off
	s_barrier
	s_waitcnt lgkmcnt(0)
	v_mfma_f32_16x16x32_bf16 v[60:63], v[154:157], v[174:177], v[60:63]
	v_mfma_f32_16x16x32_bf16 v[56:59], v[162:165], v[174:177], v[56:59]
	v_mfma_f32_16x16x32_bf16 v[44:47], v[154:157], v[182:185], v[44:47]
	v_mfma_f32_16x16x32_bf16 v[40:43], v[162:165], v[182:185], v[40:43]
	v_mfma_f32_16x16x32_bf16 v[28:31], v[154:157], v[190:193], v[28:31]
	v_mfma_f32_16x16x32_bf16 v[24:27], v[162:165], v[190:193], v[24:27]
	v_mfma_f32_16x16x32_bf16 v[12:15], v[154:157], v[198:201], v[12:15]
	v_mfma_f32_16x16x32_bf16 v[8:11], v[162:165], v[198:201], v[8:11]
	v_mfma_f32_16x16x32_bf16 v[60:63], v[158:161], v[178:181], v[60:63]
	v_mfma_f32_16x16x32_bf16 v[56:59], v[170:173], v[178:181], v[56:59]
	v_mfma_f32_16x16x32_bf16 v[44:47], v[158:161], v[186:189], v[44:47]
	v_mfma_f32_16x16x32_bf16 v[40:43], v[170:173], v[186:189], v[40:43]
	v_mfma_f32_16x16x32_bf16 v[28:31], v[158:161], v[194:197], v[28:31]
	v_mfma_f32_16x16x32_bf16 v[24:27], v[170:173], v[194:197], v[24:27]
	v_mfma_f32_16x16x32_bf16 v[12:15], v[158:161], v[206:209], v[12:15]
	v_mfma_f32_16x16x32_bf16 v[8:11], v[170:173], v[206:209], v[8:11]
	s_barrier
; #define PG8_STAGE(bufoff, gbase, voff) do { _Pragma("unroll") for (int _i = 0; _i < 2; ++_i) \
;         __builtin_amdgcn_global_load_lds((const unsigned*)((const char*)(gbase) + (voff)[_i]), (LAS unsigned*)(lds + (bufoff) + ldsw + _i * 8192), 16, 0, 0); } while (0)
; #define PG8_LDA(dst, b, h) do { _Pragma("unroll") for (int m = 0; m < 4; ++m) _Pragma("unroll") for (int k = 0; k < 2; ++k) dst[m][k] = *(const LAS bf16x8*)(lds + PG8_SA(b, h) + aoff + m * 2048 + k * 1024); } while (0)
; #define PG8_LDB(dst, b, h) do { _Pragma("unroll") for (int n = 0; n < 2; ++n) _Pragma("unroll") for (int k = 0; k < 2; ++k) dst[n][k] = *(const LAS bf16x8*)(lds + PG8_SB(b, h) + boff + n * 2048 + k * 1024); } while (0)
; #define PG8_MMA(ai, bj, At, Bt) do { __builtin_amdgcn_s_setprio(1); _Pragma("unroll") for (int m = 0; m < 4; ++m) _Pragma("unroll") for (int n = 0; n < 2; ++n) _Pragma("unroll") for (int k = 0; k < 2; ++k) \
;         acc[ai][bj][m][n] = __builtin_amdgcn_mfma_f32_16x16x32_bf16(Bt[n][k], At[m][k], acc[ai][bj][m][n], 0, 0, 0); __builtin_amdgcn_s_setprio(0); } while (0)
; #define PG8_WAIT_V(n) asm volatile("s_waitcnt vmcnt(" #n ")" ::: "memory")
; #define PG8_WAIT_L(n) asm volatile("s_waitcnt lgkmcnt(" #n ")" ::: "memory")
; #define PG8_BAR __builtin_amdgcn_s_barrier()
; #define PG8_SCHED __builtin_amdgcn_sched_barrier(0)
; template <class Epi, class Sched>
; __device__ __forceinline__ void gemm_phase(LAS unsigned char* lds, const Gemm g, const Sched& S, const Epi& E) {
;     ...
;             PG8_STAGE(PG8_SB(0, 1), b2 + hstep, voffB);
;             PG8_WAIT_V(6); PG8_BAR; PG8_MMA(1, 1, At, B1); PG8_BAR;
;             PG8_LDB(B0, 1, 0); PG8_SCHED; PG8_LDA(At, 1, 0); PG8_STAGE(PG8_SA(0, 1), a2 + hstep, voffA);
;             PG8_WAIT_L(8); PG8_BAR; PG8_WAIT_L(0); PG8_MMA(0, 0, At, B0); PG8_BAR; PG8_SCHED;
;             PG8_LDB(B1, 1, 1); PG8_STAGE(PG8_SB(1, 0), b3, voffB);
;             PG8_BAR; PG8_WAIT_L(0); PG8_MMA(0, 1, At, B1); PG8_BAR;
;             PG8_LDA(At, 1, 1); PG8_STAGE(PG8_SA(1, 0), a3, voffA);
;             PG8_BAR; PG8_WAIT_L(0); PG8_MMA(1, 0, At, B0); PG8_BAR; PG8_SCHED;
	s_add_u32 s64, s36, 0x4000
	s_addc_u32 s65, s37, 0
	s_add_i32 s66, s58, s46
	v_lshl_add_u64 v[154:155], s[64:65], 0, v[132:133]
	s_mov_b32 m0, s66
	s_nop 0
	global_load_lds_dwordx4 v[154:155], off
	v_lshl_add_u64 v[154:155], s[64:65], 0, v[128:129]
	s_add_i32 m0, s66, 0x2000
	s_nop 0
	global_load_lds_dwordx4 v[154:155], off
	s_waitcnt vmcnt(6)
	s_barrier
	v_mfma_f32_16x16x32_bf16 v[52:55], v[210:213], v[174:177], v[52:55]
	v_mfma_f32_16x16x32_bf16 v[48:51], v[218:221], v[174:177], v[48:51]
	v_mfma_f32_16x16x32_bf16 v[36:39], v[210:213], v[182:185], v[36:39]
	v_mfma_f32_16x16x32_bf16 v[32:35], v[218:221], v[182:185], v[32:35]
	v_mfma_f32_16x16x32_bf16 v[20:23], v[210:213], v[190:193], v[20:23]
	v_mfma_f32_16x16x32_bf16 v[16:19], v[218:221], v[190:193], v[16:19]
	v_mfma_f32_16x16x32_bf16 v[4:7], v[210:213], v[198:201], v[4:7]
	v_mfma_f32_16x16x32_bf16 v[0:3], v[218:221], v[198:201], v[0:3]
	v_mfma_f32_16x16x32_bf16 v[52:55], v[214:217], v[178:181], v[52:55]
	v_mfma_f32_16x16x32_bf16 v[48:51], v[222:225], v[178:181], v[48:51]
	v_mfma_f32_16x16x32_bf16 v[36:39], v[214:217], v[186:189], v[36:39]
	v_mfma_f32_16x16x32_bf16 v[32:35], v[222:225], v[186:189], v[32:35]
	v_mfma_f32_16x16x32_bf16 v[20:23], v[214:217], v[194:197], v[20:23]
	v_mfma_f32_16x16x32_bf16 v[16:19], v[222:225], v[194:197], v[16:19]
	v_mfma_f32_16x16x32_bf16 v[4:7], v[214:217], v[206:209], v[4:7]
	v_mfma_f32_16x16x32_bf16 v[0:3], v[222:225], v[206:209], v[0:3]
	s_add_i32 s64, 0, 0x18000
	v_add_u32_e32 v136, s64, v149
	s_barrier
	ds_read_b128 v[154:157], v136
	ds_read_b128 v[158:161], v136 offset:1024
	ds_read_b128 v[162:165], v136 offset:2048
	ds_read_b128 v[170:173], v136 offset:3072
	s_add_u32 s40, s40, 0x4000
	s_addc_u32 s41, s41, 0
	s_mov_b32 m0, s50
	v_lshl_add_u64 v[166:167], s[40:41], 0, v[134:135]
	ds_read_b128 v[174:177], v151 offset:32768
	ds_read_b128 v[178:181], v151 offset:33792
	ds_read_b128 v[182:185], v151 offset:34816
	ds_read_b128 v[186:189], v151 offset:35840
	ds_read_b128 v[190:193], v151 offset:36864
	ds_read_b128 v[194:197], v151 offset:37888
	ds_read_b128 v[198:201], v151 offset:38912
	ds_read_b128 v[206:209], v151 offset:39936
	global_load_lds_dwordx4 v[166:167], off
	v_lshl_add_u64 v[166:167], s[40:41], 0, v[130:131]
	s_mov_b32 m0, s51
	s_nop 0
	global_load_lds_dwordx4 v[166:167], off
	s_waitcnt lgkmcnt(8)
	s_barrier
	s_waitcnt lgkmcnt(0)
	v_mfma_f32_16x16x32_bf16 v[124:127], v[154:157], v[174:177], v[124:127]
	v_mfma_f32_16x16x32_bf16 v[120:123], v[162:165], v[174:177], v[120:123]
	v_mfma_f32_16x16x32_bf16 v[108:111], v[154:157], v[182:185], v[108:111]
	v_mfma_f32_16x16x32_bf16 v[104:107], v[162:165], v[182:185], v[104:107]
	v_mfma_f32_16x16x32_bf16 v[92:95], v[154:157], v[190:193], v[92:95]
	v_mfma_f32_16x16x32_bf16 v[88:91], v[162:165], v[190:193], v[88:91]
	v_mfma_f32_16x16x32_bf16 v[76:79], v[154:157], v[198:201], v[76:79]
	v_mfma_f32_16x16x32_bf16 v[72:75], v[162:165], v[198:201], v[72:75]
	v_mfma_f32_16x16x32_bf16 v[124:127], v[158:161], v[178:181], v[124:127]
	v_mfma_f32_16x16x32_bf16 v[120:123], v[170:173], v[178:181], v[120:123]
	v_mfma_f32_16x16x32_bf16 v[108:111], v[158:161], v[186:189], v[108:111]
	v_mfma_f32_16x16x32_bf16 v[104:107], v[170:173], v[186:189], v[104:107]
	v_mfma_f32_16x16x32_bf16 v[92:95], v[158:161], v[194:197], v[92:95]
	v_mfma_f32_16x16x32_bf16 v[88:91], v[170:173], v[194:197], v[88:91]
	v_mfma_f32_16x16x32_bf16 v[76:79], v[158:161], v[206:209], v[76:79]
	v_mfma_f32_16x16x32_bf16 v[72:75], v[170:173], v[206:209], v[72:75]
	s_barrier
	s_add_i32 s65, 0, 0x1c000
	s_add_u32 s40, s36, 0x8000
	s_addc_u32 s41, s37, 0
	s_add_i32 s64, s64, s46
	v_add_u32_e32 v136, s65, v149
	v_lshl_add_u64 v[166:167], s[40:41], 0, v[132:133]
	s_mov_b32 m0, s64
	ds_read_b128 v[210:213], v136
	ds_read_b128 v[214:217], v136 offset:1024
	ds_read_b128 v[218:221], v136 offset:2048
	ds_read_b128 v[222:225], v136 offset:3072
	global_load_lds_dwordx4 v[166:167], off
	v_lshl_add_u64 v[166:167], s[40:41], 0, v[128:129]
	s_add_i32 m0, s64, 0x2000
	s_nop 0
	global_load_lds_dwordx4 v[166:167], off
	s_barrier
	s_waitcnt lgkmcnt(0)
	v_mfma_f32_16x16x32_bf16 v[116:119], v[210:213], v[174:177], v[116:119]
	v_mfma_f32_16x16x32_bf16 v[112:115], v[218:221], v[174:177], v[112:115]
	v_mfma_f32_16x16x32_bf16 v[100:103], v[210:213], v[182:185], v[100:103]
	v_mfma_f32_16x16x32_bf16 v[96:99], v[218:221], v[182:185], v[96:99]
	v_mfma_f32_16x16x32_bf16 v[84:87], v[210:213], v[190:193], v[84:87]
	v_mfma_f32_16x16x32_bf16 v[80:83], v[218:221], v[190:193], v[80:83]
	v_mfma_f32_16x16x32_bf16 v[68:71], v[210:213], v[198:201], v[68:71]
	v_mfma_f32_16x16x32_bf16 v[64:67], v[218:221], v[198:201], v[64:67]
	v_mfma_f32_16x16x32_bf16 v[116:119], v[214:217], v[178:181], v[116:119]
	v_mfma_f32_16x16x32_bf16 v[112:115], v[222:225], v[178:181], v[112:115]
	v_mfma_f32_16x16x32_bf16 v[100:103], v[214:217], v[186:189], v[100:103]
	v_mfma_f32_16x16x32_bf16 v[96:99], v[222:225], v[186:189], v[96:99]
	v_mfma_f32_16x16x32_bf16 v[84:87], v[214:217], v[194:197], v[84:87]
	v_mfma_f32_16x16x32_bf16 v[80:83], v[222:225], v[194:197], v[80:83]
	v_mfma_f32_16x16x32_bf16 v[68:71], v[214:217], v[206:209], v[68:71]
	v_mfma_f32_16x16x32_bf16 v[64:67], v[222:225], v[206:209], v[64:67]
	s_mov_b32 m0, s55
	v_lshl_add_u64 v[166:167], s[38:39], 0, v[134:135]
	s_barrier
	ds_read_b128 v[174:177], v151 offset:49152
	ds_read_b128 v[178:181], v151 offset:50176
	ds_read_b128 v[182:185], v151 offset:51200
	ds_read_b128 v[186:189], v151 offset:52224
	ds_read_b128 v[190:193], v151 offset:53248
	ds_read_b128 v[194:197], v151 offset:54272
	ds_read_b128 v[198:201], v151 offset:55296
	ds_read_b128 v[206:209], v151 offset:56320
	global_load_lds_dwordx4 v[166:167], off
	v_lshl_add_u64 v[166:167], s[38:39], 0, v[130:131]
	s_mov_b32 m0, s56
	s_nop 0
	global_load_lds_dwordx4 v[166:167], off
	s_barrier
; __device__ __forceinline__ unsigned cvt_pk_bf16(float lo, float hi) { f32x2 v = {lo, hi}; bf16x2_t b = __builtin_convertvector(v, bf16x2_t); return __builtin_bit_cast(unsigned, b); }
; __device__ __forceinline__ float sigmoid_f(float x) { return __builtin_amdgcn_rcpf(1.0f + __expf(-x)); }
; __device__ __forceinline__ float silu_f(float x) { return x * sigmoid_f(x); }
; __device__ __forceinline__ size_t tl(int r, int c, int K) { return ((size_t)(r >> 8) * (size_t)(K >> 6) + (size_t)(c >> 6)) * 16384 + (size_t)((r & 255) << 6) + (size_t)(c & 63); }
; #define PG8_STAGE(bufoff, gbase, voff) do { _Pragma("unroll") for (int _i = 0; _i < 2; ++_i) \
;         __builtin_amdgcn_global_load_lds((const unsigned*)((const char*)(gbase) + (voff)[_i]), (LAS unsigned*)(lds + (bufoff) + ldsw + _i * 8192), 16, 0, 0); } while (0)
; #define PG8_WAIT_V(n) asm volatile("s_waitcnt vmcnt(" #n ")" ::: "memory")
; #define PG8_WAIT_L(n) asm volatile("s_waitcnt lgkmcnt(" #n ")" ::: "memory")
; #define PG8_BAR __builtin_amdgcn_s_barrier()
; template <class Epi, class Sched>
; __device__ __forceinline__ void gemm_phase(LAS unsigned char* lds, const Gemm g, const Sched& S, const Epi& E) {
;     ...
;             PG8_BAR; PG8_WAIT_L(0); PG8_MMA(1, 0, At, B0); PG8_BAR; PG8_SCHED;
;             PG8_STAGE(PG8_SB(1, 1), b3 + hstep, voffB);
;             PG8_WAIT_V(6); PG8_BAR; PG8_MMA(1, 1, At, B1); PG8_BAR;
;     __device__ __forceinline__ void operator()(const f32x4 (&acc)[2][2][4][2], const Unit& u, int wr, int wc, int fr, int fq) const {
;         const int row0 = u.pm * BM + wr * 64 + fr, col0 = u.pn * 128 + wc * 32 + 8 * fq;
; #pragma unroll
;         for (int ai = 0; ai < 2; ++ai)
; #pragma unroll
;             for (int m = 0; m < 4; ++m) {
;                 bf16_t* rowp = MODE == 0 ? O + tl(row0 + ai * HALF + m * 16, col0, ldo) : O + (size_t)(row0 + ai * HALF + m * 16) * ldo + col0;
;                 float v[8];
; #pragma unroll
;                 for (int n = 0; n < 2; ++n)
; #pragma unroll
;                     for (int j = 0; j < 4; ++j) { const float a = acc[ai][0][m][n][j], b = acc[ai][1][m][n][j]; v[n * 4 + j] = MODE == 0 ? silu_f(a) * b : a * sigmoid_f(b); }
;                 u32x4 w; w.x = cvt_pk_bf16(v[0], v[1]); w.y = cvt_pk_bf16(v[2], v[3]); w.z = cvt_pk_bf16(v[4], v[5]); w.w = cvt_pk_bf16(v[6], v[7]);
;                 *(u32x4*)rowp = w;
	s_waitcnt lgkmcnt(0)
	v_mfma_f32_16x16x32_bf16 v[60:63], v[154:157], v[174:177], v[60:63]
	v_mfma_f32_16x16x32_bf16 v[56:59], v[162:165], v[174:177], v[56:59]
	v_mfma_f32_16x16x32_bf16 v[44:47], v[154:157], v[182:185], v[44:47]
	v_mfma_f32_16x16x32_bf16 v[40:43], v[162:165], v[182:185], v[40:43]
	v_mfma_f32_16x16x32_bf16 v[28:31], v[154:157], v[190:193], v[28:31]
	v_mfma_f32_16x16x32_bf16 v[24:27], v[162:165], v[190:193], v[24:27]
	v_mfma_f32_16x16x32_bf16 v[12:15], v[154:157], v[198:201], v[12:15]
	v_mfma_f32_16x16x32_bf16 v[8:11], v[162:165], v[198:201], v[8:11]
	v_mfma_f32_16x16x32_bf16 v[60:63], v[158:161], v[178:181], v[60:63]
	v_mfma_f32_16x16x32_bf16 v[56:59], v[170:173], v[178:181], v[56:59]
	v_mfma_f32_16x16x32_bf16 v[44:47], v[158:161], v[186:189], v[44:47]
	v_mfma_f32_16x16x32_bf16 v[40:43], v[170:173], v[186:189], v[40:43]
	v_mfma_f32_16x16x32_bf16 v[28:31], v[158:161], v[194:197], v[28:31]
	v_mfma_f32_16x16x32_bf16 v[24:27], v[170:173], v[194:197], v[24:27]
	v_mfma_f32_16x16x32_bf16 v[12:15], v[158:161], v[206:209], v[12:15]
	v_mfma_f32_16x16x32_bf16 v[8:11], v[170:173], v[206:209], v[8:11]
	s_barrier
	s_add_u32 s36, s36, 0xc000
	s_addc_u32 s37, s37, 0
	s_add_i32 s38, s65, s46
	v_lshl_add_u64 v[154:155], s[36:37], 0, v[132:133]
	s_mov_b32 m0, s38
	s_nop 0
	global_load_lds_dwordx4 v[154:155], off
	v_lshl_add_u64 v[154:155], s[36:37], 0, v[128:129]
	s_add_i32 m0, s38, 0x2000
	s_nop 0
	global_load_lds_dwordx4 v[154:155], off
	s_waitcnt vmcnt(6)
	s_barrier
	v_mfma_f32_16x16x32_bf16 v[52:55], v[210:213], v[174:177], v[52:55]
	v_mfma_f32_16x16x32_bf16 v[48:51], v[218:221], v[174:177], v[48:51]
	v_mfma_f32_16x16x32_bf16 v[36:39], v[210:213], v[182:185], v[36:39]
	v_mfma_f32_16x16x32_bf16 v[32:35], v[218:221], v[182:185], v[32:35]
	v_mfma_f32_16x16x32_bf16 v[20:23], v[210:213], v[190:193], v[20:23]
	v_mfma_f32_16x16x32_bf16 v[16:19], v[218:221], v[190:193], v[16:19]
	v_mfma_f32_16x16x32_bf16 v[4:7], v[210:213], v[198:201], v[4:7]
	v_mfma_f32_16x16x32_bf16 v[0:3], v[218:221], v[198:201], v[0:3]
	v_mfma_f32_16x16x32_bf16 v[52:55], v[214:217], v[178:181], v[52:55]
	v_mfma_f32_16x16x32_bf16 v[48:51], v[222:225], v[178:181], v[48:51]
	v_mfma_f32_16x16x32_bf16 v[36:39], v[214:217], v[186:189], v[36:39]
	v_mfma_f32_16x16x32_bf16 v[32:35], v[222:225], v[186:189], v[32:35]
	v_mfma_f32_16x16x32_bf16 v[20:23], v[214:217], v[194:197], v[20:23]
	v_mfma_f32_16x16x32_bf16 v[16:19], v[222:225], v[194:197], v[16:19]
	v_mfma_f32_16x16x32_bf16 v[4:7], v[214:217], v[206:209], v[4:7]
	v_mfma_f32_16x16x32_bf16 v[0:3], v[222:225], v[206:209], v[0:3]
	s_add_i32 s63, s63, 2
	s_add_u32 s28, s28, 0x10000
	s_addc_u32 s29, s29, 0
	s_add_u32 s61, s61, 0x10000
	s_addc_u32 s62, s62, 0
	s_cmp_gt_u32 s63, 29
	s_barrier
	s_cbranch_scc0 .LBB0_135
	s_lshl_b32 s11, s18, 8
	s_add_i32 s11, s11, s53
	s_lshl_b32 s13, s19, 7
	v_mul_f32_e32 v136, 0xbfb8aa3b, v124
	v_or_b32_e32 v153, s11, v148
	s_or_b32 s13, s13, s54
	s_ashr_i32 s11, s11, 8
	v_exp_f32_e32 v136, v136
	v_mul_f32_e32 v147, 0xbfb8aa3b, v125
	s_ashr_i32 s18, s13, 6
	s_mulk_i32 s11, 0x56
	v_exp_f32_e32 v147, v147
	s_ashr_i32 s19, s18, 31
	s_ashr_i32 s13, s11, 31
	s_add_u32 s28, s11, s18
	s_addc_u32 s29, s13, s19
	v_add_f32_e32 v136, 1.0, v136
	s_lshl_b64 s[28:29], s[28:29], 15
	v_rcp_f32_e32 v154, v136
	v_add_f32_e32 v136, 1.0, v147
	s_add_u32 s28, s8, s28
	v_rcp_f32_e32 v155, v136
	v_lshlrev_b32_e32 v136, 7, v153
	s_addc_u32 s29, s9, s29
	v_and_b32_e32 v136, 0x6780, v136
	v_lshl_add_u64 v[156:157], s[28:29], 0, v[136:137]
	v_mul_f32_e32 v136, 0xbfb8aa3b, v126
	v_mul_f32_e32 v147, 0xbfb8aa3b, v127
	v_exp_f32_e32 v136, v136
	v_exp_f32_e32 v147, v147
	v_pk_mul_f32 v[124:125], v[124:125], v[154:155]
	s_mov_b64 s[36:37], s[16:17]
	v_pk_mul_f32 v[116:117], v[124:125], v[116:117]
	v_add_f32_e32 v124, 1.0, v136
	v_add_f32_e32 v125, 1.0, v147
	v_mul_f32_e32 v136, 0xbfb8aa3b, v120
	v_rcp_f32_e32 v124, v124
	v_rcp_f32_e32 v125, v125
	v_exp_f32_e32 v136, v136
	v_mul_f32_e32 v147, 0xbfb8aa3b, v121
	v_exp_f32_e32 v147, v147
	v_pk_mul_f32 v[124:125], v[126:127], v[124:125]
	v_add_f32_e32 v126, 1.0, v136
	v_mul_f32_e32 v136, 0xbfb8aa3b, v122
	v_add_f32_e32 v127, 1.0, v147
	v_exp_f32_e32 v136, v136
	v_mul_f32_e32 v147, 0xbfb8aa3b, v123
	v_exp_f32_e32 v147, v147
	v_rcp_f32_e32 v126, v126
	v_add_f32_e32 v136, 1.0, v136
	v_rcp_f32_e32 v127, v127
	v_rcp_f32_e32 v154, v136
	v_add_f32_e32 v136, 1.0, v147
	v_rcp_f32_e32 v155, v136
	v_pk_mul_f32 v[120:121], v[120:121], v[126:127]
	v_pk_mul_f32 v[118:119], v[124:125], v[118:119]
	v_pk_mul_f32 v[120:121], v[120:121], v[112:113]
	v_pk_mul_f32 v[112:113], v[122:123], v[154:155]
	v_mov_b32_e32 v147, v137
	v_pk_mul_f32 v[122:123], v[112:113], v[114:115]
	v_mul_f32_e32 v113, 0xbfb8aa3b, v108
	v_exp_f32_e32 v114, v113
	v_mul_f32_e32 v113, 0xbfb8aa3b, v109
	v_exp_f32_e32 v115, v113
	v_cvt_pk_bf16_f32 v112, v116, v117
	v_add_f32_e32 v114, 1.0, v114
	v_rcp_f32_e32 v116, v114
	v_add_f32_e32 v114, 1.0, v115
	v_lshl_add_u64 v[124:125], v[156:157], 0, v[146:147]
	v_cvt_pk_bf16_f32 v113, v118, v119
	v_rcp_f32_e32 v117, v114
	v_cvt_pk_bf16_f32 v114, v120, v121
	v_cvt_pk_bf16_f32 v115, v122, v123
	global_store_dwordx4 v[124:125], v[112:115], off
	v_pk_mul_f32 v[108:109], v[108:109], v[116:117]
	s_mov_b64 s[28:29], s[14:15]
	v_mul_f32_e32 v112, 0xbfb8aa3b, v110
	v_mul_f32_e32 v113, 0xbfb8aa3b, v111
	v_exp_f32_e32 v112, v112
	v_exp_f32_e32 v113, v113
	v_pk_mul_f32 v[100:101], v[108:109], v[100:101]
	v_add_f32_e32 v108, 1.0, v112
	v_add_f32_e32 v109, 1.0, v113
	v_mul_f32_e32 v112, 0xbfb8aa3b, v104
	v_mul_f32_e32 v113, 0xbfb8aa3b, v105
	v_rcp_f32_e32 v108, v108
	v_rcp_f32_e32 v109, v109
	v_exp_f32_e32 v112, v112
; __device__ __forceinline__ unsigned cvt_pk_bf16(float lo, float hi) { f32x2 v = {lo, hi}; bf16x2_t b = __builtin_convertvector(v, bf16x2_t); return __builtin_bit_cast(unsigned, b); }
; __device__ __forceinline__ float sigmoid_f(float x) { return __builtin_amdgcn_rcpf(1.0f + __expf(-x)); }
; __device__ __forceinline__ float silu_f(float x) { return x * sigmoid_f(x); }
; __device__ __forceinline__ size_t tl(int r, int c, int K) { return ((size_t)(r >> 8) * (size_t)(K >> 6) + (size_t)(c >> 6)) * 16384 + (size_t)((r & 255) << 6) + (size_t)(c & 63); }
;     __device__ __forceinline__ void operator()(const f32x4 (&acc)[2][2][4][2], const Unit& u, int wr, int wc, int fr, int fq) const {
;         const int row0 = u.pm * BM + wr * 64 + fr, col0 = u.pn * 128 + wc * 32 + 8 * fq;
; #pragma unroll
;         for (int ai = 0; ai < 2; ++ai)
; #pragma unroll
;             for (int m = 0; m < 4; ++m) {
;                 bf16_t* rowp = MODE == 0 ? O + tl(row0 + ai * HALF + m * 16, col0, ldo) : O + (size_t)(row0 + ai * HALF + m * 16) * ldo + col0;
;                 float v[8];
; #pragma unroll
;                 for (int n = 0; n < 2; ++n)
; #pragma unroll
;                     for (int j = 0; j < 4; ++j) { const float a = acc[ai][0][m][n][j], b = acc[ai][1][m][n][j]; v[n * 4 + j] = MODE == 0 ? silu_f(a) * b : a * sigmoid_f(b); }
;                 u32x4 w; w.x = cvt_pk_bf16(v[0], v[1]); w.y = cvt_pk_bf16(v[2], v[3]); w.z = cvt_pk_bf16(v[4], v[5]); w.w = cvt_pk_bf16(v[6], v[7]);
;                 *(u32x4*)rowp = w;
	v_exp_f32_e32 v113, v113
	v_pk_mul_f32 v[108:109], v[110:111], v[108:109]
	v_add_f32_e32 v110, 1.0, v112
	v_add_f32_e32 v111, 1.0, v113
	v_mul_f32_e32 v112, 0xbfb8aa3b, v106
	v_mul_f32_e32 v113, 0xbfb8aa3b, v107
	v_exp_f32_e32 v112, v112
	v_exp_f32_e32 v113, v113
	v_rcp_f32_e32 v110, v110
	v_rcp_f32_e32 v111, v111
	v_add_f32_e32 v112, 1.0, v112
	v_add_f32_e32 v113, 1.0, v113
	v_rcp_f32_e32 v112, v112
	v_rcp_f32_e32 v113, v113
	v_pk_mul_f32 v[104:105], v[104:105], v[110:111]
	v_pk_mul_f32 v[102:103], v[108:109], v[102:103]
	v_pk_mul_f32 v[104:105], v[104:105], v[96:97]
	v_pk_mul_f32 v[96:97], v[106:107], v[112:113]
	s_nop 0
	v_pk_mul_f32 v[106:107], v[96:97], v[98:99]
	v_mul_f32_e32 v97, 0xbfb8aa3b, v92
	v_exp_f32_e32 v98, v97
	v_mul_f32_e32 v97, 0xbfb8aa3b, v93
	v_exp_f32_e32 v99, v97
	v_cvt_pk_bf16_f32 v96, v100, v101
	v_add_f32_e32 v98, 1.0, v98
	v_rcp_f32_e32 v100, v98
	v_add_f32_e32 v98, 1.0, v99
	v_cvt_pk_bf16_f32 v97, v102, v103
	v_rcp_f32_e32 v101, v98
	v_cvt_pk_bf16_f32 v98, v104, v105
	v_cvt_pk_bf16_f32 v99, v106, v107
	global_store_dwordx4 v[124:125], v[96:99], off offset:2048
	v_pk_mul_f32 v[92:93], v[92:93], v[100:101]
	s_nop 0
	v_mul_f32_e32 v96, 0xbfb8aa3b, v94
	v_mul_f32_e32 v97, 0xbfb8aa3b, v95
	v_exp_f32_e32 v96, v96
	v_exp_f32_e32 v97, v97
	v_pk_mul_f32 v[84:85], v[92:93], v[84:85]
	v_add_f32_e32 v92, 1.0, v96
	v_add_f32_e32 v93, 1.0, v97
	v_mul_f32_e32 v96, 0xbfb8aa3b, v88
	v_mul_f32_e32 v97, 0xbfb8aa3b, v89
	v_rcp_f32_e32 v92, v92
	v_rcp_f32_e32 v93, v93
	v_exp_f32_e32 v96, v96
	v_exp_f32_e32 v97, v97
	v_pk_mul_f32 v[92:93], v[94:95], v[92:93]
	v_add_f32_e32 v94, 1.0, v96
	v_add_f32_e32 v95, 1.0, v97
	v_mul_f32_e32 v96, 0xbfb8aa3b, v90
	v_mul_f32_e32 v97, 0xbfb8aa3b, v91
	v_exp_f32_e32 v96, v96
	v_exp_f32_e32 v97, v97
	v_rcp_f32_e32 v94, v94
	v_rcp_f32_e32 v95, v95
	v_add_f32_e32 v96, 1.0, v96
	v_add_f32_e32 v97, 1.0, v97
	v_rcp_f32_e32 v96, v96
	v_rcp_f32_e32 v97, v97
	v_pk_mul_f32 v[88:89], v[88:89], v[94:95]
	v_pk_mul_f32 v[86:87], v[92:93], v[86:87]
	v_pk_mul_f32 v[88:89], v[88:89], v[80:81]
	v_pk_mul_f32 v[80:81], v[90:91], v[96:97]
	s_nop 0
	v_pk_mul_f32 v[90:91], v[80:81], v[82:83]
	v_mul_f32_e32 v83, 0xbfb8aa3b, v76
	v_cvt_pk_bf16_f32 v80, v84, v85
	v_exp_f32_e32 v84, v83
	v_mul_f32_e32 v83, 0xbfb8aa3b, v77
	v_exp_f32_e32 v85, v83
	v_cvt_pk_bf16_f32 v81, v86, v87
	v_add_co_u32_e32 v86, vcc, s59, v124
	v_cvt_pk_bf16_f32 v82, v88, v89
	v_cvt_pk_bf16_f32 v83, v90, v91
	v_add_f32_e32 v84, 1.0, v84
	v_add_f32_e32 v85, 1.0, v85
	v_addc_co_u32_e32 v87, vcc, 0, v125, vcc
	v_rcp_f32_e32 v84, v84
	v_rcp_f32_e32 v85, v85
	global_store_dwordx4 v[86:87], v[80:83], off
	v_pk_mul_f32 v[76:77], v[76:77], v[84:85]
	s_nop 0
	v_mul_f32_e32 v80, 0xbfb8aa3b, v78
	v_mul_f32_e32 v81, 0xbfb8aa3b, v79
	v_exp_f32_e32 v80, v80
	v_exp_f32_e32 v81, v81
	v_pk_mul_f32 v[68:69], v[76:77], v[68:69]
	v_add_f32_e32 v76, 1.0, v80
	v_add_f32_e32 v77, 1.0, v81
	v_mul_f32_e32 v80, 0xbfb8aa3b, v72
	v_mul_f32_e32 v81, 0xbfb8aa3b, v73
	v_rcp_f32_e32 v76, v76
	v_rcp_f32_e32 v77, v77
	v_exp_f32_e32 v80, v80
	v_exp_f32_e32 v81, v81
	v_pk_mul_f32 v[76:77], v[78:79], v[76:77]
	v_add_f32_e32 v78, 1.0, v80
	v_add_f32_e32 v79, 1.0, v81
	v_mul_f32_e32 v80, 0xbfb8aa3b, v74
	v_mul_f32_e32 v81, 0xbfb8aa3b, v75
	v_exp_f32_e32 v80, v80
	v_exp_f32_e32 v81, v81
	v_rcp_f32_e32 v78, v78
	v_rcp_f32_e32 v79, v79
	v_add_f32_e32 v80, 1.0, v80
	v_add_f32_e32 v81, 1.0, v81
	v_rcp_f32_e32 v80, v80
	v_rcp_f32_e32 v81, v81
	v_pk_mul_f32 v[72:73], v[72:73], v[78:79]
	v_pk_mul_f32 v[70:71], v[76:77], v[70:71]
	v_pk_mul_f32 v[72:73], v[72:73], v[64:65]
	v_pk_mul_f32 v[64:65], v[74:75], v[80:81]
	s_nop 0
	v_pk_mul_f32 v[74:75], v[64:65], v[66:67]
	v_cvt_pk_bf16_f32 v64, v68, v69
	v_cvt_pk_bf16_f32 v65, v70, v71
	v_cvt_pk_bf16_f32 v66, v72, v73
	v_cvt_pk_bf16_f32 v67, v74, v75
	global_store_dwordx4 v[86:87], v[64:67], off offset:2048
	v_add_u32_e32 v68, 0x80, v153
	s_nop 0
	v_mul_f32_e32 v66, 0xbfb8aa3b, v60
	v_mul_f32_e32 v67, 0xbfb8aa3b, v61
	v_exp_f32_e32 v66, v66
	v_exp_f32_e32 v67, v67
	v_lshrrev_b32_e32 v64, 8, v68
	v_mul_i32_i24_e32 v64, 0x56, v64
	v_add_f32_e32 v66, 1.0, v66
	v_add_f32_e32 v67, 1.0, v67
	v_rcp_f32_e32 v66, v66
	v_rcp_f32_e32 v67, v67
	v_ashrrev_i32_e32 v65, 31, v64
	v_lshl_add_u64 v[64:65], v[64:65], 0, s[18:19]
	v_lshlrev_b64 v[64:65], 15, v[64:65]
	v_pk_mul_f32 v[60:61], v[60:61], v[66:67]
	v_mul_f32_e32 v66, 0xbfb8aa3b, v62
	v_mul_f32_e32 v67, 0xbfb8aa3b, v63
	v_exp_f32_e32 v66, v66
	v_exp_f32_e32 v67, v67
	v_pk_mul_f32 v[52:53], v[60:61], v[52:53]
	v_lshlrev_b32_e32 v68, 7, v68
	v_add_f32_e32 v60, 1.0, v66
	v_add_f32_e32 v61, 1.0, v67
	v_mul_f32_e32 v66, 0xbfb8aa3b, v56
	v_mul_f32_e32 v67, 0xbfb8aa3b, v57
	v_rcp_f32_e32 v60, v60
	v_rcp_f32_e32 v61, v61
	v_exp_f32_e32 v66, v66
	v_exp_f32_e32 v67, v67
	v_lshl_add_u64 v[64:65], s[8:9], 0, v[64:65]
	v_pk_mul_f32 v[60:61], v[62:63], v[60:61]
	v_add_f32_e32 v62, 1.0, v66
	v_add_f32_e32 v63, 1.0, v67
	v_mul_f32_e32 v66, 0xbfb8aa3b, v58
	v_mul_f32_e32 v67, 0xbfb8aa3b, v59
	v_exp_f32_e32 v66, v66
	v_exp_f32_e32 v67, v67
	v_rcp_f32_e32 v62, v62
	v_rcp_f32_e32 v63, v63
	v_add_f32_e32 v66, 1.0, v66
	v_add_f32_e32 v67, 1.0, v67
; __device__ __forceinline__ unsigned cvt_pk_bf16(float lo, float hi) { f32x2 v = {lo, hi}; bf16x2_t b = __builtin_convertvector(v, bf16x2_t); return __builtin_bit_cast(unsigned, b); }
; __device__ __forceinline__ float sigmoid_f(float x) { return __builtin_amdgcn_rcpf(1.0f + __expf(-x)); }
; __device__ __forceinline__ float silu_f(float x) { return x * sigmoid_f(x); }
; __device__ __forceinline__ size_t tl(int r, int c, int K) { return ((size_t)(r >> 8) * (size_t)(K >> 6) + (size_t)(c >> 6)) * 16384 + (size_t)((r & 255) << 6) + (size_t)(c & 63); }
;     __device__ __forceinline__ void operator()(const f32x4 (&acc)[2][2][4][2], const Unit& u, int wr, int wc, int fr, int fq) const {
;         const int row0 = u.pm * BM + wr * 64 + fr, col0 = u.pn * 128 + wc * 32 + 8 * fq;
; #pragma unroll
;         for (int ai = 0; ai < 2; ++ai)
; #pragma unroll
;             for (int m = 0; m < 4; ++m) {
;                 bf16_t* rowp = MODE == 0 ? O + tl(row0 + ai * HALF + m * 16, col0, ldo) : O + (size_t)(row0 + ai * HALF + m * 16) * ldo + col0;
;                 float v[8];
; #pragma unroll
;                 for (int n = 0; n < 2; ++n)
; #pragma unroll
;                     for (int j = 0; j < 4; ++j) { const float a = acc[ai][0][m][n][j], b = acc[ai][1][m][n][j]; v[n * 4 + j] = MODE == 0 ? silu_f(a) * b : a * sigmoid_f(b); }
;                 u32x4 w; w.x = cvt_pk_bf16(v[0], v[1]); w.y = cvt_pk_bf16(v[2], v[3]); w.z = cvt_pk_bf16(v[4], v[5]); w.w = cvt_pk_bf16(v[6], v[7]);
;                 *(u32x4*)rowp = w;
	v_rcp_f32_e32 v66, v66
	v_rcp_f32_e32 v67, v67
	v_pk_mul_f32 v[56:57], v[56:57], v[62:63]
	v_and_b32_e32 v136, 0x6780, v68
	v_pk_mul_f32 v[56:57], v[56:57], v[48:49]
	v_pk_mul_f32 v[48:49], v[58:59], v[66:67]
	v_lshl_add_u64 v[64:65], v[64:65], 0, v[136:137]
	v_pk_mul_f32 v[58:59], v[48:49], v[50:51]
	v_mul_f32_e32 v49, 0xbfb8aa3b, v44
	v_exp_f32_e32 v50, v49
	v_mul_f32_e32 v49, 0xbfb8aa3b, v45
	v_exp_f32_e32 v51, v49
	v_pk_mul_f32 v[54:55], v[60:61], v[54:55]
	v_add_f32_e32 v50, 1.0, v50
	v_cvt_pk_bf16_f32 v48, v52, v53
	v_rcp_f32_e32 v52, v50
	v_add_f32_e32 v50, 1.0, v51
	v_lshl_add_u64 v[60:61], v[64:65], 0, v[146:147]
	v_cvt_pk_bf16_f32 v49, v54, v55
	v_rcp_f32_e32 v53, v50
	v_cvt_pk_bf16_f32 v50, v56, v57
	v_cvt_pk_bf16_f32 v51, v58, v59
	global_store_dwordx4 v[60:61], v[48:51], off
	v_pk_mul_f32 v[44:45], v[44:45], v[52:53]
	s_mov_b32 s19, s10
	v_mul_f32_e32 v48, 0xbfb8aa3b, v46
	v_mul_f32_e32 v49, 0xbfb8aa3b, v47
	v_exp_f32_e32 v48, v48
	v_exp_f32_e32 v49, v49
	v_pk_mul_f32 v[36:37], v[44:45], v[36:37]
	s_mov_b32 s18, s12
	v_add_f32_e32 v44, 1.0, v48
	v_add_f32_e32 v45, 1.0, v49
	v_mul_f32_e32 v48, 0xbfb8aa3b, v40
	v_mul_f32_e32 v49, 0xbfb8aa3b, v41
	v_rcp_f32_e32 v44, v44
	v_rcp_f32_e32 v45, v45
	v_exp_f32_e32 v48, v48
	v_exp_f32_e32 v49, v49
	v_pk_mul_f32 v[44:45], v[46:47], v[44:45]
	v_add_f32_e32 v46, 1.0, v48
	v_add_f32_e32 v47, 1.0, v49
	v_mul_f32_e32 v48, 0xbfb8aa3b, v42
	v_mul_f32_e32 v49, 0xbfb8aa3b, v43
	v_exp_f32_e32 v48, v48
	v_exp_f32_e32 v49, v49
	v_rcp_f32_e32 v46, v46
	v_rcp_f32_e32 v47, v47
	v_add_f32_e32 v48, 1.0, v48
	v_add_f32_e32 v49, 1.0, v49
	v_rcp_f32_e32 v48, v48
	v_rcp_f32_e32 v49, v49
	v_pk_mul_f32 v[40:41], v[40:41], v[46:47]
	v_pk_mul_f32 v[38:39], v[44:45], v[38:39]
	v_pk_mul_f32 v[40:41], v[40:41], v[32:33]
	v_pk_mul_f32 v[32:33], v[42:43], v[48:49]
	s_nop 0
	v_pk_mul_f32 v[42:43], v[32:33], v[34:35]
	v_mul_f32_e32 v33, 0xbfb8aa3b, v28
	v_exp_f32_e32 v34, v33
	v_mul_f32_e32 v33, 0xbfb8aa3b, v29
	v_exp_f32_e32 v35, v33
	v_cvt_pk_bf16_f32 v32, v36, v37
	v_add_f32_e32 v34, 1.0, v34
	v_rcp_f32_e32 v36, v34
	v_add_f32_e32 v34, 1.0, v35
	v_cvt_pk_bf16_f32 v33, v38, v39
	v_rcp_f32_e32 v37, v34
	v_cvt_pk_bf16_f32 v34, v40, v41
	v_cvt_pk_bf16_f32 v35, v42, v43
	global_store_dwordx4 v[60:61], v[32:35], off offset:2048
	v_pk_mul_f32 v[28:29], v[28:29], v[36:37]
	s_nop 0
	v_mul_f32_e32 v32, 0xbfb8aa3b, v30
	v_mul_f32_e32 v33, 0xbfb8aa3b, v31
	v_exp_f32_e32 v32, v32
	v_exp_f32_e32 v33, v33
	v_pk_mul_f32 v[20:21], v[28:29], v[20:21]
	v_add_f32_e32 v28, 1.0, v32
	v_add_f32_e32 v29, 1.0, v33
	v_mul_f32_e32 v32, 0xbfb8aa3b, v24
	v_mul_f32_e32 v33, 0xbfb8aa3b, v25
	v_rcp_f32_e32 v28, v28
	v_rcp_f32_e32 v29, v29
	v_exp_f32_e32 v32, v32
	v_exp_f32_e32 v33, v33
	v_pk_mul_f32 v[28:29], v[30:31], v[28:29]
	v_add_f32_e32 v30, 1.0, v32
	v_add_f32_e32 v31, 1.0, v33
	v_mul_f32_e32 v32, 0xbfb8aa3b, v26
	v_mul_f32_e32 v33, 0xbfb8aa3b, v27
	v_exp_f32_e32 v32, v32
	v_exp_f32_e32 v33, v33
	v_rcp_f32_e32 v30, v30
	v_rcp_f32_e32 v31, v31
	v_add_f32_e32 v32, 1.0, v32
	v_add_f32_e32 v33, 1.0, v33
	v_rcp_f32_e32 v32, v32
	v_rcp_f32_e32 v33, v33
	v_pk_mul_f32 v[24:25], v[24:25], v[30:31]
	v_pk_mul_f32 v[22:23], v[28:29], v[22:23]
	v_pk_mul_f32 v[24:25], v[24:25], v[16:17]
	v_pk_mul_f32 v[16:17], v[26:27], v[32:33]
	s_nop 0
	v_pk_mul_f32 v[26:27], v[16:17], v[18:19]
	v_mul_f32_e32 v19, 0xbfb8aa3b, v12
	v_cvt_pk_bf16_f32 v16, v20, v21
	v_exp_f32_e32 v20, v19
	v_mul_f32_e32 v19, 0xbfb8aa3b, v13
	v_exp_f32_e32 v21, v19
	v_cvt_pk_bf16_f32 v17, v22, v23
	v_add_co_u32_e32 v22, vcc, s59, v60
	v_cvt_pk_bf16_f32 v18, v24, v25
	v_cvt_pk_bf16_f32 v19, v26, v27
	v_add_f32_e32 v20, 1.0, v20
	v_add_f32_e32 v21, 1.0, v21
	v_addc_co_u32_e32 v23, vcc, 0, v61, vcc
	v_rcp_f32_e32 v20, v20
	v_rcp_f32_e32 v21, v21
	global_store_dwordx4 v[22:23], v[16:19], off
	s_and_b64 vcc, exec, s[6:7]
	v_pk_mul_f32 v[12:13], v[12:13], v[20:21]
	v_mul_f32_e32 v16, 0xbfb8aa3b, v14
	v_mul_f32_e32 v17, 0xbfb8aa3b, v15
	v_exp_f32_e32 v16, v16
	v_exp_f32_e32 v17, v17
	v_pk_mul_f32 v[4:5], v[12:13], v[4:5]
	v_add_f32_e32 v12, 1.0, v16
	v_add_f32_e32 v13, 1.0, v17
	v_mul_f32_e32 v16, 0xbfb8aa3b, v8
	v_mul_f32_e32 v17, 0xbfb8aa3b, v9
	v_rcp_f32_e32 v12, v12
	v_rcp_f32_e32 v13, v13
	v_exp_f32_e32 v16, v16
	v_exp_f32_e32 v17, v17
	v_pk_mul_f32 v[12:13], v[14:15], v[12:13]
	v_add_f32_e32 v14, 1.0, v16
	v_add_f32_e32 v15, 1.0, v17
	v_mul_f32_e32 v16, 0xbfb8aa3b, v10
	v_mul_f32_e32 v17, 0xbfb8aa3b, v11
	v_exp_f32_e32 v16, v16
	v_exp_f32_e32 v17, v17
	v_rcp_f32_e32 v14, v14
	v_rcp_f32_e32 v15, v15
	v_add_f32_e32 v16, 1.0, v16
	v_add_f32_e32 v17, 1.0, v17
	v_rcp_f32_e32 v16, v16
	v_rcp_f32_e32 v17, v17
	v_pk_mul_f32 v[8:9], v[8:9], v[14:15]
	v_pk_mul_f32 v[6:7], v[12:13], v[6:7]
	v_pk_mul_f32 v[8:9], v[8:9], v[0:1]
	v_pk_mul_f32 v[0:1], v[10:11], v[16:17]
	s_nop 0
	v_pk_mul_f32 v[10:11], v[0:1], v[2:3]
	v_cvt_pk_bf16_f32 v0, v4, v5
	v_cvt_pk_bf16_f32 v1, v6, v7
	v_cvt_pk_bf16_f32 v2, v8, v9
	v_cvt_pk_bf16_f32 v3, v10, v11
	global_store_dwordx4 v[22:23], v[0:3], off offset:2048
	s_cbranch_vccz .LBB0_132
	s_waitcnt vmcnt(0)
	s_cmpk_gt_u32 s25, 0xff
	s_cbranch_scc1 .LBB0_139
	s_barrier

; #define PG8_STAGE(bufoff, gbase, voff) do { _Pragma("unroll") for (int _i = 0; _i < 2; ++_i) \
;         __builtin_amdgcn_global_load_lds((const unsigned*)((const char*)(gbase) + (voff)[_i]), (LAS unsigned*)(lds + (bufoff) + ldsw + _i * 8192), 16, 0, 0); } while (0)
; #define PG8_LDA(dst, b, h) do { _Pragma("unroll") for (int m = 0; m < 4; ++m) _Pragma("unroll") for (int k = 0; k < 2; ++k) dst[m][k] = *(const LAS bf16x8*)(lds + PG8_SA(b, h) + aoff + m * 2048 + k * 1024); } while (0)
; #define PG8_LDB(dst, b, h) do { _Pragma("unroll") for (int n = 0; n < 2; ++n) _Pragma("unroll") for (int k = 0; k < 2; ++k) dst[n][k] = *(const LAS bf16x8*)(lds + PG8_SB(b, h) + boff + n * 2048 + k * 1024); } while (0)
; #define PG8_MMA(ai, bj, At, Bt) do { __builtin_amdgcn_s_setprio(1); _Pragma("unroll") for (int m = 0; m < 4; ++m) _Pragma("unroll") for (int n = 0; n < 2; ++n) _Pragma("unroll") for (int k = 0; k < 2; ++k) \
;         acc[ai][bj][m][n] = __builtin_amdgcn_mfma_f32_16x16x32_bf16(Bt[n][k], At[m][k], acc[ai][bj][m][n], 0, 0, 0); __builtin_amdgcn_s_setprio(0); } while (0)
; #define PG8_WAIT_V(n) asm volatile("s_waitcnt vmcnt(" #n ")" ::: "memory")
; #define PG8_WAIT_L(n) asm volatile("s_waitcnt lgkmcnt(" #n ")" ::: "memory")
; #define PG8_BAR __builtin_amdgcn_s_barrier()
; #define PG8_SCHED __builtin_amdgcn_sched_barrier(0)
; template <class Epi, class Sched>
; __device__ __forceinline__ void gemm_phase(LAS unsigned char* lds, const Gemm g, const Sched& S, const Epi& E) {
;     ...
;             PG8_LDB(B0, 0, 0); PG8_SCHED; PG8_LDA(At, 0, 0); PG8_STAGE(PG8_SA(1, 1), a1 + hstep, voffA);
;             PG8_WAIT_L(8); PG8_BAR; PG8_WAIT_L(0); PG8_MMA(0, 0, At, B0); PG8_BAR; PG8_SCHED;
;             PG8_LDB(B1, 0, 1); PG8_STAGE(PG8_SB(0, 0), b2, voffB);
;             PG8_BAR; PG8_WAIT_L(0); PG8_MMA(0, 1, At, B1); PG8_BAR;
;             PG8_LDA(At, 0, 1); PG8_STAGE(PG8_SA(0, 0), a2, voffA);
;             PG8_BAR; PG8_WAIT_L(0); PG8_MMA(1, 0, At, B0); PG8_BAR; PG8_SCHED;
;             PG8_STAGE(PG8_SB(0, 1), b2 + hstep, voffB);
;             PG8_WAIT_V(6); PG8_BAR; PG8_MMA(1, 1, At, B1); PG8_BAR;
.LBB0_148:
	ds_read_b128 v[146:149], v143
	ds_read_b128 v[150:153], v143 offset:1024
	ds_read_b128 v[154:157], v143 offset:2048
	ds_read_b128 v[158:161], v143 offset:3072
	s_add_u32 s38, s36, 0x4000
	s_addc_u32 s39, s37, 0
	s_cmp_eq_u32 s65, 28
	s_cselect_b32 s42, s61, s38
	s_cselect_b32 s43, s17, s39
	s_cselect_b32 s38, s62, s63
	s_cselect_b32 s39, s15, s64
	s_add_u32 s40, s42, 0x8000
	s_addc_u32 s41, s43, 0
	v_lshl_add_u64 v[166:167], s[36:37], 0, v[136:137]
	s_add_i32 m0, s11, 0xc000
	ds_read_b128 v[162:165], v144
	ds_read_b128 v[170:173], v144 offset:1024
	ds_read_b128 v[174:177], v144 offset:2048
	ds_read_b128 v[178:181], v144 offset:3072
	ds_read_b128 v[182:185], v144 offset:4096
	ds_read_b128 v[186:189], v144 offset:5120
	ds_read_b128 v[190:193], v144 offset:6144
	ds_read_b128 v[194:197], v144 offset:7168
	global_load_lds_dwordx4 v[166:167], off
	v_lshl_add_u64 v[166:167], s[36:37], 0, v[138:139]
	s_add_i32 m0, s11, 0xe000
	s_nop 0
	global_load_lds_dwordx4 v[166:167], off
	s_waitcnt lgkmcnt(8)
	s_barrier
	s_waitcnt lgkmcnt(0)
	v_mfma_f32_16x16x32_bf16 v[124:127], v[146:149], v[162:165], v[124:127]
	v_mfma_f32_16x16x32_bf16 v[120:123], v[154:157], v[162:165], v[120:123]
	v_mfma_f32_16x16x32_bf16 v[116:119], v[146:149], v[174:177], v[116:119]
	v_mfma_f32_16x16x32_bf16 v[112:115], v[154:157], v[174:177], v[112:115]
	v_mfma_f32_16x16x32_bf16 v[100:103], v[146:149], v[182:185], v[100:103]
	v_mfma_f32_16x16x32_bf16 v[96:99], v[154:157], v[182:185], v[96:99]
	v_mfma_f32_16x16x32_bf16 v[84:87], v[146:149], v[190:193], v[84:87]
	v_mfma_f32_16x16x32_bf16 v[80:83], v[154:157], v[190:193], v[80:83]
	v_mfma_f32_16x16x32_bf16 v[124:127], v[150:153], v[170:173], v[124:127]
	v_mfma_f32_16x16x32_bf16 v[120:123], v[158:161], v[170:173], v[120:123]
	v_mfma_f32_16x16x32_bf16 v[116:119], v[150:153], v[178:181], v[116:119]
	v_mfma_f32_16x16x32_bf16 v[112:115], v[158:161], v[178:181], v[112:115]
	v_mfma_f32_16x16x32_bf16 v[100:103], v[150:153], v[186:189], v[100:103]
	v_mfma_f32_16x16x32_bf16 v[96:99], v[158:161], v[186:189], v[96:99]
	v_mfma_f32_16x16x32_bf16 v[84:87], v[150:153], v[194:197], v[84:87]
	v_mfma_f32_16x16x32_bf16 v[80:83], v[158:161], v[194:197], v[80:83]
	s_barrier
	s_add_i32 s66, s57, s50
	v_lshl_add_u64 v[166:167], s[38:39], 0, v[130:131]
	s_mov_b32 m0, s66
	ds_read_b128 v[198:201], v145
	ds_read_b128 v[206:209], v145 offset:1024
	ds_read_b128 v[210:213], v145 offset:2048
	ds_read_b128 v[214:217], v145 offset:3072
	global_load_lds_dwordx4 v[166:167], off
	v_lshl_add_u64 v[166:167], s[38:39], 0, v[134:135]
	s_add_i32 m0, s66, 0x2000
	s_nop 0
	global_load_lds_dwordx4 v[166:167], off
	s_barrier
	s_waitcnt lgkmcnt(0)
	v_mfma_f32_16x16x32_bf16 v[108:111], v[198:201], v[162:165], v[108:111]
	v_mfma_f32_16x16x32_bf16 v[104:107], v[210:213], v[162:165], v[104:107]
	v_mfma_f32_16x16x32_bf16 v[92:95], v[198:201], v[174:177], v[92:95]
	v_mfma_f32_16x16x32_bf16 v[88:91], v[210:213], v[174:177], v[88:91]
	v_mfma_f32_16x16x32_bf16 v[76:79], v[198:201], v[182:185], v[76:79]
	v_mfma_f32_16x16x32_bf16 v[72:75], v[210:213], v[182:185], v[72:75]
	v_mfma_f32_16x16x32_bf16 v[68:71], v[198:201], v[190:193], v[68:71]
	v_mfma_f32_16x16x32_bf16 v[64:67], v[210:213], v[190:193], v[64:67]
	v_mfma_f32_16x16x32_bf16 v[108:111], v[206:209], v[170:173], v[108:111]
	v_mfma_f32_16x16x32_bf16 v[104:107], v[214:217], v[170:173], v[104:107]
	v_mfma_f32_16x16x32_bf16 v[92:95], v[206:209], v[178:181], v[92:95]
	v_mfma_f32_16x16x32_bf16 v[88:91], v[214:217], v[178:181], v[88:91]
	v_mfma_f32_16x16x32_bf16 v[76:79], v[206:209], v[186:189], v[76:79]
	v_mfma_f32_16x16x32_bf16 v[72:75], v[214:217], v[186:189], v[72:75]
	v_mfma_f32_16x16x32_bf16 v[68:71], v[206:209], v[194:197], v[68:71]
	v_mfma_f32_16x16x32_bf16 v[64:67], v[214:217], v[194:197], v[64:67]
	s_mov_b32 m0, s11
	v_lshl_add_u64 v[166:167], s[42:43], 0, v[128:129]
	s_barrier
	ds_read_b128 v[162:165], v144 offset:16384
	ds_read_b128 v[170:173], v144 offset:17408
	ds_read_b128 v[174:177], v144 offset:18432
	ds_read_b128 v[178:181], v144 offset:19456
	ds_read_b128 v[182:185], v144 offset:20480
	ds_read_b128 v[186:189], v144 offset:21504
	ds_read_b128 v[190:193], v144 offset:22528
	ds_read_b128 v[194:197], v144 offset:23552
	global_load_lds_dwordx4 v[166:167], off
	v_lshl_add_u64 v[166:167], s[42:43], 0, v[132:133]
	s_mov_b32 m0, s52
	s_nop 0
	global_load_lds_dwordx4 v[166:167], off
	s_barrier
	s_waitcnt lgkmcnt(0)
	v_mfma_f32_16x16x32_bf16 v[60:63], v[146:149], v[162:165], v[60:63]
	v_mfma_f32_16x16x32_bf16 v[56:59], v[154:157], v[162:165], v[56:59]
	v_mfma_f32_16x16x32_bf16 v[52:55], v[146:149], v[174:177], v[52:55]
	v_mfma_f32_16x16x32_bf16 v[48:51], v[154:157], v[174:177], v[48:51]
	v_mfma_f32_16x16x32_bf16 v[36:39], v[146:149], v[182:185], v[36:39]
	v_mfma_f32_16x16x32_bf16 v[32:35], v[154:157], v[182:185], v[32:35]
	v_mfma_f32_16x16x32_bf16 v[20:23], v[146:149], v[190:193], v[20:23]
	v_mfma_f32_16x16x32_bf16 v[16:19], v[154:157], v[190:193], v[16:19]
	v_mfma_f32_16x16x32_bf16 v[60:63], v[150:153], v[170:173], v[60:63]
	v_mfma_f32_16x16x32_bf16 v[56:59], v[158:161], v[170:173], v[56:59]
	v_mfma_f32_16x16x32_bf16 v[52:55], v[150:153], v[178:181], v[52:55]
	v_mfma_f32_16x16x32_bf16 v[48:51], v[158:161], v[178:181], v[48:51]
	v_mfma_f32_16x16x32_bf16 v[36:39], v[150:153], v[186:189], v[36:39]
	v_mfma_f32_16x16x32_bf16 v[32:35], v[158:161], v[186:189], v[32:35]
	v_mfma_f32_16x16x32_bf16 v[20:23], v[150:153], v[194:197], v[20:23]
	v_mfma_f32_16x16x32_bf16 v[16:19], v[158:161], v[194:197], v[16:19]
	s_barrier
; #define PG8_STAGE(bufoff, gbase, voff) do { _Pragma("unroll") for (int _i = 0; _i < 2; ++_i) \
;         __builtin_amdgcn_global_load_lds((const unsigned*)((const char*)(gbase) + (voff)[_i]), (LAS unsigned*)(lds + (bufoff) + ldsw + _i * 8192), 16, 0, 0); } while (0)
; #define PG8_LDA(dst, b, h) do { _Pragma("unroll") for (int m = 0; m < 4; ++m) _Pragma("unroll") for (int k = 0; k < 2; ++k) dst[m][k] = *(const LAS bf16x8*)(lds + PG8_SA(b, h) + aoff + m * 2048 + k * 1024); } while (0)
; #define PG8_LDB(dst, b, h) do { _Pragma("unroll") for (int n = 0; n < 2; ++n) _Pragma("unroll") for (int k = 0; k < 2; ++k) dst[n][k] = *(const LAS bf16x8*)(lds + PG8_SB(b, h) + boff + n * 2048 + k * 1024); } while (0)
; #define PG8_MMA(ai, bj, At, Bt) do { __builtin_amdgcn_s_setprio(1); _Pragma("unroll") for (int m = 0; m < 4; ++m) _Pragma("unroll") for (int n = 0; n < 2; ++n) _Pragma("unroll") for (int k = 0; k < 2; ++k) \
;         acc[ai][bj][m][n] = __builtin_amdgcn_mfma_f32_16x16x32_bf16(Bt[n][k], At[m][k], acc[ai][bj][m][n], 0, 0, 0); __builtin_amdgcn_s_setprio(0); } while (0)
; #define PG8_WAIT_V(n) asm volatile("s_waitcnt vmcnt(" #n ")" ::: "memory")
; #define PG8_WAIT_L(n) asm volatile("s_waitcnt lgkmcnt(" #n ")" ::: "memory")
; #define PG8_BAR __builtin_amdgcn_s_barrier()
; #define PG8_SCHED __builtin_amdgcn_sched_barrier(0)
; template <class Epi, class Sched>
; __device__ __forceinline__ void gemm_phase(LAS unsigned char* lds, const Gemm g, const Sched& S, const Epi& E) {
;     ...
;             PG8_STAGE(PG8_SB(0, 1), b2 + hstep, voffB);
;             PG8_WAIT_V(6); PG8_BAR; PG8_MMA(1, 1, At, B1); PG8_BAR;
;             PG8_LDB(B0, 1, 0); PG8_SCHED; PG8_LDA(At, 1, 0); PG8_STAGE(PG8_SA(0, 1), a2 + hstep, voffA);
;             PG8_WAIT_L(8); PG8_BAR; PG8_WAIT_L(0); PG8_MMA(0, 0, At, B0); PG8_BAR; PG8_SCHED;
;             PG8_LDB(B1, 1, 1); PG8_STAGE(PG8_SB(1, 0), b3, voffB);
;             PG8_BAR; PG8_WAIT_L(0); PG8_MMA(0, 1, At, B1); PG8_BAR;
;             PG8_LDA(At, 1, 1); PG8_STAGE(PG8_SA(1, 0), a3, voffA);
;             PG8_BAR; PG8_WAIT_L(0); PG8_MMA(1, 0, At, B0); PG8_BAR; PG8_SCHED;
	s_add_u32 s66, s38, 0x4000
	s_addc_u32 s67, s39, 0
	s_add_i32 s68, s58, s50
	v_lshl_add_u64 v[146:147], s[66:67], 0, v[130:131]
	s_mov_b32 m0, s68
	s_nop 0
	global_load_lds_dwordx4 v[146:147], off
	v_lshl_add_u64 v[146:147], s[66:67], 0, v[134:135]
	s_add_i32 m0, s68, 0x2000
	s_nop 0
	global_load_lds_dwordx4 v[146:147], off
	s_waitcnt vmcnt(6)
	s_barrier
	v_mfma_f32_16x16x32_bf16 v[44:47], v[198:201], v[162:165], v[44:47]
	v_mfma_f32_16x16x32_bf16 v[40:43], v[210:213], v[162:165], v[40:43]
	v_mfma_f32_16x16x32_bf16 v[28:31], v[198:201], v[174:177], v[28:31]
	v_mfma_f32_16x16x32_bf16 v[24:27], v[210:213], v[174:177], v[24:27]
	v_mfma_f32_16x16x32_bf16 v[12:15], v[198:201], v[182:185], v[12:15]
	v_mfma_f32_16x16x32_bf16 v[8:11], v[210:213], v[182:185], v[8:11]
	v_mfma_f32_16x16x32_bf16 v[4:7], v[198:201], v[190:193], v[4:7]
	v_mfma_f32_16x16x32_bf16 v[0:3], v[210:213], v[190:193], v[0:3]
	v_mfma_f32_16x16x32_bf16 v[44:47], v[206:209], v[170:173], v[44:47]
	v_mfma_f32_16x16x32_bf16 v[40:43], v[214:217], v[170:173], v[40:43]
	v_mfma_f32_16x16x32_bf16 v[28:31], v[206:209], v[178:181], v[28:31]
	v_mfma_f32_16x16x32_bf16 v[24:27], v[214:217], v[178:181], v[24:27]
	v_mfma_f32_16x16x32_bf16 v[12:15], v[206:209], v[186:189], v[12:15]
	v_mfma_f32_16x16x32_bf16 v[8:11], v[214:217], v[186:189], v[8:11]
	v_mfma_f32_16x16x32_bf16 v[4:7], v[206:209], v[194:197], v[4:7]
	v_mfma_f32_16x16x32_bf16 v[0:3], v[214:217], v[194:197], v[0:3]
	s_add_i32 s66, 0, 0x18000
	v_add_u32_e32 v158, s66, v141
	s_barrier
	ds_read_b128 v[146:149], v158
	ds_read_b128 v[150:153], v158 offset:1024
	ds_read_b128 v[154:157], v158 offset:2048
	ds_read_b128 v[158:161], v158 offset:3072
	s_add_u32 s42, s42, 0x4000
	s_addc_u32 s43, s43, 0
	s_mov_b32 m0, s53
	v_lshl_add_u64 v[166:167], s[42:43], 0, v[128:129]
	ds_read_b128 v[162:165], v144 offset:32768
	ds_read_b128 v[170:173], v144 offset:33792
	ds_read_b128 v[174:177], v144 offset:34816
	ds_read_b128 v[178:181], v144 offset:35840
	ds_read_b128 v[182:185], v144 offset:36864
	ds_read_b128 v[186:189], v144 offset:37888
	ds_read_b128 v[190:193], v144 offset:38912
	ds_read_b128 v[194:197], v144 offset:39936
	global_load_lds_dwordx4 v[166:167], off
	v_lshl_add_u64 v[166:167], s[42:43], 0, v[132:133]
	s_mov_b32 m0, s33
	s_nop 0
	global_load_lds_dwordx4 v[166:167], off
	s_waitcnt lgkmcnt(8)
	s_barrier
	s_waitcnt lgkmcnt(0)
	v_mfma_f32_16x16x32_bf16 v[124:127], v[146:149], v[162:165], v[124:127]
	v_mfma_f32_16x16x32_bf16 v[120:123], v[154:157], v[162:165], v[120:123]
	v_mfma_f32_16x16x32_bf16 v[116:119], v[146:149], v[174:177], v[116:119]
	v_mfma_f32_16x16x32_bf16 v[112:115], v[154:157], v[174:177], v[112:115]
	v_mfma_f32_16x16x32_bf16 v[100:103], v[146:149], v[182:185], v[100:103]
	v_mfma_f32_16x16x32_bf16 v[96:99], v[154:157], v[182:185], v[96:99]
	v_mfma_f32_16x16x32_bf16 v[84:87], v[146:149], v[190:193], v[84:87]
	v_mfma_f32_16x16x32_bf16 v[80:83], v[154:157], v[190:193], v[80:83]
	v_mfma_f32_16x16x32_bf16 v[124:127], v[150:153], v[170:173], v[124:127]
	v_mfma_f32_16x16x32_bf16 v[120:123], v[158:161], v[170:173], v[120:123]
	v_mfma_f32_16x16x32_bf16 v[116:119], v[150:153], v[178:181], v[116:119]
	v_mfma_f32_16x16x32_bf16 v[112:115], v[158:161], v[178:181], v[112:115]
	v_mfma_f32_16x16x32_bf16 v[100:103], v[150:153], v[186:189], v[100:103]
	v_mfma_f32_16x16x32_bf16 v[96:99], v[158:161], v[186:189], v[96:99]
	v_mfma_f32_16x16x32_bf16 v[84:87], v[150:153], v[194:197], v[84:87]
	v_mfma_f32_16x16x32_bf16 v[80:83], v[158:161], v[194:197], v[80:83]
	s_barrier
	s_add_i32 s67, 0, 0x1c000
	s_add_u32 s42, s38, 0x8000
	v_add_u32_e32 v166, s67, v141
	s_addc_u32 s43, s39, 0
	s_add_i32 s66, s66, s50
	ds_read_b128 v[198:201], v166
	ds_read_b128 v[206:209], v166 offset:1024
	ds_read_b128 v[210:213], v166 offset:2048
	ds_read_b128 v[214:217], v166 offset:3072
	v_lshl_add_u64 v[166:167], s[42:43], 0, v[130:131]
	s_mov_b32 m0, s66
	s_nop 0
	global_load_lds_dwordx4 v[166:167], off
	v_lshl_add_u64 v[166:167], s[42:43], 0, v[134:135]
	s_add_i32 m0, s66, 0x2000
	s_nop 0
	global_load_lds_dwordx4 v[166:167], off
	s_barrier
	s_waitcnt lgkmcnt(0)
	v_mfma_f32_16x16x32_bf16 v[108:111], v[198:201], v[162:165], v[108:111]
	v_mfma_f32_16x16x32_bf16 v[104:107], v[210:213], v[162:165], v[104:107]
	v_mfma_f32_16x16x32_bf16 v[92:95], v[198:201], v[174:177], v[92:95]
	v_mfma_f32_16x16x32_bf16 v[88:91], v[210:213], v[174:177], v[88:91]
	v_mfma_f32_16x16x32_bf16 v[76:79], v[198:201], v[182:185], v[76:79]
	v_mfma_f32_16x16x32_bf16 v[72:75], v[210:213], v[182:185], v[72:75]
	v_mfma_f32_16x16x32_bf16 v[68:71], v[198:201], v[190:193], v[68:71]
	v_mfma_f32_16x16x32_bf16 v[64:67], v[210:213], v[190:193], v[64:67]
	v_mfma_f32_16x16x32_bf16 v[108:111], v[206:209], v[170:173], v[108:111]
	v_mfma_f32_16x16x32_bf16 v[104:107], v[214:217], v[170:173], v[104:107]
	v_mfma_f32_16x16x32_bf16 v[92:95], v[206:209], v[178:181], v[92:95]
	v_mfma_f32_16x16x32_bf16 v[88:91], v[214:217], v[178:181], v[88:91]
	v_mfma_f32_16x16x32_bf16 v[76:79], v[206:209], v[186:189], v[76:79]
	v_mfma_f32_16x16x32_bf16 v[72:75], v[214:217], v[186:189], v[72:75]
	v_mfma_f32_16x16x32_bf16 v[68:71], v[206:209], v[194:197], v[68:71]
	v_mfma_f32_16x16x32_bf16 v[64:67], v[214:217], v[194:197], v[64:67]
	s_mov_b32 m0, s55
	v_lshl_add_u64 v[166:167], s[40:41], 0, v[128:129]
	s_barrier
	ds_read_b128 v[162:165], v144 offset:49152
	ds_read_b128 v[170:173], v144 offset:50176
	ds_read_b128 v[174:177], v144 offset:51200
	ds_read_b128 v[178:181], v144 offset:52224
	ds_read_b128 v[182:185], v144 offset:53248
	ds_read_b128 v[186:189], v144 offset:54272
	ds_read_b128 v[190:193], v144 offset:55296
	ds_read_b128 v[194:197], v144 offset:56320
	global_load_lds_dwordx4 v[166:167], off
	v_lshl_add_u64 v[166:167], s[40:41], 0, v[132:133]
	s_mov_b32 m0, s56
	s_nop 0
	global_load_lds_dwordx4 v[166:167], off
	s_barrier
; #define PG8_STAGE(bufoff, gbase, voff) do { _Pragma("unroll") for (int _i = 0; _i < 2; ++_i) \
;         __builtin_amdgcn_global_load_lds((const unsigned*)((const char*)(gbase) + (voff)[_i]), (LAS unsigned*)(lds + (bufoff) + ldsw + _i * 8192), 16, 0, 0); } while (0)
; #define PG8_MMA(ai, bj, At, Bt) do { __builtin_amdgcn_s_setprio(1); _Pragma("unroll") for (int m = 0; m < 4; ++m) _Pragma("unroll") for (int n = 0; n < 2; ++n) _Pragma("unroll") for (int k = 0; k < 2; ++k) \
;         acc[ai][bj][m][n] = __builtin_amdgcn_mfma_f32_16x16x32_bf16(Bt[n][k], At[m][k], acc[ai][bj][m][n], 0, 0, 0); __builtin_amdgcn_s_setprio(0); } while (0)
; #define PG8_WAIT_V(n) asm volatile("s_waitcnt vmcnt(" #n ")" ::: "memory")
; #define PG8_WAIT_L(n) asm volatile("s_waitcnt lgkmcnt(" #n ")" ::: "memory")
; #define PG8_BAR __builtin_amdgcn_s_barrier()
; #define PG8_SCHED __builtin_amdgcn_sched_barrier(0)
; template <class Epi, class Sched>
; __device__ __forceinline__ void gemm_phase(LAS unsigned char* lds, const Gemm g, const Sched& S, const Epi& E) {
;     ...
;             PG8_BAR; PG8_WAIT_L(0); PG8_MMA(1, 0, At, B0); PG8_BAR; PG8_SCHED;
;             PG8_STAGE(PG8_SB(1, 1), b3 + hstep, voffB);
;             PG8_WAIT_V(6); PG8_BAR; PG8_MMA(1, 1, At, B1); PG8_BAR;
	s_waitcnt lgkmcnt(0)
	v_mfma_f32_16x16x32_bf16 v[60:63], v[146:149], v[162:165], v[60:63]
	v_mfma_f32_16x16x32_bf16 v[56:59], v[154:157], v[162:165], v[56:59]
	v_mfma_f32_16x16x32_bf16 v[52:55], v[146:149], v[174:177], v[52:55]
	v_mfma_f32_16x16x32_bf16 v[48:51], v[154:157], v[174:177], v[48:51]
	v_mfma_f32_16x16x32_bf16 v[36:39], v[146:149], v[182:185], v[36:39]
	v_mfma_f32_16x16x32_bf16 v[32:35], v[154:157], v[182:185], v[32:35]
	v_mfma_f32_16x16x32_bf16 v[20:23], v[146:149], v[190:193], v[20:23]
	v_mfma_f32_16x16x32_bf16 v[16:19], v[154:157], v[190:193], v[16:19]
	v_mfma_f32_16x16x32_bf16 v[60:63], v[150:153], v[170:173], v[60:63]
	v_mfma_f32_16x16x32_bf16 v[56:59], v[158:161], v[170:173], v[56:59]
	v_mfma_f32_16x16x32_bf16 v[52:55], v[150:153], v[178:181], v[52:55]
	v_mfma_f32_16x16x32_bf16 v[48:51], v[158:161], v[178:181], v[48:51]
	v_mfma_f32_16x16x32_bf16 v[36:39], v[150:153], v[186:189], v[36:39]
	v_mfma_f32_16x16x32_bf16 v[32:35], v[158:161], v[186:189], v[32:35]
	v_mfma_f32_16x16x32_bf16 v[20:23], v[150:153], v[194:197], v[20:23]
	v_mfma_f32_16x16x32_bf16 v[16:19], v[158:161], v[194:197], v[16:19]
	s_barrier
	s_add_u32 s38, s38, 0xc000
	s_addc_u32 s39, s39, 0
	s_add_i32 s40, s67, s50
	v_lshl_add_u64 v[146:147], s[38:39], 0, v[130:131]
	s_mov_b32 m0, s40
	s_nop 0
	global_load_lds_dwordx4 v[146:147], off
	v_lshl_add_u64 v[146:147], s[38:39], 0, v[134:135]
	s_add_i32 m0, s40, 0x2000
	s_nop 0
	global_load_lds_dwordx4 v[146:147], off
	s_waitcnt vmcnt(6)
	s_barrier
	v_mfma_f32_16x16x32_bf16 v[44:47], v[198:201], v[162:165], v[44:47]
	v_mfma_f32_16x16x32_bf16 v[40:43], v[210:213], v[162:165], v[40:43]
	v_mfma_f32_16x16x32_bf16 v[28:31], v[198:201], v[174:177], v[28:31]
	v_mfma_f32_16x16x32_bf16 v[24:27], v[210:213], v[174:177], v[24:27]
	v_mfma_f32_16x16x32_bf16 v[12:15], v[198:201], v[182:185], v[12:15]
	v_mfma_f32_16x16x32_bf16 v[8:11], v[210:213], v[182:185], v[8:11]
	v_mfma_f32_16x16x32_bf16 v[4:7], v[198:201], v[190:193], v[4:7]
	v_mfma_f32_16x16x32_bf16 v[0:3], v[210:213], v[190:193], v[0:3]
	v_mfma_f32_16x16x32_bf16 v[44:47], v[206:209], v[170:173], v[44:47]
	v_mfma_f32_16x16x32_bf16 v[40:43], v[214:217], v[170:173], v[40:43]
	v_mfma_f32_16x16x32_bf16 v[28:31], v[206:209], v[178:181], v[28:31]
	v_mfma_f32_16x16x32_bf16 v[24:27], v[214:217], v[178:181], v[24:27]
	v_mfma_f32_16x16x32_bf16 v[12:15], v[206:209], v[186:189], v[12:15]
	v_mfma_f32_16x16x32_bf16 v[8:11], v[214:217], v[186:189], v[8:11]
	v_mfma_f32_16x16x32_bf16 v[4:7], v[206:209], v[194:197], v[4:7]
	v_mfma_f32_16x16x32_bf16 v[0:3], v[214:217], v[194:197], v[0:3]
	s_add_i32 s65, s65, 2
	s_add_u32 s36, s36, 0x10000
	s_addc_u32 s37, s37, 0
	s_add_u32 s63, s63, 0x10000
	s_addc_u32 s64, s64, 0
	s_cmp_gt_u32 s65, 29
	s_barrier
	s_cbranch_scc0 .LBB0_148
; __device__ __forceinline__ unsigned cvt_pk_bf16(float lo, float hi) { f32x2 v = {lo, hi}; bf16x2_t b = __builtin_convertvector(v, bf16x2_t); return __builtin_bit_cast(unsigned, b); }
; __device__ __forceinline__ float gelu_f(float x) { const float u = 1.5957691216f * (x + 0.044715f * x * x * x); return x * sigmoid_f(u); }
;     __device__ __forceinline__ void operator()(const f32x4 (&acc)[2][2][4][2], const Unit& u, int wr, int wc, int fr, int fq) const {
;         const int row0 = u.pm * BM + wr * 64 + fr, col0 = u.pn * BM + wc * 32 + 8 * fq;
;         const int kind = ACT == 0 ? 0 : (u.pn < 4 ? 0 : (u.pn < 12 ? 1 : 2));
; #pragma unroll
;         for (int ai = 0; ai < 2; ++ai)
; #pragma unroll
;             for (int m = 0; m < 4; ++m) {
;                 bf16_t* rowp = O + (size_t)(row0 + ai * HALF + m * 16) * ldo + col0;
; #pragma unroll
;                 for (int bj = 0; bj < 2; ++bj) {
;                     float v[8];
; #pragma unroll
;                     for (int n = 0; n < 2; ++n)
; #pragma unroll
;                         for (int j = 0; j < 4; ++j) { const float a = acc[ai][bj][m][n][j]; v[n * 4 + j] = kind == 1 ? gelu_f(a) : (kind == 2 ? a * 0.0625f : a); }
;                     u32x4 w; w.x = cvt_pk_bf16(v[0], v[1]); w.y = cvt_pk_bf16(v[2], v[3]); w.z = cvt_pk_bf16(v[4], v[5]); w.w = cvt_pk_bf16(v[6], v[7]);
;                     *(u32x4*)(rowp + bj * HALF) = w;
;                 }
;             }
	v_lshl_add_u32 v152, s10, 8, v140
	v_lshl_or_b32 v146, s60, 8, v142
	v_ashrrev_i32_e32 v147, 31, v146
	v_mov_b64_e32 v[148:149], s[8:9]
	v_cvt_pk_bf16_f32 v68, v68, v69
	v_cvt_pk_bf16_f32 v69, v70, v71
	v_cvt_pk_bf16_f32 v70, v64, v65
	v_add_u32_e32 v64, 0x80, v152
	v_mad_i64_i32 v[150:151], s[36:37], v152, s59, v[148:149]
	v_lshlrev_b64 v[146:147], 1, v[146:147]
	v_cvt_pk_bf16_f32 v108, v108, v109
	v_cvt_pk_bf16_f32 v109, v110, v111
	v_cvt_pk_bf16_f32 v110, v104, v105
	v_or_b32_e32 v104, 16, v152
	v_mad_i64_i32 v[64:65], s[36:37], v64, s59, v[148:149]
	v_cvt_pk_bf16_f32 v44, v44, v45
	v_cvt_pk_bf16_f32 v45, v46, v47
	v_cvt_pk_bf16_f32 v46, v40, v41
	v_add_u32_e32 v40, 0x90, v152
	v_lshl_add_u64 v[150:151], v[150:151], 0, v[146:147]
	v_cvt_pk_bf16_f32 v111, v106, v107
	v_mad_i64_i32 v[104:105], s[36:37], v104, s59, v[148:149]
	v_cvt_pk_bf16_f32 v92, v92, v93
	v_cvt_pk_bf16_f32 v93, v94, v95
	v_cvt_pk_bf16_f32 v94, v88, v89
	v_or_b32_e32 v88, 32, v152
	v_lshl_add_u64 v[64:65], v[64:65], 0, v[146:147]
	v_cvt_pk_bf16_f32 v47, v42, v43
	v_mad_i64_i32 v[40:41], s[36:37], v40, s59, v[148:149]
	v_cvt_pk_bf16_f32 v28, v28, v29
	v_cvt_pk_bf16_f32 v29, v30, v31
	v_cvt_pk_bf16_f32 v30, v24, v25
	v_add_u32_e32 v24, 0xa0, v152
	global_store_dwordx4 v[150:151], v[108:111], off offset:256
	v_cvt_pk_bf16_f32 v95, v90, v91
	v_mad_i64_i32 v[88:89], s[36:37], v88, s59, v[148:149]
	v_lshl_add_u64 v[108:109], v[104:105], 0, v[146:147]
	v_cvt_pk_bf16_f32 v76, v76, v77
	v_cvt_pk_bf16_f32 v77, v78, v79
	v_cvt_pk_bf16_f32 v78, v72, v73
	v_or_b32_e32 v72, 48, v152
	global_store_dwordx4 v[64:65], v[44:47], off offset:256
	v_cvt_pk_bf16_f32 v31, v26, v27
	v_mad_i64_i32 v[24:25], s[36:37], v24, s59, v[148:149]
	v_lshl_add_u64 v[44:45], v[40:41], 0, v[146:147]
	v_cvt_pk_bf16_f32 v12, v12, v13
	v_cvt_pk_bf16_f32 v13, v14, v15
	v_cvt_pk_bf16_f32 v14, v8, v9
	v_add_u32_e32 v8, 0xb0, v152
	global_store_dwordx4 v[108:109], v[92:95], off offset:256
	v_cvt_pk_bf16_f32 v79, v74, v75
	v_mad_i64_i32 v[72:73], s[36:37], v72, s59, v[148:149]
	v_lshl_add_u64 v[92:93], v[88:89], 0, v[146:147]
	global_store_dwordx4 v[44:45], v[28:31], off offset:256
	v_cvt_pk_bf16_f32 v15, v10, v11
	v_mad_i64_i32 v[8:9], s[36:37], v8, s59, v[148:149]
	v_lshl_add_u64 v[28:29], v[24:25], 0, v[146:147]
	v_cvt_pk_bf16_f32 v124, v124, v125
	v_cvt_pk_bf16_f32 v125, v126, v127
	v_cvt_pk_bf16_f32 v126, v120, v121
	v_cvt_pk_bf16_f32 v127, v122, v123
	v_cvt_pk_bf16_f32 v104, v116, v117
	v_cvt_pk_bf16_f32 v105, v118, v119
	v_cvt_pk_bf16_f32 v106, v112, v113
	v_cvt_pk_bf16_f32 v107, v114, v115
	v_cvt_pk_bf16_f32 v88, v100, v101
	v_cvt_pk_bf16_f32 v89, v102, v103
	v_cvt_pk_bf16_f32 v90, v96, v97
	v_cvt_pk_bf16_f32 v91, v98, v99
	global_store_dwordx4 v[92:93], v[76:79], off offset:256
	v_cvt_pk_bf16_f32 v74, v80, v81
	v_cvt_pk_bf16_f32 v75, v82, v83
	v_lshl_add_u64 v[76:77], v[72:73], 0, v[146:147]
	v_cvt_pk_bf16_f32 v72, v84, v85
	v_cvt_pk_bf16_f32 v73, v86, v87
	v_cvt_pk_bf16_f32 v71, v66, v67
	v_cvt_pk_bf16_f32 v60, v60, v61
	v_cvt_pk_bf16_f32 v61, v62, v63
	v_cvt_pk_bf16_f32 v62, v56, v57
	v_cvt_pk_bf16_f32 v63, v58, v59
	v_cvt_pk_bf16_f32 v40, v52, v53
	v_cvt_pk_bf16_f32 v41, v54, v55
	v_cvt_pk_bf16_f32 v42, v48, v49
	v_cvt_pk_bf16_f32 v43, v50, v51
	v_cvt_pk_bf16_f32 v24, v36, v37
	v_cvt_pk_bf16_f32 v25, v38, v39
	v_cvt_pk_bf16_f32 v26, v32, v33
	v_cvt_pk_bf16_f32 v27, v34, v35
	global_store_dwordx4 v[28:29], v[12:15], off offset:256
	v_cvt_pk_bf16_f32 v10, v16, v17
	v_cvt_pk_bf16_f32 v11, v18, v19
	v_lshl_add_u64 v[12:13], v[8:9], 0, v[146:147]
	v_cvt_pk_bf16_f32 v8, v20, v21
	v_cvt_pk_bf16_f32 v9, v22, v23
	v_cvt_pk_bf16_f32 v4, v4, v5
	v_cvt_pk_bf16_f32 v5, v6, v7
	v_cvt_pk_bf16_f32 v6, v0, v1
	v_cvt_pk_bf16_f32 v7, v2, v3
	s_and_b64 vcc, exec, s[12:13]
	s_mov_b32 s60, s14
	s_mov_b32 s10, s16
	s_mov_b64 s[38:39], s[28:29]
	s_mov_b64 s[36:37], s[18:19]
	global_store_dwordx4 v[150:151], v[124:127], off
	global_store_dwordx4 v[108:109], v[104:107], off
	global_store_dwordx4 v[92:93], v[88:91], off
	global_store_dwordx4 v[76:77], v[72:75], off
	global_store_dwordx4 v[76:77], v[68:71], off offset:256
	global_store_dwordx4 v[64:65], v[60:63], off
	global_store_dwordx4 v[44:45], v[40:43], off
	global_store_dwordx4 v[28:29], v[24:27], off
	global_store_dwordx4 v[12:13], v[8:11], off
	global_store_dwordx4 v[12:13], v[4:7], off offset:256
	s_cbranch_vccz .LBB0_145
	s_waitcnt vmcnt(0)
	s_cmpk_gt_u32 s47, 0xff
	s_cbranch_scc1 .LBB0_152
	s_barrier

; #define PG8_STAGE(bufoff, gbase, voff) do { _Pragma("unroll") for (int _i = 0; _i < 2; ++_i) \
;         __builtin_amdgcn_global_load_lds((const unsigned*)((const char*)(gbase) + (voff)[_i]), (LAS unsigned*)(lds + (bufoff) + ldsw + _i * 8192), 16, 0, 0); } while (0)
; #define PG8_LDA(dst, b, h) do { _Pragma("unroll") for (int m = 0; m < 4; ++m) _Pragma("unroll") for (int k = 0; k < 2; ++k) dst[m][k] = *(const LAS bf16x8*)(lds + PG8_SA(b, h) + aoff + m * 2048 + k * 1024); } while (0)
; #define PG8_LDB(dst, b, h) do { _Pragma("unroll") for (int n = 0; n < 2; ++n) _Pragma("unroll") for (int k = 0; k < 2; ++k) dst[n][k] = *(const LAS bf16x8*)(lds + PG8_SB(b, h) + boff + n * 2048 + k * 1024); } while (0)
; #define PG8_MMA(ai, bj, At, Bt) do { __builtin_amdgcn_s_setprio(1); _Pragma("unroll") for (int m = 0; m < 4; ++m) _Pragma("unroll") for (int n = 0; n < 2; ++n) _Pragma("unroll") for (int k = 0; k < 2; ++k) \
;         acc[ai][bj][m][n] = __builtin_amdgcn_mfma_f32_16x16x32_bf16(Bt[n][k], At[m][k], acc[ai][bj][m][n], 0, 0, 0); __builtin_amdgcn_s_setprio(0); } while (0)
; #define PG8_WAIT_V(n) asm volatile("s_waitcnt vmcnt(" #n ")" ::: "memory")
; #define PG8_WAIT_L(n) asm volatile("s_waitcnt lgkmcnt(" #n ")" ::: "memory")
; #define PG8_BAR __builtin_amdgcn_s_barrier()
; #define PG8_SCHED __builtin_amdgcn_sched_barrier(0)
; template <class Epi, class Sched>
; __device__ __forceinline__ void gemm_phase(LAS unsigned char* lds, const Gemm g, const Sched& S, const Epi& E) {
;     ...
;             PG8_LDB(B0, 0, 0); PG8_SCHED; PG8_LDA(At, 0, 0); PG8_STAGE(PG8_SA(1, 1), a1 + hstep, voffA);
;             PG8_WAIT_L(8); PG8_BAR; PG8_WAIT_L(0); PG8_MMA(0, 0, At, B0); PG8_BAR; PG8_SCHED;
;             PG8_LDB(B1, 0, 1); PG8_STAGE(PG8_SB(0, 0), b2, voffB);
;             PG8_BAR; PG8_WAIT_L(0); PG8_MMA(0, 1, At, B1); PG8_BAR;
;             PG8_LDA(At, 0, 1); PG8_STAGE(PG8_SA(0, 0), a2, voffA);
;             PG8_BAR; PG8_WAIT_L(0); PG8_MMA(1, 0, At, B0); PG8_BAR; PG8_SCHED;
;             PG8_STAGE(PG8_SB(0, 1), b2 + hstep, voffB);
;             PG8_WAIT_V(6); PG8_BAR; PG8_MMA(1, 1, At, B1); PG8_BAR;
.LBB0_161:
	ds_read_b128 v[146:149], v143
	ds_read_b128 v[150:153], v143 offset:1024
	ds_read_b128 v[154:157], v143 offset:2048
	ds_read_b128 v[158:161], v143 offset:3072
	s_add_u32 s44, s42, 0x4000
	s_addc_u32 s45, s43, 0
	s_cmp_eq_u32 s73, 28
	s_cselect_b32 s48, s69, s44
	s_cselect_b32 s49, s37, s45
	s_cselect_b32 s44, s70, s71
	s_cselect_b32 s45, s29, s72
	s_add_u32 s46, s48, 0x8000
	s_addc_u32 s47, s49, 0
	v_lshl_add_u64 v[166:167], s[42:43], 0, v[136:137]
	s_add_i32 m0, s56, 0xc000
	ds_read_b128 v[162:165], v144
	ds_read_b128 v[170:173], v144 offset:1024
	ds_read_b128 v[174:177], v144 offset:2048
	ds_read_b128 v[178:181], v144 offset:3072
	ds_read_b128 v[182:185], v144 offset:4096
	ds_read_b128 v[186:189], v144 offset:5120
	ds_read_b128 v[190:193], v144 offset:6144
	ds_read_b128 v[194:197], v144 offset:7168
	global_load_lds_dwordx4 v[166:167], off
	v_lshl_add_u64 v[166:167], s[42:43], 0, v[138:139]
	s_add_i32 m0, s56, 0xe000
	s_nop 0
	global_load_lds_dwordx4 v[166:167], off
	s_waitcnt lgkmcnt(8)
	s_barrier
	s_waitcnt lgkmcnt(0)
	v_mfma_f32_16x16x32_bf16 v[124:127], v[146:149], v[162:165], v[124:127]
	v_mfma_f32_16x16x32_bf16 v[120:123], v[154:157], v[162:165], v[120:123]
	v_mfma_f32_16x16x32_bf16 v[116:119], v[146:149], v[174:177], v[116:119]
	v_mfma_f32_16x16x32_bf16 v[108:111], v[154:157], v[174:177], v[108:111]
	v_mfma_f32_16x16x32_bf16 v[100:103], v[146:149], v[182:185], v[100:103]
	v_mfma_f32_16x16x32_bf16 v[92:95], v[154:157], v[182:185], v[92:95]
	v_mfma_f32_16x16x32_bf16 v[84:87], v[146:149], v[190:193], v[84:87]
	v_mfma_f32_16x16x32_bf16 v[76:79], v[154:157], v[190:193], v[76:79]
	v_mfma_f32_16x16x32_bf16 v[124:127], v[150:153], v[170:173], v[124:127]
	v_mfma_f32_16x16x32_bf16 v[120:123], v[158:161], v[170:173], v[120:123]
	v_mfma_f32_16x16x32_bf16 v[116:119], v[150:153], v[178:181], v[116:119]
	v_mfma_f32_16x16x32_bf16 v[108:111], v[158:161], v[178:181], v[108:111]
	v_mfma_f32_16x16x32_bf16 v[100:103], v[150:153], v[186:189], v[100:103]
	v_mfma_f32_16x16x32_bf16 v[92:95], v[158:161], v[186:189], v[92:95]
	v_mfma_f32_16x16x32_bf16 v[84:87], v[150:153], v[194:197], v[84:87]
	v_mfma_f32_16x16x32_bf16 v[76:79], v[158:161], v[194:197], v[76:79]
	s_barrier
	s_add_i32 s74, s62, s55
	v_lshl_add_u64 v[166:167], s[44:45], 0, v[130:131]
	s_mov_b32 m0, s74
	ds_read_b128 v[198:201], v145
	ds_read_b128 v[206:209], v145 offset:1024
	ds_read_b128 v[210:213], v145 offset:2048
	ds_read_b128 v[214:217], v145 offset:3072
	global_load_lds_dwordx4 v[166:167], off
	v_lshl_add_u64 v[166:167], s[44:45], 0, v[134:135]
	s_add_i32 m0, s74, 0x2000
	s_nop 0
	global_load_lds_dwordx4 v[166:167], off
	s_barrier
	s_waitcnt lgkmcnt(0)
	v_mfma_f32_16x16x32_bf16 v[112:115], v[198:201], v[162:165], v[112:115]
	v_mfma_f32_16x16x32_bf16 v[104:107], v[210:213], v[162:165], v[104:107]
	v_mfma_f32_16x16x32_bf16 v[96:99], v[198:201], v[174:177], v[96:99]
	v_mfma_f32_16x16x32_bf16 v[88:91], v[210:213], v[174:177], v[88:91]
	v_mfma_f32_16x16x32_bf16 v[80:83], v[198:201], v[182:185], v[80:83]
	v_mfma_f32_16x16x32_bf16 v[72:75], v[210:213], v[182:185], v[72:75]
	v_mfma_f32_16x16x32_bf16 v[68:71], v[198:201], v[190:193], v[68:71]
	v_mfma_f32_16x16x32_bf16 v[64:67], v[210:213], v[190:193], v[64:67]
	v_mfma_f32_16x16x32_bf16 v[112:115], v[206:209], v[170:173], v[112:115]
	v_mfma_f32_16x16x32_bf16 v[104:107], v[214:217], v[170:173], v[104:107]
	v_mfma_f32_16x16x32_bf16 v[96:99], v[206:209], v[178:181], v[96:99]
	v_mfma_f32_16x16x32_bf16 v[88:91], v[214:217], v[178:181], v[88:91]
	v_mfma_f32_16x16x32_bf16 v[80:83], v[206:209], v[186:189], v[80:83]
	v_mfma_f32_16x16x32_bf16 v[72:75], v[214:217], v[186:189], v[72:75]
	v_mfma_f32_16x16x32_bf16 v[68:71], v[206:209], v[194:197], v[68:71]
	v_mfma_f32_16x16x32_bf16 v[64:67], v[214:217], v[194:197], v[64:67]
	s_mov_b32 m0, s56
	v_lshl_add_u64 v[166:167], s[48:49], 0, v[128:129]
	s_barrier
	ds_read_b128 v[162:165], v144 offset:16384
	ds_read_b128 v[170:173], v144 offset:17408
	ds_read_b128 v[174:177], v144 offset:18432
	ds_read_b128 v[178:181], v144 offset:19456
	ds_read_b128 v[182:185], v144 offset:20480
	ds_read_b128 v[186:189], v144 offset:21504
	ds_read_b128 v[190:193], v144 offset:22528
	ds_read_b128 v[194:197], v144 offset:23552
	global_load_lds_dwordx4 v[166:167], off
	v_lshl_add_u64 v[166:167], s[48:49], 0, v[132:133]
	s_mov_b32 m0, s57
	s_nop 0
	global_load_lds_dwordx4 v[166:167], off
	s_barrier
	s_waitcnt lgkmcnt(0)
	v_mfma_f32_16x16x32_bf16 v[60:63], v[146:149], v[162:165], v[60:63]
	v_mfma_f32_16x16x32_bf16 v[56:59], v[154:157], v[162:165], v[56:59]
	v_mfma_f32_16x16x32_bf16 v[52:55], v[146:149], v[174:177], v[52:55]
	v_mfma_f32_16x16x32_bf16 v[48:51], v[154:157], v[174:177], v[48:51]
	v_mfma_f32_16x16x32_bf16 v[36:39], v[146:149], v[182:185], v[36:39]
	v_mfma_f32_16x16x32_bf16 v[32:35], v[154:157], v[182:185], v[32:35]
	v_mfma_f32_16x16x32_bf16 v[20:23], v[146:149], v[190:193], v[20:23]
	v_mfma_f32_16x16x32_bf16 v[16:19], v[154:157], v[190:193], v[16:19]
	v_mfma_f32_16x16x32_bf16 v[60:63], v[150:153], v[170:173], v[60:63]
	v_mfma_f32_16x16x32_bf16 v[56:59], v[158:161], v[170:173], v[56:59]
	v_mfma_f32_16x16x32_bf16 v[52:55], v[150:153], v[178:181], v[52:55]
	v_mfma_f32_16x16x32_bf16 v[48:51], v[158:161], v[178:181], v[48:51]
	v_mfma_f32_16x16x32_bf16 v[36:39], v[150:153], v[186:189], v[36:39]
	v_mfma_f32_16x16x32_bf16 v[32:35], v[158:161], v[186:189], v[32:35]
	v_mfma_f32_16x16x32_bf16 v[20:23], v[150:153], v[194:197], v[20:23]
	v_mfma_f32_16x16x32_bf16 v[16:19], v[158:161], v[194:197], v[16:19]
	s_barrier
; #define PG8_STAGE(bufoff, gbase, voff) do { _Pragma("unroll") for (int _i = 0; _i < 2; ++_i) \
;         __builtin_amdgcn_global_load_lds((const unsigned*)((const char*)(gbase) + (voff)[_i]), (LAS unsigned*)(lds + (bufoff) + ldsw + _i * 8192), 16, 0, 0); } while (0)
; #define PG8_LDA(dst, b, h) do { _Pragma("unroll") for (int m = 0; m < 4; ++m) _Pragma("unroll") for (int k = 0; k < 2; ++k) dst[m][k] = *(const LAS bf16x8*)(lds + PG8_SA(b, h) + aoff + m * 2048 + k * 1024); } while (0)
; #define PG8_LDB(dst, b, h) do { _Pragma("unroll") for (int n = 0; n < 2; ++n) _Pragma("unroll") for (int k = 0; k < 2; ++k) dst[n][k] = *(const LAS bf16x8*)(lds + PG8_SB(b, h) + boff + n * 2048 + k * 1024); } while (0)
; #define PG8_MMA(ai, bj, At, Bt) do { __builtin_amdgcn_s_setprio(1); _Pragma("unroll") for (int m = 0; m < 4; ++m) _Pragma("unroll") for (int n = 0; n < 2; ++n) _Pragma("unroll") for (int k = 0; k < 2; ++k) \
;         acc[ai][bj][m][n] = __builtin_amdgcn_mfma_f32_16x16x32_bf16(Bt[n][k], At[m][k], acc[ai][bj][m][n], 0, 0, 0); __builtin_amdgcn_s_setprio(0); } while (0)
; #define PG8_WAIT_V(n) asm volatile("s_waitcnt vmcnt(" #n ")" ::: "memory")
; #define PG8_WAIT_L(n) asm volatile("s_waitcnt lgkmcnt(" #n ")" ::: "memory")
; #define PG8_BAR __builtin_amdgcn_s_barrier()
; #define PG8_SCHED __builtin_amdgcn_sched_barrier(0)
; template <class Epi, class Sched>
; __device__ __forceinline__ void gemm_phase(LAS unsigned char* lds, const Gemm g, const Sched& S, const Epi& E) {
;     ...
;             PG8_STAGE(PG8_SB(0, 1), b2 + hstep, voffB);
;             PG8_WAIT_V(6); PG8_BAR; PG8_MMA(1, 1, At, B1); PG8_BAR;
;             PG8_LDB(B0, 1, 0); PG8_SCHED; PG8_LDA(At, 1, 0); PG8_STAGE(PG8_SA(0, 1), a2 + hstep, voffA);
;             PG8_WAIT_L(8); PG8_BAR; PG8_WAIT_L(0); PG8_MMA(0, 0, At, B0); PG8_BAR; PG8_SCHED;
;             PG8_LDB(B1, 1, 1); PG8_STAGE(PG8_SB(1, 0), b3, voffB);
;             PG8_BAR; PG8_WAIT_L(0); PG8_MMA(0, 1, At, B1); PG8_BAR;
;             PG8_LDA(At, 1, 1); PG8_STAGE(PG8_SA(1, 0), a3, voffA);
;             PG8_BAR; PG8_WAIT_L(0); PG8_MMA(1, 0, At, B0); PG8_BAR; PG8_SCHED;
	s_add_u32 s74, s44, 0x4000
	s_addc_u32 s75, s45, 0
	s_add_i32 s76, s63, s55
	v_lshl_add_u64 v[146:147], s[74:75], 0, v[130:131]
	s_mov_b32 m0, s76
	s_nop 0
	global_load_lds_dwordx4 v[146:147], off
	v_lshl_add_u64 v[146:147], s[74:75], 0, v[134:135]
	s_add_i32 m0, s76, 0x2000
	s_nop 0
	global_load_lds_dwordx4 v[146:147], off
	s_waitcnt vmcnt(6)
	s_barrier
	v_mfma_f32_16x16x32_bf16 v[44:47], v[198:201], v[162:165], v[44:47]
	v_mfma_f32_16x16x32_bf16 v[40:43], v[210:213], v[162:165], v[40:43]
	v_mfma_f32_16x16x32_bf16 v[28:31], v[198:201], v[174:177], v[28:31]
	v_mfma_f32_16x16x32_bf16 v[24:27], v[210:213], v[174:177], v[24:27]
	v_mfma_f32_16x16x32_bf16 v[12:15], v[198:201], v[182:185], v[12:15]
	v_mfma_f32_16x16x32_bf16 v[8:11], v[210:213], v[182:185], v[8:11]
	v_mfma_f32_16x16x32_bf16 v[4:7], v[198:201], v[190:193], v[4:7]
	v_mfma_f32_16x16x32_bf16 v[0:3], v[210:213], v[190:193], v[0:3]
	v_mfma_f32_16x16x32_bf16 v[44:47], v[206:209], v[170:173], v[44:47]
	v_mfma_f32_16x16x32_bf16 v[40:43], v[214:217], v[170:173], v[40:43]
	v_mfma_f32_16x16x32_bf16 v[28:31], v[206:209], v[178:181], v[28:31]
	v_mfma_f32_16x16x32_bf16 v[24:27], v[214:217], v[178:181], v[24:27]
	v_mfma_f32_16x16x32_bf16 v[12:15], v[206:209], v[186:189], v[12:15]
	v_mfma_f32_16x16x32_bf16 v[8:11], v[214:217], v[186:189], v[8:11]
	v_mfma_f32_16x16x32_bf16 v[4:7], v[206:209], v[194:197], v[4:7]
	v_mfma_f32_16x16x32_bf16 v[0:3], v[214:217], v[194:197], v[0:3]
	s_add_i32 s74, 0, 0x18000
	v_add_u32_e32 v158, s74, v141
	s_barrier
	ds_read_b128 v[146:149], v158
	ds_read_b128 v[150:153], v158 offset:1024
	ds_read_b128 v[154:157], v158 offset:2048
	ds_read_b128 v[158:161], v158 offset:3072
	s_add_u32 s48, s48, 0x4000
	s_addc_u32 s49, s49, 0
	s_mov_b32 m0, s58
	v_lshl_add_u64 v[166:167], s[48:49], 0, v[128:129]
	ds_read_b128 v[162:165], v144 offset:32768
	ds_read_b128 v[170:173], v144 offset:33792
	ds_read_b128 v[174:177], v144 offset:34816
	ds_read_b128 v[178:181], v144 offset:35840
	ds_read_b128 v[182:185], v144 offset:36864
	ds_read_b128 v[186:189], v144 offset:37888
	ds_read_b128 v[190:193], v144 offset:38912
	ds_read_b128 v[194:197], v144 offset:39936
	global_load_lds_dwordx4 v[166:167], off
	v_lshl_add_u64 v[166:167], s[48:49], 0, v[132:133]
	s_mov_b32 m0, s59
	s_nop 0
	global_load_lds_dwordx4 v[166:167], off
	s_waitcnt lgkmcnt(8)
	s_barrier
	s_waitcnt lgkmcnt(0)
	v_mfma_f32_16x16x32_bf16 v[124:127], v[146:149], v[162:165], v[124:127]
	v_mfma_f32_16x16x32_bf16 v[120:123], v[154:157], v[162:165], v[120:123]
	v_mfma_f32_16x16x32_bf16 v[116:119], v[146:149], v[174:177], v[116:119]
	v_mfma_f32_16x16x32_bf16 v[108:111], v[154:157], v[174:177], v[108:111]
	v_mfma_f32_16x16x32_bf16 v[100:103], v[146:149], v[182:185], v[100:103]
	v_mfma_f32_16x16x32_bf16 v[92:95], v[154:157], v[182:185], v[92:95]
	v_mfma_f32_16x16x32_bf16 v[84:87], v[146:149], v[190:193], v[84:87]
	v_mfma_f32_16x16x32_bf16 v[76:79], v[154:157], v[190:193], v[76:79]
	v_mfma_f32_16x16x32_bf16 v[124:127], v[150:153], v[170:173], v[124:127]
	v_mfma_f32_16x16x32_bf16 v[120:123], v[158:161], v[170:173], v[120:123]
	v_mfma_f32_16x16x32_bf16 v[116:119], v[150:153], v[178:181], v[116:119]
	v_mfma_f32_16x16x32_bf16 v[108:111], v[158:161], v[178:181], v[108:111]
	v_mfma_f32_16x16x32_bf16 v[100:103], v[150:153], v[186:189], v[100:103]
	v_mfma_f32_16x16x32_bf16 v[92:95], v[158:161], v[186:189], v[92:95]
	v_mfma_f32_16x16x32_bf16 v[84:87], v[150:153], v[194:197], v[84:87]
	v_mfma_f32_16x16x32_bf16 v[76:79], v[158:161], v[194:197], v[76:79]
	s_barrier
	s_add_i32 s75, 0, 0x1c000
	s_add_u32 s48, s44, 0x8000
	v_add_u32_e32 v166, s75, v141
	s_addc_u32 s49, s45, 0
	s_add_i32 s74, s74, s55
	ds_read_b128 v[198:201], v166
	ds_read_b128 v[206:209], v166 offset:1024
	ds_read_b128 v[210:213], v166 offset:2048
	ds_read_b128 v[214:217], v166 offset:3072
	v_lshl_add_u64 v[166:167], s[48:49], 0, v[130:131]
	s_mov_b32 m0, s74
	s_nop 0
	global_load_lds_dwordx4 v[166:167], off
	v_lshl_add_u64 v[166:167], s[48:49], 0, v[134:135]
	s_add_i32 m0, s74, 0x2000
	s_nop 0
	global_load_lds_dwordx4 v[166:167], off
	s_barrier
	s_waitcnt lgkmcnt(0)
	v_mfma_f32_16x16x32_bf16 v[112:115], v[198:201], v[162:165], v[112:115]
	v_mfma_f32_16x16x32_bf16 v[104:107], v[210:213], v[162:165], v[104:107]
	v_mfma_f32_16x16x32_bf16 v[96:99], v[198:201], v[174:177], v[96:99]
	v_mfma_f32_16x16x32_bf16 v[88:91], v[210:213], v[174:177], v[88:91]
	v_mfma_f32_16x16x32_bf16 v[80:83], v[198:201], v[182:185], v[80:83]
	v_mfma_f32_16x16x32_bf16 v[72:75], v[210:213], v[182:185], v[72:75]
	v_mfma_f32_16x16x32_bf16 v[68:71], v[198:201], v[190:193], v[68:71]
	v_mfma_f32_16x16x32_bf16 v[64:67], v[210:213], v[190:193], v[64:67]
	v_mfma_f32_16x16x32_bf16 v[112:115], v[206:209], v[170:173], v[112:115]
	v_mfma_f32_16x16x32_bf16 v[104:107], v[214:217], v[170:173], v[104:107]
	v_mfma_f32_16x16x32_bf16 v[96:99], v[206:209], v[178:181], v[96:99]
	v_mfma_f32_16x16x32_bf16 v[88:91], v[214:217], v[178:181], v[88:91]
	v_mfma_f32_16x16x32_bf16 v[80:83], v[206:209], v[186:189], v[80:83]
	v_mfma_f32_16x16x32_bf16 v[72:75], v[214:217], v[186:189], v[72:75]
	v_mfma_f32_16x16x32_bf16 v[68:71], v[206:209], v[194:197], v[68:71]
	v_mfma_f32_16x16x32_bf16 v[64:67], v[214:217], v[194:197], v[64:67]
	s_mov_b32 m0, s33
	v_lshl_add_u64 v[166:167], s[46:47], 0, v[128:129]
	s_barrier
	ds_read_b128 v[162:165], v144 offset:49152
	ds_read_b128 v[170:173], v144 offset:50176
	ds_read_b128 v[174:177], v144 offset:51200
	ds_read_b128 v[178:181], v144 offset:52224
	ds_read_b128 v[182:185], v144 offset:53248
	ds_read_b128 v[186:189], v144 offset:54272
	ds_read_b128 v[190:193], v144 offset:55296
	ds_read_b128 v[194:197], v144 offset:56320
	global_load_lds_dwordx4 v[166:167], off
	v_lshl_add_u64 v[166:167], s[46:47], 0, v[132:133]
	s_mov_b32 m0, s60
	s_nop 0
	global_load_lds_dwordx4 v[166:167], off
	s_barrier
; #define PG8_STAGE(bufoff, gbase, voff) do { _Pragma("unroll") for (int _i = 0; _i < 2; ++_i) \
;         __builtin_amdgcn_global_load_lds((const unsigned*)((const char*)(gbase) + (voff)[_i]), (LAS unsigned*)(lds + (bufoff) + ldsw + _i * 8192), 16, 0, 0); } while (0)
; #define PG8_MMA(ai, bj, At, Bt) do { __builtin_amdgcn_s_setprio(1); _Pragma("unroll") for (int m = 0; m < 4; ++m) _Pragma("unroll") for (int n = 0; n < 2; ++n) _Pragma("unroll") for (int k = 0; k < 2; ++k) \
;         acc[ai][bj][m][n] = __builtin_amdgcn_mfma_f32_16x16x32_bf16(Bt[n][k], At[m][k], acc[ai][bj][m][n], 0, 0, 0); __builtin_amdgcn_s_setprio(0); } while (0)
; #define PG8_WAIT_V(n) asm volatile("s_waitcnt vmcnt(" #n ")" ::: "memory")
; #define PG8_WAIT_L(n) asm volatile("s_waitcnt lgkmcnt(" #n ")" ::: "memory")
; #define PG8_BAR __builtin_amdgcn_s_barrier()
; #define PG8_SCHED __builtin_amdgcn_sched_barrier(0)
; template <class Epi, class Sched>
; __device__ __forceinline__ void gemm_phase(LAS unsigned char* lds, const Gemm g, const Sched& S, const Epi& E) {
;     ...
;             PG8_BAR; PG8_WAIT_L(0); PG8_MMA(1, 0, At, B0); PG8_BAR; PG8_SCHED;
;             PG8_STAGE(PG8_SB(1, 1), b3 + hstep, voffB);
;             PG8_WAIT_V(6); PG8_BAR; PG8_MMA(1, 1, At, B1); PG8_BAR;
	s_waitcnt lgkmcnt(0)
	v_mfma_f32_16x16x32_bf16 v[60:63], v[146:149], v[162:165], v[60:63]
	v_mfma_f32_16x16x32_bf16 v[56:59], v[154:157], v[162:165], v[56:59]
	v_mfma_f32_16x16x32_bf16 v[52:55], v[146:149], v[174:177], v[52:55]
	v_mfma_f32_16x16x32_bf16 v[48:51], v[154:157], v[174:177], v[48:51]
	v_mfma_f32_16x16x32_bf16 v[36:39], v[146:149], v[182:185], v[36:39]
	v_mfma_f32_16x16x32_bf16 v[32:35], v[154:157], v[182:185], v[32:35]
	v_mfma_f32_16x16x32_bf16 v[20:23], v[146:149], v[190:193], v[20:23]
	v_mfma_f32_16x16x32_bf16 v[16:19], v[154:157], v[190:193], v[16:19]
	v_mfma_f32_16x16x32_bf16 v[60:63], v[150:153], v[170:173], v[60:63]
	v_mfma_f32_16x16x32_bf16 v[56:59], v[158:161], v[170:173], v[56:59]
	v_mfma_f32_16x16x32_bf16 v[52:55], v[150:153], v[178:181], v[52:55]
	v_mfma_f32_16x16x32_bf16 v[48:51], v[158:161], v[178:181], v[48:51]
	v_mfma_f32_16x16x32_bf16 v[36:39], v[150:153], v[186:189], v[36:39]
	v_mfma_f32_16x16x32_bf16 v[32:35], v[158:161], v[186:189], v[32:35]
	v_mfma_f32_16x16x32_bf16 v[20:23], v[150:153], v[194:197], v[20:23]
	v_mfma_f32_16x16x32_bf16 v[16:19], v[158:161], v[194:197], v[16:19]
	s_barrier
	s_add_u32 s44, s44, 0xc000
	s_addc_u32 s45, s45, 0
	s_add_i32 s46, s75, s55
	v_lshl_add_u64 v[146:147], s[44:45], 0, v[130:131]
	s_mov_b32 m0, s46
	s_nop 0
	global_load_lds_dwordx4 v[146:147], off
	v_lshl_add_u64 v[146:147], s[44:45], 0, v[134:135]
	s_add_i32 m0, s46, 0x2000
	s_nop 0
	global_load_lds_dwordx4 v[146:147], off
	s_waitcnt vmcnt(6)
	s_barrier
	v_mfma_f32_16x16x32_bf16 v[44:47], v[198:201], v[162:165], v[44:47]
	v_mfma_f32_16x16x32_bf16 v[40:43], v[210:213], v[162:165], v[40:43]
	v_mfma_f32_16x16x32_bf16 v[28:31], v[198:201], v[174:177], v[28:31]
	v_mfma_f32_16x16x32_bf16 v[24:27], v[210:213], v[174:177], v[24:27]
	v_mfma_f32_16x16x32_bf16 v[12:15], v[198:201], v[182:185], v[12:15]
	v_mfma_f32_16x16x32_bf16 v[8:11], v[210:213], v[182:185], v[8:11]
	v_mfma_f32_16x16x32_bf16 v[4:7], v[198:201], v[190:193], v[4:7]
	v_mfma_f32_16x16x32_bf16 v[0:3], v[210:213], v[190:193], v[0:3]
	v_mfma_f32_16x16x32_bf16 v[44:47], v[206:209], v[170:173], v[44:47]
	v_mfma_f32_16x16x32_bf16 v[40:43], v[214:217], v[170:173], v[40:43]
	v_mfma_f32_16x16x32_bf16 v[28:31], v[206:209], v[178:181], v[28:31]
	v_mfma_f32_16x16x32_bf16 v[24:27], v[214:217], v[178:181], v[24:27]
	v_mfma_f32_16x16x32_bf16 v[12:15], v[206:209], v[186:189], v[12:15]
	v_mfma_f32_16x16x32_bf16 v[8:11], v[214:217], v[186:189], v[8:11]
	v_mfma_f32_16x16x32_bf16 v[4:7], v[206:209], v[194:197], v[4:7]
	v_mfma_f32_16x16x32_bf16 v[0:3], v[214:217], v[194:197], v[0:3]
	s_add_i32 s73, s73, 2
	s_add_u32 s42, s42, 0x10000
	s_addc_u32 s43, s43, 0
	s_add_u32 s71, s71, 0x10000
	s_addc_u32 s72, s72, 0
	s_cmp_gt_u32 s73, 29
	s_barrier
	s_cbranch_scc0 .LBB0_161
; __device__ __forceinline__ unsigned cvt_pk_bf16(float lo, float hi) { f32x2 v = {lo, hi}; bf16x2_t b = __builtin_convertvector(v, bf16x2_t); return __builtin_bit_cast(unsigned, b); }
; __device__ __forceinline__ float gelu_f(float x) { const float u = 1.5957691216f * (x + 0.044715f * x * x * x); return x * sigmoid_f(u); }
;     __device__ __forceinline__ void operator()(const f32x4 (&acc)[2][2][4][2], const Unit& u, int wr, int wc, int fr, int fq) const {
;         const int row0 = u.pm * BM + wr * 64 + fr, col0 = u.pn * BM + wc * 32 + 8 * fq;
;         const int kind = ACT == 0 ? 0 : (u.pn < 4 ? 0 : (u.pn < 12 ? 1 : 2));
; #pragma unroll
;         for (int ai = 0; ai < 2; ++ai)
; #pragma unroll
;             for (int m = 0; m < 4; ++m) {
;                 bf16_t* rowp = O + (size_t)(row0 + ai * HALF + m * 16) * ldo + col0;
; #pragma unroll
;                 for (int bj = 0; bj < 2; ++bj) {
;                     float v[8];
; #pragma unroll
;                     for (int n = 0; n < 2; ++n)
; #pragma unroll
;                         for (int j = 0; j < 4; ++j) { const float a = acc[ai][bj][m][n][j]; v[n * 4 + j] = kind == 1 ? gelu_f(a) : (kind == 2 ? a * 0.0625f : a); }
;                     u32x4 w; w.x = cvt_pk_bf16(v[0], v[1]); w.y = cvt_pk_bf16(v[2], v[3]); w.z = cvt_pk_bf16(v[4], v[5]); w.w = cvt_pk_bf16(v[6], v[7]);
;                     *(u32x4*)(rowp + bj * HALF) = w;
;                 }
;             }
	v_lshl_add_u32 v146, s6, 8, v140
	v_lshl_or_b32 v148, s68, 8, v142
	v_ashrrev_i32_e32 v147, 31, v146
	v_ashrrev_i32_e32 v149, 31, v148
	v_lshlrev_b64 v[150:151], 11, v[146:147]
	v_lshl_add_u64 v[150:151], s[8:9], 0, v[150:151]
	v_lshlrev_b64 v[148:149], 1, v[148:149]
	v_lshl_add_u64 v[150:151], v[150:151], 0, v[148:149]
	v_cvt_pk_bf16_f32 v60, v60, v61
	v_cvt_pk_bf16_f32 v61, v62, v63
	v_cvt_pk_bf16_f32 v62, v56, v57
	v_add_co_u32_e32 v56, vcc, s64, v150
	v_cvt_pk_bf16_f32 v68, v68, v69
	v_cvt_pk_bf16_f32 v69, v70, v71
	v_cvt_pk_bf16_f32 v70, v64, v65
	v_lshl_add_u64 v[64:65], v[150:151], 0, s[10:11]
	v_addc_co_u32_e32 v57, vcc, 0, v151, vcc
	v_cvt_pk_bf16_f32 v44, v44, v45
	v_cvt_pk_bf16_f32 v45, v46, v47
	v_cvt_pk_bf16_f32 v46, v40, v41
	v_cvt_pk_bf16_f32 v47, v42, v43
	v_cvt_pk_bf16_f32 v112, v112, v113
	v_cvt_pk_bf16_f32 v113, v114, v115
	v_cvt_pk_bf16_f32 v114, v104, v105
	v_or_b32_e32 v104, 16, v146
	global_store_dwordx4 v[64:65], v[44:47], off offset:256
	v_ashrrev_i32_e32 v105, 31, v104
	v_cvt_pk_bf16_f32 v96, v96, v97
	v_add_co_u32_e32 v46, vcc, s65, v150
	v_cvt_pk_bf16_f32 v97, v98, v99
	v_cvt_pk_bf16_f32 v98, v88, v89
	v_or_b32_e32 v88, 32, v146
	v_lshl_add_u64 v[44:45], v[150:151], 0, s[12:13]
	v_addc_co_u32_e32 v47, vcc, 0, v151, vcc
	v_cvt_pk_bf16_f32 v28, v28, v29
	v_cvt_pk_bf16_f32 v29, v30, v31
	v_cvt_pk_bf16_f32 v30, v24, v25
	v_cvt_pk_bf16_f32 v31, v26, v27
	v_lshlrev_b64 v[104:105], 11, v[104:105]
	v_ashrrev_i32_e32 v89, 31, v88
	v_cvt_pk_bf16_f32 v80, v80, v81
	v_cvt_pk_bf16_f32 v81, v82, v83
	v_cvt_pk_bf16_f32 v82, v72, v73
	v_or_b32_e32 v72, 48, v146
	global_store_dwordx4 v[44:45], v[28:31], off offset:256
	v_cvt_pk_bf16_f32 v115, v106, v107
	v_lshl_add_u64 v[104:105], s[8:9], 0, v[104:105]
	v_add_co_u32_e32 v30, vcc, s66, v150
	v_lshlrev_b64 v[88:89], 11, v[88:89]
	v_ashrrev_i32_e32 v73, 31, v72
	v_lshl_add_u64 v[28:29], v[150:151], 0, s[14:15]
	v_addc_co_u32_e32 v31, vcc, 0, v151, vcc
	v_cvt_pk_bf16_f32 v12, v12, v13
	v_cvt_pk_bf16_f32 v13, v14, v15
	v_cvt_pk_bf16_f32 v14, v8, v9
	v_cvt_pk_bf16_f32 v15, v10, v11
	global_store_dwordx4 v[150:151], v[112:115], off offset:256
	v_cvt_pk_bf16_f32 v99, v90, v91
	v_lshl_add_u64 v[88:89], s[8:9], 0, v[88:89]
	v_lshl_add_u64 v[112:113], v[104:105], 0, v[148:149]
	v_lshlrev_b64 v[72:73], 11, v[72:73]
	global_store_dwordx4 v[28:29], v[12:15], off offset:256
	global_store_dwordx4 v[112:113], v[96:99], off offset:256
	v_cvt_pk_bf16_f32 v83, v74, v75
	v_add_co_u32_e32 v14, vcc, s67, v150
	v_lshl_add_u64 v[96:97], v[88:89], 0, v[148:149]
	v_lshl_add_u64 v[72:73], s[8:9], 0, v[72:73]
	v_addc_co_u32_e32 v15, vcc, 0, v151, vcc
	v_cvt_pk_bf16_f32 v124, v124, v125
	v_cvt_pk_bf16_f32 v125, v126, v127
	v_cvt_pk_bf16_f32 v126, v120, v121
	v_cvt_pk_bf16_f32 v127, v122, v123
	v_cvt_pk_bf16_f32 v104, v116, v117
	v_cvt_pk_bf16_f32 v105, v118, v119
	v_cvt_pk_bf16_f32 v106, v108, v109
	v_cvt_pk_bf16_f32 v107, v110, v111
	v_cvt_pk_bf16_f32 v88, v100, v101
	v_cvt_pk_bf16_f32 v89, v102, v103
	v_cvt_pk_bf16_f32 v90, v92, v93
	v_cvt_pk_bf16_f32 v91, v94, v95
	global_store_dwordx4 v[96:97], v[80:83], off offset:256
	v_cvt_pk_bf16_f32 v74, v76, v77
	v_cvt_pk_bf16_f32 v75, v78, v79
	v_lshl_add_u64 v[80:81], v[72:73], 0, v[148:149]
	v_cvt_pk_bf16_f32 v72, v84, v85
	v_cvt_pk_bf16_f32 v73, v86, v87
	v_cvt_pk_bf16_f32 v71, v66, v67
	v_cvt_pk_bf16_f32 v63, v58, v59
	v_cvt_pk_bf16_f32 v40, v52, v53
	v_cvt_pk_bf16_f32 v41, v54, v55
	v_cvt_pk_bf16_f32 v42, v48, v49
	v_cvt_pk_bf16_f32 v43, v50, v51
	v_cvt_pk_bf16_f32 v24, v36, v37
	v_cvt_pk_bf16_f32 v25, v38, v39
	v_cvt_pk_bf16_f32 v26, v32, v33
	v_cvt_pk_bf16_f32 v27, v34, v35
	v_lshl_add_u64 v[12:13], v[150:151], 0, s[16:17]
	v_cvt_pk_bf16_f32 v8, v20, v21
	v_cvt_pk_bf16_f32 v9, v22, v23
	v_cvt_pk_bf16_f32 v10, v16, v17
	v_cvt_pk_bf16_f32 v11, v18, v19
	v_cvt_pk_bf16_f32 v4, v4, v5
	v_cvt_pk_bf16_f32 v5, v6, v7
	v_cvt_pk_bf16_f32 v6, v0, v1
	v_cvt_pk_bf16_f32 v7, v2, v3
	s_and_b64 vcc, exec, s[18:19]
	s_mov_b32 s68, s28
	s_mov_b32 s6, s36
	s_mov_b64 s[44:45], s[40:41]
	s_mov_b64 s[42:43], s[38:39]
	global_store_dwordx4 v[150:151], v[124:127], off
	global_store_dwordx4 v[112:113], v[104:107], off
	global_store_dwordx4 v[96:97], v[88:91], off
	global_store_dwordx4 v[80:81], v[72:75], off
	global_store_dwordx4 v[80:81], v[68:71], off offset:256
	global_store_dwordx4 v[56:57], v[60:63], off
	global_store_dwordx4 v[46:47], v[40:43], off
	global_store_dwordx4 v[30:31], v[24:27], off
	global_store_dwordx4 v[14:15], v[8:11], off
	global_store_dwordx4 v[12:13], v[4:7], off offset:256
	s_cbranch_vccz .LBB0_158
	s_waitcnt vmcnt(0)
	s_cmpk_gt_u32 s50, 0xff
	s_cbranch_scc1 .LBB0_165
	s_barrier

; #define PG8_STAGE(bufoff, gbase, voff) do { _Pragma("unroll") for (int _i = 0; _i < 2; ++_i) \
;         __builtin_amdgcn_global_load_lds((const unsigned*)((const char*)(gbase) + (voff)[_i]), (LAS unsigned*)(lds + (bufoff) + ldsw + _i * 8192), 16, 0, 0); } while (0)
; #define PG8_LDA(dst, b, h) do { _Pragma("unroll") for (int m = 0; m < 4; ++m) _Pragma("unroll") for (int k = 0; k < 2; ++k) dst[m][k] = *(const LAS bf16x8*)(lds + PG8_SA(b, h) + aoff + m * 2048 + k * 1024); } while (0)
; #define PG8_LDB(dst, b, h) do { _Pragma("unroll") for (int n = 0; n < 2; ++n) _Pragma("unroll") for (int k = 0; k < 2; ++k) dst[n][k] = *(const LAS bf16x8*)(lds + PG8_SB(b, h) + boff + n * 2048 + k * 1024); } while (0)
; #define PG8_MMA(ai, bj, At, Bt) do { __builtin_amdgcn_s_setprio(1); _Pragma("unroll") for (int m = 0; m < 4; ++m) _Pragma("unroll") for (int n = 0; n < 2; ++n) _Pragma("unroll") for (int k = 0; k < 2; ++k) \
;         acc[ai][bj][m][n] = __builtin_amdgcn_mfma_f32_16x16x32_bf16(Bt[n][k], At[m][k], acc[ai][bj][m][n], 0, 0, 0); __builtin_amdgcn_s_setprio(0); } while (0)
; #define PG8_WAIT_V(n) asm volatile("s_waitcnt vmcnt(" #n ")" ::: "memory")
; #define PG8_WAIT_L(n) asm volatile("s_waitcnt lgkmcnt(" #n ")" ::: "memory")
; #define PG8_BAR __builtin_amdgcn_s_barrier()
; #define PG8_SCHED __builtin_amdgcn_sched_barrier(0)
; template <class Epi, class Sched>
; __device__ __forceinline__ void gemm_phase(LAS unsigned char* lds, const Gemm g, const Sched& S, const Epi& E) {
;     ...
;             PG8_LDB(B0, 0, 0); PG8_SCHED; PG8_LDA(At, 0, 0); PG8_STAGE(PG8_SA(1, 1), a1 + hstep, voffA);
;             PG8_WAIT_L(8); PG8_BAR; PG8_WAIT_L(0); PG8_MMA(0, 0, At, B0); PG8_BAR; PG8_SCHED;
;             PG8_LDB(B1, 0, 1); PG8_STAGE(PG8_SB(0, 0), b2, voffB);
;             PG8_BAR; PG8_WAIT_L(0); PG8_MMA(0, 1, At, B1); PG8_BAR;
;             PG8_LDA(At, 0, 1); PG8_STAGE(PG8_SA(0, 0), a2, voffA);
;             PG8_BAR; PG8_WAIT_L(0); PG8_MMA(1, 0, At, B0); PG8_BAR; PG8_SCHED;
;             PG8_STAGE(PG8_SB(0, 1), b2 + hstep, voffB);
;             PG8_WAIT_V(6); PG8_BAR; PG8_MMA(1, 1, At, B1); PG8_BAR;
.LBB0_240:
	ds_read_b128 v[128:131], v172
	ds_read_b128 v[132:135], v172 offset:1024
	ds_read_b128 v[136:139], v172 offset:2048
	ds_read_b128 v[140:143], v172 offset:3072
	s_add_u32 s38, s36, 0x4000
	s_addc_u32 s39, s37, 0
	s_cmpk_eq_i32 s68, 0x52
	s_cselect_b32 s42, s8, s38
	s_cselect_b32 s43, s9, s39
	s_cselect_b32 s38, s10, s66
	s_cselect_b32 s39, s11, s67
	s_add_u32 s40, s42, 0x8000
	s_addc_u32 s41, s43, 0
	v_lshl_add_u64 v[166:167], s[36:37], 0, v[150:151]
	s_add_i32 m0, s48, 0xc000
	ds_read_b128 v[158:161], v173
	ds_read_b128 v[162:165], v173 offset:1024
	ds_read_b128 v[176:179], v173 offset:2048
	ds_read_b128 v[180:183], v173 offset:3072
	ds_read_b128 v[184:187], v173 offset:4096
	ds_read_b128 v[188:191], v173 offset:5120
	ds_read_b128 v[192:195], v173 offset:6144
	ds_read_b128 v[196:199], v173 offset:7168
	global_load_lds_dwordx4 v[166:167], off
	v_lshl_add_u64 v[166:167], s[36:37], 0, v[152:153]
	s_add_i32 m0, s48, 0xe000
	s_nop 0
	global_load_lds_dwordx4 v[166:167], off
	s_waitcnt lgkmcnt(8)
	s_barrier
	s_waitcnt lgkmcnt(0)
	v_mfma_f32_16x16x32_bf16 v[124:127], v[128:131], v[158:161], v[124:127]
	v_mfma_f32_16x16x32_bf16 v[120:123], v[136:139], v[158:161], v[120:123]
	v_mfma_f32_16x16x32_bf16 v[108:111], v[128:131], v[176:179], v[108:111]
	v_mfma_f32_16x16x32_bf16 v[104:107], v[136:139], v[176:179], v[104:107]
	v_mfma_f32_16x16x32_bf16 v[92:95], v[128:131], v[184:187], v[92:95]
	v_mfma_f32_16x16x32_bf16 v[88:91], v[136:139], v[184:187], v[88:91]
	v_mfma_f32_16x16x32_bf16 v[84:87], v[128:131], v[192:195], v[84:87]
	v_mfma_f32_16x16x32_bf16 v[80:83], v[136:139], v[192:195], v[80:83]
	v_mfma_f32_16x16x32_bf16 v[124:127], v[132:135], v[162:165], v[124:127]
	v_mfma_f32_16x16x32_bf16 v[120:123], v[140:143], v[162:165], v[120:123]
	v_mfma_f32_16x16x32_bf16 v[108:111], v[132:135], v[180:183], v[108:111]
	v_mfma_f32_16x16x32_bf16 v[104:107], v[140:143], v[180:183], v[104:107]
	v_mfma_f32_16x16x32_bf16 v[92:95], v[132:135], v[188:191], v[92:95]
	v_mfma_f32_16x16x32_bf16 v[88:91], v[140:143], v[188:191], v[88:91]
	v_mfma_f32_16x16x32_bf16 v[84:87], v[132:135], v[196:199], v[84:87]
	v_mfma_f32_16x16x32_bf16 v[80:83], v[140:143], v[196:199], v[80:83]
	s_barrier
	s_add_i32 s69, s56, s47
	v_lshl_add_u64 v[166:167], s[38:39], 0, v[144:145]
	s_mov_b32 m0, s69
	ds_read_b128 v[200:203], v174
	ds_read_b128 v[206:209], v174 offset:1024
	ds_read_b128 v[210:213], v174 offset:2048
	ds_read_b128 v[214:217], v174 offset:3072
	global_load_lds_dwordx4 v[166:167], off
	v_lshl_add_u64 v[166:167], s[38:39], 0, v[146:147]
	s_add_i32 m0, s69, 0x2000
	s_nop 0
	global_load_lds_dwordx4 v[166:167], off
	s_barrier
	s_waitcnt lgkmcnt(0)
	v_mfma_f32_16x16x32_bf16 v[116:119], v[200:203], v[158:161], v[116:119]
	v_mfma_f32_16x16x32_bf16 v[112:115], v[210:213], v[158:161], v[112:115]
	v_mfma_f32_16x16x32_bf16 v[100:103], v[200:203], v[176:179], v[100:103]
	v_mfma_f32_16x16x32_bf16 v[96:99], v[210:213], v[176:179], v[96:99]
	v_mfma_f32_16x16x32_bf16 v[76:79], v[200:203], v[184:187], v[76:79]
	v_mfma_f32_16x16x32_bf16 v[72:75], v[210:213], v[184:187], v[72:75]
	v_mfma_f32_16x16x32_bf16 v[68:71], v[200:203], v[192:195], v[68:71]
	v_mfma_f32_16x16x32_bf16 v[64:67], v[210:213], v[192:195], v[64:67]
	v_mfma_f32_16x16x32_bf16 v[116:119], v[206:209], v[162:165], v[116:119]
	v_mfma_f32_16x16x32_bf16 v[112:115], v[214:217], v[162:165], v[112:115]
	v_mfma_f32_16x16x32_bf16 v[100:103], v[206:209], v[180:183], v[100:103]
	v_mfma_f32_16x16x32_bf16 v[96:99], v[214:217], v[180:183], v[96:99]
	v_mfma_f32_16x16x32_bf16 v[76:79], v[206:209], v[188:191], v[76:79]
	v_mfma_f32_16x16x32_bf16 v[72:75], v[214:217], v[188:191], v[72:75]
	v_mfma_f32_16x16x32_bf16 v[68:71], v[206:209], v[196:199], v[68:71]
	v_mfma_f32_16x16x32_bf16 v[64:67], v[214:217], v[196:199], v[64:67]
	s_mov_b32 m0, s48
	v_lshl_add_u64 v[166:167], s[42:43], 0, v[144:145]
	s_barrier
	ds_read_b128 v[158:161], v173 offset:16384
	ds_read_b128 v[162:165], v173 offset:17408
	ds_read_b128 v[176:179], v173 offset:18432
	ds_read_b128 v[180:183], v173 offset:19456
	ds_read_b128 v[184:187], v173 offset:20480
	ds_read_b128 v[188:191], v173 offset:21504
	ds_read_b128 v[192:195], v173 offset:22528
	ds_read_b128 v[196:199], v173 offset:23552
	global_load_lds_dwordx4 v[166:167], off
	v_lshl_add_u64 v[166:167], s[42:43], 0, v[146:147]
	s_mov_b32 m0, s49
	s_nop 0
	global_load_lds_dwordx4 v[166:167], off
	s_barrier
	s_waitcnt lgkmcnt(0)
	v_mfma_f32_16x16x32_bf16 v[60:63], v[128:131], v[158:161], v[60:63]
	v_mfma_f32_16x16x32_bf16 v[56:59], v[136:139], v[158:161], v[56:59]
	v_mfma_f32_16x16x32_bf16 v[44:47], v[128:131], v[176:179], v[44:47]
	v_mfma_f32_16x16x32_bf16 v[40:43], v[136:139], v[176:179], v[40:43]
	v_mfma_f32_16x16x32_bf16 v[28:31], v[128:131], v[184:187], v[28:31]
	v_mfma_f32_16x16x32_bf16 v[24:27], v[136:139], v[184:187], v[24:27]
	v_mfma_f32_16x16x32_bf16 v[20:23], v[128:131], v[192:195], v[20:23]
	v_mfma_f32_16x16x32_bf16 v[16:19], v[136:139], v[192:195], v[16:19]
	v_mfma_f32_16x16x32_bf16 v[60:63], v[132:135], v[162:165], v[60:63]
	v_mfma_f32_16x16x32_bf16 v[56:59], v[140:143], v[162:165], v[56:59]
	v_mfma_f32_16x16x32_bf16 v[44:47], v[132:135], v[180:183], v[44:47]
	v_mfma_f32_16x16x32_bf16 v[40:43], v[140:143], v[180:183], v[40:43]
	v_mfma_f32_16x16x32_bf16 v[28:31], v[132:135], v[188:191], v[28:31]
	v_mfma_f32_16x16x32_bf16 v[24:27], v[140:143], v[188:191], v[24:27]
	v_mfma_f32_16x16x32_bf16 v[20:23], v[132:135], v[196:199], v[20:23]
	v_mfma_f32_16x16x32_bf16 v[16:19], v[140:143], v[196:199], v[16:19]
	s_barrier
; #define PG8_STAGE(bufoff, gbase, voff) do { _Pragma("unroll") for (int _i = 0; _i < 2; ++_i) \
;         __builtin_amdgcn_global_load_lds((const unsigned*)((const char*)(gbase) + (voff)[_i]), (LAS unsigned*)(lds + (bufoff) + ldsw + _i * 8192), 16, 0, 0); } while (0)
; #define PG8_LDA(dst, b, h) do { _Pragma("unroll") for (int m = 0; m < 4; ++m) _Pragma("unroll") for (int k = 0; k < 2; ++k) dst[m][k] = *(const LAS bf16x8*)(lds + PG8_SA(b, h) + aoff + m * 2048 + k * 1024); } while (0)
; #define PG8_LDB(dst, b, h) do { _Pragma("unroll") for (int n = 0; n < 2; ++n) _Pragma("unroll") for (int k = 0; k < 2; ++k) dst[n][k] = *(const LAS bf16x8*)(lds + PG8_SB(b, h) + boff + n * 2048 + k * 1024); } while (0)
; #define PG8_MMA(ai, bj, At, Bt) do { __builtin_amdgcn_s_setprio(1); _Pragma("unroll") for (int m = 0; m < 4; ++m) _Pragma("unroll") for (int n = 0; n < 2; ++n) _Pragma("unroll") for (int k = 0; k < 2; ++k) \
;         acc[ai][bj][m][n] = __builtin_amdgcn_mfma_f32_16x16x32_bf16(Bt[n][k], At[m][k], acc[ai][bj][m][n], 0, 0, 0); __builtin_amdgcn_s_setprio(0); } while (0)
; #define PG8_WAIT_V(n) asm volatile("s_waitcnt vmcnt(" #n ")" ::: "memory")
; #define PG8_WAIT_L(n) asm volatile("s_waitcnt lgkmcnt(" #n ")" ::: "memory")
; #define PG8_BAR __builtin_amdgcn_s_barrier()
; #define PG8_SCHED __builtin_amdgcn_sched_barrier(0)
; template <class Epi, class Sched>
; __device__ __forceinline__ void gemm_phase(LAS unsigned char* lds, const Gemm g, const Sched& S, const Epi& E) {
;     ...
;             PG8_STAGE(PG8_SB(0, 1), b2 + hstep, voffB);
;             PG8_WAIT_V(6); PG8_BAR; PG8_MMA(1, 1, At, B1); PG8_BAR;
;             PG8_LDB(B0, 1, 0); PG8_SCHED; PG8_LDA(At, 1, 0); PG8_STAGE(PG8_SA(0, 1), a2 + hstep, voffA);
;             PG8_WAIT_L(8); PG8_BAR; PG8_WAIT_L(0); PG8_MMA(0, 0, At, B0); PG8_BAR; PG8_SCHED;
;             PG8_LDB(B1, 1, 1); PG8_STAGE(PG8_SB(1, 0), b3, voffB);
;             PG8_BAR; PG8_WAIT_L(0); PG8_MMA(0, 1, At, B1); PG8_BAR;
;             PG8_LDA(At, 1, 1); PG8_STAGE(PG8_SA(1, 0), a3, voffA);
;             PG8_BAR; PG8_WAIT_L(0); PG8_MMA(1, 0, At, B0); PG8_BAR; PG8_SCHED;
	s_add_u32 s70, s38, 0x4000
	s_addc_u32 s71, s39, 0
	s_add_i32 s69, s57, s47
	v_lshl_add_u64 v[128:129], s[70:71], 0, v[144:145]
	s_mov_b32 m0, s69
	s_nop 0
	global_load_lds_dwordx4 v[128:129], off
	v_lshl_add_u64 v[128:129], s[70:71], 0, v[146:147]
	s_add_i32 m0, s69, 0x2000
	s_nop 0
	global_load_lds_dwordx4 v[128:129], off
	s_waitcnt vmcnt(6)
	s_barrier
	v_mfma_f32_16x16x32_bf16 v[52:55], v[200:203], v[158:161], v[52:55]
	v_mfma_f32_16x16x32_bf16 v[48:51], v[210:213], v[158:161], v[48:51]
	v_mfma_f32_16x16x32_bf16 v[36:39], v[200:203], v[176:179], v[36:39]
	v_mfma_f32_16x16x32_bf16 v[32:35], v[210:213], v[176:179], v[32:35]
	v_mfma_f32_16x16x32_bf16 v[12:15], v[200:203], v[184:187], v[12:15]
	v_mfma_f32_16x16x32_bf16 v[8:11], v[210:213], v[184:187], v[8:11]
	v_mfma_f32_16x16x32_bf16 v[4:7], v[200:203], v[192:195], v[4:7]
	v_mfma_f32_16x16x32_bf16 v[0:3], v[210:213], v[192:195], v[0:3]
	v_mfma_f32_16x16x32_bf16 v[52:55], v[206:209], v[162:165], v[52:55]
	v_mfma_f32_16x16x32_bf16 v[48:51], v[214:217], v[162:165], v[48:51]
	v_mfma_f32_16x16x32_bf16 v[36:39], v[206:209], v[180:183], v[36:39]
	v_mfma_f32_16x16x32_bf16 v[32:35], v[214:217], v[180:183], v[32:35]
	v_mfma_f32_16x16x32_bf16 v[12:15], v[206:209], v[188:191], v[12:15]
	v_mfma_f32_16x16x32_bf16 v[8:11], v[214:217], v[188:191], v[8:11]
	v_mfma_f32_16x16x32_bf16 v[4:7], v[206:209], v[196:199], v[4:7]
	v_mfma_f32_16x16x32_bf16 v[0:3], v[214:217], v[196:199], v[0:3]
	s_add_i32 s69, 0, 0x18000
	v_add_u32_e32 v140, s69, v170
	s_barrier
	ds_read_b128 v[128:131], v140
	ds_read_b128 v[132:135], v140 offset:1024
	ds_read_b128 v[136:139], v140 offset:2048
	ds_read_b128 v[140:143], v140 offset:3072
	s_add_u32 s42, s42, 0x4000
	s_addc_u32 s43, s43, 0
	s_mov_b32 m0, s50
	v_lshl_add_u64 v[166:167], s[42:43], 0, v[144:145]
	ds_read_b128 v[158:161], v173 offset:32768
	ds_read_b128 v[162:165], v173 offset:33792
	ds_read_b128 v[176:179], v173 offset:34816
	ds_read_b128 v[180:183], v173 offset:35840
	ds_read_b128 v[184:187], v173 offset:36864
	ds_read_b128 v[188:191], v173 offset:37888
	ds_read_b128 v[192:195], v173 offset:38912
	ds_read_b128 v[196:199], v173 offset:39936
	global_load_lds_dwordx4 v[166:167], off
	v_lshl_add_u64 v[166:167], s[42:43], 0, v[146:147]
	s_mov_b32 m0, s51
	s_nop 0
	global_load_lds_dwordx4 v[166:167], off
	s_waitcnt lgkmcnt(8)
	s_barrier
	s_waitcnt lgkmcnt(0)
	v_mfma_f32_16x16x32_bf16 v[124:127], v[128:131], v[158:161], v[124:127]
	v_mfma_f32_16x16x32_bf16 v[120:123], v[136:139], v[158:161], v[120:123]
	v_mfma_f32_16x16x32_bf16 v[108:111], v[128:131], v[176:179], v[108:111]
	v_mfma_f32_16x16x32_bf16 v[104:107], v[136:139], v[176:179], v[104:107]
	v_mfma_f32_16x16x32_bf16 v[92:95], v[128:131], v[184:187], v[92:95]
	v_mfma_f32_16x16x32_bf16 v[88:91], v[136:139], v[184:187], v[88:91]
	v_mfma_f32_16x16x32_bf16 v[84:87], v[128:131], v[192:195], v[84:87]
	v_mfma_f32_16x16x32_bf16 v[80:83], v[136:139], v[192:195], v[80:83]
	v_mfma_f32_16x16x32_bf16 v[124:127], v[132:135], v[162:165], v[124:127]
	v_mfma_f32_16x16x32_bf16 v[120:123], v[140:143], v[162:165], v[120:123]
	v_mfma_f32_16x16x32_bf16 v[108:111], v[132:135], v[180:183], v[108:111]
	v_mfma_f32_16x16x32_bf16 v[104:107], v[140:143], v[180:183], v[104:107]
	v_mfma_f32_16x16x32_bf16 v[92:95], v[132:135], v[188:191], v[92:95]
	v_mfma_f32_16x16x32_bf16 v[88:91], v[140:143], v[188:191], v[88:91]
	v_mfma_f32_16x16x32_bf16 v[84:87], v[132:135], v[196:199], v[84:87]
	v_mfma_f32_16x16x32_bf16 v[80:83], v[140:143], v[196:199], v[80:83]
	s_barrier
	s_add_i32 s70, 0, 0x1c000
	s_add_u32 s42, s38, 0x8000
	s_addc_u32 s43, s39, 0
	s_add_i32 s69, s69, s47
	v_add_u32_e32 v148, s70, v170
	v_lshl_add_u64 v[166:167], s[42:43], 0, v[144:145]
	s_mov_b32 m0, s69
	ds_read_b128 v[200:203], v148
	ds_read_b128 v[206:209], v148 offset:1024
	ds_read_b128 v[210:213], v148 offset:2048
	ds_read_b128 v[214:217], v148 offset:3072
	global_load_lds_dwordx4 v[166:167], off
	v_lshl_add_u64 v[166:167], s[42:43], 0, v[146:147]
	s_add_i32 m0, s69, 0x2000
	s_nop 0
	global_load_lds_dwordx4 v[166:167], off
	s_barrier
	s_waitcnt lgkmcnt(0)
	v_mfma_f32_16x16x32_bf16 v[116:119], v[200:203], v[158:161], v[116:119]
	v_mfma_f32_16x16x32_bf16 v[112:115], v[210:213], v[158:161], v[112:115]
	v_mfma_f32_16x16x32_bf16 v[100:103], v[200:203], v[176:179], v[100:103]
	v_mfma_f32_16x16x32_bf16 v[96:99], v[210:213], v[176:179], v[96:99]
	v_mfma_f32_16x16x32_bf16 v[76:79], v[200:203], v[184:187], v[76:79]
	v_mfma_f32_16x16x32_bf16 v[72:75], v[210:213], v[184:187], v[72:75]
	v_mfma_f32_16x16x32_bf16 v[68:71], v[200:203], v[192:195], v[68:71]
	v_mfma_f32_16x16x32_bf16 v[64:67], v[210:213], v[192:195], v[64:67]
	v_mfma_f32_16x16x32_bf16 v[116:119], v[206:209], v[162:165], v[116:119]
	v_mfma_f32_16x16x32_bf16 v[112:115], v[214:217], v[162:165], v[112:115]
	v_mfma_f32_16x16x32_bf16 v[100:103], v[206:209], v[180:183], v[100:103]
	v_mfma_f32_16x16x32_bf16 v[96:99], v[214:217], v[180:183], v[96:99]
	v_mfma_f32_16x16x32_bf16 v[76:79], v[206:209], v[188:191], v[76:79]
	v_mfma_f32_16x16x32_bf16 v[72:75], v[214:217], v[188:191], v[72:75]
	v_mfma_f32_16x16x32_bf16 v[68:71], v[206:209], v[196:199], v[68:71]
	v_mfma_f32_16x16x32_bf16 v[64:67], v[214:217], v[196:199], v[64:67]
	s_mov_b32 m0, s54
	v_lshl_add_u64 v[166:167], s[40:41], 0, v[144:145]
	s_barrier
	ds_read_b128 v[158:161], v173 offset:49152
	ds_read_b128 v[162:165], v173 offset:50176
	ds_read_b128 v[176:179], v173 offset:51200
	ds_read_b128 v[180:183], v173 offset:52224
	ds_read_b128 v[184:187], v173 offset:53248
	ds_read_b128 v[188:191], v173 offset:54272
	ds_read_b128 v[192:195], v173 offset:55296
	ds_read_b128 v[196:199], v173 offset:56320
	global_load_lds_dwordx4 v[166:167], off
	v_lshl_add_u64 v[166:167], s[40:41], 0, v[146:147]
	s_mov_b32 m0, s55
	s_nop 0
	global_load_lds_dwordx4 v[166:167], off
	s_barrier
; #define PG8_STAGE(bufoff, gbase, voff) do { _Pragma("unroll") for (int _i = 0; _i < 2; ++_i) \
;         __builtin_amdgcn_global_load_lds((const unsigned*)((const char*)(gbase) + (voff)[_i]), (LAS unsigned*)(lds + (bufoff) + ldsw + _i * 8192), 16, 0, 0); } while (0)
; #define PG8_MMA(ai, bj, At, Bt) do { __builtin_amdgcn_s_setprio(1); _Pragma("unroll") for (int m = 0; m < 4; ++m) _Pragma("unroll") for (int n = 0; n < 2; ++n) _Pragma("unroll") for (int k = 0; k < 2; ++k) \
;         acc[ai][bj][m][n] = __builtin_amdgcn_mfma_f32_16x16x32_bf16(Bt[n][k], At[m][k], acc[ai][bj][m][n], 0, 0, 0); __builtin_amdgcn_s_setprio(0); } while (0)
; #define PG8_WAIT_V(n) asm volatile("s_waitcnt vmcnt(" #n ")" ::: "memory")
; #define PG8_WAIT_L(n) asm volatile("s_waitcnt lgkmcnt(" #n ")" ::: "memory")
; #define PG8_BAR __builtin_amdgcn_s_barrier()
; #define PG8_SCHED __builtin_amdgcn_sched_barrier(0)
; template <class Epi, class Sched>
; __device__ __forceinline__ void gemm_phase(LAS unsigned char* lds, const Gemm g, const Sched& S, const Epi& E) {
;     ...
;             PG8_BAR; PG8_WAIT_L(0); PG8_MMA(1, 0, At, B0); PG8_BAR; PG8_SCHED;
;             PG8_STAGE(PG8_SB(1, 1), b3 + hstep, voffB);
;             PG8_WAIT_V(6); PG8_BAR; PG8_MMA(1, 1, At, B1); PG8_BAR;
;     __device__ __forceinline__ void operator()(const f32x4 (&acc)[2][2][4][2], const Unit& u, int wr, int wc, int fr, int fq) const {
;     ...
;                 for (int mm = 0; mm < 2; ++mm) {
;                     const int r = row0 + ai * HALF + (mh * 2 + mm) * 16;
;                     const float* rp = MODE == 0 ? ((r < 8192 ? x0 + (size_t)r * DM : x1 + (size_t)(r - 8192) * DM) + col0) : (Z + (size_t)r * DM + col0);
;                     if (MODE == 1) st[mm] = stats[r];
; #pragma unroll
;                     for (int bj = 0; bj < 2; ++bj)
; #pragma unroll
;                         for (int n = 0; n < 2; ++n) rv[mm][bj][n] = *(const f32x4*)(rp + bj * HALF + n * 16);
	s_waitcnt lgkmcnt(0)
	v_mfma_f32_16x16x32_bf16 v[60:63], v[128:131], v[158:161], v[60:63]
	v_mfma_f32_16x16x32_bf16 v[56:59], v[136:139], v[158:161], v[56:59]
	v_mfma_f32_16x16x32_bf16 v[44:47], v[128:131], v[176:179], v[44:47]
	v_mfma_f32_16x16x32_bf16 v[40:43], v[136:139], v[176:179], v[40:43]
	v_mfma_f32_16x16x32_bf16 v[28:31], v[128:131], v[184:187], v[28:31]
	v_mfma_f32_16x16x32_bf16 v[24:27], v[136:139], v[184:187], v[24:27]
	v_mfma_f32_16x16x32_bf16 v[20:23], v[128:131], v[192:195], v[20:23]
	v_mfma_f32_16x16x32_bf16 v[16:19], v[136:139], v[192:195], v[16:19]
	v_mfma_f32_16x16x32_bf16 v[60:63], v[132:135], v[162:165], v[60:63]
	v_mfma_f32_16x16x32_bf16 v[56:59], v[140:143], v[162:165], v[56:59]
	v_mfma_f32_16x16x32_bf16 v[44:47], v[132:135], v[180:183], v[44:47]
	v_mfma_f32_16x16x32_bf16 v[40:43], v[140:143], v[180:183], v[40:43]
	v_mfma_f32_16x16x32_bf16 v[28:31], v[132:135], v[188:191], v[28:31]
	v_mfma_f32_16x16x32_bf16 v[24:27], v[140:143], v[188:191], v[24:27]
	v_mfma_f32_16x16x32_bf16 v[20:23], v[132:135], v[196:199], v[20:23]
	v_mfma_f32_16x16x32_bf16 v[16:19], v[140:143], v[196:199], v[16:19]
	s_barrier
	s_add_u32 s38, s38, 0xc000
	s_addc_u32 s39, s39, 0
	s_add_i32 s40, s70, s47
	v_lshl_add_u64 v[128:129], s[38:39], 0, v[144:145]
	s_mov_b32 m0, s40
	s_nop 0
	global_load_lds_dwordx4 v[128:129], off
	v_lshl_add_u64 v[128:129], s[38:39], 0, v[146:147]
	s_add_i32 m0, s40, 0x2000
	s_nop 0
	global_load_lds_dwordx4 v[128:129], off
	s_waitcnt vmcnt(6)
	s_barrier
	v_mfma_f32_16x16x32_bf16 v[52:55], v[200:203], v[158:161], v[52:55]
	v_mfma_f32_16x16x32_bf16 v[48:51], v[210:213], v[158:161], v[48:51]
	v_mfma_f32_16x16x32_bf16 v[36:39], v[200:203], v[176:179], v[36:39]
	v_mfma_f32_16x16x32_bf16 v[32:35], v[210:213], v[176:179], v[32:35]
	v_mfma_f32_16x16x32_bf16 v[12:15], v[200:203], v[184:187], v[12:15]
	v_mfma_f32_16x16x32_bf16 v[8:11], v[210:213], v[184:187], v[8:11]
	v_mfma_f32_16x16x32_bf16 v[4:7], v[200:203], v[192:195], v[4:7]
	v_mfma_f32_16x16x32_bf16 v[0:3], v[210:213], v[192:195], v[0:3]
	v_mfma_f32_16x16x32_bf16 v[52:55], v[206:209], v[162:165], v[52:55]
	v_mfma_f32_16x16x32_bf16 v[48:51], v[214:217], v[162:165], v[48:51]
	v_mfma_f32_16x16x32_bf16 v[36:39], v[206:209], v[180:183], v[36:39]
	v_mfma_f32_16x16x32_bf16 v[32:35], v[214:217], v[180:183], v[32:35]
	v_mfma_f32_16x16x32_bf16 v[12:15], v[206:209], v[188:191], v[12:15]
	v_mfma_f32_16x16x32_bf16 v[8:11], v[214:217], v[188:191], v[8:11]
	v_mfma_f32_16x16x32_bf16 v[4:7], v[206:209], v[196:199], v[4:7]
	v_mfma_f32_16x16x32_bf16 v[0:3], v[214:217], v[196:199], v[0:3]
	s_add_i32 s68, s68, 2
	s_add_u32 s36, s36, 0x10000
	s_addc_u32 s37, s37, 0
	s_add_u32 s66, s66, 0x10000
	s_addc_u32 s67, s67, 0
	s_cmpk_gt_u32 s68, 0x53
	s_barrier
	s_cbranch_scc0 .LBB0_240
	v_lshl_add_u32 v160, s33, 8, v169
	v_add_u32_e32 v128, 0xffffe000, v160
	v_ashrrev_i32_e32 v161, 31, v160
	v_cmp_gt_i32_e32 vcc, s52, v160
	v_mov_b32_e32 v130, s19
	v_mov_b32_e32 v131, s17
	v_cndmask_b32_e32 v129, 0, v161, vcc
	v_cndmask_b32_e32 v128, v128, v160, vcc
	v_cndmask_b32_e32 v131, v130, v131, vcc
	v_mov_b32_e32 v130, s18
	v_mov_b32_e32 v132, s16
	v_lshl_or_b32 v158, s65, 8, v171
	v_cndmask_b32_e32 v130, v130, v132, vcc
	v_lshlrev_b64 v[128:129], 13, v[128:129]
	v_ashrrev_i32_e32 v159, 31, v158
	v_lshl_add_u64 v[128:129], v[130:131], 0, v[128:129]
	v_lshl_add_u64 v[128:129], v[158:159], 2, v[128:129]
	global_load_dwordx4 v[140:143], v[128:129], off
	global_load_dwordx4 v[136:139], v[128:129], off offset:64
	global_load_dwordx4 v[132:135], v[128:129], off offset:512
	s_nop 0
	global_load_dwordx4 v[128:131], v[128:129], off offset:576
	v_or_b32_e32 v164, 16, v160
	v_cmp_lt_i32_e32 vcc, s58, v164
	s_and_saveexec_b64 s[36:37], vcc
	s_xor_b64 s[36:37], exec, s[36:37]
	v_add_u32_e32 v148, 0xffffe010, v160
	v_lshlrev_b64 v[162:163], 13, v[148:149]
	v_mov_b32_e32 v165, v149
	v_lshl_add_u64 v[166:167], s[18:19], 0, v[162:163]
	v_lshlrev_b64 v[162:163], 13, v[164:165]
	s_andn2_saveexec_b64 s[36:37], s[36:37]
	v_ashrrev_i32_e32 v165, 31, v164
	v_lshlrev_b64 v[162:163], 13, v[164:165]
	v_lshl_add_u64 v[166:167], s[16:17], 0, v[162:163]
	s_or_b64 exec, exec, s[36:37]
	v_lshlrev_b64 v[158:159], 2, v[158:159]
	v_lshl_add_u64 v[184:185], v[166:167], 0, v[158:159]
	global_load_dwordx4 v[164:167], v[184:185], off
	global_load_dwordx4 v[176:179], v[184:185], off offset:64
	global_load_dwordx4 v[180:183], v[184:185], off offset:512
	s_nop 0
	global_load_dwordx4 v[184:187], v[184:185], off offset:576
	v_lshlrev_b64 v[188:189], 13, v[160:161]
	s_waitcnt vmcnt(0)
;     __device__ __forceinline__ void operator()(const f32x4 (&acc)[2][2][4][2], const Unit& u, int wr, int wc, int fr, int fq) const {
;     ...
; #pragma unroll
;                 for (int mm = 0; mm < 2; ++mm) {
;                     const int m = mh * 2 + mm, r = row0 + ai * HALF + m * 16;
;                     float* zp = Z + (size_t)r * DM + col0;
; #pragma unroll
;                     for (int bj = 0; bj < 2; ++bj)
; #pragma unroll
;                         for (int n = 0; n < 2; ++n) {
;                             f32x4 res = rv[mm][bj][n];
;                             if (MODE == 1) res = (res - st[mm].x) * st[mm].y * gv[bj][n] + bv[bj][n];
;                             *(f32x4*)(zp + bj * HALF + n * 16) = res * ALPHA + acc[ai][bj][m][n] * scale;
;                         }
;                 }
	v_pk_mul_f32 v[142:143], v[142:143], s[14:15] op_sel_hi:[1,0]
	v_pk_mul_f32 v[140:141], v[140:141], s[14:15] op_sel_hi:[1,0]
	v_pk_mul_f32 v[132:133], v[132:133], s[14:15] op_sel_hi:[1,0]
	v_pk_mul_f32 v[130:131], v[130:131], s[14:15] op_sel_hi:[1,0]
	v_or_b32_e32 v190, 32, v160
	v_lshl_add_u64 v[188:189], s[12:13], 0, v[188:189]
	v_pk_mul_f32 v[138:139], v[138:139], s[14:15] op_sel_hi:[1,0]
	v_pk_mul_f32 v[136:137], v[136:137], s[14:15] op_sel_hi:[1,0]
	v_pk_mul_f32 v[134:135], v[134:135], s[14:15] op_sel_hi:[1,0]
	v_pk_mul_f32 v[128:129], v[128:129], s[14:15] op_sel_hi:[1,0]
	v_add_u32_e32 v148, 0xffffe020, v160
	v_mov_b32_e32 v161, s19
	v_mov_b32_e32 v175, s17
	v_mov_b32_e32 v194, s18
	v_mov_b32_e32 v195, s16
	v_or_b32_e32 v192, 48, v160
	v_pk_fma_f32 v[126:127], v[126:127], 0.5, v[142:143] op_sel_hi:[1,0,1]
	v_pk_fma_f32 v[124:125], v[124:125], 0.5, v[140:141] op_sel_hi:[1,0,1]
	v_pk_fma_f32 v[116:117], v[116:117], 0.5, v[132:133] op_sel_hi:[1,0,1]
	v_pk_fma_f32 v[114:115], v[114:115], 0.5, v[130:131] op_sel_hi:[1,0,1]
	v_ashrrev_i32_e32 v191, 31, v190
	v_lshl_add_u64 v[130:131], v[188:189], 0, v[158:159]
	v_cmp_gt_i32_e32 vcc, s52, v190
	v_lshl_add_u64 v[162:163], s[12:13], 0, v[162:163]
	v_add_u32_e32 v196, 0xffffe030, v160
	v_pk_fma_f32 v[122:123], v[122:123], 0.5, v[138:139] op_sel_hi:[1,0,1]
	v_pk_fma_f32 v[120:121], v[120:121], 0.5, v[136:137] op_sel_hi:[1,0,1]
	v_pk_fma_f32 v[118:119], v[118:119], 0.5, v[134:135] op_sel_hi:[1,0,1]
	v_pk_fma_f32 v[112:113], v[112:113], 0.5, v[128:129] op_sel_hi:[1,0,1]
	v_ashrrev_i32_e32 v193, 31, v192
	v_cndmask_b32_e32 v133, 0, v191, vcc
	v_cndmask_b32_e32 v132, v148, v190, vcc
	v_cndmask_b32_e32 v135, v161, v175, vcc
	v_cndmask_b32_e32 v134, v194, v195, vcc
	v_cmp_gt_i32_e32 vcc, s52, v192
	global_store_dwordx4 v[130:131], v[124:127], off
	global_store_dwordx4 v[130:131], v[120:123], off offset:64
	global_store_dwordx4 v[130:131], v[116:119], off offset:512
	global_store_dwordx4 v[130:131], v[112:115], off offset:576
	v_lshl_add_u64 v[128:129], v[162:163], 0, v[158:159]
	v_cndmask_b32_e32 v137, 0, v193, vcc
	v_cndmask_b32_e32 v136, v196, v192, vcc
	v_lshlrev_b64 v[112:113], 13, v[132:133]
	v_cndmask_b32_e32 v139, v161, v175, vcc
	v_lshl_add_u64 v[112:113], v[134:135], 0, v[112:113]
	v_cndmask_b32_e32 v138, v194, v195, vcc
	v_lshl_add_u64 v[112:113], v[112:113], 0, v[158:159]
	v_add_u32_e32 v134, 0xffffe080, v160
	v_cmp_gt_i32_e32 vcc, s59, v160
	v_lshlrev_b64 v[132:133], 13, v[192:193]
	v_lshl_add_u64 v[132:133], s[12:13], 0, v[132:133]
	v_lshl_add_u64 v[132:133], v[132:133], 0, v[158:159]
	v_pk_mul_f32 v[114:115], v[166:167], s[14:15] op_sel_hi:[1,0]
	v_pk_mul_f32 v[116:117], v[164:165], s[14:15] op_sel_hi:[1,0]
	v_pk_mul_f32 v[118:119], v[178:179], s[14:15] op_sel_hi:[1,0]
	v_pk_mul_f32 v[130:131], v[184:185], s[14:15] op_sel_hi:[1,0]
	v_pk_mul_f32 v[120:121], v[176:177], s[14:15] op_sel_hi:[1,0]
	v_pk_mul_f32 v[122:123], v[182:183], s[14:15] op_sel_hi:[1,0]
	v_pk_mul_f32 v[124:125], v[180:181], s[14:15] op_sel_hi:[1,0]
	v_pk_mul_f32 v[126:127], v[186:187], s[14:15] op_sel_hi:[1,0]
	v_pk_fma_f32 v[108:109], v[108:109], 0.5, v[116:117] op_sel_hi:[1,0,1]
	v_pk_fma_f32 v[110:111], v[110:111], 0.5, v[114:115] op_sel_hi:[1,0,1]
	v_pk_fma_f32 v[96:97], v[96:97], 0.5, v[130:131] op_sel_hi:[1,0,1]
	v_pk_fma_f32 v[104:105], v[104:105], 0.5, v[120:121] op_sel_hi:[1,0,1]
	v_pk_fma_f32 v[106:107], v[106:107], 0.5, v[118:119] op_sel_hi:[1,0,1]
	v_pk_fma_f32 v[100:101], v[100:101], 0.5, v[124:125] op_sel_hi:[1,0,1]
	v_pk_fma_f32 v[102:103], v[102:103], 0.5, v[122:123] op_sel_hi:[1,0,1]
	v_pk_fma_f32 v[98:99], v[98:99], 0.5, v[126:127] op_sel_hi:[1,0,1]
	global_store_dwordx4 v[128:129], v[108:111], off
	global_store_dwordx4 v[128:129], v[104:107], off offset:64
	global_store_dwordx4 v[128:129], v[100:103], off offset:512
	global_store_dwordx4 v[128:129], v[96:99], off offset:576
	global_load_dwordx4 v[98:101], v[112:113], off
	v_lshlrev_b64 v[130:131], 13, v[190:191]
	v_lshlrev_b64 v[96:97], 13, v[136:137]
	v_lshl_add_u64 v[96:97], v[138:139], 0, v[96:97]
	v_lshl_add_u64 v[96:97], v[96:97], 0, v[158:159]
	global_load_dwordx4 v[102:105], v[112:113], off offset:64
	global_load_dwordx4 v[106:109], v[112:113], off offset:512
	v_cndmask_b32_e32 v137, v161, v175, vcc
	global_load_dwordx4 v[110:113], v[112:113], off offset:576
	s_nop 0
	global_load_dwordx4 v[114:117], v[96:97], off
	global_load_dwordx4 v[118:121], v[96:97], off offset:64
	global_load_dwordx4 v[122:125], v[96:97], off offset:512
	global_load_dwordx4 v[126:129], v[96:97], off offset:576
	v_add_u32_e32 v96, 0x80, v160
	v_ashrrev_i32_e32 v97, 31, v96
	v_cndmask_b32_e32 v135, 0, v97, vcc
	v_cndmask_b32_e32 v134, v134, v96, vcc
	v_cndmask_b32_e32 v136, v194, v195, vcc
	v_lshl_add_u64 v[130:131], s[12:13], 0, v[130:131]
	v_lshlrev_b64 v[134:135], 13, v[134:135]
	v_lshl_add_u64 v[130:131], v[130:131], 0, v[158:159]
	v_lshl_add_u64 v[134:135], v[136:137], 0, v[134:135]
	v_lshl_add_u64 v[134:135], v[134:135], 0, v[158:159]
	v_cmp_lt_i32_e32 vcc, s60, v160
	s_waitcnt vmcnt(0)
;     __device__ __forceinline__ void operator()(const f32x4 (&acc)[2][2][4][2], const Unit& u, int wr, int wc, int fr, int fq) const {
;     ...
;         for (int ai = 0; ai < 2; ++ai)
; #pragma unroll
;             for (int mh = 0; mh < 2; ++mh) {
;                 f32x4 rv[2][2][2]; f32x2 st[2];
; #pragma unroll
;                 for (int mm = 0; mm < 2; ++mm) {
;                     const int r = row0 + ai * HALF + (mh * 2 + mm) * 16;
;                     const float* rp = MODE == 0 ? ((r < 8192 ? x0 + (size_t)r * DM : x1 + (size_t)(r - 8192) * DM) + col0) : (Z + (size_t)r * DM + col0);
;                     if (MODE == 1) st[mm] = stats[r];
; #pragma unroll
;                     for (int bj = 0; bj < 2; ++bj)
; #pragma unroll
;                         for (int n = 0; n < 2; ++n) rv[mm][bj][n] = *(const f32x4*)(rp + bj * HALF + n * 16);
;                 }
; #pragma unroll
;                 for (int mm = 0; mm < 2; ++mm) {
;                     const int m = mh * 2 + mm, r = row0 + ai * HALF + m * 16;
;                     float* zp = Z + (size_t)r * DM + col0;
; #pragma unroll
;                     for (int bj = 0; bj < 2; ++bj)
; #pragma unroll
;                         for (int n = 0; n < 2; ++n) {
;                             f32x4 res = rv[mm][bj][n];
;                             if (MODE == 1) res = (res - st[mm].x) * st[mm].y * gv[bj][n] + bv[bj][n];
;                             *(f32x4*)(zp + bj * HALF + n * 16) = res * ALPHA + acc[ai][bj][m][n] * scale;
;                         }
;                 }
	v_pk_mul_f32 v[100:101], v[100:101], s[14:15] op_sel_hi:[1,0]
	v_pk_mul_f32 v[98:99], v[98:99], s[14:15] op_sel_hi:[1,0]
	v_pk_fma_f32 v[94:95], v[94:95], 0.5, v[100:101] op_sel_hi:[1,0,1]
	v_pk_fma_f32 v[92:93], v[92:93], 0.5, v[98:99] op_sel_hi:[1,0,1]
	v_pk_mul_f32 v[104:105], v[104:105], s[14:15] op_sel_hi:[1,0]
	v_pk_mul_f32 v[102:103], v[102:103], s[14:15] op_sel_hi:[1,0]
	v_pk_mul_f32 v[108:109], v[108:109], s[14:15] op_sel_hi:[1,0]
	v_pk_mul_f32 v[106:107], v[106:107], s[14:15] op_sel_hi:[1,0]
	v_pk_mul_f32 v[112:113], v[112:113], s[14:15] op_sel_hi:[1,0]
	v_pk_mul_f32 v[110:111], v[110:111], s[14:15] op_sel_hi:[1,0]
	v_pk_mul_f32 v[116:117], v[116:117], s[14:15] op_sel_hi:[1,0]
	v_pk_mul_f32 v[114:115], v[114:115], s[14:15] op_sel_hi:[1,0]
	v_pk_mul_f32 v[120:121], v[120:121], s[14:15] op_sel_hi:[1,0]
	v_pk_mul_f32 v[118:119], v[118:119], s[14:15] op_sel_hi:[1,0]
	v_pk_mul_f32 v[124:125], v[124:125], s[14:15] op_sel_hi:[1,0]
	v_pk_mul_f32 v[122:123], v[122:123], s[14:15] op_sel_hi:[1,0]
	v_pk_mul_f32 v[128:129], v[128:129], s[14:15] op_sel_hi:[1,0]
	v_pk_mul_f32 v[126:127], v[126:127], s[14:15] op_sel_hi:[1,0]
	v_pk_fma_f32 v[90:91], v[90:91], 0.5, v[104:105] op_sel_hi:[1,0,1]
	v_pk_fma_f32 v[88:89], v[88:89], 0.5, v[102:103] op_sel_hi:[1,0,1]
	v_pk_fma_f32 v[78:79], v[78:79], 0.5, v[108:109] op_sel_hi:[1,0,1]
	v_pk_fma_f32 v[76:77], v[76:77], 0.5, v[106:107] op_sel_hi:[1,0,1]
	v_pk_fma_f32 v[74:75], v[74:75], 0.5, v[112:113] op_sel_hi:[1,0,1]
	v_pk_fma_f32 v[72:73], v[72:73], 0.5, v[110:111] op_sel_hi:[1,0,1]
	v_pk_fma_f32 v[86:87], v[86:87], 0.5, v[116:117] op_sel_hi:[1,0,1]
	v_pk_fma_f32 v[84:85], v[84:85], 0.5, v[114:115] op_sel_hi:[1,0,1]
	v_pk_fma_f32 v[82:83], v[82:83], 0.5, v[120:121] op_sel_hi:[1,0,1]
	v_pk_fma_f32 v[80:81], v[80:81], 0.5, v[118:119] op_sel_hi:[1,0,1]
	v_pk_fma_f32 v[70:71], v[70:71], 0.5, v[124:125] op_sel_hi:[1,0,1]
	v_pk_fma_f32 v[68:69], v[68:69], 0.5, v[122:123] op_sel_hi:[1,0,1]
	v_pk_fma_f32 v[66:67], v[66:67], 0.5, v[128:129] op_sel_hi:[1,0,1]
	v_pk_fma_f32 v[64:65], v[64:65], 0.5, v[126:127] op_sel_hi:[1,0,1]
	global_store_dwordx4 v[130:131], v[92:95], off
	global_store_dwordx4 v[130:131], v[88:91], off offset:64
	global_store_dwordx4 v[130:131], v[76:79], off offset:512
	global_store_dwordx4 v[130:131], v[72:75], off offset:576
	global_store_dwordx4 v[132:133], v[84:87], off
	global_store_dwordx4 v[132:133], v[80:83], off offset:64
	global_store_dwordx4 v[132:133], v[68:71], off offset:512
	global_store_dwordx4 v[132:133], v[64:67], off offset:576
	global_load_dwordx4 v[76:79], v[134:135], off
	global_load_dwordx4 v[72:75], v[134:135], off offset:64
	s_nop 0
	global_load_dwordx4 v[68:71], v[134:135], off offset:512
	global_load_dwordx4 v[64:67], v[134:135], off offset:576
	v_add_u32_e32 v82, 0x90, v160
	s_and_saveexec_b64 s[36:37], vcc
	s_xor_b64 s[36:37], exec, s[36:37]
	v_add_u32_e32 v148, 0xffffe090, v160
	v_lshlrev_b64 v[80:81], 13, v[148:149]
	v_mov_b32_e32 v83, v149
	v_lshl_add_u64 v[84:85], s[18:19], 0, v[80:81]
	v_lshlrev_b64 v[80:81], 13, v[82:83]
	s_andn2_saveexec_b64 s[36:37], s[36:37]
	s_cbranch_execz .LBB0_228
	v_ashrrev_i32_e32 v83, 31, v82
	v_lshlrev_b64 v[80:81], 13, v[82:83]
	v_lshl_add_u64 v[84:85], s[16:17], 0, v[80:81]
	s_branch .LBB0_228

; #define PG8_STAGE(bufoff, gbase, voff) do { _Pragma("unroll") for (int _i = 0; _i < 2; ++_i) \
;         __builtin_amdgcn_global_load_lds((const unsigned*)((const char*)(gbase) + (voff)[_i]), (LAS unsigned*)(lds + (bufoff) + ldsw + _i * 8192), 16, 0, 0); } while (0)
; #define PG8_LDA(dst, b, h) do { _Pragma("unroll") for (int m = 0; m < 4; ++m) _Pragma("unroll") for (int k = 0; k < 2; ++k) dst[m][k] = *(const LAS bf16x8*)(lds + PG8_SA(b, h) + aoff + m * 2048 + k * 1024); } while (0)
; #define PG8_WAIT_V(n) asm volatile("s_waitcnt vmcnt(" #n ")" ::: "memory")
; #define PG8_WAIT_L(n) asm volatile("s_waitcnt lgkmcnt(" #n ")" ::: "memory")
; template <class Epi, class Sched>
; __device__ __forceinline__ void gemm_phase(LAS unsigned char* lds, const Gemm g, const Sched& S, const Epi& E) {
;     ...
;         for (int t = 0; t < nt; t += 2) {
;             const bool last = (t == nt - 2);
;             const char* a1 = cA + (size_t)(t + 1) * kstep;
;             const char* a2 = last ? nA : cA + (size_t)(t + 2) * kstep; const char* b2 = last ? nB : cB + (size_t)(t + 2) * kstep;
;             const char* a3 = a2 + kstep; const char* b3 = b2 + kstep;
;             PG8_LDB(B0, 0, 0); PG8_SCHED; PG8_LDA(At, 0, 0); PG8_STAGE(PG8_SA(1, 1), a1 + hstep, voffA);
;             PG8_WAIT_L(8); PG8_BAR; PG8_WAIT_L(0); PG8_MMA(0, 0, At, B0); PG8_BAR; PG8_SCHED;
;             PG8_LDB(B1, 0, 1); PG8_STAGE(PG8_SB(0, 0), b2, voffB);
;             PG8_BAR; PG8_WAIT_L(0); PG8_MMA(0, 1, At, B1); PG8_BAR;
;             PG8_LDA(At, 0, 1); PG8_STAGE(PG8_SA(0, 0), a2, voffA);
;             PG8_BAR; PG8_WAIT_L(0); PG8_MMA(1, 0, At, B0); PG8_BAR; PG8_SCHED;
;             PG8_STAGE(PG8_SB(0, 1), b2 + hstep, voffB);
;             PG8_WAIT_V(6); PG8_BAR; PG8_MMA(1, 1, At, B1); PG8_BAR;
;             PG8_LDB(B0, 1, 0); PG8_SCHED; PG8_LDA(At, 1, 0); PG8_STAGE(PG8_SA(0, 1), a2 + hstep, voffA);
;             PG8_WAIT_L(8); PG8_BAR; PG8_WAIT_L(0); PG8_MMA(0, 0, At, B0); PG8_BAR; PG8_SCHED;
;             PG8_LDB(B1, 1, 1); PG8_STAGE(PG8_SB(1, 0), b3, voffB);
;             PG8_BAR; PG8_WAIT_L(0); PG8_MMA(0, 1, At, B1); PG8_BAR;
;             PG8_LDA(At, 1, 1); PG8_STAGE(PG8_SA(1, 0), a3, voffA);
;             PG8_BAR; PG8_WAIT_L(0); PG8_MMA(1, 0, At, B0); PG8_BAR; PG8_SCHED;
;             PG8_STAGE(PG8_SB(1, 1), b3 + hstep, voffB);
;             PG8_WAIT_V(6); PG8_BAR; PG8_MMA(1, 1, At, B1); PG8_BAR;
.LBB0_429:
	ds_read_b128 v[150:153], v147
	ds_read_b128 v[154:157], v147 offset:1024
	ds_read_b128 v[158:161], v147 offset:2048
	ds_read_b128 v[162:165], v147 offset:3072
	s_add_u32 s10, s8, 0x4000
	s_addc_u32 s11, s9, 0
	s_cmp_eq_u32 s67, 28
	s_cselect_b32 s52, s41, s10
	s_cselect_b32 s53, s33, s11
	s_cselect_b32 s10, s47, s65
	s_cselect_b32 s11, s39, s66
	s_add_u32 s50, s52, 0x8000
	s_addc_u32 s51, s53, 0
	v_lshl_add_u64 v[166:167], s[8:9], 0, v[136:137]
	s_add_i32 m0, s49, 0xc000
	ds_read_b128 v[170:173], v148
	ds_read_b128 v[174:177], v148 offset:1024
	ds_read_b128 v[178:181], v148 offset:2048
	ds_read_b128 v[182:185], v148 offset:3072
	ds_read_b128 v[186:189], v148 offset:4096
	ds_read_b128 v[190:193], v148 offset:5120
	ds_read_b128 v[194:197], v148 offset:6144
	ds_read_b128 v[198:201], v148 offset:7168
	global_load_lds_dwordx4 v[166:167], off
	v_lshl_add_u64 v[166:167], s[8:9], 0, v[138:139]
	s_add_i32 m0, s49, 0xe000
	s_nop 0
	global_load_lds_dwordx4 v[166:167], off
	s_waitcnt lgkmcnt(8)
	s_barrier
	s_waitcnt lgkmcnt(0)
	v_mfma_f32_16x16x32_bf16 v[124:127], v[150:153], v[170:173], v[124:127]
	v_mfma_f32_16x16x32_bf16 v[120:123], v[158:161], v[170:173], v[120:123]
	v_mfma_f32_16x16x32_bf16 v[108:111], v[150:153], v[178:181], v[108:111]
	v_mfma_f32_16x16x32_bf16 v[104:107], v[158:161], v[178:181], v[104:107]
	v_mfma_f32_16x16x32_bf16 v[92:95], v[150:153], v[186:189], v[92:95]
	v_mfma_f32_16x16x32_bf16 v[88:91], v[158:161], v[186:189], v[88:91]
	v_mfma_f32_16x16x32_bf16 v[76:79], v[150:153], v[194:197], v[76:79]
	v_mfma_f32_16x16x32_bf16 v[72:75], v[158:161], v[194:197], v[72:75]
	v_mfma_f32_16x16x32_bf16 v[124:127], v[154:157], v[174:177], v[124:127]
	v_mfma_f32_16x16x32_bf16 v[120:123], v[162:165], v[174:177], v[120:123]
	v_mfma_f32_16x16x32_bf16 v[108:111], v[154:157], v[182:185], v[108:111]
	v_mfma_f32_16x16x32_bf16 v[104:107], v[162:165], v[182:185], v[104:107]
	v_mfma_f32_16x16x32_bf16 v[92:95], v[154:157], v[190:193], v[92:95]
	v_mfma_f32_16x16x32_bf16 v[88:91], v[162:165], v[190:193], v[88:91]
	v_mfma_f32_16x16x32_bf16 v[76:79], v[154:157], v[198:201], v[76:79]
	v_mfma_f32_16x16x32_bf16 v[72:75], v[162:165], v[198:201], v[72:75]
	s_barrier
	s_add_i32 s68, s63, s56
	v_lshl_add_u64 v[166:167], s[10:11], 0, v[130:131]
	s_mov_b32 m0, s68
	ds_read_b128 v[206:209], v149
	ds_read_b128 v[210:213], v149 offset:1024
	ds_read_b128 v[214:217], v149 offset:2048
	ds_read_b128 v[218:221], v149 offset:3072
	global_load_lds_dwordx4 v[166:167], off
	v_lshl_add_u64 v[166:167], s[10:11], 0, v[134:135]
	s_add_i32 m0, s68, 0x2000
	s_nop 0
	global_load_lds_dwordx4 v[166:167], off
	s_barrier
	s_waitcnt lgkmcnt(0)
	v_mfma_f32_16x16x32_bf16 v[116:119], v[206:209], v[170:173], v[116:119]
	v_mfma_f32_16x16x32_bf16 v[112:115], v[214:217], v[170:173], v[112:115]
	v_mfma_f32_16x16x32_bf16 v[100:103], v[206:209], v[178:181], v[100:103]
	v_mfma_f32_16x16x32_bf16 v[96:99], v[214:217], v[178:181], v[96:99]
	v_mfma_f32_16x16x32_bf16 v[84:87], v[206:209], v[186:189], v[84:87]
	v_mfma_f32_16x16x32_bf16 v[80:83], v[214:217], v[186:189], v[80:83]
	v_mfma_f32_16x16x32_bf16 v[68:71], v[206:209], v[194:197], v[68:71]
	v_mfma_f32_16x16x32_bf16 v[64:67], v[214:217], v[194:197], v[64:67]
	v_mfma_f32_16x16x32_bf16 v[116:119], v[210:213], v[174:177], v[116:119]
	v_mfma_f32_16x16x32_bf16 v[112:115], v[218:221], v[174:177], v[112:115]
	v_mfma_f32_16x16x32_bf16 v[100:103], v[210:213], v[182:185], v[100:103]
	v_mfma_f32_16x16x32_bf16 v[96:99], v[218:221], v[182:185], v[96:99]
	v_mfma_f32_16x16x32_bf16 v[84:87], v[210:213], v[190:193], v[84:87]
	v_mfma_f32_16x16x32_bf16 v[80:83], v[218:221], v[190:193], v[80:83]
	v_mfma_f32_16x16x32_bf16 v[68:71], v[210:213], v[198:201], v[68:71]
	v_mfma_f32_16x16x32_bf16 v[64:67], v[218:221], v[198:201], v[64:67]
	s_mov_b32 m0, s49
	v_lshl_add_u64 v[166:167], s[52:53], 0, v[128:129]
	s_barrier
	ds_read_b128 v[170:173], v148 offset:16384
	ds_read_b128 v[174:177], v148 offset:17408
	ds_read_b128 v[178:181], v148 offset:18432
	ds_read_b128 v[182:185], v148 offset:19456
	ds_read_b128 v[186:189], v148 offset:20480
	ds_read_b128 v[190:193], v148 offset:21504
	ds_read_b128 v[194:197], v148 offset:22528
	ds_read_b128 v[198:201], v148 offset:23552
	global_load_lds_dwordx4 v[166:167], off
	v_lshl_add_u64 v[166:167], s[52:53], 0, v[132:133]
	s_mov_b32 m0, s57
	s_nop 0
	global_load_lds_dwordx4 v[166:167], off
	s_barrier
	s_waitcnt lgkmcnt(0)
	v_mfma_f32_16x16x32_bf16 v[60:63], v[150:153], v[170:173], v[60:63]
	v_mfma_f32_16x16x32_bf16 v[56:59], v[158:161], v[170:173], v[56:59]
	v_mfma_f32_16x16x32_bf16 v[44:47], v[150:153], v[178:181], v[44:47]
	v_mfma_f32_16x16x32_bf16 v[40:43], v[158:161], v[178:181], v[40:43]
	v_mfma_f32_16x16x32_bf16 v[28:31], v[150:153], v[186:189], v[28:31]
	v_mfma_f32_16x16x32_bf16 v[24:27], v[158:161], v[186:189], v[24:27]
	v_mfma_f32_16x16x32_bf16 v[12:15], v[150:153], v[194:197], v[12:15]
	v_mfma_f32_16x16x32_bf16 v[8:11], v[158:161], v[194:197], v[8:11]
	v_mfma_f32_16x16x32_bf16 v[60:63], v[154:157], v[174:177], v[60:63]
	v_mfma_f32_16x16x32_bf16 v[56:59], v[162:165], v[174:177], v[56:59]
	v_mfma_f32_16x16x32_bf16 v[44:47], v[154:157], v[182:185], v[44:47]
	v_mfma_f32_16x16x32_bf16 v[40:43], v[162:165], v[182:185], v[40:43]
	v_mfma_f32_16x16x32_bf16 v[28:31], v[154:157], v[190:193], v[28:31]
	v_mfma_f32_16x16x32_bf16 v[24:27], v[162:165], v[190:193], v[24:27]
	v_mfma_f32_16x16x32_bf16 v[12:15], v[154:157], v[198:201], v[12:15]
	v_mfma_f32_16x16x32_bf16 v[8:11], v[162:165], v[198:201], v[8:11]
	s_barrier
; #define PG8_STAGE(bufoff, gbase, voff) do { _Pragma("unroll") for (int _i = 0; _i < 2; ++_i) \
;         __builtin_amdgcn_global_load_lds((const unsigned*)((const char*)(gbase) + (voff)[_i]), (LAS unsigned*)(lds + (bufoff) + ldsw + _i * 8192), 16, 0, 0); } while (0)
; #define PG8_LDA(dst, b, h) do { _Pragma("unroll") for (int m = 0; m < 4; ++m) _Pragma("unroll") for (int k = 0; k < 2; ++k) dst[m][k] = *(const LAS bf16x8*)(lds + PG8_SA(b, h) + aoff + m * 2048 + k * 1024); } while (0)
; #define PG8_WAIT_V(n) asm volatile("s_waitcnt vmcnt(" #n ")" ::: "memory")
; #define PG8_WAIT_L(n) asm volatile("s_waitcnt lgkmcnt(" #n ")" ::: "memory")
; template <class Epi, class Sched>
; __device__ __forceinline__ void gemm_phase(LAS unsigned char* lds, const Gemm g, const Sched& S, const Epi& E) {
;     ...
;         for (int t = 0; t < nt; t += 2) {
;             const bool last = (t == nt - 2);
;             const char* a1 = cA + (size_t)(t + 1) * kstep;
;             const char* a2 = last ? nA : cA + (size_t)(t + 2) * kstep; const char* b2 = last ? nB : cB + (size_t)(t + 2) * kstep;
;             const char* a3 = a2 + kstep; const char* b3 = b2 + kstep;
;             PG8_LDB(B0, 0, 0); PG8_SCHED; PG8_LDA(At, 0, 0); PG8_STAGE(PG8_SA(1, 1), a1 + hstep, voffA);
;             PG8_WAIT_L(8); PG8_BAR; PG8_WAIT_L(0); PG8_MMA(0, 0, At, B0); PG8_BAR; PG8_SCHED;
;             PG8_LDB(B1, 0, 1); PG8_STAGE(PG8_SB(0, 0), b2, voffB);
;             PG8_BAR; PG8_WAIT_L(0); PG8_MMA(0, 1, At, B1); PG8_BAR;
;             PG8_LDA(At, 0, 1); PG8_STAGE(PG8_SA(0, 0), a2, voffA);
;             PG8_BAR; PG8_WAIT_L(0); PG8_MMA(1, 0, At, B0); PG8_BAR; PG8_SCHED;
;             PG8_STAGE(PG8_SB(0, 1), b2 + hstep, voffB);
;             PG8_WAIT_V(6); PG8_BAR; PG8_MMA(1, 1, At, B1); PG8_BAR;
;             PG8_LDB(B0, 1, 0); PG8_SCHED; PG8_LDA(At, 1, 0); PG8_STAGE(PG8_SA(0, 1), a2 + hstep, voffA);
;             PG8_WAIT_L(8); PG8_BAR; PG8_WAIT_L(0); PG8_MMA(0, 0, At, B0); PG8_BAR; PG8_SCHED;
;             PG8_LDB(B1, 1, 1); PG8_STAGE(PG8_SB(1, 0), b3, voffB);
;             PG8_BAR; PG8_WAIT_L(0); PG8_MMA(0, 1, At, B1); PG8_BAR;
;             PG8_LDA(At, 1, 1); PG8_STAGE(PG8_SA(1, 0), a3, voffA);
;             PG8_BAR; PG8_WAIT_L(0); PG8_MMA(1, 0, At, B0); PG8_BAR; PG8_SCHED;
;             PG8_STAGE(PG8_SB(1, 1), b3 + hstep, voffB);
;             PG8_WAIT_V(6); PG8_BAR; PG8_MMA(1, 1, At, B1); PG8_BAR;
	s_add_u32 s68, s10, 0x4000
	s_addc_u32 s69, s11, 0
	s_add_i32 s71, s64, s56
	v_lshl_add_u64 v[150:151], s[68:69], 0, v[130:131]
	s_mov_b32 m0, s71
	s_nop 0
	global_load_lds_dwordx4 v[150:151], off
	v_lshl_add_u64 v[150:151], s[68:69], 0, v[134:135]
	s_add_i32 m0, s71, 0x2000
	s_nop 0
	global_load_lds_dwordx4 v[150:151], off
	s_waitcnt vmcnt(6)
	s_barrier
	v_mfma_f32_16x16x32_bf16 v[52:55], v[206:209], v[170:173], v[52:55]
	v_mfma_f32_16x16x32_bf16 v[48:51], v[214:217], v[170:173], v[48:51]
	v_mfma_f32_16x16x32_bf16 v[36:39], v[206:209], v[178:181], v[36:39]
	v_mfma_f32_16x16x32_bf16 v[32:35], v[214:217], v[178:181], v[32:35]
	v_mfma_f32_16x16x32_bf16 v[20:23], v[206:209], v[186:189], v[20:23]
	v_mfma_f32_16x16x32_bf16 v[16:19], v[214:217], v[186:189], v[16:19]
	v_mfma_f32_16x16x32_bf16 v[4:7], v[206:209], v[194:197], v[4:7]
	v_mfma_f32_16x16x32_bf16 v[0:3], v[214:217], v[194:197], v[0:3]
	v_mfma_f32_16x16x32_bf16 v[52:55], v[210:213], v[174:177], v[52:55]
	v_mfma_f32_16x16x32_bf16 v[48:51], v[218:221], v[174:177], v[48:51]
	v_mfma_f32_16x16x32_bf16 v[36:39], v[210:213], v[182:185], v[36:39]
	v_mfma_f32_16x16x32_bf16 v[32:35], v[218:221], v[182:185], v[32:35]
	v_mfma_f32_16x16x32_bf16 v[20:23], v[210:213], v[190:193], v[20:23]
	v_mfma_f32_16x16x32_bf16 v[16:19], v[218:221], v[190:193], v[16:19]
	v_mfma_f32_16x16x32_bf16 v[4:7], v[210:213], v[198:201], v[4:7]
	v_mfma_f32_16x16x32_bf16 v[0:3], v[218:221], v[198:201], v[0:3]
	s_add_i32 s68, 0, 0x18000
	v_add_u32_e32 v162, s68, v145
	s_barrier
	ds_read_b128 v[150:153], v162
	ds_read_b128 v[154:157], v162 offset:1024
	ds_read_b128 v[158:161], v162 offset:2048
	ds_read_b128 v[162:165], v162 offset:3072
	s_add_u32 s52, s52, 0x4000
	s_addc_u32 s53, s53, 0
	s_mov_b32 m0, s58
	v_lshl_add_u64 v[166:167], s[52:53], 0, v[128:129]
	ds_read_b128 v[170:173], v148 offset:32768
	ds_read_b128 v[174:177], v148 offset:33792
	ds_read_b128 v[178:181], v148 offset:34816
	ds_read_b128 v[182:185], v148 offset:35840
	ds_read_b128 v[186:189], v148 offset:36864
	ds_read_b128 v[190:193], v148 offset:37888
	ds_read_b128 v[194:197], v148 offset:38912
	ds_read_b128 v[198:201], v148 offset:39936
	global_load_lds_dwordx4 v[166:167], off
	v_lshl_add_u64 v[166:167], s[52:53], 0, v[132:133]
	s_mov_b32 m0, s59
	s_nop 0
	global_load_lds_dwordx4 v[166:167], off
	s_waitcnt lgkmcnt(8)
	s_barrier
	s_waitcnt lgkmcnt(0)
	v_mfma_f32_16x16x32_bf16 v[124:127], v[150:153], v[170:173], v[124:127]
	v_mfma_f32_16x16x32_bf16 v[120:123], v[158:161], v[170:173], v[120:123]
	v_mfma_f32_16x16x32_bf16 v[108:111], v[150:153], v[178:181], v[108:111]
	v_mfma_f32_16x16x32_bf16 v[104:107], v[158:161], v[178:181], v[104:107]
	v_mfma_f32_16x16x32_bf16 v[92:95], v[150:153], v[186:189], v[92:95]
	v_mfma_f32_16x16x32_bf16 v[88:91], v[158:161], v[186:189], v[88:91]
	v_mfma_f32_16x16x32_bf16 v[76:79], v[150:153], v[194:197], v[76:79]
	v_mfma_f32_16x16x32_bf16 v[72:75], v[158:161], v[194:197], v[72:75]
	v_mfma_f32_16x16x32_bf16 v[124:127], v[154:157], v[174:177], v[124:127]
	v_mfma_f32_16x16x32_bf16 v[120:123], v[162:165], v[174:177], v[120:123]
	v_mfma_f32_16x16x32_bf16 v[108:111], v[154:157], v[182:185], v[108:111]
	v_mfma_f32_16x16x32_bf16 v[104:107], v[162:165], v[182:185], v[104:107]
	v_mfma_f32_16x16x32_bf16 v[92:95], v[154:157], v[190:193], v[92:95]
	v_mfma_f32_16x16x32_bf16 v[88:91], v[162:165], v[190:193], v[88:91]
	v_mfma_f32_16x16x32_bf16 v[76:79], v[154:157], v[198:201], v[76:79]
	v_mfma_f32_16x16x32_bf16 v[72:75], v[162:165], v[198:201], v[72:75]
	s_barrier
	s_add_i32 s69, 0, 0x1c000
	s_add_u32 s52, s10, 0x8000
	v_add_u32_e32 v166, s69, v145
	s_addc_u32 s53, s11, 0
	s_add_i32 s68, s68, s56
	ds_read_b128 v[206:209], v166
	ds_read_b128 v[210:213], v166 offset:1024
	ds_read_b128 v[214:217], v166 offset:2048
	ds_read_b128 v[218:221], v166 offset:3072
	v_lshl_add_u64 v[166:167], s[52:53], 0, v[130:131]
	s_mov_b32 m0, s68
	s_nop 0
	global_load_lds_dwordx4 v[166:167], off
	v_lshl_add_u64 v[166:167], s[52:53], 0, v[134:135]
	s_add_i32 m0, s68, 0x2000
	s_nop 0
	global_load_lds_dwordx4 v[166:167], off
	s_barrier
	s_waitcnt lgkmcnt(0)
	v_mfma_f32_16x16x32_bf16 v[116:119], v[206:209], v[170:173], v[116:119]
	v_mfma_f32_16x16x32_bf16 v[112:115], v[214:217], v[170:173], v[112:115]
	v_mfma_f32_16x16x32_bf16 v[100:103], v[206:209], v[178:181], v[100:103]
	v_mfma_f32_16x16x32_bf16 v[96:99], v[214:217], v[178:181], v[96:99]
	v_mfma_f32_16x16x32_bf16 v[84:87], v[206:209], v[186:189], v[84:87]
	v_mfma_f32_16x16x32_bf16 v[80:83], v[214:217], v[186:189], v[80:83]
	v_mfma_f32_16x16x32_bf16 v[68:71], v[206:209], v[194:197], v[68:71]
	v_mfma_f32_16x16x32_bf16 v[64:67], v[214:217], v[194:197], v[64:67]
	v_mfma_f32_16x16x32_bf16 v[116:119], v[210:213], v[174:177], v[116:119]
	v_mfma_f32_16x16x32_bf16 v[112:115], v[218:221], v[174:177], v[112:115]
	v_mfma_f32_16x16x32_bf16 v[100:103], v[210:213], v[182:185], v[100:103]
	v_mfma_f32_16x16x32_bf16 v[96:99], v[218:221], v[182:185], v[96:99]
	v_mfma_f32_16x16x32_bf16 v[84:87], v[210:213], v[190:193], v[84:87]
	v_mfma_f32_16x16x32_bf16 v[80:83], v[218:221], v[190:193], v[80:83]
	v_mfma_f32_16x16x32_bf16 v[68:71], v[210:213], v[198:201], v[68:71]
	v_mfma_f32_16x16x32_bf16 v[64:67], v[218:221], v[198:201], v[64:67]
	s_mov_b32 m0, s61
	v_lshl_add_u64 v[166:167], s[50:51], 0, v[128:129]
	s_barrier
	ds_read_b128 v[170:173], v148 offset:49152
	ds_read_b128 v[174:177], v148 offset:50176
	ds_read_b128 v[178:181], v148 offset:51200
	ds_read_b128 v[182:185], v148 offset:52224
	ds_read_b128 v[186:189], v148 offset:53248
	ds_read_b128 v[190:193], v148 offset:54272
	ds_read_b128 v[194:197], v148 offset:55296
	ds_read_b128 v[198:201], v148 offset:56320
	global_load_lds_dwordx4 v[166:167], off
	v_lshl_add_u64 v[166:167], s[50:51], 0, v[132:133]
	s_mov_b32 m0, s62
	s_nop 0
	global_load_lds_dwordx4 v[166:167], off
	s_barrier
; #define PG8_STAGE(bufoff, gbase, voff) do { _Pragma("unroll") for (int _i = 0; _i < 2; ++_i) \
;         __builtin_amdgcn_global_load_lds((const unsigned*)((const char*)(gbase) + (voff)[_i]), (LAS unsigned*)(lds + (bufoff) + ldsw + _i * 8192), 16, 0, 0); } while (0)
; #define PG8_WAIT_V(n) asm volatile("s_waitcnt vmcnt(" #n ")" ::: "memory")
; #define PG8_WAIT_L(n) asm volatile("s_waitcnt lgkmcnt(" #n ")" ::: "memory")
; template <class Epi, class Sched>
; __device__ __forceinline__ void gemm_phase(LAS unsigned char* lds, const Gemm g, const Sched& S, const Epi& E) {
;     ...
;         for (int t = 0; t < nt; t += 2) {
;             const bool last = (t == nt - 2);
;             const char* a1 = cA + (size_t)(t + 1) * kstep;
;             const char* a2 = last ? nA : cA + (size_t)(t + 2) * kstep; const char* b2 = last ? nB : cB + (size_t)(t + 2) * kstep;
;             const char* a3 = a2 + kstep; const char* b3 = b2 + kstep;
;             PG8_LDB(B0, 0, 0); PG8_SCHED; PG8_LDA(At, 0, 0); PG8_STAGE(PG8_SA(1, 1), a1 + hstep, voffA);
;             PG8_WAIT_L(8); PG8_BAR; PG8_WAIT_L(0); PG8_MMA(0, 0, At, B0); PG8_BAR; PG8_SCHED;
;             PG8_LDB(B1, 0, 1); PG8_STAGE(PG8_SB(0, 0), b2, voffB);
;             PG8_BAR; PG8_WAIT_L(0); PG8_MMA(0, 1, At, B1); PG8_BAR;
;             PG8_LDA(At, 0, 1); PG8_STAGE(PG8_SA(0, 0), a2, voffA);
;             PG8_BAR; PG8_WAIT_L(0); PG8_MMA(1, 0, At, B0); PG8_BAR; PG8_SCHED;
;             PG8_STAGE(PG8_SB(0, 1), b2 + hstep, voffB);
;             PG8_WAIT_V(6); PG8_BAR; PG8_MMA(1, 1, At, B1); PG8_BAR;
;             PG8_LDB(B0, 1, 0); PG8_SCHED; PG8_LDA(At, 1, 0); PG8_STAGE(PG8_SA(0, 1), a2 + hstep, voffA);
;             PG8_WAIT_L(8); PG8_BAR; PG8_WAIT_L(0); PG8_MMA(0, 0, At, B0); PG8_BAR; PG8_SCHED;
;             PG8_LDB(B1, 1, 1); PG8_STAGE(PG8_SB(1, 0), b3, voffB);
;             PG8_BAR; PG8_WAIT_L(0); PG8_MMA(0, 1, At, B1); PG8_BAR;
;             PG8_LDA(At, 1, 1); PG8_STAGE(PG8_SA(1, 0), a3, voffA);
;             PG8_BAR; PG8_WAIT_L(0); PG8_MMA(1, 0, At, B0); PG8_BAR; PG8_SCHED;
;             PG8_STAGE(PG8_SB(1, 1), b3 + hstep, voffB);
;             PG8_WAIT_V(6); PG8_BAR; PG8_MMA(1, 1, At, B1); PG8_BAR;
;         }
;     __device__ __forceinline__ void operator()(const f32x4 (&acc)[2][2][4][2], const Unit& u, int wr, int wc, int fr, int fq) const {
;     ...
;         const int kind = ACT == 0 ? 0 : (u.pn < 4 ? 0 : (u.pn < 12 ? 1 : 2));
	s_waitcnt lgkmcnt(0)
	v_mfma_f32_16x16x32_bf16 v[60:63], v[150:153], v[170:173], v[60:63]
	v_mfma_f32_16x16x32_bf16 v[56:59], v[158:161], v[170:173], v[56:59]
	v_mfma_f32_16x16x32_bf16 v[44:47], v[150:153], v[178:181], v[44:47]
	v_mfma_f32_16x16x32_bf16 v[40:43], v[158:161], v[178:181], v[40:43]
	v_mfma_f32_16x16x32_bf16 v[28:31], v[150:153], v[186:189], v[28:31]
	v_mfma_f32_16x16x32_bf16 v[24:27], v[158:161], v[186:189], v[24:27]
	v_mfma_f32_16x16x32_bf16 v[12:15], v[150:153], v[194:197], v[12:15]
	v_mfma_f32_16x16x32_bf16 v[8:11], v[158:161], v[194:197], v[8:11]
	v_mfma_f32_16x16x32_bf16 v[60:63], v[154:157], v[174:177], v[60:63]
	v_mfma_f32_16x16x32_bf16 v[56:59], v[162:165], v[174:177], v[56:59]
	v_mfma_f32_16x16x32_bf16 v[44:47], v[154:157], v[182:185], v[44:47]
	v_mfma_f32_16x16x32_bf16 v[40:43], v[162:165], v[182:185], v[40:43]
	v_mfma_f32_16x16x32_bf16 v[28:31], v[154:157], v[190:193], v[28:31]
	v_mfma_f32_16x16x32_bf16 v[24:27], v[162:165], v[190:193], v[24:27]
	v_mfma_f32_16x16x32_bf16 v[12:15], v[154:157], v[198:201], v[12:15]
	v_mfma_f32_16x16x32_bf16 v[8:11], v[162:165], v[198:201], v[8:11]
	s_barrier
	s_add_u32 s10, s10, 0xc000
	s_addc_u32 s11, s11, 0
	s_add_i32 s50, s69, s56
	v_lshl_add_u64 v[150:151], s[10:11], 0, v[130:131]
	s_mov_b32 m0, s50
	s_nop 0
	global_load_lds_dwordx4 v[150:151], off
	v_lshl_add_u64 v[150:151], s[10:11], 0, v[134:135]
	s_add_i32 m0, s50, 0x2000
	s_nop 0
	global_load_lds_dwordx4 v[150:151], off
	s_waitcnt vmcnt(6)
	s_barrier
	v_mfma_f32_16x16x32_bf16 v[52:55], v[206:209], v[170:173], v[52:55]
	v_mfma_f32_16x16x32_bf16 v[48:51], v[214:217], v[170:173], v[48:51]
	v_mfma_f32_16x16x32_bf16 v[36:39], v[206:209], v[178:181], v[36:39]
	v_mfma_f32_16x16x32_bf16 v[32:35], v[214:217], v[178:181], v[32:35]
	v_mfma_f32_16x16x32_bf16 v[20:23], v[206:209], v[186:189], v[20:23]
	v_mfma_f32_16x16x32_bf16 v[16:19], v[214:217], v[186:189], v[16:19]
	v_mfma_f32_16x16x32_bf16 v[4:7], v[206:209], v[194:197], v[4:7]
	v_mfma_f32_16x16x32_bf16 v[0:3], v[214:217], v[194:197], v[0:3]
	v_mfma_f32_16x16x32_bf16 v[52:55], v[210:213], v[174:177], v[52:55]
	v_mfma_f32_16x16x32_bf16 v[48:51], v[218:221], v[174:177], v[48:51]
	v_mfma_f32_16x16x32_bf16 v[36:39], v[210:213], v[182:185], v[36:39]
	v_mfma_f32_16x16x32_bf16 v[32:35], v[218:221], v[182:185], v[32:35]
	v_mfma_f32_16x16x32_bf16 v[20:23], v[210:213], v[190:193], v[20:23]
	v_mfma_f32_16x16x32_bf16 v[16:19], v[218:221], v[190:193], v[16:19]
	v_mfma_f32_16x16x32_bf16 v[4:7], v[210:213], v[198:201], v[4:7]
	v_mfma_f32_16x16x32_bf16 v[0:3], v[218:221], v[198:201], v[0:3]
	s_add_i32 s67, s67, 2
	s_add_u32 s8, s8, 0x10000
	s_addc_u32 s9, s9, 0
	s_add_u32 s65, s65, 0x10000
	s_addc_u32 s66, s66, 0
	s_cmp_gt_u32 s67, 29
	s_barrier
	s_cbranch_scc0 .LBB0_429
	s_nop 7
	s_cmp_lt_i32 s48, 4
	s_cbranch_scc1 .Lmy_p4_store
	s_cmp_lt_i32 s48, 12
	s_cbranch_scc1 .Lmy_p4_gelu
; __device__ __forceinline__ float gelu_f(float x) { const float u = 1.5957691216f * (x + 0.044715f * x * x * x); return x * sigmoid_f(u); }
;     __device__ __forceinline__ void operator()(const f32x4 (&acc)[2][2][4][2], const Unit& u, int wr, int wc, int fr, int fq) const {
;     ...
;                         for (int j = 0; j < 4; ++j) { const float a = acc[ai][bj][m][n][j]; v[n * 4 + j] = kind == 1 ? gelu_f(a) : (kind == 2 ? a * 0.0625f : a); }
	v_mul_f32_e32 v0, 0x3d800000, v0
	v_mul_f32_e32 v1, 0x3d800000, v1
	v_mul_f32_e32 v2, 0x3d800000, v2
	v_mul_f32_e32 v3, 0x3d800000, v3
	v_mul_f32_e32 v4, 0x3d800000, v4
	v_mul_f32_e32 v5, 0x3d800000, v5
	v_mul_f32_e32 v6, 0x3d800000, v6
	v_mul_f32_e32 v7, 0x3d800000, v7
	v_mul_f32_e32 v8, 0x3d800000, v8
	v_mul_f32_e32 v9, 0x3d800000, v9
	v_mul_f32_e32 v10, 0x3d800000, v10
	v_mul_f32_e32 v11, 0x3d800000, v11
	v_mul_f32_e32 v12, 0x3d800000, v12
	v_mul_f32_e32 v13, 0x3d800000, v13
	v_mul_f32_e32 v14, 0x3d800000, v14
	v_mul_f32_e32 v15, 0x3d800000, v15
	v_mul_f32_e32 v16, 0x3d800000, v16
	v_mul_f32_e32 v17, 0x3d800000, v17
	v_mul_f32_e32 v18, 0x3d800000, v18
	v_mul_f32_e32 v19, 0x3d800000, v19
	v_mul_f32_e32 v20, 0x3d800000, v20
	v_mul_f32_e32 v21, 0x3d800000, v21
	v_mul_f32_e32 v22, 0x3d800000, v22
	v_mul_f32_e32 v23, 0x3d800000, v23
	v_mul_f32_e32 v24, 0x3d800000, v24
	v_mul_f32_e32 v25, 0x3d800000, v25
	v_mul_f32_e32 v26, 0x3d800000, v26
	v_mul_f32_e32 v27, 0x3d800000, v27
	v_mul_f32_e32 v28, 0x3d800000, v28
	v_mul_f32_e32 v29, 0x3d800000, v29
	v_mul_f32_e32 v30, 0x3d800000, v30
	v_mul_f32_e32 v31, 0x3d800000, v31
	v_mul_f32_e32 v32, 0x3d800000, v32
	v_mul_f32_e32 v33, 0x3d800000, v33
	v_mul_f32_e32 v34, 0x3d800000, v34
	v_mul_f32_e32 v35, 0x3d800000, v35
	v_mul_f32_e32 v36, 0x3d800000, v36
	v_mul_f32_e32 v37, 0x3d800000, v37
	v_mul_f32_e32 v38, 0x3d800000, v38
	v_mul_f32_e32 v39, 0x3d800000, v39
	v_mul_f32_e32 v40, 0x3d800000, v40
	v_mul_f32_e32 v41, 0x3d800000, v41
	v_mul_f32_e32 v42, 0x3d800000, v42
	v_mul_f32_e32 v43, 0x3d800000, v43
	v_mul_f32_e32 v44, 0x3d800000, v44
	v_mul_f32_e32 v45, 0x3d800000, v45
	v_mul_f32_e32 v46, 0x3d800000, v46
	v_mul_f32_e32 v47, 0x3d800000, v47
	v_mul_f32_e32 v48, 0x3d800000, v48
	v_mul_f32_e32 v49, 0x3d800000, v49
	v_mul_f32_e32 v50, 0x3d800000, v50
	v_mul_f32_e32 v51, 0x3d800000, v51
	v_mul_f32_e32 v52, 0x3d800000, v52
	v_mul_f32_e32 v53, 0x3d800000, v53
	v_mul_f32_e32 v54, 0x3d800000, v54
	v_mul_f32_e32 v55, 0x3d800000, v55
	v_mul_f32_e32 v56, 0x3d800000, v56
	v_mul_f32_e32 v57, 0x3d800000, v57
	v_mul_f32_e32 v58, 0x3d800000, v58
	v_mul_f32_e32 v59, 0x3d800000, v59
	v_mul_f32_e32 v60, 0x3d800000, v60
	v_mul_f32_e32 v61, 0x3d800000, v61
	v_mul_f32_e32 v62, 0x3d800000, v62
	v_mul_f32_e32 v63, 0x3d800000, v63
	v_mul_f32_e32 v64, 0x3d800000, v64
	v_mul_f32_e32 v65, 0x3d800000, v65
	v_mul_f32_e32 v66, 0x3d800000, v66
	v_mul_f32_e32 v67, 0x3d800000, v67
	v_mul_f32_e32 v68, 0x3d800000, v68
	v_mul_f32_e32 v69, 0x3d800000, v69
	v_mul_f32_e32 v70, 0x3d800000, v70
	v_mul_f32_e32 v71, 0x3d800000, v71
	v_mul_f32_e32 v72, 0x3d800000, v72
	v_mul_f32_e32 v73, 0x3d800000, v73
	v_mul_f32_e32 v74, 0x3d800000, v74
	v_mul_f32_e32 v75, 0x3d800000, v75
	v_mul_f32_e32 v76, 0x3d800000, v76
	v_mul_f32_e32 v77, 0x3d800000, v77
	v_mul_f32_e32 v78, 0x3d800000, v78
	v_mul_f32_e32 v79, 0x3d800000, v79
	v_mul_f32_e32 v80, 0x3d800000, v80
	v_mul_f32_e32 v81, 0x3d800000, v81
	v_mul_f32_e32 v82, 0x3d800000, v82
	v_mul_f32_e32 v83, 0x3d800000, v83
	v_mul_f32_e32 v84, 0x3d800000, v84
	v_mul_f32_e32 v85, 0x3d800000, v85
	v_mul_f32_e32 v86, 0x3d800000, v86
	v_mul_f32_e32 v87, 0x3d800000, v87
	v_mul_f32_e32 v88, 0x3d800000, v88
	v_mul_f32_e32 v89, 0x3d800000, v89
	v_mul_f32_e32 v90, 0x3d800000, v90
	v_mul_f32_e32 v91, 0x3d800000, v91
	v_mul_f32_e32 v92, 0x3d800000, v92
	v_mul_f32_e32 v93, 0x3d800000, v93
	v_mul_f32_e32 v94, 0x3d800000, v94
	v_mul_f32_e32 v95, 0x3d800000, v95
	v_mul_f32_e32 v96, 0x3d800000, v96
	v_mul_f32_e32 v97, 0x3d800000, v97
	v_mul_f32_e32 v98, 0x3d800000, v98
	v_mul_f32_e32 v99, 0x3d800000, v99
	v_mul_f32_e32 v100, 0x3d800000, v100
	v_mul_f32_e32 v101, 0x3d800000, v101
	v_mul_f32_e32 v102, 0x3d800000, v102
	v_mul_f32_e32 v103, 0x3d800000, v103
	v_mul_f32_e32 v104, 0x3d800000, v104
	v_mul_f32_e32 v105, 0x3d800000, v105
	v_mul_f32_e32 v106, 0x3d800000, v106
	v_mul_f32_e32 v107, 0x3d800000, v107
	v_mul_f32_e32 v108, 0x3d800000, v108
	v_mul_f32_e32 v109, 0x3d800000, v109
	v_mul_f32_e32 v110, 0x3d800000, v110
	v_mul_f32_e32 v111, 0x3d800000, v111
	v_mul_f32_e32 v112, 0x3d800000, v112
	v_mul_f32_e32 v113, 0x3d800000, v113
	v_mul_f32_e32 v114, 0x3d800000, v114
	v_mul_f32_e32 v115, 0x3d800000, v115
	v_mul_f32_e32 v116, 0x3d800000, v116
	v_mul_f32_e32 v117, 0x3d800000, v117
	v_mul_f32_e32 v118, 0x3d800000, v118
	v_mul_f32_e32 v119, 0x3d800000, v119
	v_mul_f32_e32 v120, 0x3d800000, v120
	v_mul_f32_e32 v121, 0x3d800000, v121
	v_mul_f32_e32 v122, 0x3d800000, v122
	v_mul_f32_e32 v123, 0x3d800000, v123
	v_mul_f32_e32 v124, 0x3d800000, v124
	v_mul_f32_e32 v125, 0x3d800000, v125
	v_mul_f32_e32 v126, 0x3d800000, v126
	v_mul_f32_e32 v127, 0x3d800000, v127
	s_branch .Lmy_p4_store

; #define ATT_LOAD(src, half) do { _Pragma("unroll") for (int j = 0; j < 8; ++j) t[j] = src[((half) * 64 + wid * 8 + j) * 64]; } while (0)
; #define ATT_PUT() do { __syncthreads(); _Pragma("unroll") for (int j = 0; j < 8; ++j) stage[(wid * 8 + j) * 64 + lane] = t[j]; __syncthreads(); } while (0)
; #define ATT_QK(half) do { _Pragma("unroll") for (int kbl = 0; kbl < 8; ++kbl) { f32x4 acc = (f32x4){0.f, 0.f, 0.f, 0.f}; \
;         _Pragma("unroll") for (int ks = 0; ks < 8; ++ks) acc = MFMA16(Q[ks], *(const bf16x8*)&stage[(kbl * 8 + ks) * 64 + lane], acc); S[(half) * 8 + kbl] = acc; } } while (0)
; __device__ __forceinline__ void attn_item(KP P, int rbk, int h, unsigned char* lds) {
;     ...
;     const int tid = threadIdx.x, wid = tid >> 6, lane = tid & 63, q = lane >> 4, l15 = lane & 15, r0 = rbk * 128 + wid * 16;
;     const int b = r0 < 4096 ? 0 : (r0 < 8192 ? 1 : 2);
;     bf16_t* Pl = (bf16_t*)(lds + 65536 + wid * 8448);
;     u32x4* stage = (u32x4*)lds;
;     const u32x4* kf = (const u32x4*)(P->ws + OFF_KF) + (size_t)(b * 4 + h) * 128 * 64 + lane;
;     const u32x4* vf = (const u32x4*)(P->ws + OFF_VF) + (size_t)(b * 4 + h) * 128 * 64 + lane;
;     const bf16_t* qp = proj + (size_t)(r0 + l15) * 4096 + 3072 + h * 256 + 8 * q;
;     bf16x8 Q[8];
; #pragma unroll
;     for (int ks = 0; ks < 8; ++ks) Q[ks] = *(const bf16x8*)(qp + ks * 32);
;     f32x4 S[16];
;     u32x4 t[8];
;     ...
;     ATT_LOAD(kf, 0); ATT_PUT();
;     ATT_LOAD(kf, 1); ATT_QK(0); ATT_PUT();
.LBB0_1089:
	s_andn2_saveexec_b64 s[12:13], s[52:53]
	s_cbranch_execz .LBB0_1091
	v_and_b32_e32 v156, 3, v0
	v_lshlrev_b32_e32 v0, 5, v0
	v_and_b32_e32 v0, 0x7f80, v0
	v_add_u32_e32 v155, v143, v0
	v_cmp_gt_u32_e32 vcc, s59, v155
	s_nop 1
	v_cndmask_b32_e64 v0, 8, 4, vcc
	v_cmp_lt_u32_e32 vcc, s60, v155
	s_nop 1
	v_cndmask_b32_e32 v0, 0, v0, vcc
	v_or_b32_e32 v2, v0, v156
	v_or_b32_e32 v0, v155, v166
	v_lshlrev_b32_e32 v102, 13, v0
	v_lshl_add_u64 v[0:1], s[34:35], 0, v[102:103]
	v_lshlrev_b32_e32 v102, 9, v156
	v_lshl_add_u64 v[0:1], v[0:1], 0, v[102:103]
	v_lshlrev_b32_e32 v102, 1, v98
	v_lshl_add_u64 v[32:33], v[0:1], 0, v[102:103]
	v_lshlrev_b32_e32 v102, 17, v2
	v_lshl_add_u64 v[24:25], v[106:107], 0, v[102:103]
	v_add_co_u32_e32 v34, vcc, s61, v32
	v_lshl_add_u64 v[40:41], v[24:25], 0, v[116:117]
	v_lshl_add_u64 v[16:17], v[24:25], 0, v[118:119]
	v_lshl_add_u64 v[20:21], v[24:25], 0, v[120:121]
	v_lshl_add_u64 v[26:27], v[24:25], 0, v[122:123]
	v_lshl_add_u64 v[28:29], v[24:25], 0, v[124:125]
	v_addc_co_u32_e32 v35, vcc, 0, v33, vcc
	global_load_dwordx4 v[0:3], v[40:41], off
	global_load_dwordx4 v[4:7], v[40:41], off offset:1024
	global_load_dwordx4 v[8:11], v[40:41], off offset:2048
	global_load_dwordx4 v[12:15], v[40:41], off offset:3072
	s_nop 0
	global_load_dwordx4 v[16:19], v[16:17], off
	s_nop 0
	global_load_dwordx4 v[20:23], v[20:21], off
	s_nop 0
	global_load_dwordx4 v[24:27], v[26:27], off
	s_nop 0
	global_load_dwordx4 v[28:31], v[28:29], off
	v_lshl_add_u64 v[32:33], v[32:33], 0, s[46:47]
	global_load_dwordx4 v[84:87], v[34:35], off offset:2048
	global_load_dwordx4 v[88:91], v[32:33], off offset:64
	global_load_dwordx4 v[80:83], v[32:33], off offset:128
	global_load_dwordx4 v[76:79], v[32:33], off offset:192
	global_load_dwordx4 v[72:75], v[32:33], off offset:256
	global_load_dwordx4 v[68:71], v[32:33], off offset:320
	global_load_dwordx4 v[64:67], v[32:33], off offset:384
	global_load_dwordx4 v[60:63], v[32:33], off offset:448
	s_barrier
	v_add_co_u32_e32 v44, vcc, s18, v40
	s_waitcnt vmcnt(15)
	ds_write_b128 v167, v[0:3]
	s_waitcnt vmcnt(14)
	ds_write_b128 v167, v[4:7] offset:1024
	s_waitcnt vmcnt(13)
	ds_write_b128 v167, v[8:11] offset:2048
	s_waitcnt vmcnt(12)
	ds_write_b128 v167, v[12:15] offset:3072
	s_waitcnt vmcnt(11)
	ds_write_b128 v167, v[16:19] offset:4096
	s_waitcnt vmcnt(10)
	ds_write_b128 v167, v[20:23] offset:5120
	s_waitcnt vmcnt(9)
	ds_write_b128 v167, v[24:27] offset:6144
	s_waitcnt vmcnt(8)
	ds_write_b128 v167, v[28:31] offset:7168
	s_waitcnt lgkmcnt(0)
	s_barrier
	ds_read_b128 v[0:3], v165
	ds_read_b128 v[4:7], v165 offset:1024
	ds_read_b128 v[8:11], v165 offset:8192
	ds_read_b128 v[12:15], v165 offset:9216
	ds_read_b128 v[16:19], v165 offset:16384
	ds_read_b128 v[20:23], v165 offset:17408
	s_waitcnt vmcnt(7) lgkmcnt(5)
	v_mfma_f32_16x16x32_bf16 v[0:3], v[84:87], v[0:3], 0
	ds_read_b128 v[24:27], v165 offset:24576
	ds_read_b128 v[28:31], v165 offset:25600
	v_addc_co_u32_e32 v45, vcc, 0, v41, vcc
	s_waitcnt lgkmcnt(5)
	v_mfma_f32_16x16x32_bf16 v[8:11], v[84:87], v[8:11], 0
	v_add_co_u32_e32 v126, vcc, s62, v40
	s_waitcnt lgkmcnt(3)
	v_mfma_f32_16x16x32_bf16 v[16:19], v[84:87], v[16:19], 0
	v_addc_co_u32_e32 v127, vcc, 0, v41, vcc
	s_waitcnt lgkmcnt(1)
	v_mfma_f32_16x16x32_bf16 v[24:27], v[84:87], v[24:27], 0
	s_waitcnt vmcnt(6)
	v_mfma_f32_16x16x32_bf16 v[0:3], v[88:91], v[4:7], v[0:3]
	v_mfma_f32_16x16x32_bf16 v[4:7], v[88:91], v[12:15], v[8:11]
	v_mfma_f32_16x16x32_bf16 v[8:11], v[88:91], v[20:23], v[16:19]
	s_nop 2
	ds_read_b128 v[16:19], v165 offset:2048
	ds_read_b128 v[20:23], v165 offset:3072
	s_waitcnt lgkmcnt(2)
	v_mfma_f32_16x16x32_bf16 v[12:15], v[88:91], v[28:31], v[24:27]
	s_waitcnt vmcnt(5) lgkmcnt(1)
	v_mfma_f32_16x16x32_bf16 v[0:3], v[80:83], v[16:19], v[0:3]
	ds_read_b128 v[16:19], v165 offset:10240
	ds_read_b128 v[24:27], v165 offset:11264
	s_waitcnt lgkmcnt(1)
	v_mfma_f32_16x16x32_bf16 v[4:7], v[80:83], v[16:19], v[4:7]
	ds_read_b128 v[16:19], v165 offset:18432
	ds_read_b128 v[28:31], v165 offset:19456
	s_waitcnt lgkmcnt(1)
	v_mfma_f32_16x16x32_bf16 v[8:11], v[80:83], v[16:19], v[8:11]
	ds_read_b128 v[16:19], v165 offset:26624
	ds_read_b128 v[32:35], v165 offset:27648
	s_waitcnt lgkmcnt(1)
	v_mfma_f32_16x16x32_bf16 v[12:15], v[80:83], v[16:19], v[12:15]
	s_waitcnt vmcnt(4)
	v_mfma_f32_16x16x32_bf16 v[0:3], v[76:79], v[20:23], v[0:3]
	ds_read_b128 v[16:19], v165 offset:4096
	ds_read_b128 v[20:23], v165 offset:5120
	v_mfma_f32_16x16x32_bf16 v[4:7], v[76:79], v[24:27], v[4:7]
	s_waitcnt vmcnt(3) lgkmcnt(1)
	v_mfma_f32_16x16x32_bf16 v[0:3], v[72:75], v[16:19], v[0:3]
	ds_read_b128 v[16:19], v165 offset:12288
	ds_read_b128 v[24:27], v165 offset:13312
	v_mfma_f32_16x16x32_bf16 v[8:11], v[76:79], v[28:31], v[8:11]
	s_waitcnt lgkmcnt(1)
	v_mfma_f32_16x16x32_bf16 v[4:7], v[72:75], v[16:19], v[4:7]
	ds_read_b128 v[16:19], v165 offset:20480
	ds_read_b128 v[28:31], v165 offset:21504
	v_mfma_f32_16x16x32_bf16 v[12:15], v[76:79], v[32:35], v[12:15]
	s_waitcnt lgkmcnt(1)
	v_mfma_f32_16x16x32_bf16 v[8:11], v[72:75], v[16:19], v[8:11]
	ds_read_b128 v[16:19], v165 offset:28672
	ds_read_b128 v[32:35], v165 offset:29696
	s_waitcnt lgkmcnt(1)
	v_mfma_f32_16x16x32_bf16 v[12:15], v[72:75], v[16:19], v[12:15]
	s_waitcnt vmcnt(2)
	v_mfma_f32_16x16x32_bf16 v[0:3], v[68:71], v[20:23], v[0:3]
	ds_read_b128 v[16:19], v165 offset:6144
	ds_read_b128 v[20:23], v165 offset:7168
	v_mfma_f32_16x16x32_bf16 v[4:7], v[68:71], v[24:27], v[4:7]
	s_waitcnt vmcnt(1) lgkmcnt(1)
	v_mfma_f32_16x16x32_bf16 v[0:3], v[64:67], v[16:19], v[0:3]
	ds_read_b128 v[16:19], v165 offset:14336
	ds_read_b128 v[24:27], v165 offset:15360
	v_mfma_f32_16x16x32_bf16 v[8:11], v[68:71], v[28:31], v[8:11]
	s_waitcnt lgkmcnt(1)
; #define ATT_LOAD(src, half) do { _Pragma("unroll") for (int j = 0; j < 8; ++j) t[j] = src[((half) * 64 + wid * 8 + j) * 64]; } while (0)
; #define ATT_PUT() do { __syncthreads(); _Pragma("unroll") for (int j = 0; j < 8; ++j) stage[(wid * 8 + j) * 64 + lane] = t[j]; __syncthreads(); } while (0)
; #define ATT_QK(half) do { _Pragma("unroll") for (int kbl = 0; kbl < 8; ++kbl) { f32x4 acc = (f32x4){0.f, 0.f, 0.f, 0.f}; \
;         _Pragma("unroll") for (int ks = 0; ks < 8; ++ks) acc = MFMA16(Q[ks], *(const bf16x8*)&stage[(kbl * 8 + ks) * 64 + lane], acc); S[(half) * 8 + kbl] = acc; } } while (0)
; __device__ __forceinline__ void attn_item(KP P, int rbk, int h, unsigned char* lds) {
;     ...
;     ATT_LOAD(kf, 0); ATT_PUT();
;     ATT_LOAD(kf, 1); ATT_QK(0); ATT_PUT();
	v_mfma_f32_16x16x32_bf16 v[4:7], v[64:67], v[16:19], v[4:7]
	ds_read_b128 v[16:19], v165 offset:22528
	ds_read_b128 v[28:31], v165 offset:23552
	v_mfma_f32_16x16x32_bf16 v[12:15], v[68:71], v[32:35], v[12:15]
	s_waitcnt lgkmcnt(1)
	v_mfma_f32_16x16x32_bf16 v[16:19], v[64:67], v[16:19], v[8:11]
	s_nop 2
	ds_read_b128 v[8:11], v165 offset:30720
	ds_read_b128 v[32:35], v165 offset:31744
	s_waitcnt lgkmcnt(1)
	v_mfma_f32_16x16x32_bf16 v[36:39], v[64:67], v[8:11], v[12:15]
	s_waitcnt vmcnt(0)
	v_mfma_f32_16x16x32_bf16 v[12:15], v[60:63], v[20:23], v[0:3]
	v_mfma_f32_16x16x32_bf16 v[8:11], v[60:63], v[24:27], v[4:7]
	v_mfma_f32_16x16x32_bf16 v[4:7], v[60:63], v[28:31], v[16:19]
	s_nop 2
	ds_read_b128 v[16:19], v165 offset:32768
	ds_read_b128 v[20:23], v165 offset:33792
	s_waitcnt lgkmcnt(1)
	v_mfma_f32_16x16x32_bf16 v[16:19], v[84:87], v[16:19], 0
	s_waitcnt lgkmcnt(0)
	v_mfma_f32_16x16x32_bf16 v[16:19], v[88:91], v[20:23], v[16:19]
	ds_read_b128 v[20:23], v165 offset:34816
	ds_read_b128 v[24:27], v165 offset:35840
	s_waitcnt lgkmcnt(1)
	v_mfma_f32_16x16x32_bf16 v[16:19], v[80:83], v[20:23], v[16:19]
	s_waitcnt lgkmcnt(0)
	v_mfma_f32_16x16x32_bf16 v[16:19], v[76:79], v[24:27], v[16:19]
	ds_read_b128 v[20:23], v165 offset:36864
	ds_read_b128 v[24:27], v165 offset:37888
	s_waitcnt lgkmcnt(1)
	v_mfma_f32_16x16x32_bf16 v[16:19], v[72:75], v[20:23], v[16:19]
	s_waitcnt lgkmcnt(0)
	v_mfma_f32_16x16x32_bf16 v[16:19], v[68:71], v[24:27], v[16:19]
	ds_read_b128 v[20:23], v165 offset:38912
	ds_read_b128 v[24:27], v165 offset:39936
	s_waitcnt lgkmcnt(1)
	v_mfma_f32_16x16x32_bf16 v[16:19], v[64:67], v[20:23], v[16:19]
	s_waitcnt lgkmcnt(0)
	v_mfma_f32_16x16x32_bf16 v[16:19], v[60:63], v[24:27], v[16:19]
	ds_read_b128 v[20:23], v165 offset:40960
	ds_read_b128 v[24:27], v165 offset:41984
	s_waitcnt lgkmcnt(1)
	v_mfma_f32_16x16x32_bf16 v[20:23], v[84:87], v[20:23], 0
	s_waitcnt lgkmcnt(0)
	v_mfma_f32_16x16x32_bf16 v[20:23], v[88:91], v[24:27], v[20:23]
	ds_read_b128 v[24:27], v165 offset:43008
	ds_read_b128 v[28:31], v165 offset:44032
	s_waitcnt lgkmcnt(1)
	v_mfma_f32_16x16x32_bf16 v[20:23], v[80:83], v[24:27], v[20:23]
	s_waitcnt lgkmcnt(0)
	v_mfma_f32_16x16x32_bf16 v[20:23], v[76:79], v[28:31], v[20:23]
	ds_read_b128 v[24:27], v165 offset:45056
	ds_read_b128 v[28:31], v165 offset:46080
	s_waitcnt lgkmcnt(1)
	v_mfma_f32_16x16x32_bf16 v[20:23], v[72:75], v[24:27], v[20:23]
	s_waitcnt lgkmcnt(0)
	v_mfma_f32_16x16x32_bf16 v[20:23], v[68:71], v[28:31], v[20:23]
	ds_read_b128 v[24:27], v165 offset:47104
	ds_read_b128 v[28:31], v165 offset:48128
	s_waitcnt lgkmcnt(1)
	v_mfma_f32_16x16x32_bf16 v[20:23], v[64:67], v[24:27], v[20:23]
	s_waitcnt lgkmcnt(0)
	v_mfma_f32_16x16x32_bf16 v[20:23], v[60:63], v[28:31], v[20:23]
	ds_read_b128 v[24:27], v165 offset:49152
	ds_read_b128 v[28:31], v165 offset:50176
	s_waitcnt lgkmcnt(1)
	v_mfma_f32_16x16x32_bf16 v[24:27], v[84:87], v[24:27], 0
	v_mfma_f32_16x16x32_bf16 v[0:3], v[60:63], v[32:35], v[36:39]
	s_waitcnt lgkmcnt(0)
	v_mfma_f32_16x16x32_bf16 v[24:27], v[88:91], v[28:31], v[24:27]
	ds_read_b128 v[28:31], v165 offset:51200
	ds_read_b128 v[32:35], v165 offset:52224
	s_waitcnt lgkmcnt(1)
	v_mfma_f32_16x16x32_bf16 v[24:27], v[80:83], v[28:31], v[24:27]
	ds_read_b128 v[28:31], v165 offset:53248
	s_waitcnt lgkmcnt(1)
	v_mfma_f32_16x16x32_bf16 v[24:27], v[76:79], v[32:35], v[24:27]
	ds_read_b128 v[32:35], v165 offset:54272
	s_waitcnt lgkmcnt(1)
	v_mfma_f32_16x16x32_bf16 v[24:27], v[72:75], v[28:31], v[24:27]
	ds_read_b128 v[28:31], v165 offset:55296
	s_waitcnt lgkmcnt(1)
	v_mfma_f32_16x16x32_bf16 v[24:27], v[68:71], v[32:35], v[24:27]
	global_load_dwordx4 v[32:35], v[44:45], off offset:1024
	global_load_dwordx4 v[36:39], v[44:45], off offset:2048
	ds_read_b128 v[40:43], v165 offset:56320
	s_waitcnt lgkmcnt(1)
	v_mfma_f32_16x16x32_bf16 v[24:27], v[64:67], v[28:31], v[24:27]
	global_load_dwordx4 v[28:31], v[126:127], off offset:-4096
	s_nop 0
	global_load_dwordx4 v[44:47], v[44:45], off offset:3072
	ds_read_b128 v[48:51], v165 offset:57344
	s_waitcnt lgkmcnt(1)
	v_mfma_f32_16x16x32_bf16 v[24:27], v[60:63], v[40:43], v[24:27]
	global_load_dwordx4 v[40:43], v[126:127], off
	global_load_dwordx4 v[52:55], v[126:127], off offset:1024
	ds_read_b128 v[56:59], v165 offset:58368
	global_load_dwordx4 v[92:95], v[126:127], off offset:2048
	global_load_dwordx4 v[158:161], v[126:127], off offset:3072
	s_waitcnt lgkmcnt(1)
	v_mfma_f32_16x16x32_bf16 v[48:51], v[84:87], v[48:51], 0
	ds_read_b128 v[168:171], v165 offset:59392
	v_and_b32_e32 v126, 64, v205
	v_add_u32_e32 v126, 64, v126
	s_waitcnt lgkmcnt(1)
	v_mfma_f32_16x16x32_bf16 v[48:51], v[88:91], v[56:59], v[48:51]
	ds_read_b128 v[56:59], v165 offset:60416
	ds_read_b128 v[172:175], v165 offset:61440
	ds_read_b128 v[176:179], v165 offset:62464
	s_waitcnt lgkmcnt(3)
	v_mfma_f32_16x16x32_bf16 v[48:51], v[80:83], v[168:171], v[48:51]
	ds_read_b128 v[168:171], v165 offset:63488
	ds_read_b128 v[180:183], v165 offset:64512
	s_waitcnt lgkmcnt(0)
	s_barrier
	s_waitcnt vmcnt(5)
	ds_write_b128 v167, v[28:31]
	ds_write_b128 v167, v[32:35] offset:1024
	ds_write_b128 v167, v[36:39] offset:2048
	s_waitcnt vmcnt(4)
	ds_write_b128 v167, v[44:47] offset:3072
	s_waitcnt vmcnt(3)
	ds_write_b128 v167, v[40:43] offset:4096
	s_waitcnt vmcnt(2)
	ds_write_b128 v167, v[52:55] offset:5120
	s_waitcnt vmcnt(1)
	ds_write_b128 v167, v[92:95] offset:6144
	s_waitcnt vmcnt(0)
	ds_write_b128 v167, v[158:161] offset:7168
	s_waitcnt lgkmcnt(0)
	s_barrier
; #define ATT_LOAD(src, half) do { _Pragma("unroll") for (int j = 0; j < 8; ++j) t[j] = src[((half) * 64 + wid * 8 + j) * 64]; } while (0)
; #define ATT_PUT() do { __syncthreads(); _Pragma("unroll") for (int j = 0; j < 8; ++j) stage[(wid * 8 + j) * 64 + lane] = t[j]; __syncthreads(); } while (0)
; #define ATT_QK(half) do { _Pragma("unroll") for (int kbl = 0; kbl < 8; ++kbl) { f32x4 acc = (f32x4){0.f, 0.f, 0.f, 0.f}; \
;         _Pragma("unroll") for (int ks = 0; ks < 8; ++ks) acc = MFMA16(Q[ks], *(const bf16x8*)&stage[(kbl * 8 + ks) * 64 + lane], acc); S[(half) * 8 + kbl] = acc; } } while (0)
; __device__ __forceinline__ void attn_item(KP P, int rbk, int h, unsigned char* lds) {
;     ...
;     ATT_LOAD(kf, 0); ATT_PUT();
;     ATT_LOAD(kf, 1); ATT_QK(0); ATT_PUT();
;     ATT_LOAD(vf, 0); ATT_QK(1);
	ds_read_b128 v[32:35], v165
	ds_read_b128 v[36:39], v165 offset:1024
	s_waitcnt lgkmcnt(1)
	v_mfma_f32_16x16x32_bf16 v[32:35], v[84:87], v[32:35], 0
	s_waitcnt lgkmcnt(0)
	v_mfma_f32_16x16x32_bf16 v[32:35], v[88:91], v[36:39], v[32:35]
	ds_read_b128 v[36:39], v165 offset:2048
	ds_read_b128 v[40:43], v165 offset:3072
	s_waitcnt lgkmcnt(1)
	v_mfma_f32_16x16x32_bf16 v[32:35], v[80:83], v[36:39], v[32:35]
	s_waitcnt lgkmcnt(0)
	v_mfma_f32_16x16x32_bf16 v[32:35], v[76:79], v[40:43], v[32:35]
	ds_read_b128 v[36:39], v165 offset:4096
	ds_read_b128 v[40:43], v165 offset:5120
	s_waitcnt lgkmcnt(1)
	v_mfma_f32_16x16x32_bf16 v[32:35], v[72:75], v[36:39], v[32:35]
	s_waitcnt lgkmcnt(0)
	v_mfma_f32_16x16x32_bf16 v[32:35], v[68:71], v[40:43], v[32:35]
	ds_read_b128 v[36:39], v165 offset:6144
	ds_read_b128 v[40:43], v165 offset:7168
	s_waitcnt lgkmcnt(1)
	v_mfma_f32_16x16x32_bf16 v[32:35], v[64:67], v[36:39], v[32:35]
	s_waitcnt lgkmcnt(0)
	v_mfma_f32_16x16x32_bf16 v[32:35], v[60:63], v[40:43], v[32:35]
	ds_read_b128 v[36:39], v165 offset:8192
	ds_read_b128 v[40:43], v165 offset:9216
	s_waitcnt lgkmcnt(1)
	v_mfma_f32_16x16x32_bf16 v[36:39], v[84:87], v[36:39], 0
	s_waitcnt lgkmcnt(0)
	v_mfma_f32_16x16x32_bf16 v[36:39], v[88:91], v[40:43], v[36:39]
	ds_read_b128 v[40:43], v165 offset:10240
	ds_read_b128 v[44:47], v165 offset:11264
	s_waitcnt lgkmcnt(1)
	v_mfma_f32_16x16x32_bf16 v[36:39], v[80:83], v[40:43], v[36:39]
	s_waitcnt lgkmcnt(0)
	v_mfma_f32_16x16x32_bf16 v[36:39], v[76:79], v[44:47], v[36:39]
	ds_read_b128 v[40:43], v165 offset:12288
	ds_read_b128 v[44:47], v165 offset:13312
	s_waitcnt lgkmcnt(1)
	v_mfma_f32_16x16x32_bf16 v[36:39], v[72:75], v[40:43], v[36:39]
	s_waitcnt lgkmcnt(0)
	v_mfma_f32_16x16x32_bf16 v[36:39], v[68:71], v[44:47], v[36:39]
	ds_read_b128 v[40:43], v165 offset:14336
	ds_read_b128 v[44:47], v165 offset:15360
	s_waitcnt lgkmcnt(1)
	v_mfma_f32_16x16x32_bf16 v[36:39], v[64:67], v[40:43], v[36:39]
	s_waitcnt lgkmcnt(0)
	v_mfma_f32_16x16x32_bf16 v[36:39], v[60:63], v[44:47], v[36:39]
	ds_read_b128 v[40:43], v165 offset:16384
	ds_read_b128 v[44:47], v165 offset:17408
	v_mfma_f32_16x16x32_bf16 v[48:51], v[76:79], v[56:59], v[48:51]
	s_waitcnt lgkmcnt(1)
	v_mfma_f32_16x16x32_bf16 v[40:43], v[84:87], v[40:43], 0
	v_mfma_f32_16x16x32_bf16 v[28:31], v[72:75], v[172:175], v[48:51]
	s_waitcnt lgkmcnt(0)
	v_mfma_f32_16x16x32_bf16 v[40:43], v[88:91], v[44:47], v[40:43]
	ds_read_b128 v[44:47], v165 offset:18432
	s_nop 1
	ds_read_b128 v[48:51], v165 offset:19456
	s_waitcnt lgkmcnt(1)
	v_mfma_f32_16x16x32_bf16 v[40:43], v[80:83], v[44:47], v[40:43]
	s_waitcnt lgkmcnt(0)
	v_mfma_f32_16x16x32_bf16 v[40:43], v[76:79], v[48:51], v[40:43]
	ds_read_b128 v[44:47], v165 offset:20480
	ds_read_b128 v[48:51], v165 offset:21504
	s_waitcnt lgkmcnt(1)
	v_mfma_f32_16x16x32_bf16 v[40:43], v[72:75], v[44:47], v[40:43]
	s_waitcnt lgkmcnt(0)
	v_mfma_f32_16x16x32_bf16 v[40:43], v[68:71], v[48:51], v[40:43]
	ds_read_b128 v[44:47], v165 offset:22528
	ds_read_b128 v[48:51], v165 offset:23552
	s_waitcnt lgkmcnt(1)
	v_mfma_f32_16x16x32_bf16 v[40:43], v[64:67], v[44:47], v[40:43]
	s_waitcnt lgkmcnt(0)
	v_mfma_f32_16x16x32_bf16 v[40:43], v[60:63], v[48:51], v[40:43]
	ds_read_b128 v[44:47], v165 offset:24576
	ds_read_b128 v[48:51], v165 offset:25600
	s_waitcnt lgkmcnt(1)
	v_mfma_f32_16x16x32_bf16 v[44:47], v[84:87], v[44:47], 0
	s_waitcnt lgkmcnt(0)
	v_mfma_f32_16x16x32_bf16 v[44:47], v[88:91], v[48:51], v[44:47]
	ds_read_b128 v[48:51], v165 offset:26624
	ds_read_b128 v[52:55], v165 offset:27648
	s_waitcnt lgkmcnt(1)
	v_mfma_f32_16x16x32_bf16 v[44:47], v[80:83], v[48:51], v[44:47]
	s_waitcnt lgkmcnt(0)
	v_mfma_f32_16x16x32_bf16 v[44:47], v[76:79], v[52:55], v[44:47]
	ds_read_b128 v[48:51], v165 offset:28672
	ds_read_b128 v[52:55], v165 offset:29696
	s_waitcnt lgkmcnt(1)
	v_mfma_f32_16x16x32_bf16 v[44:47], v[72:75], v[48:51], v[44:47]
	s_waitcnt lgkmcnt(0)
	v_mfma_f32_16x16x32_bf16 v[44:47], v[68:71], v[52:55], v[44:47]
	ds_read_b128 v[48:51], v165 offset:30720
	ds_read_b128 v[52:55], v165 offset:31744
	s_waitcnt lgkmcnt(1)
	v_mfma_f32_16x16x32_bf16 v[44:47], v[64:67], v[48:51], v[44:47]
	s_waitcnt lgkmcnt(0)
	v_mfma_f32_16x16x32_bf16 v[44:47], v[60:63], v[52:55], v[44:47]
	ds_read_b128 v[48:51], v165 offset:32768
	ds_read_b128 v[52:55], v165 offset:33792
	s_waitcnt lgkmcnt(1)
	v_mfma_f32_16x16x32_bf16 v[48:51], v[84:87], v[48:51], 0
	s_waitcnt lgkmcnt(0)
	v_mfma_f32_16x16x32_bf16 v[48:51], v[88:91], v[52:55], v[48:51]
	ds_read_b128 v[52:55], v165 offset:34816
	ds_read_b128 v[56:59], v165 offset:35840
	s_waitcnt lgkmcnt(1)
	v_mfma_f32_16x16x32_bf16 v[48:51], v[80:83], v[52:55], v[48:51]
	s_waitcnt lgkmcnt(0)
	v_mfma_f32_16x16x32_bf16 v[48:51], v[76:79], v[56:59], v[48:51]
	ds_read_b128 v[52:55], v165 offset:36864
	ds_read_b128 v[56:59], v165 offset:37888
	s_waitcnt lgkmcnt(1)
	v_mfma_f32_16x16x32_bf16 v[48:51], v[72:75], v[52:55], v[48:51]
	s_waitcnt lgkmcnt(0)
	v_mfma_f32_16x16x32_bf16 v[48:51], v[68:71], v[56:59], v[48:51]
	ds_read_b128 v[52:55], v165 offset:38912
	ds_read_b128 v[56:59], v165 offset:39936
	s_waitcnt lgkmcnt(1)
	v_mfma_f32_16x16x32_bf16 v[48:51], v[64:67], v[52:55], v[48:51]
	s_waitcnt lgkmcnt(0)
	v_mfma_f32_16x16x32_bf16 v[48:51], v[60:63], v[56:59], v[48:51]
	ds_read_b128 v[52:55], v165 offset:40960
	ds_read_b128 v[56:59], v165 offset:41984
	s_waitcnt lgkmcnt(1)
	v_mfma_f32_16x16x32_bf16 v[52:55], v[84:87], v[52:55], 0
	s_waitcnt lgkmcnt(0)
	v_mfma_f32_16x16x32_bf16 v[52:55], v[88:91], v[56:59], v[52:55]
	ds_read_b128 v[56:59], v165 offset:43008
	ds_read_b128 v[92:95], v165 offset:44032
	s_waitcnt lgkmcnt(1)
; __device__ __forceinline__ bf16_t f2bf(float v) { return (bf16_t)(cvt_pk_bf16(v, 0.f) & 0xffffu); }
; #define ATT_LOAD(src, half) do { _Pragma("unroll") for (int j = 0; j < 8; ++j) t[j] = src[((half) * 64 + wid * 8 + j) * 64]; } while (0)
; #define ATT_PUT() do { __syncthreads(); _Pragma("unroll") for (int j = 0; j < 8; ++j) stage[(wid * 8 + j) * 64 + lane] = t[j]; __syncthreads(); } while (0)
; #define ATT_QK(half) do { _Pragma("unroll") for (int kbl = 0; kbl < 8; ++kbl) { f32x4 acc = (f32x4){0.f, 0.f, 0.f, 0.f}; \
;         _Pragma("unroll") for (int ks = 0; ks < 8; ++ks) acc = MFMA16(Q[ks], *(const bf16x8*)&stage[(kbl * 8 + ks) * 64 + lane], acc); S[(half) * 8 + kbl] = acc; } } while (0)
; __device__ __forceinline__ void attn_item(KP P, int rbk, int h, unsigned char* lds) {
;     ...
;     ATT_LOAD(kf, 0); ATT_PUT();
;     ATT_LOAD(kf, 1); ATT_QK(0); ATT_PUT();
;     ATT_LOAD(vf, 0); ATT_QK(1);
; #pragma unroll
;     for (int reg = 0; reg < 4; ++reg) {
;         float mx = S[0][reg];
; #pragma unroll
;         for (int kb = 1; kb < 16; ++kb) mx = fmaxf(mx, S[kb][reg]);
; #pragma unroll
;         for (int o2 = 8; o2 >= 1; o2 >>= 1) mx = fmaxf(mx, __shfl_xor(mx, o2));
;         float sum = 0.f;
; #pragma unroll
;         for (int kb = 0; kb < 16; ++kb) { const float e = __expf(S[kb][reg] - mx); S[kb][reg] = e; sum += e; }
; #pragma unroll
;         for (int o2 = 8; o2 >= 1; o2 >>= 1) sum += __shfl_xor(sum, o2);
;         const float inv = 1.0f / sum;
; #pragma unroll
;         for (int kb = 0; kb < 16; ++kb) Pl[(q * 4 + reg) * 264 + kb * 16 + l15] = f2bf(S[kb][reg] * inv);
	v_mfma_f32_16x16x32_bf16 v[52:55], v[80:83], v[56:59], v[52:55]
	s_waitcnt lgkmcnt(0)
	v_mfma_f32_16x16x32_bf16 v[52:55], v[76:79], v[92:95], v[52:55]
	ds_read_b128 v[56:59], v165 offset:45056
	ds_read_b128 v[92:95], v165 offset:46080
	s_waitcnt lgkmcnt(1)
	v_mfma_f32_16x16x32_bf16 v[52:55], v[72:75], v[56:59], v[52:55]
	s_waitcnt lgkmcnt(0)
	v_mfma_f32_16x16x32_bf16 v[52:55], v[68:71], v[92:95], v[52:55]
	ds_read_b128 v[56:59], v165 offset:47104
	ds_read_b128 v[92:95], v165 offset:48128
	s_waitcnt lgkmcnt(1)
	v_mfma_f32_16x16x32_bf16 v[52:55], v[64:67], v[56:59], v[52:55]
	s_waitcnt lgkmcnt(0)
	v_mfma_f32_16x16x32_bf16 v[52:55], v[60:63], v[92:95], v[52:55]
	ds_read_b128 v[56:59], v165 offset:49152
	ds_read_b128 v[92:95], v165 offset:50176
	s_waitcnt lgkmcnt(1)
	v_mfma_f32_16x16x32_bf16 v[56:59], v[84:87], v[56:59], 0
	s_waitcnt lgkmcnt(0)
	v_mfma_f32_16x16x32_bf16 v[56:59], v[88:91], v[92:95], v[56:59]
	ds_read_b128 v[92:95], v165 offset:51200
	ds_read_b128 v[158:161], v165 offset:52224
	s_waitcnt lgkmcnt(1)
	v_mfma_f32_16x16x32_bf16 v[56:59], v[80:83], v[92:95], v[56:59]
	s_waitcnt lgkmcnt(0)
	v_mfma_f32_16x16x32_bf16 v[56:59], v[76:79], v[158:161], v[56:59]
	ds_read_b128 v[92:95], v165 offset:53248
	ds_read_b128 v[158:161], v165 offset:54272
	s_waitcnt lgkmcnt(1)
	v_mfma_f32_16x16x32_bf16 v[56:59], v[72:75], v[92:95], v[56:59]
	s_waitcnt lgkmcnt(0)
	v_mfma_f32_16x16x32_bf16 v[56:59], v[68:71], v[158:161], v[56:59]
	ds_read_b128 v[92:95], v165 offset:55296
	ds_read_b128 v[158:161], v165 offset:56320
	s_waitcnt lgkmcnt(1)
	v_mfma_f32_16x16x32_bf16 v[56:59], v[64:67], v[92:95], v[56:59]
	s_waitcnt lgkmcnt(0)
	v_mfma_f32_16x16x32_bf16 v[56:59], v[60:63], v[158:161], v[56:59]
	ds_read_b128 v[92:95], v165 offset:57344
	ds_read_b128 v[158:161], v165 offset:58368
	s_waitcnt lgkmcnt(1)
	v_mfma_f32_16x16x32_bf16 v[84:87], v[84:87], v[92:95], 0
	s_waitcnt lgkmcnt(0)
	v_mfma_f32_16x16x32_bf16 v[84:87], v[88:91], v[158:161], v[84:87]
	ds_read_b128 v[88:91], v165 offset:59392
	ds_read_b128 v[92:95], v165 offset:60416
	s_waitcnt lgkmcnt(1)
	v_mfma_f32_16x16x32_bf16 v[80:83], v[80:83], v[88:91], v[84:87]
	s_nop 3
	ds_read_b128 v[84:87], v165 offset:61440
	ds_read_b128 v[88:91], v165 offset:62464
	s_waitcnt lgkmcnt(2)
	v_mfma_f32_16x16x32_bf16 v[76:79], v[76:79], v[92:95], v[80:83]
	s_nop 2
	ds_read_b128 v[80:83], v165 offset:63488
	ds_read_b128 v[92:95], v165 offset:64512
	v_mfma_f32_16x16x32_bf16 v[28:31], v[68:71], v[176:179], v[28:31]
	s_waitcnt lgkmcnt(3)
	v_mfma_f32_16x16x32_bf16 v[72:75], v[72:75], v[84:87], v[76:79]
	v_mfma_f32_16x16x32_bf16 v[28:31], v[64:67], v[168:171], v[28:31]
	s_nop 1
	v_max_f32_e32 v76, v8, v8
	v_max_f32_e32 v77, v12, v12
	v_max_f32_e32 v76, v77, v76
	s_waitcnt lgkmcnt(2)
	v_mfma_f32_16x16x32_bf16 v[68:71], v[68:71], v[88:91], v[72:75]
	v_lshl_add_u64 v[88:89], v[108:109], 0, v[102:103]
	v_lshl_add_u64 v[84:85], v[88:89], 0, v[120:121]
	v_lshl_add_u64 v[90:91], v[88:89], 0, v[122:123]
	v_mfma_f32_16x16x32_bf16 v[28:31], v[60:63], v[180:183], v[28:31]
	v_max3_f32 v72, v76, v4, v0
	v_max3_f32 v72, v72, v16, v20
	s_waitcnt lgkmcnt(1)
	v_mfma_f32_16x16x32_bf16 v[64:67], v[64:67], v[80:83], v[68:71]
	v_lshl_add_u64 v[80:81], v[88:89], 0, v[118:119]
	s_nop 2
	v_max3_f32 v72, v72, v24, v28
	s_waitcnt lgkmcnt(0)
	v_mfma_f32_16x16x32_bf16 v[60:63], v[60:63], v[92:95], v[64:67]
	v_max3_f32 v68, v72, v32, v36
	v_max3_f32 v68, v68, v40, v44
	v_max3_f32 v68, v68, v48, v52
	v_xor_b32_e32 v65, 8, v205
	v_cmp_lt_i32_e32 vcc, v65, v126
	s_nop 2
	v_max3_f32 v64, v68, v56, v60
	v_cndmask_b32_e32 v65, v205, v65, vcc
	v_lshlrev_b32_e32 v157, 2, v65
	ds_bpermute_b32 v65, v157, v64
	s_waitcnt lgkmcnt(0)
	v_max_f32_e32 v65, v65, v65
	v_max_f32_e32 v64, v64, v65
	v_xor_b32_e32 v65, 4, v205
	v_cmp_lt_i32_e32 vcc, v65, v126
	s_nop 1
	v_cndmask_b32_e32 v65, v205, v65, vcc
	v_lshlrev_b32_e32 v158, 2, v65
	ds_bpermute_b32 v65, v158, v64
	s_waitcnt lgkmcnt(0)
	v_max_f32_e32 v65, v65, v65
	v_max_f32_e32 v64, v64, v65
	v_xor_b32_e32 v65, 2, v205
	v_cmp_lt_i32_e32 vcc, v65, v126
	s_nop 1
	v_cndmask_b32_e32 v65, v205, v65, vcc
	v_lshlrev_b32_e32 v159, 2, v65
	ds_bpermute_b32 v65, v159, v64
	s_waitcnt lgkmcnt(0)
	v_max_f32_e32 v65, v65, v65
	v_max_f32_e32 v64, v64, v65
	v_xor_b32_e32 v65, 1, v205
	v_cmp_lt_i32_e32 vcc, v65, v126
	v_lshl_add_u64 v[126:127], v[88:89], 0, v[116:117]
	s_nop 0
	v_cndmask_b32_e32 v65, v205, v65, vcc
	v_lshlrev_b32_e32 v160, 2, v65
	ds_bpermute_b32 v65, v160, v64
	s_waitcnt lgkmcnt(0)
	v_max_f32_e32 v65, v65, v65
	v_max_f32_e32 v64, v64, v65
	v_sub_f32_e32 v12, v12, v64
	v_mul_f32_e32 v12, 0x3fb8aa3b, v12
	v_sub_f32_e32 v8, v8, v64
	v_exp_f32_e32 v12, v12
	v_mul_f32_e32 v8, 0x3fb8aa3b, v8
	v_sub_f32_e32 v4, v4, v64
	v_exp_f32_e32 v8, v8
	v_mul_f32_e32 v4, 0x3fb8aa3b, v4
	v_sub_f32_e32 v0, v0, v64
	v_exp_f32_e32 v4, v4
	v_mul_f32_e32 v0, 0x3fb8aa3b, v0
	v_sub_f32_e32 v16, v16, v64
	v_exp_f32_e32 v0, v0
	v_mul_f32_e32 v16, 0x3fb8aa3b, v16
	v_sub_f32_e32 v20, v20, v64
	v_add_f32_e32 v65, 0, v12
	v_exp_f32_e32 v16, v16
	v_mul_f32_e32 v20, 0x3fb8aa3b, v20
	v_sub_f32_e32 v24, v24, v64
	v_add_f32_e32 v65, v8, v65
	v_exp_f32_e32 v20, v20
	v_mul_f32_e32 v24, 0x3fb8aa3b, v24
	v_sub_f32_e32 v28, v28, v64
	v_add_f32_e32 v65, v4, v65
	v_exp_f32_e32 v24, v24
	v_mul_f32_e32 v28, 0x3fb8aa3b, v28
	v_sub_f32_e32 v32, v32, v64
	v_add_f32_e32 v65, v0, v65
	v_exp_f32_e32 v28, v28
	v_mul_f32_e32 v32, 0x3fb8aa3b, v32
	v_sub_f32_e32 v36, v36, v64
	v_add_f32_e32 v65, v16, v65
	v_exp_f32_e32 v32, v32
	v_mul_f32_e32 v36, 0x3fb8aa3b, v36
	v_sub_f32_e32 v40, v40, v64
	v_add_f32_e32 v65, v20, v65
	v_exp_f32_e32 v36, v36
	v_mul_f32_e32 v40, 0x3fb8aa3b, v40
	v_sub_f32_e32 v44, v44, v64
	v_add_f32_e32 v65, v24, v65
	v_exp_f32_e32 v40, v40
	v_mul_f32_e32 v44, 0x3fb8aa3b, v44
	v_sub_f32_e32 v48, v48, v64
	v_add_f32_e32 v65, v28, v65
	v_exp_f32_e32 v44, v44
	v_mul_f32_e32 v48, 0x3fb8aa3b, v48
	v_sub_f32_e32 v52, v52, v64
	v_add_f32_e32 v65, v32, v65
	v_exp_f32_e32 v48, v48
	v_mul_f32_e32 v52, 0x3fb8aa3b, v52
	v_sub_f32_e32 v56, v56, v64
	v_add_f32_e32 v65, v36, v65
	v_exp_f32_e32 v52, v52
	v_mul_f32_e32 v56, 0x3fb8aa3b, v56
	v_sub_f32_e32 v60, v60, v64
	v_add_f32_e32 v65, v40, v65
	v_exp_f32_e32 v56, v56
	v_mul_f32_e32 v60, 0x3fb8aa3b, v60
	v_add_f32_e32 v65, v44, v65
	v_exp_f32_e32 v60, v60
	v_add_f32_e32 v64, v48, v65
	v_add_f32_e32 v64, v52, v64
	v_add_f32_e32 v64, v56, v64
	v_add_f32_e32 v64, v60, v64
	ds_bpermute_b32 v65, v157, v64
	s_waitcnt lgkmcnt(0)
; __device__ __forceinline__ bf16_t f2bf(float v) { return (bf16_t)(cvt_pk_bf16(v, 0.f) & 0xffffu); }
; #define ATT_LOAD(src, half) do { _Pragma("unroll") for (int j = 0; j < 8; ++j) t[j] = src[((half) * 64 + wid * 8 + j) * 64]; } while (0)
; #define ATT_QK(half) do { _Pragma("unroll") for (int kbl = 0; kbl < 8; ++kbl) { f32x4 acc = (f32x4){0.f, 0.f, 0.f, 0.f}; \
;         _Pragma("unroll") for (int ks = 0; ks < 8; ++ks) acc = MFMA16(Q[ks], *(const bf16x8*)&stage[(kbl * 8 + ks) * 64 + lane], acc); S[(half) * 8 + kbl] = acc; } } while (0)
; __device__ __forceinline__ void attn_item(KP P, int rbk, int h, unsigned char* lds) {
;     ...
;     ATT_LOAD(vf, 0); ATT_QK(1);
; #pragma unroll
;     for (int reg = 0; reg < 4; ++reg) {
;         float mx = S[0][reg];
; #pragma unroll
;         for (int kb = 1; kb < 16; ++kb) mx = fmaxf(mx, S[kb][reg]);
; #pragma unroll
;         for (int o2 = 8; o2 >= 1; o2 >>= 1) mx = fmaxf(mx, __shfl_xor(mx, o2));
;         float sum = 0.f;
; #pragma unroll
;         for (int kb = 0; kb < 16; ++kb) { const float e = __expf(S[kb][reg] - mx); S[kb][reg] = e; sum += e; }
; #pragma unroll
;         for (int o2 = 8; o2 >= 1; o2 >>= 1) sum += __shfl_xor(sum, o2);
;         const float inv = 1.0f / sum;
; #pragma unroll
;         for (int kb = 0; kb < 16; ++kb) Pl[(q * 4 + reg) * 264 + kb * 16 + l15] = f2bf(S[kb][reg] * inv);
	v_add_f32_e32 v64, v64, v65
	ds_bpermute_b32 v65, v158, v64
	s_waitcnt lgkmcnt(0)
	v_add_f32_e32 v82, v64, v65
	ds_bpermute_b32 v83, v159, v82
	global_load_dwordx4 v[64:67], v[126:127], off
	global_load_dwordx4 v[68:71], v[126:127], off offset:1024
	global_load_dwordx4 v[72:75], v[126:127], off offset:2048
	global_load_dwordx4 v[76:79], v[126:127], off offset:3072
	s_waitcnt lgkmcnt(0)
	v_add_f32_e32 v92, v82, v83
	ds_bpermute_b32 v93, v160, v92
	global_load_dwordx4 v[80:83], v[80:81], off
	s_nop 0
	global_load_dwordx4 v[84:87], v[84:85], off
	s_waitcnt lgkmcnt(0)
	v_add_f32_e32 v102, v92, v93
	v_div_scale_f32 v161, s[14:15], v102, v102, 1.0
	v_rcp_f32_e32 v162, v161
	v_lshl_add_u64 v[92:93], v[88:89], 0, v[124:125]
	global_load_dwordx4 v[88:91], v[90:91], off
	s_nop 0
	global_load_dwordx4 v[92:95], v[92:93], off
	v_fma_f32 v163, -v161, v162, 1.0
	v_fmac_f32_e32 v162, v163, v162
	v_div_scale_f32 v163, vcc, 1.0, v102, 1.0
	v_mul_f32_e32 v168, v163, v162
	v_fma_f32 v169, -v161, v168, v163
	v_fmac_f32_e32 v168, v169, v162
	v_fma_f32 v161, -v161, v168, v163
	v_div_fmas_f32 v161, v161, v162, v168
	v_div_fixup_f32 v102, v161, v102, 1.0
	v_mul_f32_e32 v8, v8, v102
	v_mul_f32_e32 v4, v4, v102
	v_cvt_pk_bf16_f32 v8, v8, s0
	v_cvt_pk_bf16_f32 v4, v4, s0
	ds_write_b16 v144, v8 offset:32
	ds_write_b16 v144, v4 offset:64
	v_max_f32_e32 v4, v9, v9
	v_max_f32_e32 v8, v13, v13
	v_max_f32_e32 v4, v8, v4
	v_max3_f32 v4, v4, v5, v1
	v_max3_f32 v4, v4, v17, v21
	v_max3_f32 v4, v4, v25, v29
	v_max3_f32 v4, v4, v33, v37
	v_max3_f32 v4, v4, v41, v45
	v_max3_f32 v4, v4, v49, v53
	v_max3_f32 v4, v4, v57, v61
	ds_bpermute_b32 v8, v157, v4
	v_mul_f32_e32 v0, v0, v102
	v_cvt_pk_bf16_f32 v0, v0, s0
	ds_write_b16 v144, v0 offset:96
	v_mul_f32_e32 v0, v16, v102
	s_waitcnt lgkmcnt(1)
	v_max_f32_e32 v8, v8, v8
	v_max_f32_e32 v4, v4, v8
	v_cvt_pk_bf16_f32 v0, v0, s0
	ds_bpermute_b32 v8, v158, v4
	ds_write_b16 v144, v0 offset:128
	v_mul_f32_e32 v0, v20, v102
	v_cvt_pk_bf16_f32 v0, v0, s0
	ds_write_b16 v144, v0 offset:160
	v_mul_f32_e32 v0, v24, v102
	v_cvt_pk_bf16_f32 v0, v0, s0
	ds_write_b16 v144, v0 offset:192
	s_waitcnt lgkmcnt(3)
	v_max_f32_e32 v0, v8, v8
	v_max_f32_e32 v0, v4, v0
	ds_bpermute_b32 v4, v159, v0
	v_mul_f32_e32 v12, v12, v102
	v_cvt_pk_bf16_f32 v12, v12, s0
	ds_write_b16 v144, v12
	v_mul_f32_e32 v8, v28, v102
	s_waitcnt lgkmcnt(1)
	v_max_f32_e32 v4, v4, v4
	v_max_f32_e32 v0, v0, v4
	ds_bpermute_b32 v4, v160, v0
	v_cvt_pk_bf16_f32 v8, v8, s0
	ds_write_b16 v144, v8 offset:224
	v_mul_f32_e32 v8, v32, v102
	v_cvt_pk_bf16_f32 v8, v8, s0
	s_waitcnt lgkmcnt(1)
	v_max_f32_e32 v4, v4, v4
	v_max_f32_e32 v0, v0, v4
	v_sub_f32_e32 v4, v13, v0
	v_mul_f32_e32 v4, 0x3fb8aa3b, v4
	v_sub_f32_e32 v9, v9, v0
	v_exp_f32_e32 v4, v4
	v_mul_f32_e32 v9, 0x3fb8aa3b, v9
	v_sub_f32_e32 v5, v5, v0
	v_exp_f32_e32 v9, v9
	v_mul_f32_e32 v5, 0x3fb8aa3b, v5
	v_sub_f32_e32 v1, v1, v0
	v_exp_f32_e32 v5, v5
	v_mul_f32_e32 v1, 0x3fb8aa3b, v1
	v_sub_f32_e32 v13, v17, v0
	v_exp_f32_e32 v1, v1
	v_mul_f32_e32 v13, 0x3fb8aa3b, v13
	v_sub_f32_e32 v16, v21, v0
	v_add_f32_e32 v12, 0, v4
	v_exp_f32_e32 v13, v13
	v_mul_f32_e32 v16, 0x3fb8aa3b, v16
	v_sub_f32_e32 v17, v25, v0
	v_add_f32_e32 v12, v9, v12
	v_exp_f32_e32 v16, v16
	v_mul_f32_e32 v17, 0x3fb8aa3b, v17
	v_sub_f32_e32 v20, v29, v0
	v_add_f32_e32 v12, v5, v12
	v_exp_f32_e32 v17, v17
	v_mul_f32_e32 v20, 0x3fb8aa3b, v20
	v_sub_f32_e32 v21, v33, v0
	v_add_f32_e32 v12, v1, v12
	v_exp_f32_e32 v20, v20
	v_mul_f32_e32 v21, 0x3fb8aa3b, v21
	v_sub_f32_e32 v24, v37, v0
	v_add_f32_e32 v12, v13, v12
	v_exp_f32_e32 v21, v21
	v_mul_f32_e32 v24, 0x3fb8aa3b, v24
	v_sub_f32_e32 v25, v41, v0
	v_add_f32_e32 v12, v16, v12
	v_exp_f32_e32 v24, v24
	v_mul_f32_e32 v25, 0x3fb8aa3b, v25
	v_sub_f32_e32 v28, v45, v0
	v_add_f32_e32 v12, v17, v12
	v_exp_f32_e32 v25, v25
	v_mul_f32_e32 v28, 0x3fb8aa3b, v28
	v_sub_f32_e32 v29, v49, v0
	v_add_f32_e32 v12, v20, v12
	v_exp_f32_e32 v28, v28
	v_mul_f32_e32 v29, 0x3fb8aa3b, v29
	v_sub_f32_e32 v32, v53, v0
	v_add_f32_e32 v12, v21, v12
	v_exp_f32_e32 v29, v29
	v_mul_f32_e32 v32, 0x3fb8aa3b, v32
	v_sub_f32_e32 v33, v57, v0
	v_add_f32_e32 v12, v24, v12
	v_exp_f32_e32 v32, v32
	v_mul_f32_e32 v33, 0x3fb8aa3b, v33
	v_sub_f32_e32 v0, v61, v0
	v_add_f32_e32 v12, v25, v12
	v_exp_f32_e32 v33, v33
	v_mul_f32_e32 v0, 0x3fb8aa3b, v0
	v_add_f32_e32 v12, v28, v12
	v_exp_f32_e32 v0, v0
	v_add_f32_e32 v12, v29, v12
	v_add_f32_e32 v12, v32, v12
	v_add_f32_e32 v12, v33, v12
	v_add_f32_e32 v12, v0, v12
	ds_write_b16 v144, v8 offset:256
	v_mul_f32_e32 v8, v36, v102
	ds_bpermute_b32 v36, v157, v12
	v_cvt_pk_bf16_f32 v8, v8, s0
	ds_write_b16 v144, v8 offset:288
	v_mul_f32_e32 v8, v40, v102
	v_cvt_pk_bf16_f32 v8, v8, s0
	ds_write_b16 v144, v8 offset:320
	s_waitcnt lgkmcnt(2)
	v_add_f32_e32 v8, v12, v36
	ds_bpermute_b32 v12, v158, v8
	v_mul_f32_e32 v36, v44, v102
	v_cvt_pk_bf16_f32 v36, v36, s0
	ds_write_b16 v144, v36 offset:352
	v_mul_f32_e32 v36, v48, v102
	s_waitcnt lgkmcnt(1)
	v_add_f32_e32 v8, v8, v12
	ds_bpermute_b32 v12, v159, v8
	v_cvt_pk_bf16_f32 v36, v36, s0
	ds_write_b16 v144, v36 offset:384
	v_mul_f32_e32 v36, v52, v102
	v_cvt_pk_bf16_f32 v36, v36, s0
	s_waitcnt lgkmcnt(1)
	v_add_f32_e32 v8, v8, v12
	ds_bpermute_b32 v12, v160, v8
	ds_write_b16 v144, v36 offset:416
	v_mul_f32_e32 v36, v56, v102
	v_cvt_pk_bf16_f32 v36, v36, s0
	ds_write_b16 v144, v36 offset:448
	s_waitcnt lgkmcnt(2)
; __device__ __forceinline__ bf16_t f2bf(float v) { return (bf16_t)(cvt_pk_bf16(v, 0.f) & 0xffffu); }
; __device__ __forceinline__ void attn_item(KP P, int rbk, int h, unsigned char* lds) {
;     ...
;     for (int reg = 0; reg < 4; ++reg) {
;         float mx = S[0][reg];
; #pragma unroll
;         for (int kb = 1; kb < 16; ++kb) mx = fmaxf(mx, S[kb][reg]);
; #pragma unroll
;         for (int o2 = 8; o2 >= 1; o2 >>= 1) mx = fmaxf(mx, __shfl_xor(mx, o2));
;         float sum = 0.f;
; #pragma unroll
;         for (int kb = 0; kb < 16; ++kb) { const float e = __expf(S[kb][reg] - mx); S[kb][reg] = e; sum += e; }
; #pragma unroll
;         for (int o2 = 8; o2 >= 1; o2 >>= 1) sum += __shfl_xor(sum, o2);
;         const float inv = 1.0f / sum;
; #pragma unroll
;         for (int kb = 0; kb < 16; ++kb) Pl[(q * 4 + reg) * 264 + kb * 16 + l15] = f2bf(S[kb][reg] * inv);
	v_add_f32_e32 v8, v8, v12
	v_div_scale_f32 v12, s[14:15], v8, v8, 1.0
	v_rcp_f32_e32 v36, v12
	v_mul_f32_e32 v37, v60, v102
	v_cvt_pk_bf16_f32 v37, v37, s0
	ds_write_b16 v144, v37 offset:480
	v_fma_f32 v37, -v12, v36, 1.0
	v_fmac_f32_e32 v36, v37, v36
	v_div_scale_f32 v37, vcc, 1.0, v8, 1.0
	v_mul_f32_e32 v40, v37, v36
	v_fma_f32 v41, -v12, v40, v37
	v_fmac_f32_e32 v40, v41, v36
	v_fma_f32 v12, -v12, v40, v37
	v_div_fmas_f32 v12, v12, v36, v40
	v_div_fixup_f32 v8, v12, v8, 1.0
	v_mul_f32_e32 v4, v4, v8
	v_cvt_pk_bf16_f32 v4, v4, s0
	ds_write_b16 v144, v4 offset:528
	v_mul_f32_e32 v4, v9, v8
	v_cvt_pk_bf16_f32 v4, v4, s0
	ds_write_b16 v144, v4 offset:560
	v_mul_f32_e32 v4, v5, v8
	v_cvt_pk_bf16_f32 v4, v4, s0
	ds_write_b16 v144, v4 offset:592
	v_max_f32_e32 v4, v10, v10
	v_max_f32_e32 v5, v14, v14
	v_max_f32_e32 v4, v5, v4
	v_max3_f32 v4, v4, v6, v2
	v_max3_f32 v4, v4, v18, v22
	v_max3_f32 v4, v4, v26, v30
	v_max3_f32 v4, v4, v34, v38
	v_max3_f32 v4, v4, v42, v46
	v_max3_f32 v4, v4, v50, v54
	v_max3_f32 v4, v4, v58, v62
	ds_bpermute_b32 v5, v157, v4
	v_mul_f32_e32 v1, v1, v8
	v_cvt_pk_bf16_f32 v1, v1, s0
	ds_write_b16 v144, v1 offset:624
	v_mul_f32_e32 v1, v13, v8
	s_waitcnt lgkmcnt(1)
	v_max_f32_e32 v5, v5, v5
	v_max_f32_e32 v4, v4, v5
	v_cvt_pk_bf16_f32 v1, v1, s0
	ds_bpermute_b32 v5, v158, v4
	ds_write_b16 v144, v1 offset:656
	v_mul_f32_e32 v1, v16, v8
	v_cvt_pk_bf16_f32 v1, v1, s0
	ds_write_b16 v144, v1 offset:688
	v_mul_f32_e32 v1, v17, v8
	v_cvt_pk_bf16_f32 v1, v1, s0
	ds_write_b16 v144, v1 offset:720
	s_waitcnt lgkmcnt(3)
	v_max_f32_e32 v1, v5, v5
	v_max_f32_e32 v1, v4, v1
	ds_bpermute_b32 v4, v159, v1
	v_mul_f32_e32 v5, v20, v8
	v_cvt_pk_bf16_f32 v5, v5, s0
	ds_write_b16 v144, v5 offset:752
	v_mul_f32_e32 v5, v21, v8
	s_waitcnt lgkmcnt(1)
	v_max_f32_e32 v4, v4, v4
	v_max_f32_e32 v1, v1, v4
	ds_bpermute_b32 v4, v160, v1
	v_cvt_pk_bf16_f32 v5, v5, s0
	ds_write_b16 v144, v5 offset:784
	v_mul_f32_e32 v5, v24, v8
	v_cvt_pk_bf16_f32 v5, v5, s0
	s_waitcnt lgkmcnt(1)
	v_max_f32_e32 v4, v4, v4
	v_max_f32_e32 v1, v1, v4
	v_sub_f32_e32 v4, v14, v1
	v_mul_f32_e32 v4, 0x3fb8aa3b, v4
	v_sub_f32_e32 v9, v10, v1
	v_exp_f32_e32 v4, v4
	v_mul_f32_e32 v9, 0x3fb8aa3b, v9
	v_sub_f32_e32 v6, v6, v1
	v_exp_f32_e32 v9, v9
	v_mul_f32_e32 v6, 0x3fb8aa3b, v6
	v_sub_f32_e32 v2, v2, v1
	v_exp_f32_e32 v6, v6
	v_mul_f32_e32 v2, 0x3fb8aa3b, v2
	v_sub_f32_e32 v12, v18, v1
	v_exp_f32_e32 v2, v2
	v_mul_f32_e32 v12, 0x3fb8aa3b, v12
	v_sub_f32_e32 v13, v22, v1
	v_add_f32_e32 v10, 0, v4
	v_exp_f32_e32 v12, v12
	v_mul_f32_e32 v13, 0x3fb8aa3b, v13
	v_sub_f32_e32 v14, v26, v1
	v_add_f32_e32 v10, v9, v10
	v_exp_f32_e32 v13, v13
	v_mul_f32_e32 v14, 0x3fb8aa3b, v14
	v_sub_f32_e32 v16, v30, v1
	v_add_f32_e32 v10, v6, v10
	v_exp_f32_e32 v14, v14
	v_mul_f32_e32 v16, 0x3fb8aa3b, v16
	v_sub_f32_e32 v17, v34, v1
	v_add_f32_e32 v10, v2, v10
	v_exp_f32_e32 v16, v16
	v_mul_f32_e32 v17, 0x3fb8aa3b, v17
	v_sub_f32_e32 v18, v38, v1
	v_add_f32_e32 v10, v12, v10
	v_exp_f32_e32 v17, v17
	v_mul_f32_e32 v18, 0x3fb8aa3b, v18
	v_sub_f32_e32 v20, v42, v1
	v_add_f32_e32 v10, v13, v10
	v_exp_f32_e32 v18, v18
	v_mul_f32_e32 v20, 0x3fb8aa3b, v20
	v_sub_f32_e32 v21, v46, v1
	v_add_f32_e32 v10, v14, v10
	v_exp_f32_e32 v20, v20
	v_mul_f32_e32 v21, 0x3fb8aa3b, v21
	v_sub_f32_e32 v22, v50, v1
	v_add_f32_e32 v10, v16, v10
	v_exp_f32_e32 v21, v21
	v_mul_f32_e32 v22, 0x3fb8aa3b, v22
	v_sub_f32_e32 v24, v54, v1
	v_add_f32_e32 v10, v17, v10
	v_exp_f32_e32 v22, v22
	v_mul_f32_e32 v24, 0x3fb8aa3b, v24
	v_sub_f32_e32 v26, v58, v1
	v_add_f32_e32 v10, v18, v10
	v_exp_f32_e32 v24, v24
	v_mul_f32_e32 v26, 0x3fb8aa3b, v26
	v_sub_f32_e32 v1, v62, v1
	v_add_f32_e32 v10, v20, v10
	v_exp_f32_e32 v26, v26
	v_mul_f32_e32 v1, 0x3fb8aa3b, v1
	v_add_f32_e32 v10, v21, v10
	v_exp_f32_e32 v1, v1
	v_add_f32_e32 v10, v22, v10
	v_add_f32_e32 v10, v24, v10
	v_add_f32_e32 v10, v26, v10
	v_add_f32_e32 v10, v1, v10
	ds_bpermute_b32 v30, v157, v10
	ds_write_b16 v144, v5 offset:816
	v_mul_f32_e32 v5, v25, v8
	v_cvt_pk_bf16_f32 v5, v5, s0
	ds_write_b16 v144, v5 offset:848
	s_waitcnt lgkmcnt(2)
	v_add_f32_e32 v5, v10, v30
	ds_bpermute_b32 v10, v158, v5
	v_mul_f32_e32 v25, v28, v8
	v_cvt_pk_bf16_f32 v25, v25, s0
	ds_write_b16 v144, v25 offset:880
	v_mul_f32_e32 v25, v29, v8
	s_waitcnt lgkmcnt(1)
	v_add_f32_e32 v5, v5, v10
	ds_bpermute_b32 v10, v159, v5
	v_cvt_pk_bf16_f32 v25, v25, s0
	ds_write_b16 v144, v25 offset:912
	v_mul_f32_e32 v25, v32, v8
	v_cvt_pk_bf16_f32 v25, v25, s0
	s_waitcnt lgkmcnt(1)
	v_add_f32_e32 v5, v5, v10
	ds_bpermute_b32 v10, v160, v5
	ds_write_b16 v144, v25 offset:944
	v_mul_f32_e32 v25, v33, v8
	v_cvt_pk_bf16_f32 v25, v25, s0
	ds_write_b16 v144, v25 offset:976
	s_waitcnt lgkmcnt(2)
	v_add_f32_e32 v5, v5, v10
	v_div_scale_f32 v10, s[14:15], v5, v5, 1.0
	v_rcp_f32_e32 v25, v10
	v_mul_f32_e32 v0, v0, v8
	v_cvt_pk_bf16_f32 v0, v0, s0
	ds_write_b16 v144, v0 offset:1008
	v_fma_f32 v0, -v10, v25, 1.0
	v_fmac_f32_e32 v25, v0, v25
	v_div_scale_f32 v0, vcc, 1.0, v5, 1.0
	v_mul_f32_e32 v8, v0, v25
	v_fma_f32 v28, -v10, v8, v0
	v_fmac_f32_e32 v8, v28, v25
	v_fma_f32 v0, -v10, v8, v0
	v_div_fmas_f32 v0, v0, v25, v8
	v_div_fixup_f32 v0, v0, v5, 1.0
	v_mul_f32_e32 v4, v4, v0
	v_cvt_pk_bf16_f32 v4, v4, s0
	ds_write_b16 v144, v4 offset:1056
	v_mul_f32_e32 v4, v9, v0
	v_cvt_pk_bf16_f32 v4, v4, s0
	ds_write_b16 v144, v4 offset:1088
	v_mul_f32_e32 v4, v6, v0
	v_cvt_pk_bf16_f32 v4, v4, s0
	ds_write_b16 v144, v4 offset:1120
	v_max_f32_e32 v4, v11, v11
	v_max_f32_e32 v5, v15, v15
	v_max_f32_e32 v4, v5, v4
	v_max3_f32 v4, v4, v7, v3
	v_max3_f32 v4, v4, v19, v23
	v_max3_f32 v4, v4, v27, v31
	v_max3_f32 v4, v4, v35, v39
	v_max3_f32 v4, v4, v43, v47
	v_max3_f32 v4, v4, v51, v55
	v_max3_f32 v4, v4, v59, v63
	ds_bpermute_b32 v5, v157, v4
	v_mul_f32_e32 v2, v2, v0
	v_cvt_pk_bf16_f32 v2, v2, s0
	ds_write_b16 v144, v2 offset:1152
	v_mul_f32_e32 v2, v12, v0
	s_waitcnt lgkmcnt(1)
; __device__ __forceinline__ bf16_t f2bf(float v) { return (bf16_t)(cvt_pk_bf16(v, 0.f) & 0xffffu); }
; #define ATT_PUT() do { __syncthreads(); _Pragma("unroll") for (int j = 0; j < 8; ++j) stage[(wid * 8 + j) * 64 + lane] = t[j]; __syncthreads(); } while (0)
; __device__ __forceinline__ void attn_item(KP P, int rbk, int h, unsigned char* lds) {
;     ...
;         for (int kb = 0; kb < 16; ++kb) { const float e = __expf(S[kb][reg] - mx); S[kb][reg] = e; sum += e; }
; #pragma unroll
;         for (int o2 = 8; o2 >= 1; o2 >>= 1) sum += __shfl_xor(sum, o2);
;         const float inv = 1.0f / sum;
; #pragma unroll
;         for (int kb = 0; kb < 16; ++kb) Pl[(q * 4 + reg) * 264 + kb * 16 + l15] = f2bf(S[kb][reg] * inv);
;     }
;     asm volatile("s_waitcnt lgkmcnt(0)" ::: "memory");
;     bf16x8 Pa[8];
; #pragma unroll
;     for (int ks = 0; ks < 8; ++ks) Pa[ks] = *(const bf16x8*)(Pl + l15 * 264 + ks * 32 + 8 * q);
;     asm volatile("s_waitcnt lgkmcnt(0)" ::: "memory");
;     ...
;     ATT_PUT();
	v_max_f32_e32 v5, v5, v5
	v_max_f32_e32 v4, v4, v5
	v_cvt_pk_bf16_f32 v2, v2, s0
	ds_bpermute_b32 v5, v158, v4
	ds_write_b16 v144, v2 offset:1184
	v_mul_f32_e32 v2, v13, v0
	v_cvt_pk_bf16_f32 v2, v2, s0
	ds_write_b16 v144, v2 offset:1216
	v_mul_f32_e32 v2, v14, v0
	v_cvt_pk_bf16_f32 v2, v2, s0
	ds_write_b16 v144, v2 offset:1248
	s_waitcnt lgkmcnt(3)
	v_max_f32_e32 v2, v5, v5
	v_max_f32_e32 v2, v4, v2
	ds_bpermute_b32 v4, v159, v2
	v_mul_f32_e32 v5, v16, v0
	v_cvt_pk_bf16_f32 v5, v5, s0
	ds_write_b16 v144, v5 offset:1280
	v_mul_f32_e32 v5, v17, v0
	s_waitcnt lgkmcnt(1)
	v_max_f32_e32 v4, v4, v4
	v_max_f32_e32 v2, v2, v4
	ds_bpermute_b32 v4, v160, v2
	v_cvt_pk_bf16_f32 v5, v5, s0
	ds_write_b16 v144, v5 offset:1312
	v_mul_f32_e32 v5, v18, v0
	v_cvt_pk_bf16_f32 v5, v5, s0
	s_waitcnt lgkmcnt(1)
	v_max_f32_e32 v4, v4, v4
	v_max_f32_e32 v2, v2, v4
	v_sub_f32_e32 v4, v15, v2
	v_mul_f32_e32 v4, 0x3fb8aa3b, v4
	v_sub_f32_e32 v6, v11, v2
	v_exp_f32_e32 v4, v4
	v_mul_f32_e32 v6, 0x3fb8aa3b, v6
	v_sub_f32_e32 v7, v7, v2
	v_exp_f32_e32 v6, v6
	v_mul_f32_e32 v7, 0x3fb8aa3b, v7
	v_sub_f32_e32 v3, v3, v2
	v_exp_f32_e32 v7, v7
	v_mul_f32_e32 v3, 0x3fb8aa3b, v3
	v_sub_f32_e32 v9, v19, v2
	v_exp_f32_e32 v3, v3
	v_mul_f32_e32 v9, 0x3fb8aa3b, v9
	v_sub_f32_e32 v10, v23, v2
	v_add_f32_e32 v8, 0, v4
	v_exp_f32_e32 v9, v9
	v_mul_f32_e32 v10, 0x3fb8aa3b, v10
	v_sub_f32_e32 v11, v27, v2
	v_add_f32_e32 v8, v6, v8
	v_exp_f32_e32 v10, v10
	v_mul_f32_e32 v11, 0x3fb8aa3b, v11
	v_sub_f32_e32 v12, v31, v2
	v_add_f32_e32 v8, v7, v8
	v_exp_f32_e32 v11, v11
	v_mul_f32_e32 v12, 0x3fb8aa3b, v12
	v_sub_f32_e32 v13, v35, v2
	v_add_f32_e32 v8, v3, v8
	v_exp_f32_e32 v12, v12
	v_mul_f32_e32 v13, 0x3fb8aa3b, v13
	v_sub_f32_e32 v14, v39, v2
	v_add_f32_e32 v8, v9, v8
	v_exp_f32_e32 v13, v13
	v_mul_f32_e32 v14, 0x3fb8aa3b, v14
	v_sub_f32_e32 v15, v43, v2
	v_add_f32_e32 v8, v10, v8
	v_exp_f32_e32 v14, v14
	v_mul_f32_e32 v15, 0x3fb8aa3b, v15
	v_sub_f32_e32 v16, v47, v2
	v_add_f32_e32 v8, v11, v8
	v_exp_f32_e32 v15, v15
	v_mul_f32_e32 v16, 0x3fb8aa3b, v16
	v_sub_f32_e32 v17, v51, v2
	v_add_f32_e32 v8, v12, v8
	v_exp_f32_e32 v16, v16
	v_mul_f32_e32 v17, 0x3fb8aa3b, v17
	v_sub_f32_e32 v18, v55, v2
	v_add_f32_e32 v8, v13, v8
	v_exp_f32_e32 v17, v17
	v_mul_f32_e32 v18, 0x3fb8aa3b, v18
	v_sub_f32_e32 v19, v59, v2
	v_add_f32_e32 v8, v14, v8
	v_exp_f32_e32 v18, v18
	v_mul_f32_e32 v19, 0x3fb8aa3b, v19
	v_sub_f32_e32 v2, v63, v2
	v_add_f32_e32 v8, v15, v8
	v_exp_f32_e32 v19, v19
	v_mul_f32_e32 v2, 0x3fb8aa3b, v2
	v_add_f32_e32 v8, v16, v8
	v_exp_f32_e32 v2, v2
	v_add_f32_e32 v8, v17, v8
	v_add_f32_e32 v8, v18, v8
	v_add_f32_e32 v8, v19, v8
	v_add_f32_e32 v8, v2, v8
	ds_bpermute_b32 v23, v157, v8
	ds_write_b16 v144, v5 offset:1344
	v_mul_f32_e32 v5, v20, v0
	v_cvt_pk_bf16_f32 v5, v5, s0
	ds_write_b16 v144, v5 offset:1376
	s_waitcnt lgkmcnt(2)
	v_add_f32_e32 v5, v8, v23
	ds_bpermute_b32 v8, v158, v5
	v_mul_f32_e32 v20, v21, v0
	v_cvt_pk_bf16_f32 v20, v20, s0
	ds_write_b16 v144, v20 offset:1408
	v_mul_f32_e32 v20, v22, v0
	s_waitcnt lgkmcnt(1)
	v_add_f32_e32 v5, v5, v8
	ds_bpermute_b32 v8, v159, v5
	v_cvt_pk_bf16_f32 v20, v20, s0
	ds_write_b16 v144, v20 offset:1440
	v_mul_f32_e32 v20, v24, v0
	v_cvt_pk_bf16_f32 v20, v20, s0
	s_waitcnt lgkmcnt(1)
	v_add_f32_e32 v5, v5, v8
	ds_bpermute_b32 v8, v160, v5
	ds_write_b16 v144, v20 offset:1472
	v_mul_f32_e32 v20, v26, v0
	v_cvt_pk_bf16_f32 v20, v20, s0
	ds_write_b16 v144, v20 offset:1504
	s_waitcnt lgkmcnt(2)
	v_add_f32_e32 v5, v5, v8
	v_div_scale_f32 v8, s[14:15], v5, v5, 1.0
	v_rcp_f32_e32 v20, v8
	v_mul_f32_e32 v0, v1, v0
	v_cvt_pk_bf16_f32 v0, v0, s0
	ds_write_b16 v144, v0 offset:1536
	v_fma_f32 v0, -v8, v20, 1.0
	v_fmac_f32_e32 v20, v0, v20
	v_div_scale_f32 v0, vcc, 1.0, v5, 1.0
	v_mul_f32_e32 v1, v0, v20
	v_fma_f32 v21, -v8, v1, v0
	v_fmac_f32_e32 v1, v21, v20
	v_fma_f32 v0, -v8, v1, v0
	v_div_fmas_f32 v0, v0, v20, v1
	v_div_fixup_f32 v0, v0, v5, 1.0
	v_mul_f32_e32 v1, v4, v0
	v_cvt_pk_bf16_f32 v1, v1, s0
	ds_write_b16 v144, v1 offset:1584
	v_mul_f32_e32 v1, v6, v0
	v_cvt_pk_bf16_f32 v1, v1, s0
	ds_write_b16 v144, v1 offset:1616
	v_mul_f32_e32 v1, v7, v0
	v_cvt_pk_bf16_f32 v1, v1, s0
	ds_write_b16 v144, v1 offset:1648
	v_mul_f32_e32 v1, v3, v0
	v_cvt_pk_bf16_f32 v1, v1, s0
	ds_write_b16 v144, v1 offset:1680
	v_mul_f32_e32 v1, v9, v0
	v_cvt_pk_bf16_f32 v1, v1, s0
	ds_write_b16 v144, v1 offset:1712
	v_mul_f32_e32 v1, v10, v0
	v_cvt_pk_bf16_f32 v1, v1, s0
	ds_write_b16 v144, v1 offset:1744
	v_mul_f32_e32 v1, v11, v0
	v_cvt_pk_bf16_f32 v1, v1, s0
	ds_write_b16 v144, v1 offset:1776
	v_mul_f32_e32 v1, v12, v0
	v_cvt_pk_bf16_f32 v1, v1, s0
	ds_write_b16 v144, v1 offset:1808
	v_mul_f32_e32 v1, v13, v0
	v_cvt_pk_bf16_f32 v1, v1, s0
	ds_write_b16 v144, v1 offset:1840
	v_mul_f32_e32 v1, v14, v0
	v_cvt_pk_bf16_f32 v1, v1, s0
	ds_write_b16 v144, v1 offset:1872
	v_mul_f32_e32 v1, v15, v0
	v_cvt_pk_bf16_f32 v1, v1, s0
	ds_write_b16 v144, v1 offset:1904
	v_mul_f32_e32 v1, v16, v0
	v_cvt_pk_bf16_f32 v1, v1, s0
	ds_write_b16 v144, v1 offset:1936
	v_mul_f32_e32 v1, v17, v0
	v_cvt_pk_bf16_f32 v1, v1, s0
	ds_write_b16 v144, v1 offset:1968
	v_mul_f32_e32 v1, v18, v0
	v_cvt_pk_bf16_f32 v1, v1, s0
	ds_write_b16 v144, v1 offset:2000
	v_mul_f32_e32 v1, v19, v0
	v_mul_f32_e32 v0, v2, v0
	v_cvt_pk_bf16_f32 v1, v1, s0
	v_cvt_pk_bf16_f32 v0, v0, s0
	ds_write_b16 v144, v1 offset:2032
	ds_write_b16 v144, v0 offset:2064
	s_waitcnt lgkmcnt(0)
	ds_read_b128 v[28:31], v145
	ds_read_b128 v[24:27], v145 offset:64
	ds_read_b128 v[20:23], v145 offset:128
	ds_read_b128 v[16:19], v145 offset:192
	ds_read_b128 v[12:15], v145 offset:256
	ds_read_b128 v[8:11], v145 offset:320
	ds_read_b128 v[4:7], v145 offset:384
	ds_read_b128 v[0:3], v145 offset:448
	s_waitcnt lgkmcnt(0)
	s_barrier
; #define ATT_LOAD(src, half) do { _Pragma("unroll") for (int j = 0; j < 8; ++j) t[j] = src[((half) * 64 + wid * 8 + j) * 64]; } while (0)
; #define ATT_PUT() do { __syncthreads(); _Pragma("unroll") for (int j = 0; j < 8; ++j) stage[(wid * 8 + j) * 64 + lane] = t[j]; __syncthreads(); } while (0)
; __device__ __forceinline__ void attn_item(KP P, int rbk, int h, unsigned char* lds) {
;     ...
;     ATT_PUT();
;     ATT_LOAD(vf, 1); ATT_PV(0); ATT_PUT();
	s_waitcnt vmcnt(7)
	ds_write_b128 v167, v[64:67]
	s_waitcnt vmcnt(6)
	ds_write_b128 v167, v[68:71] offset:1024
	s_waitcnt vmcnt(5)
	ds_write_b128 v167, v[72:75] offset:2048
	s_waitcnt vmcnt(4)
	ds_write_b128 v167, v[76:79] offset:3072
	s_waitcnt vmcnt(3)
	ds_write_b128 v167, v[80:83] offset:4096
	s_waitcnt vmcnt(2)
	ds_write_b128 v167, v[84:87] offset:5120
	s_waitcnt vmcnt(1)
	ds_write_b128 v167, v[88:91] offset:6144
	s_waitcnt vmcnt(0)
	ds_write_b128 v167, v[92:95] offset:7168
	s_waitcnt lgkmcnt(0)
	s_barrier
	ds_read_b128 v[32:35], v165
	ds_read_b128 v[36:39], v165 offset:1024
	s_waitcnt lgkmcnt(1)
	v_mfma_f32_16x16x32_bf16 v[32:35], v[28:31], v[32:35], 0
	v_add_co_u32_e32 v56, vcc, s18, v126
	s_waitcnt lgkmcnt(0)
	v_mfma_f32_16x16x32_bf16 v[32:35], v[24:27], v[36:39], v[32:35]
	ds_read_b128 v[36:39], v165 offset:2048
	ds_read_b128 v[40:43], v165 offset:3072
	v_addc_co_u32_e32 v57, vcc, 0, v127, vcc
	s_waitcnt lgkmcnt(1)
	v_mfma_f32_16x16x32_bf16 v[32:35], v[20:23], v[36:39], v[32:35]
	ds_read_b128 v[36:39], v165 offset:4096
	v_add_co_u32_e32 v60, vcc, s62, v126
	s_waitcnt lgkmcnt(1)
	v_mfma_f32_16x16x32_bf16 v[32:35], v[16:19], v[40:43], v[32:35]
	ds_read_b128 v[40:43], v165 offset:5120
	v_addc_co_u32_e32 v61, vcc, 0, v127, vcc
	s_waitcnt lgkmcnt(1)
	v_mfma_f32_16x16x32_bf16 v[44:47], v[12:15], v[36:39], v[32:35]
	s_nop 3
	global_load_dwordx4 v[32:35], v[56:57], off offset:1024
	global_load_dwordx4 v[36:39], v[56:57], off offset:2048
	ds_read_b128 v[48:51], v165 offset:6144
	s_waitcnt lgkmcnt(1)
	v_mfma_f32_16x16x32_bf16 v[52:55], v[8:11], v[40:43], v[44:47]
	s_nop 2
	global_load_dwordx4 v[44:47], v[60:61], off offset:-4096
	global_load_dwordx4 v[40:43], v[56:57], off offset:3072
	ds_read_b128 v[64:67], v165 offset:7168
	s_waitcnt lgkmcnt(1)
	v_mfma_f32_16x16x32_bf16 v[68:71], v[4:7], v[48:51], v[52:55]
	global_load_dwordx4 v[48:51], v[60:61], off
	s_nop 1
	global_load_dwordx4 v[52:55], v[60:61], off offset:1024
	global_load_dwordx4 v[56:59], v[60:61], off offset:2048
	s_nop 0
	global_load_dwordx4 v[60:63], v[60:61], off offset:3072
	ds_read_b128 v[78:81], v165 offset:10240
	s_waitcnt lgkmcnt(1)
	v_mfma_f32_16x16x32_bf16 v[66:69], v[0:3], v[64:67], v[68:71]
	v_lshlrev_b32_e32 v64, 16, v156
	v_lshlrev_b32_e32 v65, 10, v155
	v_and_or_b32 v64, v65, s63, v64
	v_lshlrev_b32_e32 v65, 6, v155
	ds_read_b128 v[70:73], v165 offset:8192
	v_and_or_b32 v65, v65, s64, v146
	v_or3_b32 v74, v65, v166, v64
	s_nop 0
	v_cvt_pk_bf16_f32 v66, v66, s0
	v_lshlrev_b32_e32 v74, 1, v74
	global_store_short v74, v66, s[42:43]
	ds_read_b128 v[74:77], v165 offset:9216
	s_waitcnt lgkmcnt(1)
	v_mfma_f32_16x16x32_bf16 v[70:73], v[28:31], v[70:73], 0
	v_or_b32_e32 v66, v65, v148
	v_cvt_pk_bf16_f32 v67, v67, s0
	v_cvt_pk_bf16_f32 v68, v68, s0
	s_waitcnt lgkmcnt(0)
	v_mfma_f32_16x16x32_bf16 v[70:73], v[24:27], v[74:77], v[70:73]
	v_or_b32_e32 v74, v66, v64
	v_lshlrev_b32_e32 v82, 1, v74
	ds_read_b128 v[74:77], v165 offset:11264
	v_mfma_f32_16x16x32_bf16 v[70:73], v[20:23], v[78:81], v[70:73]
	ds_read_b128 v[78:81], v165 offset:12288
	global_store_short v82, v67, s[42:43]
	v_or_b32_e32 v67, v65, v149
	s_waitcnt lgkmcnt(1)
	v_mfma_f32_16x16x32_bf16 v[70:73], v[16:19], v[74:77], v[70:73]
	ds_read_b128 v[74:77], v165 offset:13312
	v_or_b32_e32 v82, v67, v64
	v_cvt_pk_bf16_f32 v69, v69, s0
	s_waitcnt lgkmcnt(1)
	v_mfma_f32_16x16x32_bf16 v[70:73], v[12:15], v[78:81], v[70:73]
	v_lshlrev_b32_e32 v78, 1, v82
	global_store_short v78, v68, s[42:43]
	ds_read_b128 v[78:81], v165 offset:14336
	s_waitcnt lgkmcnt(1)
	v_mfma_f32_16x16x32_bf16 v[70:73], v[8:11], v[74:77], v[70:73]
	ds_read_b128 v[74:77], v165 offset:15360
	v_or_b32_e32 v68, v65, v150
	s_waitcnt lgkmcnt(1)
	v_mfma_f32_16x16x32_bf16 v[70:73], v[4:7], v[78:81], v[70:73]
	v_or_b32_e32 v78, v68, v64
	v_lshlrev_b32_e32 v78, 1, v78
	global_store_short v78, v69, s[42:43]
	s_waitcnt lgkmcnt(0)
	v_mfma_f32_16x16x32_bf16 v[70:73], v[0:3], v[74:77], v[70:73]
	ds_read_b128 v[74:77], v165 offset:16384
	ds_read_b128 v[78:81], v165 offset:17408
	v_or_b32_e32 v69, 16, v64
	s_waitcnt lgkmcnt(1)
	v_mfma_f32_16x16x32_bf16 v[74:77], v[28:31], v[74:77], 0
	v_or3_b32 v82, v69, v166, v65
	s_nop 1
	v_cvt_pk_bf16_f32 v70, v70, s0
	v_lshlrev_b32_e32 v82, 1, v82
	global_store_short v82, v70, s[42:43]
	ds_read_b128 v[82:85], v165 offset:18432
	s_waitcnt lgkmcnt(1)
	v_mfma_f32_16x16x32_bf16 v[74:77], v[24:27], v[78:81], v[74:77]
	ds_read_b128 v[78:81], v165 offset:19456
	v_cvt_pk_bf16_f32 v70, v71, s0
	v_or_b32_e32 v71, v66, v69
	s_waitcnt lgkmcnt(1)
	v_mfma_f32_16x16x32_bf16 v[74:77], v[20:23], v[82:85], v[74:77]
	ds_read_b128 v[82:85], v165 offset:20480
	v_lshlrev_b32_e32 v71, 1, v71
	global_store_short v71, v70, s[42:43]
	s_waitcnt lgkmcnt(1)
	v_mfma_f32_16x16x32_bf16 v[74:77], v[16:19], v[78:81], v[74:77]
	ds_read_b128 v[78:81], v165 offset:21504
	v_or_b32_e32 v71, v67, v69
	v_cvt_pk_bf16_f32 v70, v72, s0
	s_waitcnt lgkmcnt(1)
	v_mfma_f32_16x16x32_bf16 v[74:77], v[12:15], v[82:85], v[74:77]
	ds_read_b128 v[82:85], v165 offset:22528
	v_lshlrev_b32_e32 v71, 1, v71
	v_or_b32_e32 v69, v68, v69
	s_waitcnt lgkmcnt(1)
	v_mfma_f32_16x16x32_bf16 v[74:77], v[8:11], v[78:81], v[74:77]
	global_store_short v71, v70, s[42:43]
	v_cvt_pk_bf16_f32 v78, v73, s0
	ds_read_b128 v[70:73], v165 offset:23552
	v_lshlrev_b32_e32 v69, 1, v69
	s_waitcnt lgkmcnt(1)
	v_mfma_f32_16x16x32_bf16 v[74:77], v[4:7], v[82:85], v[74:77]
	global_store_short v69, v78, s[42:43]
	ds_read_b128 v[78:81], v165 offset:24576
	v_or_b32_e32 v69, 32, v64
	s_waitcnt lgkmcnt(1)
	v_mfma_f32_16x16x32_bf16 v[70:73], v[0:3], v[70:73], v[74:77]
	v_or3_b32 v82, v69, v166, v65
	v_lshlrev_b32_e32 v86, 1, v82
	ds_read_b128 v[82:85], v165 offset:26624
	ds_read_b128 v[74:77], v165 offset:25600
	s_waitcnt lgkmcnt(2)
; #define ATT_LOAD(src, half) do { _Pragma("unroll") for (int j = 0; j < 8; ++j) t[j] = src[((half) * 64 + wid * 8 + j) * 64]; } while (0)
; #define ATT_PUT() do { __syncthreads(); _Pragma("unroll") for (int j = 0; j < 8; ++j) stage[(wid * 8 + j) * 64 + lane] = t[j]; __syncthreads(); } while (0)
; __device__ __forceinline__ void attn_item(KP P, int rbk, int h, unsigned char* lds) {
;     ...
;     ATT_PUT();
;     ATT_LOAD(vf, 1); ATT_PV(0); ATT_PUT();
	v_mfma_f32_16x16x32_bf16 v[78:81], v[28:31], v[78:81], 0
	s_nop 1
	v_cvt_pk_bf16_f32 v70, v70, s0
	global_store_short v86, v70, s[42:43]
	v_cvt_pk_bf16_f32 v70, v71, s0
	s_waitcnt lgkmcnt(0)
	v_mfma_f32_16x16x32_bf16 v[74:77], v[24:27], v[74:77], v[78:81]
	v_or_b32_e32 v71, v66, v69
	v_lshlrev_b32_e32 v71, 1, v71
	global_store_short v71, v70, s[42:43]
	ds_read_b128 v[78:81], v165 offset:27648
	v_mfma_f32_16x16x32_bf16 v[74:77], v[20:23], v[82:85], v[74:77]
	ds_read_b128 v[82:85], v165 offset:28672
	v_or_b32_e32 v71, v67, v69
	v_cvt_pk_bf16_f32 v70, v72, s0
	s_waitcnt lgkmcnt(1)
	v_mfma_f32_16x16x32_bf16 v[74:77], v[16:19], v[78:81], v[74:77]
	ds_read_b128 v[78:81], v165 offset:29696
	v_lshlrev_b32_e32 v71, 1, v71
	global_store_short v71, v70, s[42:43]
	s_waitcnt lgkmcnt(1)
	v_mfma_f32_16x16x32_bf16 v[74:77], v[12:15], v[82:85], v[74:77]
	ds_read_b128 v[82:85], v165 offset:30720
	v_or_b32_e32 v69, v68, v69
	v_lshlrev_b32_e32 v69, 1, v69
	s_waitcnt lgkmcnt(1)
	v_mfma_f32_16x16x32_bf16 v[74:77], v[8:11], v[78:81], v[74:77]
	v_cvt_pk_bf16_f32 v78, v73, s0
	ds_read_b128 v[70:73], v165 offset:31744
	global_store_short v69, v78, s[42:43]
	s_waitcnt lgkmcnt(1)
	v_mfma_f32_16x16x32_bf16 v[74:77], v[4:7], v[82:85], v[74:77]
	ds_read_b128 v[78:81], v165 offset:33792
	v_or_b32_e32 v69, 48, v64
	v_or3_b32 v82, v69, v166, v65
	s_waitcnt lgkmcnt(1)
	v_mfma_f32_16x16x32_bf16 v[70:73], v[0:3], v[70:73], v[74:77]
	v_lshlrev_b32_e32 v82, 1, v82
	s_nop 1
	ds_read_b128 v[74:77], v165 offset:32768
	s_waitcnt lgkmcnt(0)
	v_mfma_f32_16x16x32_bf16 v[74:77], v[28:31], v[74:77], 0
	s_nop 1
	v_cvt_pk_bf16_f32 v70, v70, s0
	global_store_short v82, v70, s[42:43]
	ds_read_b128 v[82:85], v165 offset:34816
	v_mfma_f32_16x16x32_bf16 v[74:77], v[24:27], v[78:81], v[74:77]
	ds_read_b128 v[78:81], v165 offset:35840
	v_cvt_pk_bf16_f32 v70, v71, s0
	v_or_b32_e32 v71, v66, v69
	s_waitcnt lgkmcnt(1)
	v_mfma_f32_16x16x32_bf16 v[74:77], v[20:23], v[82:85], v[74:77]
	ds_read_b128 v[82:85], v165 offset:36864
	v_lshlrev_b32_e32 v71, 1, v71
	global_store_short v71, v70, s[42:43]
	s_waitcnt lgkmcnt(1)
	v_mfma_f32_16x16x32_bf16 v[74:77], v[16:19], v[78:81], v[74:77]
	ds_read_b128 v[78:81], v165 offset:37888
	v_or_b32_e32 v71, v67, v69
	v_cvt_pk_bf16_f32 v70, v72, s0
	s_waitcnt lgkmcnt(1)
	v_mfma_f32_16x16x32_bf16 v[74:77], v[12:15], v[82:85], v[74:77]
	ds_read_b128 v[82:85], v165 offset:38912
	v_lshlrev_b32_e32 v71, 1, v71
	v_or_b32_e32 v69, v68, v69
	s_waitcnt lgkmcnt(1)
	v_mfma_f32_16x16x32_bf16 v[74:77], v[8:11], v[78:81], v[74:77]
	global_store_short v71, v70, s[42:43]
	v_cvt_pk_bf16_f32 v78, v73, s0
	ds_read_b128 v[70:73], v165 offset:39936
	v_lshlrev_b32_e32 v69, 1, v69
	s_waitcnt lgkmcnt(1)
	v_mfma_f32_16x16x32_bf16 v[74:77], v[4:7], v[82:85], v[74:77]
	global_store_short v69, v78, s[42:43]
	ds_read_b128 v[78:81], v165 offset:40960
	v_or_b32_e32 v69, 0x4000, v64
	s_waitcnt lgkmcnt(1)
	v_mfma_f32_16x16x32_bf16 v[70:73], v[0:3], v[70:73], v[74:77]
	v_or3_b32 v82, v69, v166, v65
	v_lshlrev_b32_e32 v86, 1, v82
	ds_read_b128 v[82:85], v165 offset:43008
	ds_read_b128 v[74:77], v165 offset:41984
	s_waitcnt lgkmcnt(2)
	v_mfma_f32_16x16x32_bf16 v[78:81], v[28:31], v[78:81], 0
	s_nop 1
	v_cvt_pk_bf16_f32 v70, v70, s0
	global_store_short v86, v70, s[42:43]
	v_cvt_pk_bf16_f32 v70, v71, s0
	s_waitcnt lgkmcnt(0)
	v_mfma_f32_16x16x32_bf16 v[74:77], v[24:27], v[74:77], v[78:81]
	v_or_b32_e32 v71, v66, v69
	v_lshlrev_b32_e32 v71, 1, v71
	global_store_short v71, v70, s[42:43]
	ds_read_b128 v[78:81], v165 offset:44032
	v_mfma_f32_16x16x32_bf16 v[74:77], v[20:23], v[82:85], v[74:77]
	ds_read_b128 v[82:85], v165 offset:45056
	v_or_b32_e32 v71, v67, v69
	v_cvt_pk_bf16_f32 v70, v72, s0
	s_waitcnt lgkmcnt(1)
	v_mfma_f32_16x16x32_bf16 v[74:77], v[16:19], v[78:81], v[74:77]
	ds_read_b128 v[78:81], v165 offset:46080
	v_lshlrev_b32_e32 v71, 1, v71
	global_store_short v71, v70, s[42:43]
	s_waitcnt lgkmcnt(1)
	v_mfma_f32_16x16x32_bf16 v[74:77], v[12:15], v[82:85], v[74:77]
	ds_read_b128 v[82:85], v165 offset:47104
	v_or_b32_e32 v69, v68, v69
	v_lshlrev_b32_e32 v69, 1, v69
	s_waitcnt lgkmcnt(1)
	v_mfma_f32_16x16x32_bf16 v[74:77], v[8:11], v[78:81], v[74:77]
	v_cvt_pk_bf16_f32 v78, v73, s0
	ds_read_b128 v[70:73], v165 offset:48128
	global_store_short v69, v78, s[42:43]
	s_waitcnt lgkmcnt(1)
	v_mfma_f32_16x16x32_bf16 v[74:77], v[4:7], v[82:85], v[74:77]
	ds_read_b128 v[78:81], v165 offset:50176
	v_or_b32_e32 v69, 0x4010, v64
	v_or3_b32 v82, v69, v166, v65
	s_waitcnt lgkmcnt(1)
	v_mfma_f32_16x16x32_bf16 v[70:73], v[0:3], v[70:73], v[74:77]
	v_lshlrev_b32_e32 v82, 1, v82
	s_nop 1
	ds_read_b128 v[74:77], v165 offset:49152
	s_waitcnt lgkmcnt(0)
	v_mfma_f32_16x16x32_bf16 v[74:77], v[28:31], v[74:77], 0
	s_nop 1
	v_cvt_pk_bf16_f32 v70, v70, s0
	global_store_short v82, v70, s[42:43]
	ds_read_b128 v[82:85], v165 offset:51200
	v_mfma_f32_16x16x32_bf16 v[74:77], v[24:27], v[78:81], v[74:77]
	ds_read_b128 v[78:81], v165 offset:52224
	v_cvt_pk_bf16_f32 v70, v71, s0
	v_or_b32_e32 v71, v66, v69
	s_waitcnt lgkmcnt(1)
	v_mfma_f32_16x16x32_bf16 v[74:77], v[20:23], v[82:85], v[74:77]
	ds_read_b128 v[82:85], v165 offset:53248
	v_lshlrev_b32_e32 v71, 1, v71
	global_store_short v71, v70, s[42:43]
	s_waitcnt lgkmcnt(1)
	v_mfma_f32_16x16x32_bf16 v[74:77], v[16:19], v[78:81], v[74:77]
	ds_read_b128 v[78:81], v165 offset:54272
	v_or_b32_e32 v71, v67, v69
	v_cvt_pk_bf16_f32 v70, v72, s0
	s_waitcnt lgkmcnt(1)
	v_mfma_f32_16x16x32_bf16 v[74:77], v[12:15], v[82:85], v[74:77]
	ds_read_b128 v[82:85], v165 offset:55296
	v_lshlrev_b32_e32 v71, 1, v71
	v_or_b32_e32 v69, v68, v69
	s_waitcnt lgkmcnt(1)
; #define ATT_LOAD(src, half) do { _Pragma("unroll") for (int j = 0; j < 8; ++j) t[j] = src[((half) * 64 + wid * 8 + j) * 64]; } while (0)
; #define ATT_PUT() do { __syncthreads(); _Pragma("unroll") for (int j = 0; j < 8; ++j) stage[(wid * 8 + j) * 64 + lane] = t[j]; __syncthreads(); } while (0)
; __device__ __forceinline__ void attn_item(KP P, int rbk, int h, unsigned char* lds) {
;     ...
;     ATT_PUT();
;     ATT_LOAD(vf, 1); ATT_PV(0); ATT_PUT();
;     ATT_PV(1);
	v_mfma_f32_16x16x32_bf16 v[74:77], v[8:11], v[78:81], v[74:77]
	global_store_short v71, v70, s[42:43]
	v_cvt_pk_bf16_f32 v78, v73, s0
	ds_read_b128 v[70:73], v165 offset:56320
	v_lshlrev_b32_e32 v69, 1, v69
	s_waitcnt lgkmcnt(1)
	v_mfma_f32_16x16x32_bf16 v[74:77], v[4:7], v[82:85], v[74:77]
	global_store_short v69, v78, s[42:43]
	ds_read_b128 v[78:81], v165 offset:57344
	v_or_b32_e32 v69, 0x4020, v64
	s_waitcnt lgkmcnt(1)
	v_mfma_f32_16x16x32_bf16 v[70:73], v[0:3], v[70:73], v[74:77]
	v_or3_b32 v82, v69, v166, v65
	v_lshlrev_b32_e32 v86, 1, v82
	ds_read_b128 v[82:85], v165 offset:59392
	ds_read_b128 v[74:77], v165 offset:58368
	s_waitcnt lgkmcnt(2)
	v_mfma_f32_16x16x32_bf16 v[78:81], v[28:31], v[78:81], 0
	s_nop 1
	v_cvt_pk_bf16_f32 v70, v70, s0
	global_store_short v86, v70, s[42:43]
	v_cvt_pk_bf16_f32 v70, v71, s0
	s_waitcnt lgkmcnt(0)
	v_mfma_f32_16x16x32_bf16 v[74:77], v[24:27], v[74:77], v[78:81]
	v_or_b32_e32 v71, v66, v69
	v_lshlrev_b32_e32 v71, 1, v71
	global_store_short v71, v70, s[42:43]
	ds_read_b128 v[78:81], v165 offset:60416
	v_mfma_f32_16x16x32_bf16 v[74:77], v[20:23], v[82:85], v[74:77]
	ds_read_b128 v[82:85], v165 offset:61440
	v_or_b32_e32 v71, v67, v69
	v_cvt_pk_bf16_f32 v70, v72, s0
	s_waitcnt lgkmcnt(1)
	v_mfma_f32_16x16x32_bf16 v[74:77], v[16:19], v[78:81], v[74:77]
	ds_read_b128 v[78:81], v165 offset:62464
	v_lshlrev_b32_e32 v71, 1, v71
	global_store_short v71, v70, s[42:43]
	s_waitcnt lgkmcnt(1)
	v_mfma_f32_16x16x32_bf16 v[74:77], v[12:15], v[82:85], v[74:77]
	ds_read_b128 v[82:85], v165 offset:63488
	v_or_b32_e32 v69, v68, v69
	v_lshlrev_b32_e32 v69, 1, v69
	s_waitcnt lgkmcnt(1)
	v_mfma_f32_16x16x32_bf16 v[74:77], v[8:11], v[78:81], v[74:77]
	v_cvt_pk_bf16_f32 v78, v73, s0
	ds_read_b128 v[70:73], v165 offset:64512
	global_store_short v69, v78, s[42:43]
	s_waitcnt lgkmcnt(1)
	v_mfma_f32_16x16x32_bf16 v[74:77], v[4:7], v[82:85], v[74:77]
	v_or_b32_e32 v69, 0x4030, v64
	s_waitcnt lgkmcnt(0)
	v_mfma_f32_16x16x32_bf16 v[70:73], v[0:3], v[70:73], v[74:77]
	s_nop 4
	v_or3_b32 v74, v69, v166, v65
	s_nop 1
	v_cvt_pk_bf16_f32 v70, v70, s0
	v_lshlrev_b32_e32 v74, 1, v74
	global_store_short v74, v70, s[42:43]
	v_cvt_pk_bf16_f32 v70, v71, s0
	v_or_b32_e32 v71, v66, v69
	v_lshlrev_b32_e32 v71, 1, v71
	global_store_short v71, v70, s[42:43]
	v_or_b32_e32 v71, v67, v69
	v_cvt_pk_bf16_f32 v70, v72, s0
	v_lshlrev_b32_e32 v71, 1, v71
	v_or_b32_e32 v69, v68, v69
	global_store_short v71, v70, s[42:43]
	v_cvt_pk_bf16_f32 v70, v73, s0
	v_lshlrev_b32_e32 v69, 1, v69
	global_store_short v69, v70, s[42:43]
	s_barrier
	s_waitcnt vmcnt(37)
	ds_write_b128 v167, v[44:47]
	ds_write_b128 v167, v[32:35] offset:1024
	ds_write_b128 v167, v[36:39] offset:2048
	s_waitcnt vmcnt(36)
	ds_write_b128 v167, v[40:43] offset:3072
	s_waitcnt vmcnt(35)
	ds_write_b128 v167, v[48:51] offset:4096
	s_waitcnt vmcnt(34)
	ds_write_b128 v167, v[52:55] offset:5120
	s_waitcnt vmcnt(33)
	ds_write_b128 v167, v[56:59] offset:6144
	s_waitcnt vmcnt(32)
	ds_write_b128 v167, v[60:63] offset:7168
	s_waitcnt lgkmcnt(0)
	s_barrier
	ds_read_b128 v[32:35], v165
	ds_read_b128 v[36:39], v165 offset:1024
	s_waitcnt lgkmcnt(1)
	v_mfma_f32_16x16x32_bf16 v[32:35], v[28:31], v[32:35], 0
	v_or_b32_e32 v48, 0x8000, v64
	v_or3_b32 v44, v48, v166, v65
	v_lshlrev_b32_e32 v49, 1, v44
	s_waitcnt lgkmcnt(0)
	v_mfma_f32_16x16x32_bf16 v[32:35], v[24:27], v[36:39], v[32:35]
	ds_read_b128 v[36:39], v165 offset:2048
	ds_read_b128 v[40:43], v165 offset:3072
	s_waitcnt lgkmcnt(1)
	v_mfma_f32_16x16x32_bf16 v[32:35], v[20:23], v[36:39], v[32:35]
	s_waitcnt lgkmcnt(0)
	v_mfma_f32_16x16x32_bf16 v[32:35], v[16:19], v[40:43], v[32:35]
	ds_read_b128 v[36:39], v165 offset:4096
	ds_read_b128 v[40:43], v165 offset:5120
	s_waitcnt lgkmcnt(1)
	v_mfma_f32_16x16x32_bf16 v[32:35], v[12:15], v[36:39], v[32:35]
	s_waitcnt lgkmcnt(0)
	v_mfma_f32_16x16x32_bf16 v[32:35], v[8:11], v[40:43], v[32:35]
	ds_read_b128 v[36:39], v165 offset:6144
	ds_read_b128 v[40:43], v165 offset:7168
	ds_read_b128 v[44:47], v165 offset:10240
	s_waitcnt lgkmcnt(2)
	v_mfma_f32_16x16x32_bf16 v[32:35], v[4:7], v[36:39], v[32:35]
	ds_read_b128 v[36:39], v165 offset:8192
	s_waitcnt lgkmcnt(2)
	v_mfma_f32_16x16x32_bf16 v[32:35], v[0:3], v[40:43], v[32:35]
	ds_read_b128 v[40:43], v165 offset:9216
	s_waitcnt lgkmcnt(1)
	v_mfma_f32_16x16x32_bf16 v[36:39], v[28:31], v[36:39], 0
	s_waitcnt lgkmcnt(0)
	v_mfma_f32_16x16x32_bf16 v[36:39], v[24:27], v[40:43], v[36:39]
	ds_read_b128 v[40:43], v165 offset:11264
	s_nop 1
	v_cvt_pk_bf16_f32 v32, v32, s0
	global_store_short v49, v32, s[42:43]
	v_mfma_f32_16x16x32_bf16 v[36:39], v[20:23], v[44:47], v[36:39]
	ds_read_b128 v[44:47], v165 offset:12288
	v_cvt_pk_bf16_f32 v32, v33, s0
	v_or_b32_e32 v33, v66, v48
	s_waitcnt lgkmcnt(1)
	v_mfma_f32_16x16x32_bf16 v[36:39], v[16:19], v[40:43], v[36:39]
	ds_read_b128 v[40:43], v165 offset:13312
	v_lshlrev_b32_e32 v33, 1, v33
	global_store_short v33, v32, s[42:43]
	s_waitcnt lgkmcnt(1)
	v_mfma_f32_16x16x32_bf16 v[36:39], v[12:15], v[44:47], v[36:39]
	ds_read_b128 v[44:47], v165 offset:14336
	v_or_b32_e32 v33, v67, v48
	v_cvt_pk_bf16_f32 v32, v34, s0
	s_waitcnt lgkmcnt(1)
	v_mfma_f32_16x16x32_bf16 v[36:39], v[8:11], v[40:43], v[36:39]
	v_lshlrev_b32_e32 v33, 1, v33
	global_store_short v33, v32, s[42:43]
	v_cvt_pk_bf16_f32 v40, v35, s0
	ds_read_b128 v[32:35], v165 offset:15360
	s_waitcnt lgkmcnt(1)
	v_mfma_f32_16x16x32_bf16 v[36:39], v[4:7], v[44:47], v[36:39]
	v_or_b32_e32 v41, v68, v48
	v_lshlrev_b32_e32 v41, 1, v41
	global_store_short v41, v40, s[42:43]
	s_waitcnt lgkmcnt(0)
; #define ATT_LOAD(src, half) do { _Pragma("unroll") for (int j = 0; j < 8; ++j) t[j] = src[((half) * 64 + wid * 8 + j) * 64]; } while (0)
; #define ATT_PUT() do { __syncthreads(); _Pragma("unroll") for (int j = 0; j < 8; ++j) stage[(wid * 8 + j) * 64 + lane] = t[j]; __syncthreads(); } while (0)
; __device__ __forceinline__ void attn_item(KP P, int rbk, int h, unsigned char* lds) {
;     ...
;     ATT_PUT();
;     ATT_LOAD(vf, 1); ATT_PV(0); ATT_PUT();
;     ATT_PV(1);
	v_mfma_f32_16x16x32_bf16 v[32:35], v[0:3], v[32:35], v[36:39]
	ds_read_b128 v[40:43], v165 offset:17408
	v_or_b32_e32 v48, 0x8010, v64
	v_or3_b32 v44, v48, v166, v65
	ds_read_b128 v[36:39], v165 offset:16384
	s_waitcnt lgkmcnt(0)
	v_mfma_f32_16x16x32_bf16 v[36:39], v[28:31], v[36:39], 0
	s_nop 1
	v_cvt_pk_bf16_f32 v32, v32, s0
	v_lshlrev_b32_e32 v44, 1, v44
	global_store_short v44, v32, s[42:43]
	ds_read_b128 v[44:47], v165 offset:18432
	v_mfma_f32_16x16x32_bf16 v[36:39], v[24:27], v[40:43], v[36:39]
	ds_read_b128 v[40:43], v165 offset:19456
	v_cvt_pk_bf16_f32 v32, v33, s0
	v_or_b32_e32 v33, v66, v48
	s_waitcnt lgkmcnt(1)
	v_mfma_f32_16x16x32_bf16 v[36:39], v[20:23], v[44:47], v[36:39]
	ds_read_b128 v[44:47], v165 offset:20480
	v_lshlrev_b32_e32 v33, 1, v33
	global_store_short v33, v32, s[42:43]
	s_waitcnt lgkmcnt(1)
	v_mfma_f32_16x16x32_bf16 v[36:39], v[16:19], v[40:43], v[36:39]
	ds_read_b128 v[40:43], v165 offset:21504
	v_or_b32_e32 v33, v67, v48
	v_cvt_pk_bf16_f32 v32, v34, s0
	s_waitcnt lgkmcnt(1)
	v_mfma_f32_16x16x32_bf16 v[36:39], v[12:15], v[44:47], v[36:39]
	ds_read_b128 v[44:47], v165 offset:22528
	v_lshlrev_b32_e32 v33, 1, v33
	global_store_short v33, v32, s[42:43]
	s_waitcnt lgkmcnt(1)
	v_mfma_f32_16x16x32_bf16 v[36:39], v[8:11], v[40:43], v[36:39]
	v_or_b32_e32 v41, v68, v48
	v_cvt_pk_bf16_f32 v40, v35, s0
	ds_read_b128 v[32:35], v165 offset:23552
	v_lshlrev_b32_e32 v41, 1, v41
	s_waitcnt lgkmcnt(1)
	v_mfma_f32_16x16x32_bf16 v[36:39], v[4:7], v[44:47], v[36:39]
	global_store_short v41, v40, s[42:43]
	ds_read_b128 v[40:43], v165 offset:24576
	v_or_b32_e32 v48, 0x8020, v64
	s_waitcnt lgkmcnt(1)
	v_mfma_f32_16x16x32_bf16 v[32:35], v[0:3], v[32:35], v[36:39]
	v_or3_b32 v44, v48, v166, v65
	v_lshlrev_b32_e32 v49, 1, v44
	ds_read_b128 v[44:47], v165 offset:26624
	ds_read_b128 v[36:39], v165 offset:25600
	s_waitcnt lgkmcnt(2)
	v_mfma_f32_16x16x32_bf16 v[40:43], v[28:31], v[40:43], 0
	s_nop 1
	v_cvt_pk_bf16_f32 v32, v32, s0
	global_store_short v49, v32, s[42:43]
	v_cvt_pk_bf16_f32 v32, v33, s0
	s_waitcnt lgkmcnt(0)
	v_mfma_f32_16x16x32_bf16 v[36:39], v[24:27], v[36:39], v[40:43]
	v_or_b32_e32 v33, v66, v48
	v_lshlrev_b32_e32 v33, 1, v33
	global_store_short v33, v32, s[42:43]
	ds_read_b128 v[40:43], v165 offset:27648
	v_mfma_f32_16x16x32_bf16 v[36:39], v[20:23], v[44:47], v[36:39]
	ds_read_b128 v[44:47], v165 offset:28672
	v_or_b32_e32 v33, v67, v48
	v_cvt_pk_bf16_f32 v32, v34, s0
	s_waitcnt lgkmcnt(1)
	v_mfma_f32_16x16x32_bf16 v[36:39], v[16:19], v[40:43], v[36:39]
	ds_read_b128 v[40:43], v165 offset:29696
	v_lshlrev_b32_e32 v33, 1, v33
	global_store_short v33, v32, s[42:43]
	s_waitcnt lgkmcnt(1)
	v_mfma_f32_16x16x32_bf16 v[36:39], v[12:15], v[44:47], v[36:39]
	ds_read_b128 v[44:47], v165 offset:30720
	s_waitcnt lgkmcnt(1)
	v_mfma_f32_16x16x32_bf16 v[36:39], v[8:11], v[40:43], v[36:39]
	v_cvt_pk_bf16_f32 v40, v35, s0
	ds_read_b128 v[32:35], v165 offset:31744
	v_or_b32_e32 v41, v68, v48
	s_waitcnt lgkmcnt(1)
	v_mfma_f32_16x16x32_bf16 v[36:39], v[4:7], v[44:47], v[36:39]
	v_lshlrev_b32_e32 v41, 1, v41
	global_store_short v41, v40, s[42:43]
	ds_read_b128 v[40:43], v165 offset:33792
	s_waitcnt lgkmcnt(1)
	v_mfma_f32_16x16x32_bf16 v[32:35], v[0:3], v[32:35], v[36:39]
	v_or_b32_e32 v48, 0x8030, v64
	v_or3_b32 v44, v48, v166, v65
	v_lshlrev_b32_e32 v44, 1, v44
	ds_read_b128 v[36:39], v165 offset:32768
	s_waitcnt lgkmcnt(0)
	v_mfma_f32_16x16x32_bf16 v[36:39], v[28:31], v[36:39], 0
	s_nop 1
	v_cvt_pk_bf16_f32 v32, v32, s0
	global_store_short v44, v32, s[42:43]
	ds_read_b128 v[44:47], v165 offset:34816
	v_mfma_f32_16x16x32_bf16 v[36:39], v[24:27], v[40:43], v[36:39]
	ds_read_b128 v[40:43], v165 offset:35840
	v_cvt_pk_bf16_f32 v32, v33, s0
	v_or_b32_e32 v33, v66, v48
	s_waitcnt lgkmcnt(1)
	v_mfma_f32_16x16x32_bf16 v[36:39], v[20:23], v[44:47], v[36:39]
	ds_read_b128 v[44:47], v165 offset:36864
	v_lshlrev_b32_e32 v33, 1, v33
	global_store_short v33, v32, s[42:43]
	s_waitcnt lgkmcnt(1)
	v_mfma_f32_16x16x32_bf16 v[36:39], v[16:19], v[40:43], v[36:39]
	ds_read_b128 v[40:43], v165 offset:37888
	v_or_b32_e32 v33, v67, v48
	v_cvt_pk_bf16_f32 v32, v34, s0
	s_waitcnt lgkmcnt(1)
	v_mfma_f32_16x16x32_bf16 v[36:39], v[12:15], v[44:47], v[36:39]
	ds_read_b128 v[44:47], v165 offset:38912
	v_lshlrev_b32_e32 v33, 1, v33
	global_store_short v33, v32, s[42:43]
	s_waitcnt lgkmcnt(1)
	v_mfma_f32_16x16x32_bf16 v[36:39], v[8:11], v[40:43], v[36:39]
	v_or_b32_e32 v41, v68, v48
	v_cvt_pk_bf16_f32 v40, v35, s0
	ds_read_b128 v[32:35], v165 offset:39936
	v_lshlrev_b32_e32 v41, 1, v41
	s_waitcnt lgkmcnt(1)
	v_mfma_f32_16x16x32_bf16 v[36:39], v[4:7], v[44:47], v[36:39]
	global_store_short v41, v40, s[42:43]
	ds_read_b128 v[40:43], v165 offset:40960
	v_or_b32_e32 v48, 0xc000, v64
	s_waitcnt lgkmcnt(1)
	v_mfma_f32_16x16x32_bf16 v[32:35], v[0:3], v[32:35], v[36:39]
	v_or3_b32 v44, v48, v166, v65
	v_lshlrev_b32_e32 v49, 1, v44
	ds_read_b128 v[44:47], v165 offset:43008
	ds_read_b128 v[36:39], v165 offset:41984
	s_waitcnt lgkmcnt(2)
; #define ATT_LOAD(src, half) do { _Pragma("unroll") for (int j = 0; j < 8; ++j) t[j] = src[((half) * 64 + wid * 8 + j) * 64]; } while (0)
; #define ATT_PUT() do { __syncthreads(); _Pragma("unroll") for (int j = 0; j < 8; ++j) stage[(wid * 8 + j) * 64 + lane] = t[j]; __syncthreads(); } while (0)
; __device__ __forceinline__ void attn_item(KP P, int rbk, int h, unsigned char* lds) {
;     ...
;     ATT_PUT();
;     ATT_LOAD(vf, 1); ATT_PV(0); ATT_PUT();
;     ATT_PV(1);
;     __syncthreads();
	v_mfma_f32_16x16x32_bf16 v[40:43], v[28:31], v[40:43], 0
	s_nop 1
	v_cvt_pk_bf16_f32 v32, v32, s0
	global_store_short v49, v32, s[42:43]
	v_cvt_pk_bf16_f32 v32, v33, s0
	s_waitcnt lgkmcnt(0)
	v_mfma_f32_16x16x32_bf16 v[36:39], v[24:27], v[36:39], v[40:43]
	v_or_b32_e32 v33, v66, v48
	v_lshlrev_b32_e32 v33, 1, v33
	global_store_short v33, v32, s[42:43]
	ds_read_b128 v[40:43], v165 offset:44032
	v_mfma_f32_16x16x32_bf16 v[36:39], v[20:23], v[44:47], v[36:39]
	ds_read_b128 v[44:47], v165 offset:45056
	v_or_b32_e32 v33, v67, v48
	v_cvt_pk_bf16_f32 v32, v34, s0
	s_waitcnt lgkmcnt(1)
	v_mfma_f32_16x16x32_bf16 v[36:39], v[16:19], v[40:43], v[36:39]
	ds_read_b128 v[40:43], v165 offset:46080
	v_lshlrev_b32_e32 v33, 1, v33
	global_store_short v33, v32, s[42:43]
	s_waitcnt lgkmcnt(1)
	v_mfma_f32_16x16x32_bf16 v[36:39], v[12:15], v[44:47], v[36:39]
	ds_read_b128 v[44:47], v165 offset:47104
	s_waitcnt lgkmcnt(1)
	v_mfma_f32_16x16x32_bf16 v[36:39], v[8:11], v[40:43], v[36:39]
	v_cvt_pk_bf16_f32 v40, v35, s0
	ds_read_b128 v[32:35], v165 offset:48128
	v_or_b32_e32 v41, v68, v48
	s_waitcnt lgkmcnt(1)
	v_mfma_f32_16x16x32_bf16 v[36:39], v[4:7], v[44:47], v[36:39]
	v_lshlrev_b32_e32 v41, 1, v41
	global_store_short v41, v40, s[42:43]
	ds_read_b128 v[40:43], v165 offset:50176
	s_waitcnt lgkmcnt(1)
	v_mfma_f32_16x16x32_bf16 v[32:35], v[0:3], v[32:35], v[36:39]
	v_or_b32_e32 v48, 0xc010, v64
	v_or3_b32 v44, v48, v166, v65
	v_lshlrev_b32_e32 v44, 1, v44
	ds_read_b128 v[36:39], v165 offset:49152
	s_waitcnt lgkmcnt(0)
	v_mfma_f32_16x16x32_bf16 v[36:39], v[28:31], v[36:39], 0
	s_nop 1
	v_cvt_pk_bf16_f32 v32, v32, s0
	global_store_short v44, v32, s[42:43]
	ds_read_b128 v[44:47], v165 offset:51200
	v_mfma_f32_16x16x32_bf16 v[36:39], v[24:27], v[40:43], v[36:39]
	ds_read_b128 v[40:43], v165 offset:52224
	v_cvt_pk_bf16_f32 v32, v33, s0
	v_or_b32_e32 v33, v66, v48
	s_waitcnt lgkmcnt(1)
	v_mfma_f32_16x16x32_bf16 v[36:39], v[20:23], v[44:47], v[36:39]
	ds_read_b128 v[44:47], v165 offset:53248
	v_lshlrev_b32_e32 v33, 1, v33
	global_store_short v33, v32, s[42:43]
	s_waitcnt lgkmcnt(1)
	v_mfma_f32_16x16x32_bf16 v[36:39], v[16:19], v[40:43], v[36:39]
	ds_read_b128 v[40:43], v165 offset:54272
	v_or_b32_e32 v33, v67, v48
	v_cvt_pk_bf16_f32 v32, v34, s0
	s_waitcnt lgkmcnt(1)
	v_mfma_f32_16x16x32_bf16 v[36:39], v[12:15], v[44:47], v[36:39]
	ds_read_b128 v[44:47], v165 offset:55296
	v_lshlrev_b32_e32 v33, 1, v33
	global_store_short v33, v32, s[42:43]
	s_waitcnt lgkmcnt(1)
	v_mfma_f32_16x16x32_bf16 v[36:39], v[8:11], v[40:43], v[36:39]
	v_or_b32_e32 v41, v68, v48
	v_cvt_pk_bf16_f32 v40, v35, s0
	ds_read_b128 v[32:35], v165 offset:56320
	v_lshlrev_b32_e32 v41, 1, v41
	s_waitcnt lgkmcnt(1)
	v_mfma_f32_16x16x32_bf16 v[36:39], v[4:7], v[44:47], v[36:39]
	global_store_short v41, v40, s[42:43]
	ds_read_b128 v[40:43], v165 offset:57344
	v_or_b32_e32 v44, 0xc020, v64
	s_waitcnt lgkmcnt(1)
	v_mfma_f32_16x16x32_bf16 v[32:35], v[0:3], v[32:35], v[36:39]
	s_nop 2
	ds_read_b128 v[36:39], v165 offset:58368
	s_waitcnt lgkmcnt(1)
	v_mfma_f32_16x16x32_bf16 v[28:31], v[28:31], v[40:43], 0
	v_or3_b32 v40, v44, v166, v65
	v_lshlrev_b32_e32 v45, 1, v40
	ds_read_b128 v[40:43], v165 offset:59392
	s_waitcnt lgkmcnt(1)
	v_mfma_f32_16x16x32_bf16 v[24:27], v[24:27], v[36:39], v[28:31]
	v_cvt_pk_bf16_f32 v32, v32, s0
	global_store_short v45, v32, s[42:43]
	v_cvt_pk_bf16_f32 v32, v33, s0
	ds_read_b128 v[28:31], v165 offset:60416
	s_waitcnt lgkmcnt(1)
	v_mfma_f32_16x16x32_bf16 v[20:23], v[20:23], v[40:43], v[24:27]
	s_nop 2
	v_or_b32_e32 v24, v66, v44
	v_lshlrev_b32_e32 v33, 1, v24
	ds_read_b128 v[24:27], v165 offset:61440
	s_waitcnt lgkmcnt(1)
	v_mfma_f32_16x16x32_bf16 v[16:19], v[16:19], v[28:31], v[20:23]
	v_cvt_pk_bf16_f32 v28, v34, s0
	global_store_short v33, v32, s[42:43]
	s_nop 0
	ds_read_b128 v[20:23], v165 offset:62464
	s_waitcnt lgkmcnt(1)
	v_mfma_f32_16x16x32_bf16 v[12:15], v[12:15], v[24:27], v[16:19]
	s_nop 2
	v_or_b32_e32 v16, v67, v44
	v_lshlrev_b32_e32 v24, 1, v16
	ds_read_b128 v[16:19], v165 offset:63488
	s_waitcnt lgkmcnt(1)
	v_mfma_f32_16x16x32_bf16 v[8:11], v[8:11], v[20:23], v[12:15]
	v_cvt_pk_bf16_f32 v20, v35, s0
	global_store_short v24, v28, s[42:43]
	s_nop 0
	ds_read_b128 v[12:15], v165 offset:64512
	s_waitcnt lgkmcnt(1)
	v_mfma_f32_16x16x32_bf16 v[4:7], v[4:7], v[16:19], v[8:11]
	s_waitcnt lgkmcnt(0)
	v_mfma_f32_16x16x32_bf16 v[0:3], v[0:3], v[12:15], v[4:7]
	s_nop 0
	v_or_b32_e32 v8, v68, v44
	v_lshlrev_b32_e32 v8, 1, v8
	global_store_short v8, v20, s[42:43]
	s_nop 1
	v_or_b32_e32 v4, 0xc030, v64
	v_or3_b32 v5, v4, v166, v65
	v_cvt_pk_bf16_f32 v0, v0, s0
	v_lshlrev_b32_e32 v5, 1, v5
	global_store_short v5, v0, s[42:43]
	v_cvt_pk_bf16_f32 v0, v1, s0
	v_or_b32_e32 v1, v66, v4
	v_lshlrev_b32_e32 v1, 1, v1
	global_store_short v1, v0, s[42:43]
	v_or_b32_e32 v1, v67, v4
	v_cvt_pk_bf16_f32 v0, v2, s0
	v_lshlrev_b32_e32 v1, 1, v1
	global_store_short v1, v0, s[42:43]
	v_or_b32_e32 v1, v68, v4
	v_cvt_pk_bf16_f32 v0, v3, s0
	v_lshlrev_b32_e32 v1, 1, v1
	global_store_short v1, v0, s[42:43]
	s_waitcnt vmcnt(63) expcnt(7) lgkmcnt(15)
	s_barrier

; #define PG8_STAGE(bufoff, gbase, voff) do { _Pragma("unroll") for (int _i = 0; _i < 2; ++_i) \
;         __builtin_amdgcn_global_load_lds((const unsigned*)((const char*)(gbase) + (voff)[_i]), (LAS unsigned*)(lds + (bufoff) + ldsw + _i * 8192), 16, 0, 0); } while (0)
; #define PG8_LDA(dst, b, h) do { _Pragma("unroll") for (int m = 0; m < 4; ++m) _Pragma("unroll") for (int k = 0; k < 2; ++k) dst[m][k] = *(const LAS bf16x8*)(lds + PG8_SA(b, h) + aoff + m * 2048 + k * 1024); } while (0)
; #define PG8_WAIT_V(n) asm volatile("s_waitcnt vmcnt(" #n ")" ::: "memory")
; #define PG8_WAIT_L(n) asm volatile("s_waitcnt lgkmcnt(" #n ")" ::: "memory")
; template <class Epi, class Sched>
; __device__ __forceinline__ void gemm_phase(LAS unsigned char* lds, const Gemm g, const Sched& S, const Epi& E) {
;     ...
;         for (int t = 0; t < nt; t += 2) {
;             const bool last = (t == nt - 2);
;             const char* a1 = cA + (size_t)(t + 1) * kstep;
;             const char* a2 = last ? nA : cA + (size_t)(t + 2) * kstep; const char* b2 = last ? nB : cB + (size_t)(t + 2) * kstep;
;             const char* a3 = a2 + kstep; const char* b3 = b2 + kstep;
;             PG8_LDB(B0, 0, 0); PG8_SCHED; PG8_LDA(At, 0, 0); PG8_STAGE(PG8_SA(1, 1), a1 + hstep, voffA);
;             PG8_WAIT_L(8); PG8_BAR; PG8_WAIT_L(0); PG8_MMA(0, 0, At, B0); PG8_BAR; PG8_SCHED;
;             PG8_LDB(B1, 0, 1); PG8_STAGE(PG8_SB(0, 0), b2, voffB);
;             PG8_BAR; PG8_WAIT_L(0); PG8_MMA(0, 1, At, B1); PG8_BAR;
;             PG8_LDA(At, 0, 1); PG8_STAGE(PG8_SA(0, 0), a2, voffA);
;             PG8_BAR; PG8_WAIT_L(0); PG8_MMA(1, 0, At, B0); PG8_BAR; PG8_SCHED;
;             PG8_STAGE(PG8_SB(0, 1), b2 + hstep, voffB);
;             PG8_WAIT_V(6); PG8_BAR; PG8_MMA(1, 1, At, B1); PG8_BAR;
;             PG8_LDB(B0, 1, 0); PG8_SCHED; PG8_LDA(At, 1, 0); PG8_STAGE(PG8_SA(0, 1), a2 + hstep, voffA);
;             PG8_WAIT_L(8); PG8_BAR; PG8_WAIT_L(0); PG8_MMA(0, 0, At, B0); PG8_BAR; PG8_SCHED;
;             PG8_LDB(B1, 1, 1); PG8_STAGE(PG8_SB(1, 0), b3, voffB);
;             PG8_BAR; PG8_WAIT_L(0); PG8_MMA(0, 1, At, B1); PG8_BAR;
;             PG8_LDA(At, 1, 1); PG8_STAGE(PG8_SA(1, 0), a3, voffA);
;             PG8_BAR; PG8_WAIT_L(0); PG8_MMA(1, 0, At, B0); PG8_BAR; PG8_SCHED;
;             PG8_STAGE(PG8_SB(1, 1), b3 + hstep, voffB);
;             PG8_WAIT_V(6); PG8_BAR; PG8_MMA(1, 1, At, B1); PG8_BAR;
.LBB0_1242:
	ds_read_b128 v[140:143], v147
	ds_read_b128 v[150:153], v147 offset:1024
	ds_read_b128 v[154:157], v147 offset:2048
	ds_read_b128 v[158:161], v147 offset:3072
	s_add_u32 s41, s42, 0x4000
	s_addc_u32 s44, s43, 0
	s_cmp_eq_u32 s35, 12
	s_cselect_b32 s48, s36, s41
	s_cselect_b32 s49, s37, s44
	s_cselect_b32 s44, s6, s31
	s_cselect_b32 s45, s7, s33
	s_add_u32 s46, s48, 0x8000
	s_addc_u32 s47, s49, 0
	v_lshl_add_u64 v[194:195], s[42:43], 0, v[136:137]
	s_add_i32 m0, s39, 0xc000
	ds_read_b128 v[162:165], v148
	ds_read_b128 v[166:169], v148 offset:1024
	ds_read_b128 v[170:173], v148 offset:2048
	ds_read_b128 v[174:177], v148 offset:3072
	ds_read_b128 v[178:181], v148 offset:4096
	ds_read_b128 v[182:185], v148 offset:5120
	ds_read_b128 v[186:189], v148 offset:6144
	ds_read_b128 v[190:193], v148 offset:7168
	global_load_lds_dwordx4 v[194:195], off
	v_lshl_add_u64 v[194:195], s[42:43], 0, v[138:139]
	s_add_i32 m0, s39, 0xe000
	s_nop 0
	global_load_lds_dwordx4 v[194:195], off
	s_waitcnt lgkmcnt(8)
	s_barrier
	s_waitcnt lgkmcnt(0)
	v_mfma_f32_16x16x32_bf16 v[120:123], v[140:143], v[162:165], v[120:123]
	v_mfma_f32_16x16x32_bf16 v[116:119], v[154:157], v[162:165], v[116:119]
	v_mfma_f32_16x16x32_bf16 v[104:107], v[140:143], v[170:173], v[104:107]
	v_mfma_f32_16x16x32_bf16 v[100:103], v[154:157], v[170:173], v[100:103]
	v_mfma_f32_16x16x32_bf16 v[88:91], v[140:143], v[178:181], v[88:91]
	v_mfma_f32_16x16x32_bf16 v[84:87], v[154:157], v[178:181], v[84:87]
	v_mfma_f32_16x16x32_bf16 v[72:75], v[140:143], v[186:189], v[72:75]
	v_mfma_f32_16x16x32_bf16 v[68:71], v[154:157], v[186:189], v[68:71]
	v_mfma_f32_16x16x32_bf16 v[120:123], v[150:153], v[166:169], v[120:123]
	v_mfma_f32_16x16x32_bf16 v[116:119], v[158:161], v[166:169], v[116:119]
	v_mfma_f32_16x16x32_bf16 v[104:107], v[150:153], v[174:177], v[104:107]
	v_mfma_f32_16x16x32_bf16 v[100:103], v[158:161], v[174:177], v[100:103]
	v_mfma_f32_16x16x32_bf16 v[88:91], v[150:153], v[182:185], v[88:91]
	v_mfma_f32_16x16x32_bf16 v[84:87], v[158:161], v[182:185], v[84:87]
	v_mfma_f32_16x16x32_bf16 v[72:75], v[150:153], v[190:193], v[72:75]
	v_mfma_f32_16x16x32_bf16 v[68:71], v[158:161], v[190:193], v[68:71]
	s_barrier
	s_add_i32 s41, s71, s54
	v_lshl_add_u64 v[202:203], s[44:45], 0, v[130:131]
	s_mov_b32 m0, s41
	ds_read_b128 v[194:197], v149
	ds_read_b128 v[198:201], v149 offset:1024
	ds_read_b128 v[206:209], v149 offset:2048
	ds_read_b128 v[210:213], v149 offset:3072
	global_load_lds_dwordx4 v[202:203], off
	v_lshl_add_u64 v[202:203], s[44:45], 0, v[134:135]
	s_add_i32 m0, s41, 0x2000
	s_nop 0
	global_load_lds_dwordx4 v[202:203], off
	s_barrier
	s_waitcnt lgkmcnt(0)
	v_mfma_f32_16x16x32_bf16 v[124:127], v[194:197], v[162:165], v[124:127]
	v_mfma_f32_16x16x32_bf16 v[112:115], v[206:209], v[162:165], v[112:115]
	v_mfma_f32_16x16x32_bf16 v[108:111], v[194:197], v[170:173], v[108:111]
	v_mfma_f32_16x16x32_bf16 v[96:99], v[206:209], v[170:173], v[96:99]
	v_mfma_f32_16x16x32_bf16 v[92:95], v[194:197], v[178:181], v[92:95]
	v_mfma_f32_16x16x32_bf16 v[80:83], v[206:209], v[178:181], v[80:83]
	v_mfma_f32_16x16x32_bf16 v[76:79], v[194:197], v[186:189], v[76:79]
	v_mfma_f32_16x16x32_bf16 v[64:67], v[206:209], v[186:189], v[64:67]
	v_mfma_f32_16x16x32_bf16 v[124:127], v[198:201], v[166:169], v[124:127]
	v_mfma_f32_16x16x32_bf16 v[112:115], v[210:213], v[166:169], v[112:115]
	v_mfma_f32_16x16x32_bf16 v[108:111], v[198:201], v[174:177], v[108:111]
	v_mfma_f32_16x16x32_bf16 v[96:99], v[210:213], v[174:177], v[96:99]
	v_mfma_f32_16x16x32_bf16 v[92:95], v[198:201], v[182:185], v[92:95]
	v_mfma_f32_16x16x32_bf16 v[80:83], v[210:213], v[182:185], v[80:83]
	v_mfma_f32_16x16x32_bf16 v[76:79], v[198:201], v[190:193], v[76:79]
	v_mfma_f32_16x16x32_bf16 v[64:67], v[210:213], v[190:193], v[64:67]
	s_mov_b32 m0, s39
	v_lshl_add_u64 v[202:203], s[48:49], 0, v[128:129]
	s_barrier
	ds_read_b128 v[162:165], v148 offset:16384
	ds_read_b128 v[166:169], v148 offset:17408
	ds_read_b128 v[170:173], v148 offset:18432
	ds_read_b128 v[174:177], v148 offset:19456
	ds_read_b128 v[178:181], v148 offset:20480
	ds_read_b128 v[182:185], v148 offset:21504
	ds_read_b128 v[186:189], v148 offset:22528
	ds_read_b128 v[190:193], v148 offset:23552
	global_load_lds_dwordx4 v[202:203], off
	v_lshl_add_u64 v[202:203], s[48:49], 0, v[132:133]
	s_mov_b32 m0, s55
	s_nop 0
	global_load_lds_dwordx4 v[202:203], off
	s_barrier
	s_waitcnt lgkmcnt(0)
	v_mfma_f32_16x16x32_bf16 v[56:59], v[140:143], v[162:165], v[56:59]
	v_mfma_f32_16x16x32_bf16 v[52:55], v[154:157], v[162:165], v[52:55]
	v_mfma_f32_16x16x32_bf16 v[40:43], v[140:143], v[170:173], v[40:43]
	v_mfma_f32_16x16x32_bf16 v[36:39], v[154:157], v[170:173], v[36:39]
	v_mfma_f32_16x16x32_bf16 v[24:27], v[140:143], v[178:181], v[24:27]
	v_mfma_f32_16x16x32_bf16 v[20:23], v[154:157], v[178:181], v[20:23]
	v_mfma_f32_16x16x32_bf16 v[8:11], v[140:143], v[186:189], v[8:11]
	v_mfma_f32_16x16x32_bf16 v[4:7], v[154:157], v[186:189], v[4:7]
	v_mfma_f32_16x16x32_bf16 v[56:59], v[150:153], v[166:169], v[56:59]
	v_mfma_f32_16x16x32_bf16 v[52:55], v[158:161], v[166:169], v[52:55]
	v_mfma_f32_16x16x32_bf16 v[40:43], v[150:153], v[174:177], v[40:43]
	v_mfma_f32_16x16x32_bf16 v[36:39], v[158:161], v[174:177], v[36:39]
	v_mfma_f32_16x16x32_bf16 v[24:27], v[150:153], v[182:185], v[24:27]
	v_mfma_f32_16x16x32_bf16 v[20:23], v[158:161], v[182:185], v[20:23]
	v_mfma_f32_16x16x32_bf16 v[8:11], v[150:153], v[190:193], v[8:11]
	v_mfma_f32_16x16x32_bf16 v[4:7], v[158:161], v[190:193], v[4:7]
	s_barrier
; #define PG8_STAGE(bufoff, gbase, voff) do { _Pragma("unroll") for (int _i = 0; _i < 2; ++_i) \
;         __builtin_amdgcn_global_load_lds((const unsigned*)((const char*)(gbase) + (voff)[_i]), (LAS unsigned*)(lds + (bufoff) + ldsw + _i * 8192), 16, 0, 0); } while (0)
; #define PG8_LDA(dst, b, h) do { _Pragma("unroll") for (int m = 0; m < 4; ++m) _Pragma("unroll") for (int k = 0; k < 2; ++k) dst[m][k] = *(const LAS bf16x8*)(lds + PG8_SA(b, h) + aoff + m * 2048 + k * 1024); } while (0)
; #define PG8_WAIT_V(n) asm volatile("s_waitcnt vmcnt(" #n ")" ::: "memory")
; #define PG8_WAIT_L(n) asm volatile("s_waitcnt lgkmcnt(" #n ")" ::: "memory")
; template <class Epi, class Sched>
; __device__ __forceinline__ void gemm_phase(LAS unsigned char* lds, const Gemm g, const Sched& S, const Epi& E) {
;     ...
;         for (int t = 0; t < nt; t += 2) {
;             const bool last = (t == nt - 2);
;             const char* a1 = cA + (size_t)(t + 1) * kstep;
;             const char* a2 = last ? nA : cA + (size_t)(t + 2) * kstep; const char* b2 = last ? nB : cB + (size_t)(t + 2) * kstep;
;             const char* a3 = a2 + kstep; const char* b3 = b2 + kstep;
;             PG8_LDB(B0, 0, 0); PG8_SCHED; PG8_LDA(At, 0, 0); PG8_STAGE(PG8_SA(1, 1), a1 + hstep, voffA);
;             PG8_WAIT_L(8); PG8_BAR; PG8_WAIT_L(0); PG8_MMA(0, 0, At, B0); PG8_BAR; PG8_SCHED;
;             PG8_LDB(B1, 0, 1); PG8_STAGE(PG8_SB(0, 0), b2, voffB);
;             PG8_BAR; PG8_WAIT_L(0); PG8_MMA(0, 1, At, B1); PG8_BAR;
;             PG8_LDA(At, 0, 1); PG8_STAGE(PG8_SA(0, 0), a2, voffA);
;             PG8_BAR; PG8_WAIT_L(0); PG8_MMA(1, 0, At, B0); PG8_BAR; PG8_SCHED;
;             PG8_STAGE(PG8_SB(0, 1), b2 + hstep, voffB);
;             PG8_WAIT_V(6); PG8_BAR; PG8_MMA(1, 1, At, B1); PG8_BAR;
;             PG8_LDB(B0, 1, 0); PG8_SCHED; PG8_LDA(At, 1, 0); PG8_STAGE(PG8_SA(0, 1), a2 + hstep, voffA);
;             PG8_WAIT_L(8); PG8_BAR; PG8_WAIT_L(0); PG8_MMA(0, 0, At, B0); PG8_BAR; PG8_SCHED;
;             PG8_LDB(B1, 1, 1); PG8_STAGE(PG8_SB(1, 0), b3, voffB);
;             PG8_BAR; PG8_WAIT_L(0); PG8_MMA(0, 1, At, B1); PG8_BAR;
;             PG8_LDA(At, 1, 1); PG8_STAGE(PG8_SA(1, 0), a3, voffA);
;             PG8_BAR; PG8_WAIT_L(0); PG8_MMA(1, 0, At, B0); PG8_BAR; PG8_SCHED;
;             PG8_STAGE(PG8_SB(1, 1), b3 + hstep, voffB);
;             PG8_WAIT_V(6); PG8_BAR; PG8_MMA(1, 1, At, B1); PG8_BAR;
	s_add_u32 s68, s44, 0x4000
	s_addc_u32 s69, s45, 0
	s_add_i32 s41, s61, s54
	v_lshl_add_u64 v[140:141], s[68:69], 0, v[130:131]
	s_mov_b32 m0, s41
	s_nop 0
	global_load_lds_dwordx4 v[140:141], off
	v_lshl_add_u64 v[140:141], s[68:69], 0, v[134:135]
	s_add_i32 m0, s41, 0x2000
	s_nop 0
	global_load_lds_dwordx4 v[140:141], off
	s_waitcnt vmcnt(6)
	s_barrier
	v_mfma_f32_16x16x32_bf16 v[60:63], v[194:197], v[162:165], v[60:63]
	v_mfma_f32_16x16x32_bf16 v[48:51], v[206:209], v[162:165], v[48:51]
	v_mfma_f32_16x16x32_bf16 v[44:47], v[194:197], v[170:173], v[44:47]
	v_mfma_f32_16x16x32_bf16 v[32:35], v[206:209], v[170:173], v[32:35]
	v_mfma_f32_16x16x32_bf16 v[28:31], v[194:197], v[178:181], v[28:31]
	v_mfma_f32_16x16x32_bf16 v[16:19], v[206:209], v[178:181], v[16:19]
	v_mfma_f32_16x16x32_bf16 v[12:15], v[194:197], v[186:189], v[12:15]
	v_mfma_f32_16x16x32_bf16 v[0:3], v[206:209], v[186:189], v[0:3]
	v_mfma_f32_16x16x32_bf16 v[60:63], v[198:201], v[166:169], v[60:63]
	v_mfma_f32_16x16x32_bf16 v[48:51], v[210:213], v[166:169], v[48:51]
	v_mfma_f32_16x16x32_bf16 v[44:47], v[198:201], v[174:177], v[44:47]
	v_mfma_f32_16x16x32_bf16 v[32:35], v[210:213], v[174:177], v[32:35]
	v_mfma_f32_16x16x32_bf16 v[28:31], v[198:201], v[182:185], v[28:31]
	v_mfma_f32_16x16x32_bf16 v[16:19], v[210:213], v[182:185], v[16:19]
	v_mfma_f32_16x16x32_bf16 v[12:15], v[198:201], v[190:193], v[12:15]
	v_mfma_f32_16x16x32_bf16 v[0:3], v[210:213], v[190:193], v[0:3]
	s_add_i32 s41, 0, 0x18000
	v_add_u32_e32 v158, s41, v145
	s_barrier
	ds_read_b128 v[140:143], v158
	ds_read_b128 v[150:153], v158 offset:1024
	ds_read_b128 v[154:157], v158 offset:2048
	ds_read_b128 v[158:161], v158 offset:3072
	s_add_u32 s48, s48, 0x4000
	s_addc_u32 s49, s49, 0
	s_mov_b32 m0, s56
	v_lshl_add_u64 v[194:195], s[48:49], 0, v[128:129]
	ds_read_b128 v[162:165], v148 offset:32768
	ds_read_b128 v[166:169], v148 offset:33792
	ds_read_b128 v[170:173], v148 offset:34816
	ds_read_b128 v[174:177], v148 offset:35840
	ds_read_b128 v[178:181], v148 offset:36864
	ds_read_b128 v[182:185], v148 offset:37888
	ds_read_b128 v[186:189], v148 offset:38912
	ds_read_b128 v[190:193], v148 offset:39936
	global_load_lds_dwordx4 v[194:195], off
	v_lshl_add_u64 v[194:195], s[48:49], 0, v[132:133]
	s_mov_b32 m0, s57
	s_nop 0
	global_load_lds_dwordx4 v[194:195], off
	s_waitcnt lgkmcnt(8)
	s_barrier
	s_waitcnt lgkmcnt(0)
	v_mfma_f32_16x16x32_bf16 v[120:123], v[140:143], v[162:165], v[120:123]
	v_mfma_f32_16x16x32_bf16 v[116:119], v[154:157], v[162:165], v[116:119]
	v_mfma_f32_16x16x32_bf16 v[104:107], v[140:143], v[170:173], v[104:107]
	v_mfma_f32_16x16x32_bf16 v[100:103], v[154:157], v[170:173], v[100:103]
	v_mfma_f32_16x16x32_bf16 v[88:91], v[140:143], v[178:181], v[88:91]
	v_mfma_f32_16x16x32_bf16 v[84:87], v[154:157], v[178:181], v[84:87]
	v_mfma_f32_16x16x32_bf16 v[72:75], v[140:143], v[186:189], v[72:75]
	v_mfma_f32_16x16x32_bf16 v[68:71], v[154:157], v[186:189], v[68:71]
	v_mfma_f32_16x16x32_bf16 v[120:123], v[150:153], v[166:169], v[120:123]
	v_mfma_f32_16x16x32_bf16 v[116:119], v[158:161], v[166:169], v[116:119]
	v_mfma_f32_16x16x32_bf16 v[104:107], v[150:153], v[174:177], v[104:107]
	v_mfma_f32_16x16x32_bf16 v[100:103], v[158:161], v[174:177], v[100:103]
	v_mfma_f32_16x16x32_bf16 v[88:91], v[150:153], v[182:185], v[88:91]
	v_mfma_f32_16x16x32_bf16 v[84:87], v[158:161], v[182:185], v[84:87]
	v_mfma_f32_16x16x32_bf16 v[72:75], v[150:153], v[190:193], v[72:75]
	v_mfma_f32_16x16x32_bf16 v[68:71], v[158:161], v[190:193], v[68:71]
	s_barrier
	s_add_i32 s68, 0, 0x1c000
	s_add_u32 s48, s44, 0x8000
	v_add_u32_e32 v202, s68, v145
	s_addc_u32 s49, s45, 0
	s_add_i32 s41, s41, s54
	ds_read_b128 v[194:197], v202
	ds_read_b128 v[198:201], v202 offset:1024
	ds_read_b128 v[206:209], v202 offset:2048
	ds_read_b128 v[210:213], v202 offset:3072
	v_lshl_add_u64 v[202:203], s[48:49], 0, v[130:131]
	s_mov_b32 m0, s41
	s_nop 0
	global_load_lds_dwordx4 v[202:203], off
	v_lshl_add_u64 v[202:203], s[48:49], 0, v[134:135]
	s_add_i32 m0, s41, 0x2000
	s_nop 0
	global_load_lds_dwordx4 v[202:203], off
	s_barrier
	s_waitcnt lgkmcnt(0)
	v_mfma_f32_16x16x32_bf16 v[124:127], v[194:197], v[162:165], v[124:127]
	v_mfma_f32_16x16x32_bf16 v[112:115], v[206:209], v[162:165], v[112:115]
	v_mfma_f32_16x16x32_bf16 v[108:111], v[194:197], v[170:173], v[108:111]
	v_mfma_f32_16x16x32_bf16 v[96:99], v[206:209], v[170:173], v[96:99]
	v_mfma_f32_16x16x32_bf16 v[92:95], v[194:197], v[178:181], v[92:95]
	v_mfma_f32_16x16x32_bf16 v[80:83], v[206:209], v[178:181], v[80:83]
	v_mfma_f32_16x16x32_bf16 v[76:79], v[194:197], v[186:189], v[76:79]
	v_mfma_f32_16x16x32_bf16 v[64:67], v[206:209], v[186:189], v[64:67]
	v_mfma_f32_16x16x32_bf16 v[124:127], v[198:201], v[166:169], v[124:127]
	v_mfma_f32_16x16x32_bf16 v[112:115], v[210:213], v[166:169], v[112:115]
	v_mfma_f32_16x16x32_bf16 v[108:111], v[198:201], v[174:177], v[108:111]
	v_mfma_f32_16x16x32_bf16 v[96:99], v[210:213], v[174:177], v[96:99]
	v_mfma_f32_16x16x32_bf16 v[92:95], v[198:201], v[182:185], v[92:95]
	v_mfma_f32_16x16x32_bf16 v[80:83], v[210:213], v[182:185], v[80:83]
	v_mfma_f32_16x16x32_bf16 v[76:79], v[198:201], v[190:193], v[76:79]
	v_mfma_f32_16x16x32_bf16 v[64:67], v[210:213], v[190:193], v[64:67]
	s_mov_b32 m0, s59
	v_lshl_add_u64 v[202:203], s[46:47], 0, v[128:129]
	s_barrier
	ds_read_b128 v[162:165], v148 offset:49152
	ds_read_b128 v[166:169], v148 offset:50176
	ds_read_b128 v[170:173], v148 offset:51200
	ds_read_b128 v[174:177], v148 offset:52224
	ds_read_b128 v[178:181], v148 offset:53248
	ds_read_b128 v[182:185], v148 offset:54272
	ds_read_b128 v[186:189], v148 offset:55296
	ds_read_b128 v[190:193], v148 offset:56320
	global_load_lds_dwordx4 v[202:203], off
	v_lshl_add_u64 v[202:203], s[46:47], 0, v[132:133]
	s_mov_b32 m0, s60
	s_nop 0
	global_load_lds_dwordx4 v[202:203], off
	s_barrier
; #define PG8_STAGE(bufoff, gbase, voff) do { _Pragma("unroll") for (int _i = 0; _i < 2; ++_i) \
;         __builtin_amdgcn_global_load_lds((const unsigned*)((const char*)(gbase) + (voff)[_i]), (LAS unsigned*)(lds + (bufoff) + ldsw + _i * 8192), 16, 0, 0); } while (0)
; #define PG8_LDA(dst, b, h) do { _Pragma("unroll") for (int m = 0; m < 4; ++m) _Pragma("unroll") for (int k = 0; k < 2; ++k) dst[m][k] = *(const LAS bf16x8*)(lds + PG8_SA(b, h) + aoff + m * 2048 + k * 1024); } while (0)
; #define PG8_WAIT_V(n) asm volatile("s_waitcnt vmcnt(" #n ")" ::: "memory")
; #define PG8_WAIT_L(n) asm volatile("s_waitcnt lgkmcnt(" #n ")" ::: "memory")
; template <class Epi, class Sched>
; __device__ __forceinline__ void gemm_phase(LAS unsigned char* lds, const Gemm g, const Sched& S, const Epi& E) {
;     ...
;         for (int t = 0; t < nt; t += 2) {
;             const bool last = (t == nt - 2);
;             const char* a1 = cA + (size_t)(t + 1) * kstep;
;             const char* a2 = last ? nA : cA + (size_t)(t + 2) * kstep; const char* b2 = last ? nB : cB + (size_t)(t + 2) * kstep;
;             const char* a3 = a2 + kstep; const char* b3 = b2 + kstep;
;             PG8_LDB(B0, 0, 0); PG8_SCHED; PG8_LDA(At, 0, 0); PG8_STAGE(PG8_SA(1, 1), a1 + hstep, voffA);
;             PG8_WAIT_L(8); PG8_BAR; PG8_WAIT_L(0); PG8_MMA(0, 0, At, B0); PG8_BAR; PG8_SCHED;
;             PG8_LDB(B1, 0, 1); PG8_STAGE(PG8_SB(0, 0), b2, voffB);
;             PG8_BAR; PG8_WAIT_L(0); PG8_MMA(0, 1, At, B1); PG8_BAR;
;             PG8_LDA(At, 0, 1); PG8_STAGE(PG8_SA(0, 0), a2, voffA);
;             PG8_BAR; PG8_WAIT_L(0); PG8_MMA(1, 0, At, B0); PG8_BAR; PG8_SCHED;
;             PG8_STAGE(PG8_SB(0, 1), b2 + hstep, voffB);
;             PG8_WAIT_V(6); PG8_BAR; PG8_MMA(1, 1, At, B1); PG8_BAR;
;             PG8_LDB(B0, 1, 0); PG8_SCHED; PG8_LDA(At, 1, 0); PG8_STAGE(PG8_SA(0, 1), a2 + hstep, voffA);
;             PG8_WAIT_L(8); PG8_BAR; PG8_WAIT_L(0); PG8_MMA(0, 0, At, B0); PG8_BAR; PG8_SCHED;
;             PG8_LDB(B1, 1, 1); PG8_STAGE(PG8_SB(1, 0), b3, voffB);
;             PG8_BAR; PG8_WAIT_L(0); PG8_MMA(0, 1, At, B1); PG8_BAR;
;             PG8_LDA(At, 1, 1); PG8_STAGE(PG8_SA(1, 0), a3, voffA);
;             PG8_BAR; PG8_WAIT_L(0); PG8_MMA(1, 0, At, B0); PG8_BAR; PG8_SCHED;
;             PG8_STAGE(PG8_SB(1, 1), b3 + hstep, voffB);
;             PG8_WAIT_V(6); PG8_BAR; PG8_MMA(1, 1, At, B1); PG8_BAR;
	s_waitcnt lgkmcnt(0)
	v_mfma_f32_16x16x32_bf16 v[56:59], v[140:143], v[162:165], v[56:59]
	v_mfma_f32_16x16x32_bf16 v[52:55], v[154:157], v[162:165], v[52:55]
	v_mfma_f32_16x16x32_bf16 v[40:43], v[140:143], v[170:173], v[40:43]
	v_mfma_f32_16x16x32_bf16 v[36:39], v[154:157], v[170:173], v[36:39]
	v_mfma_f32_16x16x32_bf16 v[24:27], v[140:143], v[178:181], v[24:27]
	v_mfma_f32_16x16x32_bf16 v[20:23], v[154:157], v[178:181], v[20:23]
	v_mfma_f32_16x16x32_bf16 v[8:11], v[140:143], v[186:189], v[8:11]
	v_mfma_f32_16x16x32_bf16 v[4:7], v[154:157], v[186:189], v[4:7]
	v_mfma_f32_16x16x32_bf16 v[56:59], v[150:153], v[166:169], v[56:59]
	v_mfma_f32_16x16x32_bf16 v[52:55], v[158:161], v[166:169], v[52:55]
	v_mfma_f32_16x16x32_bf16 v[40:43], v[150:153], v[174:177], v[40:43]
	v_mfma_f32_16x16x32_bf16 v[36:39], v[158:161], v[174:177], v[36:39]
	v_mfma_f32_16x16x32_bf16 v[24:27], v[150:153], v[182:185], v[24:27]
	v_mfma_f32_16x16x32_bf16 v[20:23], v[158:161], v[182:185], v[20:23]
	v_mfma_f32_16x16x32_bf16 v[8:11], v[150:153], v[190:193], v[8:11]
	v_mfma_f32_16x16x32_bf16 v[4:7], v[158:161], v[190:193], v[4:7]
	s_barrier
	s_add_u32 s44, s44, 0xc000
	s_addc_u32 s45, s45, 0
	s_add_i32 s41, s68, s54
	v_lshl_add_u64 v[140:141], s[44:45], 0, v[130:131]
	s_mov_b32 m0, s41
	s_nop 0
	global_load_lds_dwordx4 v[140:141], off
	v_lshl_add_u64 v[140:141], s[44:45], 0, v[134:135]
	s_add_i32 m0, s41, 0x2000
	s_nop 0
	global_load_lds_dwordx4 v[140:141], off
	s_waitcnt vmcnt(6)
	s_barrier
	v_mfma_f32_16x16x32_bf16 v[60:63], v[194:197], v[162:165], v[60:63]
	v_mfma_f32_16x16x32_bf16 v[48:51], v[206:209], v[162:165], v[48:51]
	v_mfma_f32_16x16x32_bf16 v[44:47], v[194:197], v[170:173], v[44:47]
	v_mfma_f32_16x16x32_bf16 v[32:35], v[206:209], v[170:173], v[32:35]
	v_mfma_f32_16x16x32_bf16 v[28:31], v[194:197], v[178:181], v[28:31]
	v_mfma_f32_16x16x32_bf16 v[16:19], v[206:209], v[178:181], v[16:19]
	v_mfma_f32_16x16x32_bf16 v[12:15], v[194:197], v[186:189], v[12:15]
	v_mfma_f32_16x16x32_bf16 v[0:3], v[206:209], v[186:189], v[0:3]
	v_mfma_f32_16x16x32_bf16 v[60:63], v[198:201], v[166:169], v[60:63]
	v_mfma_f32_16x16x32_bf16 v[48:51], v[210:213], v[166:169], v[48:51]
	v_mfma_f32_16x16x32_bf16 v[44:47], v[198:201], v[174:177], v[44:47]
	v_mfma_f32_16x16x32_bf16 v[32:35], v[210:213], v[174:177], v[32:35]
	v_mfma_f32_16x16x32_bf16 v[28:31], v[198:201], v[182:185], v[28:31]
	v_mfma_f32_16x16x32_bf16 v[16:19], v[210:213], v[182:185], v[16:19]
	v_mfma_f32_16x16x32_bf16 v[12:15], v[198:201], v[190:193], v[12:15]
	v_mfma_f32_16x16x32_bf16 v[0:3], v[210:213], v[190:193], v[0:3]
	s_add_i32 s35, s35, 2
	s_add_u32 s42, s42, 0x10000
	s_addc_u32 s43, s43, 0
	s_add_u32 s31, s31, 0x10000
	s_addc_u32 s33, s33, 0
	s_cmp_gt_u32 s35, 13
	s_barrier
	s_cbranch_scc0 .LBB0_1242
	s_cmp_lg_u32 s67, 0
	v_lshl_add_u32 v140, s40, 8, v144
	s_cbranch_scc0 .LBB0_1245
; __device__ __forceinline__ unsigned cvt_pk_bf16(float lo, float hi) { f32x2 v = {lo, hi}; bf16x2_t b = __builtin_convertvector(v, bf16x2_t); return __builtin_bit_cast(unsigned, b); }
; __device__ __forceinline__ float gelu_f(float x) { const float u = 1.5957691216f * (x + 0.044715f * x * x * x); return x * sigmoid_f(u); }
;     __device__ __forceinline__ void operator()(const f32x4 (&acc)[2][2][4][2], const Unit& u, int wr, int wc, int fr, int fq) const {
;         const int row0 = u.pm * BM + wr * 64 + fr, col0 = u.pn * BM + wc * 32 + 8 * fq;
;         const int kind = ACT == 0 ? 0 : (u.pn < 4 ? 0 : (u.pn < 12 ? 1 : 2));
; #pragma unroll
;         for (int ai = 0; ai < 2; ++ai)
; #pragma unroll
;             for (int m = 0; m < 4; ++m) {
;                 bf16_t* rowp = O + (size_t)(row0 + ai * HALF + m * 16) * ldo + col0;
; #pragma unroll
;                 for (int bj = 0; bj < 2; ++bj) {
;                     float v[8];
; #pragma unroll
;                     for (int n = 0; n < 2; ++n)
; #pragma unroll
;                         for (int j = 0; j < 4; ++j) { const float a = acc[ai][bj][m][n][j]; v[n * 4 + j] = kind == 1 ? gelu_f(a) : (kind == 2 ? a * 0.0625f : a); }
;                     u32x4 w; w.x = cvt_pk_bf16(v[0], v[1]); w.y = cvt_pk_bf16(v[2], v[3]); w.z = cvt_pk_bf16(v[4], v[5]); w.w = cvt_pk_bf16(v[6], v[7]);
;                     *(u32x4*)(rowp + bj * HALF) = w;
;     __device__ __forceinline__ void operator()(const f32x4 (&acc)[2][2][4][2], const Unit& u, int wr, int wc, int fr, int fq) const {
;     ...
;         else { EpiBf16<0> e{ya + (long)(u.seg == 1) * d1 + (long)(u.seg == 2) * d2, DM}; e(acc, u, wr, wc, fr, fq); }
	s_cmp_eq_u32 s67, 1
	s_cselect_b32 s31, 0x4000000, 0
	s_add_u32 s31, s8, s31
	s_addc_u32 s33, s9, 0
	s_cmp_eq_u32 s67, 2
	s_cselect_b32 s35, 0xac00000, 0
	s_add_u32 s40, s31, s35
	v_lshl_or_b32 v142, s38, 8, v146
	v_ashrrev_i32_e32 v141, 31, v140
	s_addc_u32 s41, s33, 0
	v_ashrrev_i32_e32 v143, 31, v142
	v_lshlrev_b64 v[150:151], 12, v[140:141]
	v_lshl_add_u64 v[150:151], s[40:41], 0, v[150:151]
	v_lshlrev_b64 v[142:143], 1, v[142:143]
	v_lshl_add_u64 v[154:155], v[150:151], 0, v[142:143]
	v_cvt_pk_bf16_f32 v150, v120, v121
	v_cvt_pk_bf16_f32 v151, v122, v123
	v_cvt_pk_bf16_f32 v152, v116, v117
	v_cvt_pk_bf16_f32 v153, v118, v119
	global_store_dwordx4 v[154:155], v[150:153], off
	s_nop 1
	v_cvt_pk_bf16_f32 v150, v124, v125
	v_cvt_pk_bf16_f32 v151, v126, v127
	v_cvt_pk_bf16_f32 v152, v112, v113
	v_cvt_pk_bf16_f32 v153, v114, v115
	global_store_dwordx4 v[154:155], v[150:153], off offset:256
	s_nop 1
	v_or_b32_e32 v150, 16, v140
	v_ashrrev_i32_e32 v151, 31, v150
	v_lshlrev_b64 v[150:151], 12, v[150:151]
	v_lshl_add_u64 v[150:151], s[40:41], 0, v[150:151]
	v_lshl_add_u64 v[156:157], v[150:151], 0, v[142:143]
	v_cvt_pk_bf16_f32 v150, v104, v105
	v_cvt_pk_bf16_f32 v151, v106, v107
	v_cvt_pk_bf16_f32 v152, v100, v101
	v_cvt_pk_bf16_f32 v153, v102, v103
	global_store_dwordx4 v[156:157], v[150:153], off
	s_nop 1
	v_cvt_pk_bf16_f32 v150, v108, v109
	v_cvt_pk_bf16_f32 v151, v110, v111
	v_cvt_pk_bf16_f32 v152, v96, v97
	v_cvt_pk_bf16_f32 v153, v98, v99
	global_store_dwordx4 v[156:157], v[150:153], off offset:256
	s_nop 1
	v_or_b32_e32 v150, 32, v140
	v_ashrrev_i32_e32 v151, 31, v150
	v_lshlrev_b64 v[150:151], 12, v[150:151]
	v_lshl_add_u64 v[150:151], s[40:41], 0, v[150:151]
	v_lshl_add_u64 v[156:157], v[150:151], 0, v[142:143]
	v_cvt_pk_bf16_f32 v150, v88, v89
	v_cvt_pk_bf16_f32 v151, v90, v91
	v_cvt_pk_bf16_f32 v152, v84, v85
	v_cvt_pk_bf16_f32 v153, v86, v87
	global_store_dwordx4 v[156:157], v[150:153], off
	s_nop 1
	v_cvt_pk_bf16_f32 v150, v92, v93
	v_cvt_pk_bf16_f32 v151, v94, v95
	v_cvt_pk_bf16_f32 v152, v80, v81
	v_cvt_pk_bf16_f32 v153, v82, v83
	global_store_dwordx4 v[156:157], v[150:153], off offset:256
	v_add_co_u32_e32 v156, vcc, s62, v154
	s_nop 0
	v_or_b32_e32 v150, 48, v140
	v_ashrrev_i32_e32 v151, 31, v150
	v_lshlrev_b64 v[150:151], 12, v[150:151]
	v_lshl_add_u64 v[150:151], s[40:41], 0, v[150:151]
	v_lshl_add_u64 v[142:143], v[150:151], 0, v[142:143]
	v_cvt_pk_bf16_f32 v150, v72, v73
	v_cvt_pk_bf16_f32 v151, v74, v75
	v_cvt_pk_bf16_f32 v152, v68, v69
	v_cvt_pk_bf16_f32 v153, v70, v71
	global_store_dwordx4 v[142:143], v[150:153], off
	v_addc_co_u32_e32 v157, vcc, 0, v155, vcc
	s_nop 0
	v_cvt_pk_bf16_f32 v150, v76, v77
	v_cvt_pk_bf16_f32 v151, v78, v79
	v_cvt_pk_bf16_f32 v152, v64, v65
	v_cvt_pk_bf16_f32 v153, v66, v67
	global_store_dwordx4 v[142:143], v[150:153], off offset:256
	v_lshl_add_u64 v[142:143], v[154:155], 0, s[10:11]
	s_nop 0
	v_cvt_pk_bf16_f32 v150, v56, v57
	v_cvt_pk_bf16_f32 v151, v58, v59
	v_cvt_pk_bf16_f32 v152, v52, v53
	v_cvt_pk_bf16_f32 v153, v54, v55
	global_store_dwordx4 v[156:157], v[150:153], off
	v_add_co_u32_e32 v156, vcc, s63, v154
	s_nop 0
	v_cvt_pk_bf16_f32 v150, v60, v61
	v_cvt_pk_bf16_f32 v151, v62, v63
	v_cvt_pk_bf16_f32 v152, v48, v49
	v_cvt_pk_bf16_f32 v153, v50, v51
	global_store_dwordx4 v[142:143], v[150:153], off offset:256
	v_addc_co_u32_e32 v157, vcc, 0, v155, vcc
	s_nop 0
	v_cvt_pk_bf16_f32 v150, v40, v41
	v_cvt_pk_bf16_f32 v151, v42, v43
	v_cvt_pk_bf16_f32 v152, v36, v37
	v_cvt_pk_bf16_f32 v153, v38, v39
	v_lshl_add_u64 v[142:143], v[154:155], 0, s[12:13]
	global_store_dwordx4 v[156:157], v[150:153], off
	v_add_co_u32_e32 v156, vcc, s64, v154
	s_nop 0
	v_cvt_pk_bf16_f32 v150, v44, v45
	v_cvt_pk_bf16_f32 v151, v46, v47
	v_cvt_pk_bf16_f32 v152, v32, v33
	v_cvt_pk_bf16_f32 v153, v34, v35
	global_store_dwordx4 v[142:143], v[150:153], off offset:256
	v_addc_co_u32_e32 v157, vcc, 0, v155, vcc
	s_nop 0
	v_cvt_pk_bf16_f32 v150, v24, v25
	v_cvt_pk_bf16_f32 v151, v26, v27
	v_cvt_pk_bf16_f32 v152, v20, v21
	v_cvt_pk_bf16_f32 v153, v22, v23
	v_lshl_add_u64 v[142:143], v[154:155], 0, s[14:15]
	global_store_dwordx4 v[156:157], v[150:153], off
	s_nop 1
	v_cvt_pk_bf16_f32 v150, v28, v29
	v_cvt_pk_bf16_f32 v151, v30, v31
	v_cvt_pk_bf16_f32 v152, v16, v17
	v_cvt_pk_bf16_f32 v153, v18, v19
	global_store_dwordx4 v[142:143], v[150:153], off offset:256
	v_lshl_add_u64 v[142:143], v[154:155], 0, s[16:17]
	v_add_co_u32_e32 v154, vcc, s65, v154
	v_cvt_pk_bf16_f32 v150, v8, v9
	v_cvt_pk_bf16_f32 v151, v10, v11
	v_cvt_pk_bf16_f32 v152, v4, v5
	v_cvt_pk_bf16_f32 v153, v6, v7
	v_addc_co_u32_e32 v155, vcc, 0, v155, vcc
	global_store_dwordx4 v[154:155], v[150:153], off
	s_nop 1
	v_cvt_pk_bf16_f32 v150, v12, v13
	v_cvt_pk_bf16_f32 v151, v14, v15
	v_cvt_pk_bf16_f32 v152, v0, v1
	v_cvt_pk_bf16_f32 v153, v2, v3
	global_store_dwordx4 v[142:143], v[150:153], off offset:256
	s_cbranch_execnz .LBB0_1223
	s_branch .LBB0_1246

; #define PG8_STAGE(bufoff, gbase, voff) do { _Pragma("unroll") for (int _i = 0; _i < 2; ++_i) \
;         __builtin_amdgcn_global_load_lds((const unsigned*)((const char*)(gbase) + (voff)[_i]), (LAS unsigned*)(lds + (bufoff) + ldsw + _i * 8192), 16, 0, 0); } while (0)
; #define PG8_LDA(dst, b, h) do { _Pragma("unroll") for (int m = 0; m < 4; ++m) _Pragma("unroll") for (int k = 0; k < 2; ++k) dst[m][k] = *(const LAS bf16x8*)(lds + PG8_SA(b, h) + aoff + m * 2048 + k * 1024); } while (0)
; #define PG8_WAIT_V(n) asm volatile("s_waitcnt vmcnt(" #n ")" ::: "memory")
; #define PG8_WAIT_L(n) asm volatile("s_waitcnt lgkmcnt(" #n ")" ::: "memory")
; template <class Epi, class Sched>
; __device__ __forceinline__ void gemm_phase(LAS unsigned char* lds, const Gemm g, const Sched& S, const Epi& E) {
;     ...
;         for (int t = 0; t < nt; t += 2) {
;             const bool last = (t == nt - 2);
;             const char* a1 = cA + (size_t)(t + 1) * kstep;
;             const char* a2 = last ? nA : cA + (size_t)(t + 2) * kstep; const char* b2 = last ? nB : cB + (size_t)(t + 2) * kstep;
;             const char* a3 = a2 + kstep; const char* b3 = b2 + kstep;
;             PG8_LDB(B0, 0, 0); PG8_SCHED; PG8_LDA(At, 0, 0); PG8_STAGE(PG8_SA(1, 1), a1 + hstep, voffA);
;             PG8_WAIT_L(8); PG8_BAR; PG8_WAIT_L(0); PG8_MMA(0, 0, At, B0); PG8_BAR; PG8_SCHED;
;             PG8_LDB(B1, 0, 1); PG8_STAGE(PG8_SB(0, 0), b2, voffB);
;             PG8_BAR; PG8_WAIT_L(0); PG8_MMA(0, 1, At, B1); PG8_BAR;
;             PG8_LDA(At, 0, 1); PG8_STAGE(PG8_SA(0, 0), a2, voffA);
;             PG8_BAR; PG8_WAIT_L(0); PG8_MMA(1, 0, At, B0); PG8_BAR; PG8_SCHED;
;             PG8_STAGE(PG8_SB(0, 1), b2 + hstep, voffB);
;             PG8_WAIT_V(6); PG8_BAR; PG8_MMA(1, 1, At, B1); PG8_BAR;
;             PG8_LDB(B0, 1, 0); PG8_SCHED; PG8_LDA(At, 1, 0); PG8_STAGE(PG8_SA(0, 1), a2 + hstep, voffA);
;             PG8_WAIT_L(8); PG8_BAR; PG8_WAIT_L(0); PG8_MMA(0, 0, At, B0); PG8_BAR; PG8_SCHED;
;             PG8_LDB(B1, 1, 1); PG8_STAGE(PG8_SB(1, 0), b3, voffB);
;             PG8_BAR; PG8_WAIT_L(0); PG8_MMA(0, 1, At, B1); PG8_BAR;
;             PG8_LDA(At, 1, 1); PG8_STAGE(PG8_SA(1, 0), a3, voffA);
;             PG8_BAR; PG8_WAIT_L(0); PG8_MMA(1, 0, At, B0); PG8_BAR; PG8_SCHED;
;             PG8_STAGE(PG8_SB(1, 1), b3 + hstep, voffB);
;             PG8_WAIT_V(6); PG8_BAR; PG8_MMA(1, 1, At, B1); PG8_BAR;
.LBB0_1322:
	ds_read_b128 v[128:131], v189
	ds_read_b128 v[132:135], v189 offset:1024
	ds_read_b128 v[136:139], v189 offset:2048
	ds_read_b128 v[140:143], v189 offset:3072
	s_add_u32 s36, s34, 0x4000
	s_addc_u32 s37, s35, 0
	s_cmp_eq_u32 s61, 28
	s_cselect_b32 s40, s17, s36
	s_cselect_b32 s41, s9, s37
	s_cselect_b32 s36, s33, s59
	s_cselect_b32 s37, s19, s60
	s_add_u32 s38, s40, 0x8000
	s_addc_u32 s39, s41, 0
	v_lshl_add_u64 v[196:197], s[34:35], 0, v[170:171]
	s_add_i32 m0, s47, 0xc000
	ds_read_b128 v[144:147], v190
	ds_read_b128 v[148:151], v190 offset:1024
	ds_read_b128 v[152:155], v190 offset:2048
	ds_read_b128 v[156:159], v190 offset:3072
	ds_read_b128 v[174:177], v190 offset:4096
	ds_read_b128 v[178:181], v190 offset:5120
	ds_read_b128 v[182:185], v190 offset:6144
	ds_read_b128 v[192:195], v190 offset:7168
	global_load_lds_dwordx4 v[196:197], off
	v_lshl_add_u64 v[196:197], s[34:35], 0, v[172:173]
	s_add_i32 m0, s47, 0xe000
	s_nop 0
	global_load_lds_dwordx4 v[196:197], off
	s_waitcnt lgkmcnt(8)
	s_barrier
	s_waitcnt lgkmcnt(0)
	v_mfma_f32_16x16x32_bf16 v[124:127], v[128:131], v[144:147], v[124:127]
	v_mfma_f32_16x16x32_bf16 v[120:123], v[136:139], v[144:147], v[120:123]
	v_mfma_f32_16x16x32_bf16 v[108:111], v[128:131], v[152:155], v[108:111]
	v_mfma_f32_16x16x32_bf16 v[104:107], v[136:139], v[152:155], v[104:107]
	v_mfma_f32_16x16x32_bf16 v[92:95], v[128:131], v[174:177], v[92:95]
	v_mfma_f32_16x16x32_bf16 v[88:91], v[136:139], v[174:177], v[88:91]
	v_mfma_f32_16x16x32_bf16 v[76:79], v[128:131], v[182:185], v[76:79]
	v_mfma_f32_16x16x32_bf16 v[72:75], v[136:139], v[182:185], v[72:75]
	v_mfma_f32_16x16x32_bf16 v[124:127], v[132:135], v[148:151], v[124:127]
	v_mfma_f32_16x16x32_bf16 v[120:123], v[140:143], v[148:151], v[120:123]
	v_mfma_f32_16x16x32_bf16 v[108:111], v[132:135], v[156:159], v[108:111]
	v_mfma_f32_16x16x32_bf16 v[104:107], v[140:143], v[156:159], v[104:107]
	v_mfma_f32_16x16x32_bf16 v[92:95], v[132:135], v[178:181], v[92:95]
	v_mfma_f32_16x16x32_bf16 v[88:91], v[140:143], v[178:181], v[88:91]
	v_mfma_f32_16x16x32_bf16 v[76:79], v[132:135], v[192:195], v[76:79]
	v_mfma_f32_16x16x32_bf16 v[72:75], v[140:143], v[192:195], v[72:75]
	s_barrier
	s_add_i32 s62, s71, s46
	v_lshl_add_u64 v[214:215], s[36:37], 0, v[162:163]
	s_mov_b32 m0, s62
	ds_read_b128 v[196:199], v191
	ds_read_b128 v[200:203], v191 offset:1024
	ds_read_b128 v[206:209], v191 offset:2048
	ds_read_b128 v[210:213], v191 offset:3072
	global_load_lds_dwordx4 v[214:215], off
	v_lshl_add_u64 v[214:215], s[36:37], 0, v[166:167]
	s_add_i32 m0, s62, 0x2000
	s_nop 0
	global_load_lds_dwordx4 v[214:215], off
	s_barrier
	s_waitcnt lgkmcnt(0)
	v_mfma_f32_16x16x32_bf16 v[116:119], v[196:199], v[144:147], v[116:119]
	v_mfma_f32_16x16x32_bf16 v[112:115], v[206:209], v[144:147], v[112:115]
	v_mfma_f32_16x16x32_bf16 v[100:103], v[196:199], v[152:155], v[100:103]
	v_mfma_f32_16x16x32_bf16 v[96:99], v[206:209], v[152:155], v[96:99]
	v_mfma_f32_16x16x32_bf16 v[84:87], v[196:199], v[174:177], v[84:87]
	v_mfma_f32_16x16x32_bf16 v[80:83], v[206:209], v[174:177], v[80:83]
	v_mfma_f32_16x16x32_bf16 v[68:71], v[196:199], v[182:185], v[68:71]
	v_mfma_f32_16x16x32_bf16 v[64:67], v[206:209], v[182:185], v[64:67]
	v_mfma_f32_16x16x32_bf16 v[116:119], v[200:203], v[148:151], v[116:119]
	v_mfma_f32_16x16x32_bf16 v[112:115], v[210:213], v[148:151], v[112:115]
	v_mfma_f32_16x16x32_bf16 v[100:103], v[200:203], v[156:159], v[100:103]
	v_mfma_f32_16x16x32_bf16 v[96:99], v[210:213], v[156:159], v[96:99]
	v_mfma_f32_16x16x32_bf16 v[84:87], v[200:203], v[178:181], v[84:87]
	v_mfma_f32_16x16x32_bf16 v[80:83], v[210:213], v[178:181], v[80:83]
	v_mfma_f32_16x16x32_bf16 v[68:71], v[200:203], v[192:195], v[68:71]
	v_mfma_f32_16x16x32_bf16 v[64:67], v[210:213], v[192:195], v[64:67]
	s_mov_b32 m0, s47
	v_lshl_add_u64 v[214:215], s[40:41], 0, v[160:161]
	s_barrier
	ds_read_b128 v[144:147], v190 offset:16384
	ds_read_b128 v[148:151], v190 offset:17408
	ds_read_b128 v[152:155], v190 offset:18432
	ds_read_b128 v[156:159], v190 offset:19456
	ds_read_b128 v[174:177], v190 offset:20480
	ds_read_b128 v[178:181], v190 offset:21504
	ds_read_b128 v[182:185], v190 offset:22528
	ds_read_b128 v[192:195], v190 offset:23552
	global_load_lds_dwordx4 v[214:215], off
	v_lshl_add_u64 v[214:215], s[40:41], 0, v[164:165]
	s_mov_b32 m0, s48
	s_nop 0
	global_load_lds_dwordx4 v[214:215], off
	s_barrier
	s_waitcnt lgkmcnt(0)
	v_mfma_f32_16x16x32_bf16 v[60:63], v[128:131], v[144:147], v[60:63]
	v_mfma_f32_16x16x32_bf16 v[56:59], v[136:139], v[144:147], v[56:59]
	v_mfma_f32_16x16x32_bf16 v[44:47], v[128:131], v[152:155], v[44:47]
	v_mfma_f32_16x16x32_bf16 v[40:43], v[136:139], v[152:155], v[40:43]
	v_mfma_f32_16x16x32_bf16 v[28:31], v[128:131], v[174:177], v[28:31]
	v_mfma_f32_16x16x32_bf16 v[24:27], v[136:139], v[174:177], v[24:27]
	v_mfma_f32_16x16x32_bf16 v[12:15], v[128:131], v[182:185], v[12:15]
	v_mfma_f32_16x16x32_bf16 v[8:11], v[136:139], v[182:185], v[8:11]
	v_mfma_f32_16x16x32_bf16 v[60:63], v[132:135], v[148:151], v[60:63]
	v_mfma_f32_16x16x32_bf16 v[56:59], v[140:143], v[148:151], v[56:59]
	v_mfma_f32_16x16x32_bf16 v[44:47], v[132:135], v[156:159], v[44:47]
	v_mfma_f32_16x16x32_bf16 v[40:43], v[140:143], v[156:159], v[40:43]
	v_mfma_f32_16x16x32_bf16 v[28:31], v[132:135], v[178:181], v[28:31]
	v_mfma_f32_16x16x32_bf16 v[24:27], v[140:143], v[178:181], v[24:27]
	v_mfma_f32_16x16x32_bf16 v[12:15], v[132:135], v[192:195], v[12:15]
	v_mfma_f32_16x16x32_bf16 v[8:11], v[140:143], v[192:195], v[8:11]
	s_barrier
; #define PG8_STAGE(bufoff, gbase, voff) do { _Pragma("unroll") for (int _i = 0; _i < 2; ++_i) \
;         __builtin_amdgcn_global_load_lds((const unsigned*)((const char*)(gbase) + (voff)[_i]), (LAS unsigned*)(lds + (bufoff) + ldsw + _i * 8192), 16, 0, 0); } while (0)
; #define PG8_LDA(dst, b, h) do { _Pragma("unroll") for (int m = 0; m < 4; ++m) _Pragma("unroll") for (int k = 0; k < 2; ++k) dst[m][k] = *(const LAS bf16x8*)(lds + PG8_SA(b, h) + aoff + m * 2048 + k * 1024); } while (0)
; #define PG8_WAIT_V(n) asm volatile("s_waitcnt vmcnt(" #n ")" ::: "memory")
; #define PG8_WAIT_L(n) asm volatile("s_waitcnt lgkmcnt(" #n ")" ::: "memory")
; template <class Epi, class Sched>
; __device__ __forceinline__ void gemm_phase(LAS unsigned char* lds, const Gemm g, const Sched& S, const Epi& E) {
;     ...
;         for (int t = 0; t < nt; t += 2) {
;             const bool last = (t == nt - 2);
;             const char* a1 = cA + (size_t)(t + 1) * kstep;
;             const char* a2 = last ? nA : cA + (size_t)(t + 2) * kstep; const char* b2 = last ? nB : cB + (size_t)(t + 2) * kstep;
;             const char* a3 = a2 + kstep; const char* b3 = b2 + kstep;
;             PG8_LDB(B0, 0, 0); PG8_SCHED; PG8_LDA(At, 0, 0); PG8_STAGE(PG8_SA(1, 1), a1 + hstep, voffA);
;             PG8_WAIT_L(8); PG8_BAR; PG8_WAIT_L(0); PG8_MMA(0, 0, At, B0); PG8_BAR; PG8_SCHED;
;             PG8_LDB(B1, 0, 1); PG8_STAGE(PG8_SB(0, 0), b2, voffB);
;             PG8_BAR; PG8_WAIT_L(0); PG8_MMA(0, 1, At, B1); PG8_BAR;
;             PG8_LDA(At, 0, 1); PG8_STAGE(PG8_SA(0, 0), a2, voffA);
;             PG8_BAR; PG8_WAIT_L(0); PG8_MMA(1, 0, At, B0); PG8_BAR; PG8_SCHED;
;             PG8_STAGE(PG8_SB(0, 1), b2 + hstep, voffB);
;             PG8_WAIT_V(6); PG8_BAR; PG8_MMA(1, 1, At, B1); PG8_BAR;
;             PG8_LDB(B0, 1, 0); PG8_SCHED; PG8_LDA(At, 1, 0); PG8_STAGE(PG8_SA(0, 1), a2 + hstep, voffA);
;             PG8_WAIT_L(8); PG8_BAR; PG8_WAIT_L(0); PG8_MMA(0, 0, At, B0); PG8_BAR; PG8_SCHED;
;             PG8_LDB(B1, 1, 1); PG8_STAGE(PG8_SB(1, 0), b3, voffB);
;             PG8_BAR; PG8_WAIT_L(0); PG8_MMA(0, 1, At, B1); PG8_BAR;
;             PG8_LDA(At, 1, 1); PG8_STAGE(PG8_SA(1, 0), a3, voffA);
;             PG8_BAR; PG8_WAIT_L(0); PG8_MMA(1, 0, At, B0); PG8_BAR; PG8_SCHED;
;             PG8_STAGE(PG8_SB(1, 1), b3 + hstep, voffB);
;             PG8_WAIT_V(6); PG8_BAR; PG8_MMA(1, 1, At, B1); PG8_BAR;
	s_add_u32 s62, s36, 0x4000
	s_addc_u32 s63, s37, 0
	s_add_i32 s64, s57, s46
	v_lshl_add_u64 v[128:129], s[62:63], 0, v[162:163]
	s_mov_b32 m0, s64
	s_nop 0
	global_load_lds_dwordx4 v[128:129], off
	v_lshl_add_u64 v[128:129], s[62:63], 0, v[166:167]
	s_add_i32 m0, s64, 0x2000
	s_nop 0
	global_load_lds_dwordx4 v[128:129], off
	s_waitcnt vmcnt(6)
	s_barrier
	v_mfma_f32_16x16x32_bf16 v[52:55], v[196:199], v[144:147], v[52:55]
	v_mfma_f32_16x16x32_bf16 v[48:51], v[206:209], v[144:147], v[48:51]
	v_mfma_f32_16x16x32_bf16 v[36:39], v[196:199], v[152:155], v[36:39]
	v_mfma_f32_16x16x32_bf16 v[32:35], v[206:209], v[152:155], v[32:35]
	v_mfma_f32_16x16x32_bf16 v[20:23], v[196:199], v[174:177], v[20:23]
	v_mfma_f32_16x16x32_bf16 v[16:19], v[206:209], v[174:177], v[16:19]
	v_mfma_f32_16x16x32_bf16 v[4:7], v[196:199], v[182:185], v[4:7]
	v_mfma_f32_16x16x32_bf16 v[0:3], v[206:209], v[182:185], v[0:3]
	v_mfma_f32_16x16x32_bf16 v[52:55], v[200:203], v[148:151], v[52:55]
	v_mfma_f32_16x16x32_bf16 v[48:51], v[210:213], v[148:151], v[48:51]
	v_mfma_f32_16x16x32_bf16 v[36:39], v[200:203], v[156:159], v[36:39]
	v_mfma_f32_16x16x32_bf16 v[32:35], v[210:213], v[156:159], v[32:35]
	v_mfma_f32_16x16x32_bf16 v[20:23], v[200:203], v[178:181], v[20:23]
	v_mfma_f32_16x16x32_bf16 v[16:19], v[210:213], v[178:181], v[16:19]
	v_mfma_f32_16x16x32_bf16 v[4:7], v[200:203], v[192:195], v[4:7]
	v_mfma_f32_16x16x32_bf16 v[0:3], v[210:213], v[192:195], v[0:3]
	s_add_i32 s62, 0, 0x18000
	v_add_u32_e32 v140, s62, v188
	s_barrier
	ds_read_b128 v[128:131], v140
	ds_read_b128 v[132:135], v140 offset:1024
	ds_read_b128 v[136:139], v140 offset:2048
	ds_read_b128 v[140:143], v140 offset:3072
	s_add_u32 s40, s40, 0x4000
	s_addc_u32 s41, s41, 0
	s_mov_b32 m0, s49
	v_lshl_add_u64 v[196:197], s[40:41], 0, v[160:161]
	ds_read_b128 v[144:147], v190 offset:32768
	ds_read_b128 v[148:151], v190 offset:33792
	ds_read_b128 v[152:155], v190 offset:34816
	ds_read_b128 v[156:159], v190 offset:35840
	ds_read_b128 v[174:177], v190 offset:36864
	ds_read_b128 v[178:181], v190 offset:37888
	ds_read_b128 v[182:185], v190 offset:38912
	ds_read_b128 v[192:195], v190 offset:39936
	global_load_lds_dwordx4 v[196:197], off
	v_lshl_add_u64 v[196:197], s[40:41], 0, v[164:165]
	s_mov_b32 m0, s50
	s_nop 0
	global_load_lds_dwordx4 v[196:197], off
	s_waitcnt lgkmcnt(8)
	s_barrier
	s_waitcnt lgkmcnt(0)
	v_mfma_f32_16x16x32_bf16 v[124:127], v[128:131], v[144:147], v[124:127]
	v_mfma_f32_16x16x32_bf16 v[120:123], v[136:139], v[144:147], v[120:123]
	v_mfma_f32_16x16x32_bf16 v[108:111], v[128:131], v[152:155], v[108:111]
	v_mfma_f32_16x16x32_bf16 v[104:107], v[136:139], v[152:155], v[104:107]
	v_mfma_f32_16x16x32_bf16 v[92:95], v[128:131], v[174:177], v[92:95]
	v_mfma_f32_16x16x32_bf16 v[88:91], v[136:139], v[174:177], v[88:91]
	v_mfma_f32_16x16x32_bf16 v[76:79], v[128:131], v[182:185], v[76:79]
	v_mfma_f32_16x16x32_bf16 v[72:75], v[136:139], v[182:185], v[72:75]
	v_mfma_f32_16x16x32_bf16 v[124:127], v[132:135], v[148:151], v[124:127]
	v_mfma_f32_16x16x32_bf16 v[120:123], v[140:143], v[148:151], v[120:123]
	v_mfma_f32_16x16x32_bf16 v[108:111], v[132:135], v[156:159], v[108:111]
	v_mfma_f32_16x16x32_bf16 v[104:107], v[140:143], v[156:159], v[104:107]
	v_mfma_f32_16x16x32_bf16 v[92:95], v[132:135], v[178:181], v[92:95]
	v_mfma_f32_16x16x32_bf16 v[88:91], v[140:143], v[178:181], v[88:91]
	v_mfma_f32_16x16x32_bf16 v[76:79], v[132:135], v[192:195], v[76:79]
	v_mfma_f32_16x16x32_bf16 v[72:75], v[140:143], v[192:195], v[72:75]
	s_barrier
	s_add_i32 s63, 0, 0x1c000
	s_add_u32 s40, s36, 0x8000
	s_addc_u32 s41, s37, 0
	s_add_i32 s62, s62, s46
	v_add_u32_e32 v168, s63, v188
	v_lshl_add_u64 v[214:215], s[40:41], 0, v[162:163]
	s_mov_b32 m0, s62
	ds_read_b128 v[196:199], v168
	ds_read_b128 v[200:203], v168 offset:1024
	ds_read_b128 v[206:209], v168 offset:2048
	ds_read_b128 v[210:213], v168 offset:3072
	global_load_lds_dwordx4 v[214:215], off
	v_lshl_add_u64 v[214:215], s[40:41], 0, v[166:167]
	s_add_i32 m0, s62, 0x2000
	s_nop 0
	global_load_lds_dwordx4 v[214:215], off
	s_barrier
	s_waitcnt lgkmcnt(0)
	v_mfma_f32_16x16x32_bf16 v[116:119], v[196:199], v[144:147], v[116:119]
	v_mfma_f32_16x16x32_bf16 v[112:115], v[206:209], v[144:147], v[112:115]
	v_mfma_f32_16x16x32_bf16 v[100:103], v[196:199], v[152:155], v[100:103]
	v_mfma_f32_16x16x32_bf16 v[96:99], v[206:209], v[152:155], v[96:99]
	v_mfma_f32_16x16x32_bf16 v[84:87], v[196:199], v[174:177], v[84:87]
	v_mfma_f32_16x16x32_bf16 v[80:83], v[206:209], v[174:177], v[80:83]
	v_mfma_f32_16x16x32_bf16 v[68:71], v[196:199], v[182:185], v[68:71]
	v_mfma_f32_16x16x32_bf16 v[64:67], v[206:209], v[182:185], v[64:67]
	v_mfma_f32_16x16x32_bf16 v[116:119], v[200:203], v[148:151], v[116:119]
	v_mfma_f32_16x16x32_bf16 v[112:115], v[210:213], v[148:151], v[112:115]
	v_mfma_f32_16x16x32_bf16 v[100:103], v[200:203], v[156:159], v[100:103]
	v_mfma_f32_16x16x32_bf16 v[96:99], v[210:213], v[156:159], v[96:99]
	v_mfma_f32_16x16x32_bf16 v[84:87], v[200:203], v[178:181], v[84:87]
	v_mfma_f32_16x16x32_bf16 v[80:83], v[210:213], v[178:181], v[80:83]
	v_mfma_f32_16x16x32_bf16 v[68:71], v[200:203], v[192:195], v[68:71]
	v_mfma_f32_16x16x32_bf16 v[64:67], v[210:213], v[192:195], v[64:67]
	s_mov_b32 m0, s55
	v_lshl_add_u64 v[214:215], s[38:39], 0, v[160:161]
	s_barrier
	ds_read_b128 v[144:147], v190 offset:49152
	ds_read_b128 v[148:151], v190 offset:50176
	ds_read_b128 v[152:155], v190 offset:51200
	ds_read_b128 v[156:159], v190 offset:52224
	ds_read_b128 v[174:177], v190 offset:53248
	ds_read_b128 v[178:181], v190 offset:54272
	ds_read_b128 v[182:185], v190 offset:55296
	ds_read_b128 v[192:195], v190 offset:56320
	global_load_lds_dwordx4 v[214:215], off
	v_lshl_add_u64 v[214:215], s[38:39], 0, v[164:165]
	s_mov_b32 m0, s56
	s_nop 0
	global_load_lds_dwordx4 v[214:215], off
	s_barrier
; #define PG8_BAR __builtin_amdgcn_s_barrier()
; template <class Epi, class Sched>
; __device__ __forceinline__ void gemm_phase(LAS unsigned char* lds, const Gemm g, const Sched& S, const Epi& E) {
;     ...
;             PG8_WAIT_L(8); PG8_BAR; PG8_WAIT_L(0); PG8_MMA(0, 0, At, B0); PG8_BAR; PG8_SCHED;
;             PG8_LDB(B1, 1, 1); PG8_STAGE(PG8_SB(1, 0), b3, voffB);
;             PG8_BAR; PG8_WAIT_L(0); PG8_MMA(0, 1, At, B1); PG8_BAR;
;             PG8_LDA(At, 1, 1); PG8_STAGE(PG8_SA(1, 0), a3, voffA);
;             PG8_BAR; PG8_WAIT_L(0); PG8_MMA(1, 0, At, B0); PG8_BAR; PG8_SCHED;
;             PG8_STAGE(PG8_SB(1, 1), b3 + hstep, voffB);
;             PG8_WAIT_V(6); PG8_BAR; PG8_MMA(1, 1, At, B1); PG8_BAR;
;     __device__ __forceinline__ void operator()(const f32x4 (&acc)[2][2][4][2], const Unit& u, int wr, int wc, int fr, int fq) const {
;         const int br = u.pn >> 3, pn8 = u.pn & 7;
;         const bf16_t* y = y0 + (long)(br == 1) * d1 + (long)(br == 2) * d2;
;         const int row0 = u.pm * BM + wr * 64 + fr, col0 = pn8 * BM + wc * 32 + 8 * fq;
; #pragma unroll
;         for (int ai = 0; ai < 2; ++ai)
; #pragma unroll
;             for (int mh = 0; mh < 2; ++mh) {
;                 u32x4 yw[2][2], mw[2][2];
; #pragma unroll
;                 for (int mm = 0; mm < 2; ++mm) {
;                     const int rr = row0 + ai * HALF + (mh * 2 + mm) * 16;
;                     const size_t off = (size_t)rr * DM + col0;
; #pragma unroll
;                     for (int bj = 0; bj < 2; ++bj) {
;                         yw[mm][bj] = *(const u32x4*)(y + off + bj * HALF);
;                         mw[mm][bj] = (u32x4){0u, 0u, 0u, 0u};
;                         if (br != 0) mw[mm][bj] = *(const u32x4*)(merged + tl(rr, col0 + bj * HALF, DM));
;                     }
;                 }
; #pragma unroll
;                 for (int mm = 0; mm < 2; ++mm) {
;                     const int m = mh * 2 + mm;
;                     const int rr = row0 + ai * HALF + m * 16;
; #pragma unroll
;                     for (int bj = 0; bj < 2; ++bj) {
;                         const f32x4 a0 = acc[ai][bj][m][0], a1 = acc[ai][bj][m][1];
;                         const u32x4 yv = yw[mm][bj], mv = mw[mm][bj];
;                         u32x4 w;
;                         w.x = cvt_pk_bf16(sigmoid_f(a0[0]) * bflo(yv.x) + bflo(mv.x), sigmoid_f(a0[1]) * bfhi(yv.x) + bfhi(mv.x));
	s_waitcnt lgkmcnt(0)
	v_mfma_f32_16x16x32_bf16 v[60:63], v[128:131], v[144:147], v[60:63]
	v_mfma_f32_16x16x32_bf16 v[56:59], v[136:139], v[144:147], v[56:59]
	v_mfma_f32_16x16x32_bf16 v[44:47], v[128:131], v[152:155], v[44:47]
	v_mfma_f32_16x16x32_bf16 v[40:43], v[136:139], v[152:155], v[40:43]
	v_mfma_f32_16x16x32_bf16 v[28:31], v[128:131], v[174:177], v[28:31]
	v_mfma_f32_16x16x32_bf16 v[24:27], v[136:139], v[174:177], v[24:27]
	v_mfma_f32_16x16x32_bf16 v[12:15], v[128:131], v[182:185], v[12:15]
	v_mfma_f32_16x16x32_bf16 v[8:11], v[136:139], v[182:185], v[8:11]
	v_mfma_f32_16x16x32_bf16 v[60:63], v[132:135], v[148:151], v[60:63]
	v_mfma_f32_16x16x32_bf16 v[56:59], v[140:143], v[148:151], v[56:59]
	v_mfma_f32_16x16x32_bf16 v[44:47], v[132:135], v[156:159], v[44:47]
	v_mfma_f32_16x16x32_bf16 v[40:43], v[140:143], v[156:159], v[40:43]
	v_mfma_f32_16x16x32_bf16 v[28:31], v[132:135], v[178:181], v[28:31]
	v_mfma_f32_16x16x32_bf16 v[24:27], v[140:143], v[178:181], v[24:27]
	v_mfma_f32_16x16x32_bf16 v[12:15], v[132:135], v[192:195], v[12:15]
	v_mfma_f32_16x16x32_bf16 v[8:11], v[140:143], v[192:195], v[8:11]
	s_barrier
	s_add_u32 s36, s36, 0xc000
	s_addc_u32 s37, s37, 0
	s_add_i32 s38, s63, s46
	v_lshl_add_u64 v[128:129], s[36:37], 0, v[162:163]
	s_mov_b32 m0, s38
	s_nop 0
	global_load_lds_dwordx4 v[128:129], off
	v_lshl_add_u64 v[128:129], s[36:37], 0, v[166:167]
	s_add_i32 m0, s38, 0x2000
	s_nop 0
	global_load_lds_dwordx4 v[128:129], off
	s_waitcnt vmcnt(6)
	s_barrier
	v_mfma_f32_16x16x32_bf16 v[52:55], v[196:199], v[144:147], v[52:55]
	v_mfma_f32_16x16x32_bf16 v[48:51], v[206:209], v[144:147], v[48:51]
	v_mfma_f32_16x16x32_bf16 v[36:39], v[196:199], v[152:155], v[36:39]
	v_mfma_f32_16x16x32_bf16 v[32:35], v[206:209], v[152:155], v[32:35]
	v_mfma_f32_16x16x32_bf16 v[20:23], v[196:199], v[174:177], v[20:23]
	v_mfma_f32_16x16x32_bf16 v[16:19], v[206:209], v[174:177], v[16:19]
	v_mfma_f32_16x16x32_bf16 v[4:7], v[196:199], v[182:185], v[4:7]
	v_mfma_f32_16x16x32_bf16 v[0:3], v[206:209], v[182:185], v[0:3]
	v_mfma_f32_16x16x32_bf16 v[52:55], v[200:203], v[148:151], v[52:55]
	v_mfma_f32_16x16x32_bf16 v[48:51], v[210:213], v[148:151], v[48:51]
	v_mfma_f32_16x16x32_bf16 v[36:39], v[200:203], v[156:159], v[36:39]
	v_mfma_f32_16x16x32_bf16 v[32:35], v[210:213], v[156:159], v[32:35]
	v_mfma_f32_16x16x32_bf16 v[20:23], v[200:203], v[178:181], v[20:23]
	v_mfma_f32_16x16x32_bf16 v[16:19], v[210:213], v[178:181], v[16:19]
	v_mfma_f32_16x16x32_bf16 v[4:7], v[200:203], v[192:195], v[4:7]
	v_mfma_f32_16x16x32_bf16 v[0:3], v[210:213], v[192:195], v[0:3]
	s_add_i32 s61, s61, 2
	s_add_u32 s34, s34, 0x10000
	s_addc_u32 s35, s35, 0
	s_add_u32 s59, s59, 0x10000
	s_addc_u32 s60, s60, 0
	s_cmp_gt_u32 s61, 29
	s_barrier
	s_cbranch_scc0 .LBB0_1322
	s_nop 7
	s_ashr_i32 s9, s8, 3
	s_cmp_eq_u32 s9, 1
	s_cselect_b32 s17, 0x4000000, 0
	s_add_u32 s17, s51, s17
	s_addc_u32 s19, s52, 0
	s_cmp_eq_u32 s9, 2
	s_cselect_b32 s38, 0xac00000, 0
	s_add_u32 s34, s17, s38
	s_addc_u32 s35, s19, 0
	s_lshl_b32 s36, s10, 8
	s_add_i32 s36, s36, s53
	s_lshl_b32 s37, s8, 8
	s_and_b32 s37, s37, 0x700
	s_or_b32 s37, s37, s54
	v_or_b32_e32 v174, s36, v186
	v_or_b32_e32 v175, s37, v187
	v_lshlrev_b32_e32 v176, 12, v174
	v_lshl_add_u32 v176, v175, 1, v176
	v_lshrrev_b32_e32 v177, 6, v175
	v_lshl_add_u32 v177, s10, 5, v177
	v_lshlrev_b32_e32 v177, 14, v177
	v_and_b32_e32 v198, 0xff, v174
	v_lshl_add_u32 v177, v198, 6, v177
	v_and_b32_e32 v198, 63, v175
	v_add_u32_e32 v177, v177, v198
	v_lshlrev_b32_e32 v177, 1, v177
	s_cmp_eq_u32 s9, 0
	s_cbranch_scc1 .Lmy_p9_br0
	v_mov_b32_e32 v178, v176
	v_mov_b32_e32 v180, v177
	v_add_u32_e32 v181, 0x10000, v177
	v_add_u32_e32 v179, 0x10000, v176
	v_add_u32_e32 v182, 0x800, v177
	v_add_u32_e32 v183, 0x10800, v177
	global_load_dwordx4 v[216:219], v178, s[34:35]
	global_load_dwordx4 v[220:223], v180, s[12:13]
	global_load_dwordx4 v[224:227], v178, s[34:35] offset:256
	global_load_dwordx4 v[228:231], v181, s[12:13]
	global_load_dwordx4 v[232:235], v179, s[34:35]
	global_load_dwordx4 v[236:239], v182, s[12:13]
	global_load_dwordx4 v[240:243], v179, s[34:35] offset:256
	global_load_dwordx4 v[244:247], v183, s[12:13]
	v_add_u32_e32 v192, 0x20000, v176
	v_add_u32_e32 v194, 0x1000, v177
	v_add_u32_e32 v195, 0x11000, v177
	v_add_u32_e32 v193, 0x30000, v176
	v_add_u32_e32 v196, 0x1800, v177
	v_add_u32_e32 v197, 0x11800, v177
	global_load_dwordx4 v[128:131], v192, s[34:35]
	global_load_dwordx4 v[132:135], v194, s[12:13]
	global_load_dwordx4 v[136:139], v192, s[34:35] offset:256
	global_load_dwordx4 v[140:143], v195, s[12:13]
	global_load_dwordx4 v[144:147], v193, s[34:35]
	global_load_dwordx4 v[148:151], v196, s[12:13]
	global_load_dwordx4 v[152:155], v193, s[34:35] offset:256
	global_load_dwordx4 v[156:159], v197, s[12:13]
	v_mul_f32_e32 v124, 0xbfb8aa3b, v124
	v_mul_f32_e32 v125, 0xbfb8aa3b, v125
	v_mul_f32_e32 v126, 0xbfb8aa3b, v126
	v_mul_f32_e32 v127, 0xbfb8aa3b, v127
	v_mul_f32_e32 v120, 0xbfb8aa3b, v120
	v_mul_f32_e32 v121, 0xbfb8aa3b, v121
	v_mul_f32_e32 v122, 0xbfb8aa3b, v122
	v_mul_f32_e32 v123, 0xbfb8aa3b, v123
	v_exp_f32_e32 v124, v124
	v_exp_f32_e32 v125, v125
	v_exp_f32_e32 v126, v126
	v_exp_f32_e32 v127, v127
	v_exp_f32_e32 v120, v120
	v_exp_f32_e32 v121, v121
	v_exp_f32_e32 v122, v122
	v_exp_f32_e32 v123, v123
	v_add_f32_e32 v124, 1.0, v124
	v_add_f32_e32 v125, 1.0, v125
	v_add_f32_e32 v126, 1.0, v126
	v_add_f32_e32 v127, 1.0, v127
	v_add_f32_e32 v120, 1.0, v120
	v_add_f32_e32 v121, 1.0, v121
	v_add_f32_e32 v122, 1.0, v122
	v_add_f32_e32 v123, 1.0, v123
	v_rcp_f32_e32 v124, v124
	v_rcp_f32_e32 v125, v125
	v_rcp_f32_e32 v126, v126
	v_rcp_f32_e32 v127, v127
; __device__ __forceinline__ unsigned cvt_pk_bf16(float lo, float hi) { f32x2 v = {lo, hi}; bf16x2_t b = __builtin_convertvector(v, bf16x2_t); return __builtin_bit_cast(unsigned, b); }
; __device__ __forceinline__ float bflo(unsigned w) { return __uint_as_float(w << 16); }
; __device__ __forceinline__ float bfhi(unsigned w) { return __uint_as_float(w & 0xffff0000u); }
; __device__ __forceinline__ float sigmoid_f(float x) { return __builtin_amdgcn_rcpf(1.0f + __expf(-x)); }
; __device__ __forceinline__ size_t tl(int r, int c, int K) { return ((size_t)(r >> 8) * (size_t)(K >> 6) + (size_t)(c >> 6)) * 16384 + (size_t)((r & 255) << 6) + (size_t)(c & 63); }
;     __device__ __forceinline__ void operator()(const f32x4 (&acc)[2][2][4][2], const Unit& u, int wr, int wc, int fr, int fq) const {
;     ...
;                 for (int mm = 0; mm < 2; ++mm) {
;                     const int m = mh * 2 + mm;
;                     const int rr = row0 + ai * HALF + m * 16;
; #pragma unroll
;                     for (int bj = 0; bj < 2; ++bj) {
;                         const f32x4 a0 = acc[ai][bj][m][0], a1 = acc[ai][bj][m][1];
;                         const u32x4 yv = yw[mm][bj], mv = mw[mm][bj];
;                         u32x4 w;
;                         w.x = cvt_pk_bf16(sigmoid_f(a0[0]) * bflo(yv.x) + bflo(mv.x), sigmoid_f(a0[1]) * bfhi(yv.x) + bfhi(mv.x));
;                         w.y = cvt_pk_bf16(sigmoid_f(a0[2]) * bflo(yv.y) + bflo(mv.y), sigmoid_f(a0[3]) * bfhi(yv.y) + bfhi(mv.y));
;                         w.z = cvt_pk_bf16(sigmoid_f(a1[0]) * bflo(yv.z) + bflo(mv.z), sigmoid_f(a1[1]) * bfhi(yv.z) + bfhi(mv.z));
;                         w.w = cvt_pk_bf16(sigmoid_f(a1[2]) * bflo(yv.w) + bflo(mv.w), sigmoid_f(a1[3]) * bfhi(yv.w) + bfhi(mv.w));
;                         *(u32x4*)(merged + tl(rr, col0 + bj * HALF, DM)) = w;
;                     }
	v_rcp_f32_e32 v120, v120
	v_rcp_f32_e32 v121, v121
	v_rcp_f32_e32 v122, v122
	v_rcp_f32_e32 v123, v123
	v_mul_f32_e32 v116, 0xbfb8aa3b, v116
	v_mul_f32_e32 v117, 0xbfb8aa3b, v117
	v_mul_f32_e32 v118, 0xbfb8aa3b, v118
	v_mul_f32_e32 v119, 0xbfb8aa3b, v119
	v_mul_f32_e32 v112, 0xbfb8aa3b, v112
	v_mul_f32_e32 v113, 0xbfb8aa3b, v113
	v_mul_f32_e32 v114, 0xbfb8aa3b, v114
	v_mul_f32_e32 v115, 0xbfb8aa3b, v115
	v_exp_f32_e32 v116, v116
	v_exp_f32_e32 v117, v117
	v_exp_f32_e32 v118, v118
	v_exp_f32_e32 v119, v119
	v_exp_f32_e32 v112, v112
	v_exp_f32_e32 v113, v113
	v_exp_f32_e32 v114, v114
	v_exp_f32_e32 v115, v115
	v_add_f32_e32 v116, 1.0, v116
	v_add_f32_e32 v117, 1.0, v117
	v_add_f32_e32 v118, 1.0, v118
	v_add_f32_e32 v119, 1.0, v119
	v_add_f32_e32 v112, 1.0, v112
	v_add_f32_e32 v113, 1.0, v113
	v_add_f32_e32 v114, 1.0, v114
	v_add_f32_e32 v115, 1.0, v115
	v_rcp_f32_e32 v116, v116
	v_rcp_f32_e32 v117, v117
	v_rcp_f32_e32 v118, v118
	v_rcp_f32_e32 v119, v119
	v_rcp_f32_e32 v112, v112
	v_rcp_f32_e32 v113, v113
	v_rcp_f32_e32 v114, v114
	v_rcp_f32_e32 v115, v115
	v_mul_f32_e32 v108, 0xbfb8aa3b, v108
	v_mul_f32_e32 v109, 0xbfb8aa3b, v109
	v_mul_f32_e32 v110, 0xbfb8aa3b, v110
	v_mul_f32_e32 v111, 0xbfb8aa3b, v111
	v_mul_f32_e32 v104, 0xbfb8aa3b, v104
	v_mul_f32_e32 v105, 0xbfb8aa3b, v105
	v_mul_f32_e32 v106, 0xbfb8aa3b, v106
	v_mul_f32_e32 v107, 0xbfb8aa3b, v107
	v_exp_f32_e32 v108, v108
	v_exp_f32_e32 v109, v109
	v_exp_f32_e32 v110, v110
	v_exp_f32_e32 v111, v111
	v_exp_f32_e32 v104, v104
	v_exp_f32_e32 v105, v105
	v_exp_f32_e32 v106, v106
	v_exp_f32_e32 v107, v107
	v_add_f32_e32 v108, 1.0, v108
	v_add_f32_e32 v109, 1.0, v109
	v_add_f32_e32 v110, 1.0, v110
	v_add_f32_e32 v111, 1.0, v111
	v_add_f32_e32 v104, 1.0, v104
	v_add_f32_e32 v105, 1.0, v105
	v_add_f32_e32 v106, 1.0, v106
	v_add_f32_e32 v107, 1.0, v107
	v_rcp_f32_e32 v108, v108
	v_rcp_f32_e32 v109, v109
	v_rcp_f32_e32 v110, v110
	v_rcp_f32_e32 v111, v111
	v_rcp_f32_e32 v104, v104
	v_rcp_f32_e32 v105, v105
	v_rcp_f32_e32 v106, v106
	v_rcp_f32_e32 v107, v107
	v_mul_f32_e32 v100, 0xbfb8aa3b, v100
	v_mul_f32_e32 v101, 0xbfb8aa3b, v101
	v_mul_f32_e32 v102, 0xbfb8aa3b, v102
	v_mul_f32_e32 v103, 0xbfb8aa3b, v103
	v_mul_f32_e32 v96, 0xbfb8aa3b, v96
	v_mul_f32_e32 v97, 0xbfb8aa3b, v97
	v_mul_f32_e32 v98, 0xbfb8aa3b, v98
	v_mul_f32_e32 v99, 0xbfb8aa3b, v99
	v_exp_f32_e32 v100, v100
	v_exp_f32_e32 v101, v101
	v_exp_f32_e32 v102, v102
	v_exp_f32_e32 v103, v103
	v_exp_f32_e32 v96, v96
	v_exp_f32_e32 v97, v97
	v_exp_f32_e32 v98, v98
	v_exp_f32_e32 v99, v99
	v_add_f32_e32 v100, 1.0, v100
	v_add_f32_e32 v101, 1.0, v101
	v_add_f32_e32 v102, 1.0, v102
	v_add_f32_e32 v103, 1.0, v103
	v_add_f32_e32 v96, 1.0, v96
	v_add_f32_e32 v97, 1.0, v97
	v_add_f32_e32 v98, 1.0, v98
	v_add_f32_e32 v99, 1.0, v99
	v_rcp_f32_e32 v100, v100
	v_rcp_f32_e32 v101, v101
	v_rcp_f32_e32 v102, v102
	v_rcp_f32_e32 v103, v103
	v_rcp_f32_e32 v96, v96
	v_rcp_f32_e32 v97, v97
	v_rcp_f32_e32 v98, v98
	v_rcp_f32_e32 v99, v99
	s_waitcnt vmcnt(8)
	v_lshlrev_b32_e32 v198, 16, v216
	v_and_b32_e32 v199, 0xffff0000, v216
	v_lshlrev_b32_e32 v200, 16, v220
	v_and_b32_e32 v201, 0xffff0000, v220
	v_fma_f32 v124, v124, v198, v200
	v_fma_f32 v125, v125, v199, v201
	v_cvt_pk_bf16_f32 v248, v124, v125
	v_lshlrev_b32_e32 v202, 16, v217
	v_and_b32_e32 v203, 0xffff0000, v217
	v_lshlrev_b32_e32 v214, 16, v221
	v_and_b32_e32 v215, 0xffff0000, v221
	v_fma_f32 v126, v126, v202, v214
	v_fma_f32 v127, v127, v203, v215
	v_cvt_pk_bf16_f32 v249, v126, v127
	v_lshlrev_b32_e32 v198, 16, v218
	v_and_b32_e32 v199, 0xffff0000, v218
	v_lshlrev_b32_e32 v200, 16, v222
	v_and_b32_e32 v201, 0xffff0000, v222
	v_fma_f32 v120, v120, v198, v200
	v_fma_f32 v121, v121, v199, v201
	v_cvt_pk_bf16_f32 v250, v120, v121
	v_lshlrev_b32_e32 v202, 16, v219
	v_and_b32_e32 v203, 0xffff0000, v219
	v_lshlrev_b32_e32 v214, 16, v223
	v_and_b32_e32 v215, 0xffff0000, v223
	v_fma_f32 v122, v122, v202, v214
	v_fma_f32 v123, v123, v203, v215
	v_cvt_pk_bf16_f32 v251, v122, v123
	global_store_dwordx4 v180, v[248:251], s[12:13]
	v_lshlrev_b32_e32 v198, 16, v224
	v_and_b32_e32 v199, 0xffff0000, v224
	v_lshlrev_b32_e32 v200, 16, v228
	v_and_b32_e32 v201, 0xffff0000, v228
	v_fma_f32 v116, v116, v198, v200
	v_fma_f32 v117, v117, v199, v201
	v_cvt_pk_bf16_f32 v252, v116, v117
	v_lshlrev_b32_e32 v202, 16, v225
	v_and_b32_e32 v203, 0xffff0000, v225
	v_lshlrev_b32_e32 v214, 16, v229
	v_and_b32_e32 v215, 0xffff0000, v229
	v_fma_f32 v118, v118, v202, v214
	v_fma_f32 v119, v119, v203, v215
	v_cvt_pk_bf16_f32 v253, v118, v119
	v_lshlrev_b32_e32 v198, 16, v226
	v_and_b32_e32 v199, 0xffff0000, v226
	v_lshlrev_b32_e32 v200, 16, v230
	v_and_b32_e32 v201, 0xffff0000, v230
	v_fma_f32 v112, v112, v198, v200
	v_fma_f32 v113, v113, v199, v201
	v_cvt_pk_bf16_f32 v254, v112, v113
	v_lshlrev_b32_e32 v202, 16, v227
	v_and_b32_e32 v203, 0xffff0000, v227
	v_lshlrev_b32_e32 v214, 16, v231
	v_and_b32_e32 v215, 0xffff0000, v231
	v_fma_f32 v114, v114, v202, v214
	v_fma_f32 v115, v115, v203, v215
	v_cvt_pk_bf16_f32 v255, v114, v115
	global_store_dwordx4 v181, v[252:255], s[12:13]
	v_lshlrev_b32_e32 v198, 16, v232
	v_and_b32_e32 v199, 0xffff0000, v232
	v_lshlrev_b32_e32 v200, 16, v236
	v_and_b32_e32 v201, 0xffff0000, v236
	v_fma_f32 v108, v108, v198, v200
	v_fma_f32 v109, v109, v199, v201
	v_cvt_pk_bf16_f32 v206, v108, v109
	v_lshlrev_b32_e32 v202, 16, v233
	v_and_b32_e32 v203, 0xffff0000, v233
	v_lshlrev_b32_e32 v214, 16, v237
	v_and_b32_e32 v215, 0xffff0000, v237
	v_fma_f32 v110, v110, v202, v214
	v_fma_f32 v111, v111, v203, v215
	v_cvt_pk_bf16_f32 v207, v110, v111
	v_lshlrev_b32_e32 v198, 16, v234
	v_and_b32_e32 v199, 0xffff0000, v234
; __device__ __forceinline__ unsigned cvt_pk_bf16(float lo, float hi) { f32x2 v = {lo, hi}; bf16x2_t b = __builtin_convertvector(v, bf16x2_t); return __builtin_bit_cast(unsigned, b); }
; __device__ __forceinline__ float bflo(unsigned w) { return __uint_as_float(w << 16); }
; __device__ __forceinline__ float bfhi(unsigned w) { return __uint_as_float(w & 0xffff0000u); }
;     __device__ __forceinline__ void operator()(const f32x4 (&acc)[2][2][4][2], const Unit& u, int wr, int wc, int fr, int fq) const {
;     ...
;         for (int ai = 0; ai < 2; ++ai)
; #pragma unroll
;             for (int mh = 0; mh < 2; ++mh) {
;                 u32x4 yw[2][2], mw[2][2];
; #pragma unroll
;                 for (int mm = 0; mm < 2; ++mm) {
;                     const int rr = row0 + ai * HALF + (mh * 2 + mm) * 16;
;                     const size_t off = (size_t)rr * DM + col0;
; #pragma unroll
;                     for (int bj = 0; bj < 2; ++bj) {
;                         yw[mm][bj] = *(const u32x4*)(y + off + bj * HALF);
;                         mw[mm][bj] = (u32x4){0u, 0u, 0u, 0u};
;                         if (br != 0) mw[mm][bj] = *(const u32x4*)(merged + tl(rr, col0 + bj * HALF, DM));
;                     }
;                 }
; #pragma unroll
;                 for (int mm = 0; mm < 2; ++mm) {
;                     const int m = mh * 2 + mm;
;                     const int rr = row0 + ai * HALF + m * 16;
; #pragma unroll
;                     for (int bj = 0; bj < 2; ++bj) {
;                         const f32x4 a0 = acc[ai][bj][m][0], a1 = acc[ai][bj][m][1];
;                         const u32x4 yv = yw[mm][bj], mv = mw[mm][bj];
;                         u32x4 w;
;                         w.x = cvt_pk_bf16(sigmoid_f(a0[0]) * bflo(yv.x) + bflo(mv.x), sigmoid_f(a0[1]) * bfhi(yv.x) + bfhi(mv.x));
;                         w.y = cvt_pk_bf16(sigmoid_f(a0[2]) * bflo(yv.y) + bflo(mv.y), sigmoid_f(a0[3]) * bfhi(yv.y) + bfhi(mv.y));
;                         w.z = cvt_pk_bf16(sigmoid_f(a1[0]) * bflo(yv.z) + bflo(mv.z), sigmoid_f(a1[1]) * bfhi(yv.z) + bfhi(mv.z));
;                         w.w = cvt_pk_bf16(sigmoid_f(a1[2]) * bflo(yv.w) + bflo(mv.w), sigmoid_f(a1[3]) * bfhi(yv.w) + bfhi(mv.w));
;                         *(u32x4*)(merged + tl(rr, col0 + bj * HALF, DM)) = w;
;                     }
	v_lshlrev_b32_e32 v200, 16, v238
	v_and_b32_e32 v201, 0xffff0000, v238
	v_fma_f32 v104, v104, v198, v200
	v_fma_f32 v105, v105, v199, v201
	v_cvt_pk_bf16_f32 v208, v104, v105
	v_lshlrev_b32_e32 v202, 16, v235
	v_and_b32_e32 v203, 0xffff0000, v235
	v_lshlrev_b32_e32 v214, 16, v239
	v_and_b32_e32 v215, 0xffff0000, v239
	v_fma_f32 v106, v106, v202, v214
	v_fma_f32 v107, v107, v203, v215
	v_cvt_pk_bf16_f32 v209, v106, v107
	global_store_dwordx4 v182, v[206:209], s[12:13]
	v_lshlrev_b32_e32 v198, 16, v240
	v_and_b32_e32 v199, 0xffff0000, v240
	v_lshlrev_b32_e32 v200, 16, v244
	v_and_b32_e32 v201, 0xffff0000, v244
	v_fma_f32 v100, v100, v198, v200
	v_fma_f32 v101, v101, v199, v201
	v_cvt_pk_bf16_f32 v210, v100, v101
	v_lshlrev_b32_e32 v202, 16, v241
	v_and_b32_e32 v203, 0xffff0000, v241
	v_lshlrev_b32_e32 v214, 16, v245
	v_and_b32_e32 v215, 0xffff0000, v245
	v_fma_f32 v102, v102, v202, v214
	v_fma_f32 v103, v103, v203, v215
	v_cvt_pk_bf16_f32 v211, v102, v103
	v_lshlrev_b32_e32 v198, 16, v242
	v_and_b32_e32 v199, 0xffff0000, v242
	v_lshlrev_b32_e32 v200, 16, v246
	v_and_b32_e32 v201, 0xffff0000, v246
	v_fma_f32 v96, v96, v198, v200
	v_fma_f32 v97, v97, v199, v201
	v_cvt_pk_bf16_f32 v212, v96, v97
	v_lshlrev_b32_e32 v202, 16, v243
	v_and_b32_e32 v203, 0xffff0000, v243
	v_lshlrev_b32_e32 v214, 16, v247
	v_and_b32_e32 v215, 0xffff0000, v247
	v_fma_f32 v98, v98, v202, v214
	v_fma_f32 v99, v99, v203, v215
	v_cvt_pk_bf16_f32 v213, v98, v99
	global_store_dwordx4 v183, v[210:213], s[12:13]
	v_add_u32_e32 v178, 0x80000, v176
	v_add_u32_e32 v180, 0x4000, v177
	v_add_u32_e32 v181, 0x14000, v177
	v_add_u32_e32 v179, 0x90000, v176
	v_add_u32_e32 v182, 0x4800, v177
	v_add_u32_e32 v183, 0x14800, v177
	global_load_dwordx4 v[216:219], v178, s[34:35]
	global_load_dwordx4 v[220:223], v180, s[12:13]
	global_load_dwordx4 v[224:227], v178, s[34:35] offset:256
	global_load_dwordx4 v[228:231], v181, s[12:13]
	global_load_dwordx4 v[232:235], v179, s[34:35]
	global_load_dwordx4 v[236:239], v182, s[12:13]
	global_load_dwordx4 v[240:243], v179, s[34:35] offset:256
	global_load_dwordx4 v[244:247], v183, s[12:13]
	v_mul_f32_e32 v92, 0xbfb8aa3b, v92
	v_mul_f32_e32 v93, 0xbfb8aa3b, v93
	v_mul_f32_e32 v94, 0xbfb8aa3b, v94
	v_mul_f32_e32 v95, 0xbfb8aa3b, v95
	v_mul_f32_e32 v88, 0xbfb8aa3b, v88
	v_mul_f32_e32 v89, 0xbfb8aa3b, v89
	v_mul_f32_e32 v90, 0xbfb8aa3b, v90
	v_mul_f32_e32 v91, 0xbfb8aa3b, v91
	v_exp_f32_e32 v92, v92
	v_exp_f32_e32 v93, v93
	v_exp_f32_e32 v94, v94
	v_exp_f32_e32 v95, v95
	v_exp_f32_e32 v88, v88
	v_exp_f32_e32 v89, v89
	v_exp_f32_e32 v90, v90
	v_exp_f32_e32 v91, v91
	v_add_f32_e32 v92, 1.0, v92
	v_add_f32_e32 v93, 1.0, v93
	v_add_f32_e32 v94, 1.0, v94
	v_add_f32_e32 v95, 1.0, v95
	v_add_f32_e32 v88, 1.0, v88
	v_add_f32_e32 v89, 1.0, v89
	v_add_f32_e32 v90, 1.0, v90
	v_add_f32_e32 v91, 1.0, v91
	v_rcp_f32_e32 v92, v92
	v_rcp_f32_e32 v93, v93
	v_rcp_f32_e32 v94, v94
	v_rcp_f32_e32 v95, v95
	v_rcp_f32_e32 v88, v88
	v_rcp_f32_e32 v89, v89
	v_rcp_f32_e32 v90, v90
	v_rcp_f32_e32 v91, v91
	v_mul_f32_e32 v84, 0xbfb8aa3b, v84
	v_mul_f32_e32 v85, 0xbfb8aa3b, v85
	v_mul_f32_e32 v86, 0xbfb8aa3b, v86
	v_mul_f32_e32 v87, 0xbfb8aa3b, v87
	v_mul_f32_e32 v80, 0xbfb8aa3b, v80
	v_mul_f32_e32 v81, 0xbfb8aa3b, v81
	v_mul_f32_e32 v82, 0xbfb8aa3b, v82
	v_mul_f32_e32 v83, 0xbfb8aa3b, v83
	v_exp_f32_e32 v84, v84
	v_exp_f32_e32 v85, v85
	v_exp_f32_e32 v86, v86
	v_exp_f32_e32 v87, v87
	v_exp_f32_e32 v80, v80
	v_exp_f32_e32 v81, v81
	v_exp_f32_e32 v82, v82
	v_exp_f32_e32 v83, v83
	v_add_f32_e32 v84, 1.0, v84
	v_add_f32_e32 v85, 1.0, v85
	v_add_f32_e32 v86, 1.0, v86
	v_add_f32_e32 v87, 1.0, v87
	v_add_f32_e32 v80, 1.0, v80
	v_add_f32_e32 v81, 1.0, v81
	v_add_f32_e32 v82, 1.0, v82
	v_add_f32_e32 v83, 1.0, v83
	v_rcp_f32_e32 v84, v84
	v_rcp_f32_e32 v85, v85
	v_rcp_f32_e32 v86, v86
	v_rcp_f32_e32 v87, v87
	v_rcp_f32_e32 v80, v80
	v_rcp_f32_e32 v81, v81
	v_rcp_f32_e32 v82, v82
	v_rcp_f32_e32 v83, v83
	v_mul_f32_e32 v76, 0xbfb8aa3b, v76
	v_mul_f32_e32 v77, 0xbfb8aa3b, v77
	v_mul_f32_e32 v78, 0xbfb8aa3b, v78
	v_mul_f32_e32 v79, 0xbfb8aa3b, v79
	v_mul_f32_e32 v72, 0xbfb8aa3b, v72
	v_mul_f32_e32 v73, 0xbfb8aa3b, v73
	v_mul_f32_e32 v74, 0xbfb8aa3b, v74
	v_mul_f32_e32 v75, 0xbfb8aa3b, v75
	v_exp_f32_e32 v76, v76
	v_exp_f32_e32 v77, v77
	v_exp_f32_e32 v78, v78
	v_exp_f32_e32 v79, v79
	v_exp_f32_e32 v72, v72
	v_exp_f32_e32 v73, v73
	v_exp_f32_e32 v74, v74
	v_exp_f32_e32 v75, v75
	v_add_f32_e32 v76, 1.0, v76
	v_add_f32_e32 v77, 1.0, v77
	v_add_f32_e32 v78, 1.0, v78
	v_add_f32_e32 v79, 1.0, v79
	v_add_f32_e32 v72, 1.0, v72
	v_add_f32_e32 v73, 1.0, v73
	v_add_f32_e32 v74, 1.0, v74
	v_add_f32_e32 v75, 1.0, v75
	v_rcp_f32_e32 v76, v76
	v_rcp_f32_e32 v77, v77
	v_rcp_f32_e32 v78, v78
	v_rcp_f32_e32 v79, v79
	v_rcp_f32_e32 v72, v72
	v_rcp_f32_e32 v73, v73
	v_rcp_f32_e32 v74, v74
	v_rcp_f32_e32 v75, v75
	v_mul_f32_e32 v68, 0xbfb8aa3b, v68
	v_mul_f32_e32 v69, 0xbfb8aa3b, v69
	v_mul_f32_e32 v70, 0xbfb8aa3b, v70
	v_mul_f32_e32 v71, 0xbfb8aa3b, v71
	v_mul_f32_e32 v64, 0xbfb8aa3b, v64
	v_mul_f32_e32 v65, 0xbfb8aa3b, v65
	v_mul_f32_e32 v66, 0xbfb8aa3b, v66
	v_mul_f32_e32 v67, 0xbfb8aa3b, v67
	v_exp_f32_e32 v68, v68
	v_exp_f32_e32 v69, v69
	v_exp_f32_e32 v70, v70
	v_exp_f32_e32 v71, v71
	v_exp_f32_e32 v64, v64
	v_exp_f32_e32 v65, v65
	v_exp_f32_e32 v66, v66
	v_exp_f32_e32 v67, v67
	v_add_f32_e32 v68, 1.0, v68
	v_add_f32_e32 v69, 1.0, v69
	v_add_f32_e32 v70, 1.0, v70
	v_add_f32_e32 v71, 1.0, v71
	v_add_f32_e32 v64, 1.0, v64
	v_add_f32_e32 v65, 1.0, v65
	v_add_f32_e32 v66, 1.0, v66
	v_add_f32_e32 v67, 1.0, v67
	v_rcp_f32_e32 v68, v68
	v_rcp_f32_e32 v69, v69
	v_rcp_f32_e32 v70, v70
	v_rcp_f32_e32 v71, v71
	v_rcp_f32_e32 v64, v64
	v_rcp_f32_e32 v65, v65
	v_rcp_f32_e32 v66, v66
	v_rcp_f32_e32 v67, v67
	s_waitcnt vmcnt(12)
; __device__ __forceinline__ unsigned cvt_pk_bf16(float lo, float hi) { f32x2 v = {lo, hi}; bf16x2_t b = __builtin_convertvector(v, bf16x2_t); return __builtin_bit_cast(unsigned, b); }
; __device__ __forceinline__ float bflo(unsigned w) { return __uint_as_float(w << 16); }
; __device__ __forceinline__ float bfhi(unsigned w) { return __uint_as_float(w & 0xffff0000u); }
; __device__ __forceinline__ float sigmoid_f(float x) { return __builtin_amdgcn_rcpf(1.0f + __expf(-x)); }
;     __device__ __forceinline__ void operator()(const f32x4 (&acc)[2][2][4][2], const Unit& u, int wr, int wc, int fr, int fq) const {
;     ...
;                 u32x4 yw[2][2], mw[2][2];
; #pragma unroll
;                 for (int mm = 0; mm < 2; ++mm) {
;                     const int rr = row0 + ai * HALF + (mh * 2 + mm) * 16;
;                     const size_t off = (size_t)rr * DM + col0;
; #pragma unroll
;                     for (int bj = 0; bj < 2; ++bj) {
;                         yw[mm][bj] = *(const u32x4*)(y + off + bj * HALF);
;                         mw[mm][bj] = (u32x4){0u, 0u, 0u, 0u};
;                         if (br != 0) mw[mm][bj] = *(const u32x4*)(merged + tl(rr, col0 + bj * HALF, DM));
;                     }
;                 }
; #pragma unroll
;                 for (int mm = 0; mm < 2; ++mm) {
;                     const int m = mh * 2 + mm;
;                     const int rr = row0 + ai * HALF + m * 16;
; #pragma unroll
;                     for (int bj = 0; bj < 2; ++bj) {
;                         const f32x4 a0 = acc[ai][bj][m][0], a1 = acc[ai][bj][m][1];
;                         const u32x4 yv = yw[mm][bj], mv = mw[mm][bj];
;                         u32x4 w;
;                         w.x = cvt_pk_bf16(sigmoid_f(a0[0]) * bflo(yv.x) + bflo(mv.x), sigmoid_f(a0[1]) * bfhi(yv.x) + bfhi(mv.x));
;                         w.y = cvt_pk_bf16(sigmoid_f(a0[2]) * bflo(yv.y) + bflo(mv.y), sigmoid_f(a0[3]) * bfhi(yv.y) + bfhi(mv.y));
;                         w.z = cvt_pk_bf16(sigmoid_f(a1[0]) * bflo(yv.z) + bflo(mv.z), sigmoid_f(a1[1]) * bfhi(yv.z) + bfhi(mv.z));
;                         w.w = cvt_pk_bf16(sigmoid_f(a1[2]) * bflo(yv.w) + bflo(mv.w), sigmoid_f(a1[3]) * bfhi(yv.w) + bfhi(mv.w));
;                         *(u32x4*)(merged + tl(rr, col0 + bj * HALF, DM)) = w;
;                     }
	v_lshlrev_b32_e32 v198, 16, v128
	v_and_b32_e32 v199, 0xffff0000, v128
	v_lshlrev_b32_e32 v200, 16, v132
	v_and_b32_e32 v201, 0xffff0000, v132
	v_fma_f32 v92, v92, v198, v200
	v_fma_f32 v93, v93, v199, v201
	v_cvt_pk_bf16_f32 v248, v92, v93
	v_lshlrev_b32_e32 v202, 16, v129
	v_and_b32_e32 v203, 0xffff0000, v129
	v_lshlrev_b32_e32 v214, 16, v133
	v_and_b32_e32 v215, 0xffff0000, v133
	v_fma_f32 v94, v94, v202, v214
	v_fma_f32 v95, v95, v203, v215
	v_cvt_pk_bf16_f32 v249, v94, v95
	v_lshlrev_b32_e32 v198, 16, v130
	v_and_b32_e32 v199, 0xffff0000, v130
	v_lshlrev_b32_e32 v200, 16, v134
	v_and_b32_e32 v201, 0xffff0000, v134
	v_fma_f32 v88, v88, v198, v200
	v_fma_f32 v89, v89, v199, v201
	v_cvt_pk_bf16_f32 v250, v88, v89
	v_lshlrev_b32_e32 v202, 16, v131
	v_and_b32_e32 v203, 0xffff0000, v131
	v_lshlrev_b32_e32 v214, 16, v135
	v_and_b32_e32 v215, 0xffff0000, v135
	v_fma_f32 v90, v90, v202, v214
	v_fma_f32 v91, v91, v203, v215
	v_cvt_pk_bf16_f32 v251, v90, v91
	global_store_dwordx4 v194, v[248:251], s[12:13]
	v_lshlrev_b32_e32 v198, 16, v136
	v_and_b32_e32 v199, 0xffff0000, v136
	v_lshlrev_b32_e32 v200, 16, v140
	v_and_b32_e32 v201, 0xffff0000, v140
	v_fma_f32 v84, v84, v198, v200
	v_fma_f32 v85, v85, v199, v201
	v_cvt_pk_bf16_f32 v252, v84, v85
	v_lshlrev_b32_e32 v202, 16, v137
	v_and_b32_e32 v203, 0xffff0000, v137
	v_lshlrev_b32_e32 v214, 16, v141
	v_and_b32_e32 v215, 0xffff0000, v141
	v_fma_f32 v86, v86, v202, v214
	v_fma_f32 v87, v87, v203, v215
	v_cvt_pk_bf16_f32 v253, v86, v87
	v_lshlrev_b32_e32 v198, 16, v138
	v_and_b32_e32 v199, 0xffff0000, v138
	v_lshlrev_b32_e32 v200, 16, v142
	v_and_b32_e32 v201, 0xffff0000, v142
	v_fma_f32 v80, v80, v198, v200
	v_fma_f32 v81, v81, v199, v201
	v_cvt_pk_bf16_f32 v254, v80, v81
	v_lshlrev_b32_e32 v202, 16, v139
	v_and_b32_e32 v203, 0xffff0000, v139
	v_lshlrev_b32_e32 v214, 16, v143
	v_and_b32_e32 v215, 0xffff0000, v143
	v_fma_f32 v82, v82, v202, v214
	v_fma_f32 v83, v83, v203, v215
	v_cvt_pk_bf16_f32 v255, v82, v83
	global_store_dwordx4 v195, v[252:255], s[12:13]
	v_lshlrev_b32_e32 v198, 16, v144
	v_and_b32_e32 v199, 0xffff0000, v144
	v_lshlrev_b32_e32 v200, 16, v148
	v_and_b32_e32 v201, 0xffff0000, v148
	v_fma_f32 v76, v76, v198, v200
	v_fma_f32 v77, v77, v199, v201
	v_cvt_pk_bf16_f32 v206, v76, v77
	v_lshlrev_b32_e32 v202, 16, v145
	v_and_b32_e32 v203, 0xffff0000, v145
	v_lshlrev_b32_e32 v214, 16, v149
	v_and_b32_e32 v215, 0xffff0000, v149
	v_fma_f32 v78, v78, v202, v214
	v_fma_f32 v79, v79, v203, v215
	v_cvt_pk_bf16_f32 v207, v78, v79
	v_lshlrev_b32_e32 v198, 16, v146
	v_and_b32_e32 v199, 0xffff0000, v146
	v_lshlrev_b32_e32 v200, 16, v150
	v_and_b32_e32 v201, 0xffff0000, v150
	v_fma_f32 v72, v72, v198, v200
	v_fma_f32 v73, v73, v199, v201
	v_cvt_pk_bf16_f32 v208, v72, v73
	v_lshlrev_b32_e32 v202, 16, v147
	v_and_b32_e32 v203, 0xffff0000, v147
	v_lshlrev_b32_e32 v214, 16, v151
	v_and_b32_e32 v215, 0xffff0000, v151
	v_fma_f32 v74, v74, v202, v214
	v_fma_f32 v75, v75, v203, v215
	v_cvt_pk_bf16_f32 v209, v74, v75
	global_store_dwordx4 v196, v[206:209], s[12:13]
	v_lshlrev_b32_e32 v198, 16, v152
	v_and_b32_e32 v199, 0xffff0000, v152
	v_lshlrev_b32_e32 v200, 16, v156
	v_and_b32_e32 v201, 0xffff0000, v156
	v_fma_f32 v68, v68, v198, v200
	v_fma_f32 v69, v69, v199, v201
	v_cvt_pk_bf16_f32 v210, v68, v69
	v_lshlrev_b32_e32 v202, 16, v153
	v_and_b32_e32 v203, 0xffff0000, v153
	v_lshlrev_b32_e32 v214, 16, v157
	v_and_b32_e32 v215, 0xffff0000, v157
	v_fma_f32 v70, v70, v202, v214
	v_fma_f32 v71, v71, v203, v215
	v_cvt_pk_bf16_f32 v211, v70, v71
	v_lshlrev_b32_e32 v198, 16, v154
	v_and_b32_e32 v199, 0xffff0000, v154
	v_lshlrev_b32_e32 v200, 16, v158
	v_and_b32_e32 v201, 0xffff0000, v158
	v_fma_f32 v64, v64, v198, v200
	v_fma_f32 v65, v65, v199, v201
	v_cvt_pk_bf16_f32 v212, v64, v65
	v_lshlrev_b32_e32 v202, 16, v155
	v_and_b32_e32 v203, 0xffff0000, v155
	v_lshlrev_b32_e32 v214, 16, v159
	v_and_b32_e32 v215, 0xffff0000, v159
	v_fma_f32 v66, v66, v202, v214
	v_fma_f32 v67, v67, v203, v215
	v_cvt_pk_bf16_f32 v213, v66, v67
	global_store_dwordx4 v197, v[210:213], s[12:13]
	v_add_u32_e32 v192, 0xa0000, v176
	v_add_u32_e32 v194, 0x5000, v177
	v_add_u32_e32 v195, 0x15000, v177
	v_add_u32_e32 v193, 0xb0000, v176
	v_add_u32_e32 v196, 0x5800, v177
	v_add_u32_e32 v197, 0x15800, v177
	global_load_dwordx4 v[128:131], v192, s[34:35]
	global_load_dwordx4 v[132:135], v194, s[12:13]
	global_load_dwordx4 v[136:139], v192, s[34:35] offset:256
	global_load_dwordx4 v[140:143], v195, s[12:13]
	global_load_dwordx4 v[144:147], v193, s[34:35]
	global_load_dwordx4 v[148:151], v196, s[12:13]
	global_load_dwordx4 v[152:155], v193, s[34:35] offset:256
	global_load_dwordx4 v[156:159], v197, s[12:13]
	v_mul_f32_e32 v60, 0xbfb8aa3b, v60
	v_mul_f32_e32 v61, 0xbfb8aa3b, v61
	v_mul_f32_e32 v62, 0xbfb8aa3b, v62
	v_mul_f32_e32 v63, 0xbfb8aa3b, v63
	v_mul_f32_e32 v56, 0xbfb8aa3b, v56
	v_mul_f32_e32 v57, 0xbfb8aa3b, v57
	v_mul_f32_e32 v58, 0xbfb8aa3b, v58
	v_mul_f32_e32 v59, 0xbfb8aa3b, v59
	v_exp_f32_e32 v60, v60
	v_exp_f32_e32 v61, v61
	v_exp_f32_e32 v62, v62
	v_exp_f32_e32 v63, v63
	v_exp_f32_e32 v56, v56
	v_exp_f32_e32 v57, v57
	v_exp_f32_e32 v58, v58
	v_exp_f32_e32 v59, v59
	v_add_f32_e32 v60, 1.0, v60
	v_add_f32_e32 v61, 1.0, v61
	v_add_f32_e32 v62, 1.0, v62
	v_add_f32_e32 v63, 1.0, v63
	v_add_f32_e32 v56, 1.0, v56
	v_add_f32_e32 v57, 1.0, v57
	v_add_f32_e32 v58, 1.0, v58
	v_add_f32_e32 v59, 1.0, v59
	v_rcp_f32_e32 v60, v60
	v_rcp_f32_e32 v61, v61
	v_rcp_f32_e32 v62, v62
	v_rcp_f32_e32 v63, v63
	v_rcp_f32_e32 v56, v56
	v_rcp_f32_e32 v57, v57
	v_rcp_f32_e32 v58, v58
	v_rcp_f32_e32 v59, v59
	v_mul_f32_e32 v52, 0xbfb8aa3b, v52
; __device__ __forceinline__ unsigned cvt_pk_bf16(float lo, float hi) { f32x2 v = {lo, hi}; bf16x2_t b = __builtin_convertvector(v, bf16x2_t); return __builtin_bit_cast(unsigned, b); }
; __device__ __forceinline__ float bflo(unsigned w) { return __uint_as_float(w << 16); }
; __device__ __forceinline__ float bfhi(unsigned w) { return __uint_as_float(w & 0xffff0000u); }
; __device__ __forceinline__ float sigmoid_f(float x) { return __builtin_amdgcn_rcpf(1.0f + __expf(-x)); }
; __device__ __forceinline__ size_t tl(int r, int c, int K) { return ((size_t)(r >> 8) * (size_t)(K >> 6) + (size_t)(c >> 6)) * 16384 + (size_t)((r & 255) << 6) + (size_t)(c & 63); }
;     __device__ __forceinline__ void operator()(const f32x4 (&acc)[2][2][4][2], const Unit& u, int wr, int wc, int fr, int fq) const {
;     ...
;                 for (int mm = 0; mm < 2; ++mm) {
;                     const int m = mh * 2 + mm;
;                     const int rr = row0 + ai * HALF + m * 16;
; #pragma unroll
;                     for (int bj = 0; bj < 2; ++bj) {
;                         const f32x4 a0 = acc[ai][bj][m][0], a1 = acc[ai][bj][m][1];
;                         const u32x4 yv = yw[mm][bj], mv = mw[mm][bj];
;                         u32x4 w;
;                         w.x = cvt_pk_bf16(sigmoid_f(a0[0]) * bflo(yv.x) + bflo(mv.x), sigmoid_f(a0[1]) * bfhi(yv.x) + bfhi(mv.x));
;                         w.y = cvt_pk_bf16(sigmoid_f(a0[2]) * bflo(yv.y) + bflo(mv.y), sigmoid_f(a0[3]) * bfhi(yv.y) + bfhi(mv.y));
;                         w.z = cvt_pk_bf16(sigmoid_f(a1[0]) * bflo(yv.z) + bflo(mv.z), sigmoid_f(a1[1]) * bfhi(yv.z) + bfhi(mv.z));
;                         w.w = cvt_pk_bf16(sigmoid_f(a1[2]) * bflo(yv.w) + bflo(mv.w), sigmoid_f(a1[3]) * bfhi(yv.w) + bfhi(mv.w));
;                         *(u32x4*)(merged + tl(rr, col0 + bj * HALF, DM)) = w;
;                     }
	v_mul_f32_e32 v53, 0xbfb8aa3b, v53
	v_mul_f32_e32 v54, 0xbfb8aa3b, v54
	v_mul_f32_e32 v55, 0xbfb8aa3b, v55
	v_mul_f32_e32 v48, 0xbfb8aa3b, v48
	v_mul_f32_e32 v49, 0xbfb8aa3b, v49
	v_mul_f32_e32 v50, 0xbfb8aa3b, v50
	v_mul_f32_e32 v51, 0xbfb8aa3b, v51
	v_exp_f32_e32 v52, v52
	v_exp_f32_e32 v53, v53
	v_exp_f32_e32 v54, v54
	v_exp_f32_e32 v55, v55
	v_exp_f32_e32 v48, v48
	v_exp_f32_e32 v49, v49
	v_exp_f32_e32 v50, v50
	v_exp_f32_e32 v51, v51
	v_add_f32_e32 v52, 1.0, v52
	v_add_f32_e32 v53, 1.0, v53
	v_add_f32_e32 v54, 1.0, v54
	v_add_f32_e32 v55, 1.0, v55
	v_add_f32_e32 v48, 1.0, v48
	v_add_f32_e32 v49, 1.0, v49
	v_add_f32_e32 v50, 1.0, v50
	v_add_f32_e32 v51, 1.0, v51
	v_rcp_f32_e32 v52, v52
	v_rcp_f32_e32 v53, v53
	v_rcp_f32_e32 v54, v54
	v_rcp_f32_e32 v55, v55
	v_rcp_f32_e32 v48, v48
	v_rcp_f32_e32 v49, v49
	v_rcp_f32_e32 v50, v50
	v_rcp_f32_e32 v51, v51
	v_mul_f32_e32 v44, 0xbfb8aa3b, v44
	v_mul_f32_e32 v45, 0xbfb8aa3b, v45
	v_mul_f32_e32 v46, 0xbfb8aa3b, v46
	v_mul_f32_e32 v47, 0xbfb8aa3b, v47
	v_mul_f32_e32 v40, 0xbfb8aa3b, v40
	v_mul_f32_e32 v41, 0xbfb8aa3b, v41
	v_mul_f32_e32 v42, 0xbfb8aa3b, v42
	v_mul_f32_e32 v43, 0xbfb8aa3b, v43
	v_exp_f32_e32 v44, v44
	v_exp_f32_e32 v45, v45
	v_exp_f32_e32 v46, v46
	v_exp_f32_e32 v47, v47
	v_exp_f32_e32 v40, v40
	v_exp_f32_e32 v41, v41
	v_exp_f32_e32 v42, v42
	v_exp_f32_e32 v43, v43
	v_add_f32_e32 v44, 1.0, v44
	v_add_f32_e32 v45, 1.0, v45
	v_add_f32_e32 v46, 1.0, v46
	v_add_f32_e32 v47, 1.0, v47
	v_add_f32_e32 v40, 1.0, v40
	v_add_f32_e32 v41, 1.0, v41
	v_add_f32_e32 v42, 1.0, v42
	v_add_f32_e32 v43, 1.0, v43
	v_rcp_f32_e32 v44, v44
	v_rcp_f32_e32 v45, v45
	v_rcp_f32_e32 v46, v46
	v_rcp_f32_e32 v47, v47
	v_rcp_f32_e32 v40, v40
	v_rcp_f32_e32 v41, v41
	v_rcp_f32_e32 v42, v42
	v_rcp_f32_e32 v43, v43
	v_mul_f32_e32 v36, 0xbfb8aa3b, v36
	v_mul_f32_e32 v37, 0xbfb8aa3b, v37
	v_mul_f32_e32 v38, 0xbfb8aa3b, v38
	v_mul_f32_e32 v39, 0xbfb8aa3b, v39
	v_mul_f32_e32 v32, 0xbfb8aa3b, v32
	v_mul_f32_e32 v33, 0xbfb8aa3b, v33
	v_mul_f32_e32 v34, 0xbfb8aa3b, v34
	v_mul_f32_e32 v35, 0xbfb8aa3b, v35
	v_exp_f32_e32 v36, v36
	v_exp_f32_e32 v37, v37
	v_exp_f32_e32 v38, v38
	v_exp_f32_e32 v39, v39
	v_exp_f32_e32 v32, v32
	v_exp_f32_e32 v33, v33
	v_exp_f32_e32 v34, v34
	v_exp_f32_e32 v35, v35
	v_add_f32_e32 v36, 1.0, v36
	v_add_f32_e32 v37, 1.0, v37
	v_add_f32_e32 v38, 1.0, v38
	v_add_f32_e32 v39, 1.0, v39
	v_add_f32_e32 v32, 1.0, v32
	v_add_f32_e32 v33, 1.0, v33
	v_add_f32_e32 v34, 1.0, v34
	v_add_f32_e32 v35, 1.0, v35
	v_rcp_f32_e32 v36, v36
	v_rcp_f32_e32 v37, v37
	v_rcp_f32_e32 v38, v38
	v_rcp_f32_e32 v39, v39
	v_rcp_f32_e32 v32, v32
	v_rcp_f32_e32 v33, v33
	v_rcp_f32_e32 v34, v34
	v_rcp_f32_e32 v35, v35
	s_waitcnt vmcnt(12)
	v_lshlrev_b32_e32 v198, 16, v216
	v_and_b32_e32 v199, 0xffff0000, v216
	v_lshlrev_b32_e32 v200, 16, v220
	v_and_b32_e32 v201, 0xffff0000, v220
	v_fma_f32 v60, v60, v198, v200
	v_fma_f32 v61, v61, v199, v201
	v_cvt_pk_bf16_f32 v248, v60, v61
	v_lshlrev_b32_e32 v202, 16, v217
	v_and_b32_e32 v203, 0xffff0000, v217
	v_lshlrev_b32_e32 v214, 16, v221
	v_and_b32_e32 v215, 0xffff0000, v221
	v_fma_f32 v62, v62, v202, v214
	v_fma_f32 v63, v63, v203, v215
	v_cvt_pk_bf16_f32 v249, v62, v63
	v_lshlrev_b32_e32 v198, 16, v218
	v_and_b32_e32 v199, 0xffff0000, v218
	v_lshlrev_b32_e32 v200, 16, v222
	v_and_b32_e32 v201, 0xffff0000, v222
	v_fma_f32 v56, v56, v198, v200
	v_fma_f32 v57, v57, v199, v201
	v_cvt_pk_bf16_f32 v250, v56, v57
	v_lshlrev_b32_e32 v202, 16, v219
	v_and_b32_e32 v203, 0xffff0000, v219
	v_lshlrev_b32_e32 v214, 16, v223
	v_and_b32_e32 v215, 0xffff0000, v223
	v_fma_f32 v58, v58, v202, v214
	v_fma_f32 v59, v59, v203, v215
	v_cvt_pk_bf16_f32 v251, v58, v59
	global_store_dwordx4 v180, v[248:251], s[12:13]
	v_lshlrev_b32_e32 v198, 16, v224
	v_and_b32_e32 v199, 0xffff0000, v224
	v_lshlrev_b32_e32 v200, 16, v228
	v_and_b32_e32 v201, 0xffff0000, v228
	v_fma_f32 v52, v52, v198, v200
	v_fma_f32 v53, v53, v199, v201
	v_cvt_pk_bf16_f32 v252, v52, v53
	v_lshlrev_b32_e32 v202, 16, v225
	v_and_b32_e32 v203, 0xffff0000, v225
	v_lshlrev_b32_e32 v214, 16, v229
	v_and_b32_e32 v215, 0xffff0000, v229
	v_fma_f32 v54, v54, v202, v214
	v_fma_f32 v55, v55, v203, v215
	v_cvt_pk_bf16_f32 v253, v54, v55
	v_lshlrev_b32_e32 v198, 16, v226
	v_and_b32_e32 v199, 0xffff0000, v226
	v_lshlrev_b32_e32 v200, 16, v230
	v_and_b32_e32 v201, 0xffff0000, v230
	v_fma_f32 v48, v48, v198, v200
	v_fma_f32 v49, v49, v199, v201
	v_cvt_pk_bf16_f32 v254, v48, v49
	v_lshlrev_b32_e32 v202, 16, v227
	v_and_b32_e32 v203, 0xffff0000, v227
	v_lshlrev_b32_e32 v214, 16, v231
	v_and_b32_e32 v215, 0xffff0000, v231
	v_fma_f32 v50, v50, v202, v214
	v_fma_f32 v51, v51, v203, v215
	v_cvt_pk_bf16_f32 v255, v50, v51
	global_store_dwordx4 v181, v[252:255], s[12:13]
	v_lshlrev_b32_e32 v198, 16, v232
	v_and_b32_e32 v199, 0xffff0000, v232
	v_lshlrev_b32_e32 v200, 16, v236
	v_and_b32_e32 v201, 0xffff0000, v236
	v_fma_f32 v44, v44, v198, v200
	v_fma_f32 v45, v45, v199, v201
	v_cvt_pk_bf16_f32 v206, v44, v45
	v_lshlrev_b32_e32 v202, 16, v233
	v_and_b32_e32 v203, 0xffff0000, v233
	v_lshlrev_b32_e32 v214, 16, v237
	v_and_b32_e32 v215, 0xffff0000, v237
	v_fma_f32 v46, v46, v202, v214
	v_fma_f32 v47, v47, v203, v215
	v_cvt_pk_bf16_f32 v207, v46, v47
	v_lshlrev_b32_e32 v198, 16, v234
	v_and_b32_e32 v199, 0xffff0000, v234
	v_lshlrev_b32_e32 v200, 16, v238
	v_and_b32_e32 v201, 0xffff0000, v238
	v_fma_f32 v40, v40, v198, v200
	v_fma_f32 v41, v41, v199, v201
	v_cvt_pk_bf16_f32 v208, v40, v41
	v_lshlrev_b32_e32 v202, 16, v235
	v_and_b32_e32 v203, 0xffff0000, v235
	v_lshlrev_b32_e32 v214, 16, v239
	v_and_b32_e32 v215, 0xffff0000, v239
	v_fma_f32 v42, v42, v202, v214
; __device__ __forceinline__ unsigned cvt_pk_bf16(float lo, float hi) { f32x2 v = {lo, hi}; bf16x2_t b = __builtin_convertvector(v, bf16x2_t); return __builtin_bit_cast(unsigned, b); }
; __device__ __forceinline__ float bflo(unsigned w) { return __uint_as_float(w << 16); }
; __device__ __forceinline__ float bfhi(unsigned w) { return __uint_as_float(w & 0xffff0000u); }
; __device__ __forceinline__ float sigmoid_f(float x) { return __builtin_amdgcn_rcpf(1.0f + __expf(-x)); }
; __device__ __forceinline__ size_t tl(int r, int c, int K) { return ((size_t)(r >> 8) * (size_t)(K >> 6) + (size_t)(c >> 6)) * 16384 + (size_t)((r & 255) << 6) + (size_t)(c & 63); }
;     __device__ __forceinline__ void operator()(const f32x4 (&acc)[2][2][4][2], const Unit& u, int wr, int wc, int fr, int fq) const {
;     ...
;                 for (int mm = 0; mm < 2; ++mm) {
;                     const int m = mh * 2 + mm;
;                     const int rr = row0 + ai * HALF + m * 16;
; #pragma unroll
;                     for (int bj = 0; bj < 2; ++bj) {
;                         const f32x4 a0 = acc[ai][bj][m][0], a1 = acc[ai][bj][m][1];
;                         const u32x4 yv = yw[mm][bj], mv = mw[mm][bj];
;                         u32x4 w;
;                         w.x = cvt_pk_bf16(sigmoid_f(a0[0]) * bflo(yv.x) + bflo(mv.x), sigmoid_f(a0[1]) * bfhi(yv.x) + bfhi(mv.x));
;                         w.y = cvt_pk_bf16(sigmoid_f(a0[2]) * bflo(yv.y) + bflo(mv.y), sigmoid_f(a0[3]) * bfhi(yv.y) + bfhi(mv.y));
;                         w.z = cvt_pk_bf16(sigmoid_f(a1[0]) * bflo(yv.z) + bflo(mv.z), sigmoid_f(a1[1]) * bfhi(yv.z) + bfhi(mv.z));
;                         w.w = cvt_pk_bf16(sigmoid_f(a1[2]) * bflo(yv.w) + bflo(mv.w), sigmoid_f(a1[3]) * bfhi(yv.w) + bfhi(mv.w));
;                         *(u32x4*)(merged + tl(rr, col0 + bj * HALF, DM)) = w;
;                     }
	v_fma_f32 v43, v43, v203, v215
	v_cvt_pk_bf16_f32 v209, v42, v43
	global_store_dwordx4 v182, v[206:209], s[12:13]
	v_lshlrev_b32_e32 v198, 16, v240
	v_and_b32_e32 v199, 0xffff0000, v240
	v_lshlrev_b32_e32 v200, 16, v244
	v_and_b32_e32 v201, 0xffff0000, v244
	v_fma_f32 v36, v36, v198, v200
	v_fma_f32 v37, v37, v199, v201
	v_cvt_pk_bf16_f32 v210, v36, v37
	v_lshlrev_b32_e32 v202, 16, v241
	v_and_b32_e32 v203, 0xffff0000, v241
	v_lshlrev_b32_e32 v214, 16, v245
	v_and_b32_e32 v215, 0xffff0000, v245
	v_fma_f32 v38, v38, v202, v214
	v_fma_f32 v39, v39, v203, v215
	v_cvt_pk_bf16_f32 v211, v38, v39
	v_lshlrev_b32_e32 v198, 16, v242
	v_and_b32_e32 v199, 0xffff0000, v242
	v_lshlrev_b32_e32 v200, 16, v246
	v_and_b32_e32 v201, 0xffff0000, v246
	v_fma_f32 v32, v32, v198, v200
	v_fma_f32 v33, v33, v199, v201
	v_cvt_pk_bf16_f32 v212, v32, v33
	v_lshlrev_b32_e32 v202, 16, v243
	v_and_b32_e32 v203, 0xffff0000, v243
	v_lshlrev_b32_e32 v214, 16, v247
	v_and_b32_e32 v215, 0xffff0000, v247
	v_fma_f32 v34, v34, v202, v214
	v_fma_f32 v35, v35, v203, v215
	v_cvt_pk_bf16_f32 v213, v34, v35
	global_store_dwordx4 v183, v[210:213], s[12:13]
	v_mul_f32_e32 v28, 0xbfb8aa3b, v28
	v_mul_f32_e32 v29, 0xbfb8aa3b, v29
	v_mul_f32_e32 v30, 0xbfb8aa3b, v30
	v_mul_f32_e32 v31, 0xbfb8aa3b, v31
	v_mul_f32_e32 v24, 0xbfb8aa3b, v24
	v_mul_f32_e32 v25, 0xbfb8aa3b, v25
	v_mul_f32_e32 v26, 0xbfb8aa3b, v26
	v_mul_f32_e32 v27, 0xbfb8aa3b, v27
	v_exp_f32_e32 v28, v28
	v_exp_f32_e32 v29, v29
	v_exp_f32_e32 v30, v30
	v_exp_f32_e32 v31, v31
	v_exp_f32_e32 v24, v24
	v_exp_f32_e32 v25, v25
	v_exp_f32_e32 v26, v26
	v_exp_f32_e32 v27, v27
	v_add_f32_e32 v28, 1.0, v28
	v_add_f32_e32 v29, 1.0, v29
	v_add_f32_e32 v30, 1.0, v30
	v_add_f32_e32 v31, 1.0, v31
	v_add_f32_e32 v24, 1.0, v24
	v_add_f32_e32 v25, 1.0, v25
	v_add_f32_e32 v26, 1.0, v26
	v_add_f32_e32 v27, 1.0, v27
	v_rcp_f32_e32 v28, v28
	v_rcp_f32_e32 v29, v29
	v_rcp_f32_e32 v30, v30
	v_rcp_f32_e32 v31, v31
	v_rcp_f32_e32 v24, v24
	v_rcp_f32_e32 v25, v25
	v_rcp_f32_e32 v26, v26
	v_rcp_f32_e32 v27, v27
	v_mul_f32_e32 v20, 0xbfb8aa3b, v20
	v_mul_f32_e32 v21, 0xbfb8aa3b, v21
	v_mul_f32_e32 v22, 0xbfb8aa3b, v22
	v_mul_f32_e32 v23, 0xbfb8aa3b, v23
	v_mul_f32_e32 v16, 0xbfb8aa3b, v16
	v_mul_f32_e32 v17, 0xbfb8aa3b, v17
	v_mul_f32_e32 v18, 0xbfb8aa3b, v18
	v_mul_f32_e32 v19, 0xbfb8aa3b, v19
	v_exp_f32_e32 v20, v20
	v_exp_f32_e32 v21, v21
	v_exp_f32_e32 v22, v22
	v_exp_f32_e32 v23, v23
	v_exp_f32_e32 v16, v16
	v_exp_f32_e32 v17, v17
	v_exp_f32_e32 v18, v18
	v_exp_f32_e32 v19, v19
	v_add_f32_e32 v20, 1.0, v20
	v_add_f32_e32 v21, 1.0, v21
	v_add_f32_e32 v22, 1.0, v22
	v_add_f32_e32 v23, 1.0, v23
	v_add_f32_e32 v16, 1.0, v16
	v_add_f32_e32 v17, 1.0, v17
	v_add_f32_e32 v18, 1.0, v18
	v_add_f32_e32 v19, 1.0, v19
	v_rcp_f32_e32 v20, v20
	v_rcp_f32_e32 v21, v21
	v_rcp_f32_e32 v22, v22
	v_rcp_f32_e32 v23, v23
	v_rcp_f32_e32 v16, v16
	v_rcp_f32_e32 v17, v17
	v_rcp_f32_e32 v18, v18
	v_rcp_f32_e32 v19, v19
	v_mul_f32_e32 v12, 0xbfb8aa3b, v12
	v_mul_f32_e32 v13, 0xbfb8aa3b, v13
	v_mul_f32_e32 v14, 0xbfb8aa3b, v14
	v_mul_f32_e32 v15, 0xbfb8aa3b, v15
	v_mul_f32_e32 v8, 0xbfb8aa3b, v8
	v_mul_f32_e32 v9, 0xbfb8aa3b, v9
	v_mul_f32_e32 v10, 0xbfb8aa3b, v10
	v_mul_f32_e32 v11, 0xbfb8aa3b, v11
	v_exp_f32_e32 v12, v12
	v_exp_f32_e32 v13, v13
	v_exp_f32_e32 v14, v14
	v_exp_f32_e32 v15, v15
	v_exp_f32_e32 v8, v8
	v_exp_f32_e32 v9, v9
	v_exp_f32_e32 v10, v10
	v_exp_f32_e32 v11, v11
	v_add_f32_e32 v12, 1.0, v12
	v_add_f32_e32 v13, 1.0, v13
	v_add_f32_e32 v14, 1.0, v14
	v_add_f32_e32 v15, 1.0, v15
	v_add_f32_e32 v8, 1.0, v8
	v_add_f32_e32 v9, 1.0, v9
	v_add_f32_e32 v10, 1.0, v10
	v_add_f32_e32 v11, 1.0, v11
	v_rcp_f32_e32 v12, v12
	v_rcp_f32_e32 v13, v13
	v_rcp_f32_e32 v14, v14
	v_rcp_f32_e32 v15, v15
	v_rcp_f32_e32 v8, v8
	v_rcp_f32_e32 v9, v9
	v_rcp_f32_e32 v10, v10
	v_rcp_f32_e32 v11, v11
	v_mul_f32_e32 v4, 0xbfb8aa3b, v4
	v_mul_f32_e32 v5, 0xbfb8aa3b, v5
	v_mul_f32_e32 v6, 0xbfb8aa3b, v6
	v_mul_f32_e32 v7, 0xbfb8aa3b, v7
	v_mul_f32_e32 v0, 0xbfb8aa3b, v0
	v_mul_f32_e32 v1, 0xbfb8aa3b, v1
	v_mul_f32_e32 v2, 0xbfb8aa3b, v2
	v_mul_f32_e32 v3, 0xbfb8aa3b, v3
	v_exp_f32_e32 v4, v4
	v_exp_f32_e32 v5, v5
	v_exp_f32_e32 v6, v6
	v_exp_f32_e32 v7, v7
	v_exp_f32_e32 v0, v0
	v_exp_f32_e32 v1, v1
	v_exp_f32_e32 v2, v2
	v_exp_f32_e32 v3, v3
	v_add_f32_e32 v4, 1.0, v4
	v_add_f32_e32 v5, 1.0, v5
	v_add_f32_e32 v6, 1.0, v6
	v_add_f32_e32 v7, 1.0, v7
	v_add_f32_e32 v0, 1.0, v0
	v_add_f32_e32 v1, 1.0, v1
	v_add_f32_e32 v2, 1.0, v2
	v_add_f32_e32 v3, 1.0, v3
	v_rcp_f32_e32 v4, v4
	v_rcp_f32_e32 v5, v5
	v_rcp_f32_e32 v6, v6
	v_rcp_f32_e32 v7, v7
	v_rcp_f32_e32 v0, v0
	v_rcp_f32_e32 v1, v1
	v_rcp_f32_e32 v2, v2
	v_rcp_f32_e32 v3, v3
	s_waitcnt vmcnt(4)
; __device__ __forceinline__ unsigned cvt_pk_bf16(float lo, float hi) { f32x2 v = {lo, hi}; bf16x2_t b = __builtin_convertvector(v, bf16x2_t); return __builtin_bit_cast(unsigned, b); }
; __device__ __forceinline__ float bflo(unsigned w) { return __uint_as_float(w << 16); }
; __device__ __forceinline__ float bfhi(unsigned w) { return __uint_as_float(w & 0xffff0000u); }
; __device__ __forceinline__ float sigmoid_f(float x) { return __builtin_amdgcn_rcpf(1.0f + __expf(-x)); }
; __device__ __forceinline__ size_t tl(int r, int c, int K) { return ((size_t)(r >> 8) * (size_t)(K >> 6) + (size_t)(c >> 6)) * 16384 + (size_t)((r & 255) << 6) + (size_t)(c & 63); }
;     __device__ __forceinline__ void operator()(const f32x4 (&acc)[2][2][4][2], const Unit& u, int wr, int wc, int fr, int fq) const {
;     ...
;                 for (int mm = 0; mm < 2; ++mm) {
;                     const int m = mh * 2 + mm;
;                     const int rr = row0 + ai * HALF + m * 16;
; #pragma unroll
;                     for (int bj = 0; bj < 2; ++bj) {
;                         const f32x4 a0 = acc[ai][bj][m][0], a1 = acc[ai][bj][m][1];
;                         const u32x4 yv = yw[mm][bj], mv = mw[mm][bj];
;                         u32x4 w;
;                         w.x = cvt_pk_bf16(sigmoid_f(a0[0]) * bflo(yv.x) + bflo(mv.x), sigmoid_f(a0[1]) * bfhi(yv.x) + bfhi(mv.x));
;                         w.y = cvt_pk_bf16(sigmoid_f(a0[2]) * bflo(yv.y) + bflo(mv.y), sigmoid_f(a0[3]) * bfhi(yv.y) + bfhi(mv.y));
;                         w.z = cvt_pk_bf16(sigmoid_f(a1[0]) * bflo(yv.z) + bflo(mv.z), sigmoid_f(a1[1]) * bfhi(yv.z) + bfhi(mv.z));
;                         w.w = cvt_pk_bf16(sigmoid_f(a1[2]) * bflo(yv.w) + bflo(mv.w), sigmoid_f(a1[3]) * bfhi(yv.w) + bfhi(mv.w));
;                         *(u32x4*)(merged + tl(rr, col0 + bj * HALF, DM)) = w;
;                     }
	v_lshlrev_b32_e32 v198, 16, v128
	v_and_b32_e32 v199, 0xffff0000, v128
	v_lshlrev_b32_e32 v200, 16, v132
	v_and_b32_e32 v201, 0xffff0000, v132
	v_fma_f32 v28, v28, v198, v200
	v_fma_f32 v29, v29, v199, v201
	v_cvt_pk_bf16_f32 v248, v28, v29
	v_lshlrev_b32_e32 v202, 16, v129
	v_and_b32_e32 v203, 0xffff0000, v129
	v_lshlrev_b32_e32 v214, 16, v133
	v_and_b32_e32 v215, 0xffff0000, v133
	v_fma_f32 v30, v30, v202, v214
	v_fma_f32 v31, v31, v203, v215
	v_cvt_pk_bf16_f32 v249, v30, v31
	v_lshlrev_b32_e32 v198, 16, v130
	v_and_b32_e32 v199, 0xffff0000, v130
	v_lshlrev_b32_e32 v200, 16, v134
	v_and_b32_e32 v201, 0xffff0000, v134
	v_fma_f32 v24, v24, v198, v200
	v_fma_f32 v25, v25, v199, v201
	v_cvt_pk_bf16_f32 v250, v24, v25
	v_lshlrev_b32_e32 v202, 16, v131
	v_and_b32_e32 v203, 0xffff0000, v131
	v_lshlrev_b32_e32 v214, 16, v135
	v_and_b32_e32 v215, 0xffff0000, v135
	v_fma_f32 v26, v26, v202, v214
	v_fma_f32 v27, v27, v203, v215
	v_cvt_pk_bf16_f32 v251, v26, v27
	global_store_dwordx4 v194, v[248:251], s[12:13]
	v_lshlrev_b32_e32 v198, 16, v136
	v_and_b32_e32 v199, 0xffff0000, v136
	v_lshlrev_b32_e32 v200, 16, v140
	v_and_b32_e32 v201, 0xffff0000, v140
	v_fma_f32 v20, v20, v198, v200
	v_fma_f32 v21, v21, v199, v201
	v_cvt_pk_bf16_f32 v252, v20, v21
	v_lshlrev_b32_e32 v202, 16, v137
	v_and_b32_e32 v203, 0xffff0000, v137
	v_lshlrev_b32_e32 v214, 16, v141
	v_and_b32_e32 v215, 0xffff0000, v141
	v_fma_f32 v22, v22, v202, v214
	v_fma_f32 v23, v23, v203, v215
	v_cvt_pk_bf16_f32 v253, v22, v23
	v_lshlrev_b32_e32 v198, 16, v138
	v_and_b32_e32 v199, 0xffff0000, v138
	v_lshlrev_b32_e32 v200, 16, v142
	v_and_b32_e32 v201, 0xffff0000, v142
	v_fma_f32 v16, v16, v198, v200
	v_fma_f32 v17, v17, v199, v201
	v_cvt_pk_bf16_f32 v254, v16, v17
	v_lshlrev_b32_e32 v202, 16, v139
	v_and_b32_e32 v203, 0xffff0000, v139
	v_lshlrev_b32_e32 v214, 16, v143
	v_and_b32_e32 v215, 0xffff0000, v143
	v_fma_f32 v18, v18, v202, v214
	v_fma_f32 v19, v19, v203, v215
	v_cvt_pk_bf16_f32 v255, v18, v19
	global_store_dwordx4 v195, v[252:255], s[12:13]
	v_lshlrev_b32_e32 v198, 16, v144
	v_and_b32_e32 v199, 0xffff0000, v144
	v_lshlrev_b32_e32 v200, 16, v148
	v_and_b32_e32 v201, 0xffff0000, v148
	v_fma_f32 v12, v12, v198, v200
	v_fma_f32 v13, v13, v199, v201
	v_cvt_pk_bf16_f32 v206, v12, v13
	v_lshlrev_b32_e32 v202, 16, v145
	v_and_b32_e32 v203, 0xffff0000, v145
	v_lshlrev_b32_e32 v214, 16, v149
	v_and_b32_e32 v215, 0xffff0000, v149
	v_fma_f32 v14, v14, v202, v214
	v_fma_f32 v15, v15, v203, v215
	v_cvt_pk_bf16_f32 v207, v14, v15
	v_lshlrev_b32_e32 v198, 16, v146
	v_and_b32_e32 v199, 0xffff0000, v146
	v_lshlrev_b32_e32 v200, 16, v150
	v_and_b32_e32 v201, 0xffff0000, v150
	v_fma_f32 v8, v8, v198, v200
	v_fma_f32 v9, v9, v199, v201
	v_cvt_pk_bf16_f32 v208, v8, v9
	v_lshlrev_b32_e32 v202, 16, v147
	v_and_b32_e32 v203, 0xffff0000, v147
	v_lshlrev_b32_e32 v214, 16, v151
	v_and_b32_e32 v215, 0xffff0000, v151
	v_fma_f32 v10, v10, v202, v214
	v_fma_f32 v11, v11, v203, v215
	v_cvt_pk_bf16_f32 v209, v10, v11
	global_store_dwordx4 v196, v[206:209], s[12:13]
	v_lshlrev_b32_e32 v198, 16, v152
	v_and_b32_e32 v199, 0xffff0000, v152
	v_lshlrev_b32_e32 v200, 16, v156
	v_and_b32_e32 v201, 0xffff0000, v156
	v_fma_f32 v4, v4, v198, v200
	v_fma_f32 v5, v5, v199, v201
	v_cvt_pk_bf16_f32 v210, v4, v5
	v_lshlrev_b32_e32 v202, 16, v153
	v_and_b32_e32 v203, 0xffff0000, v153
	v_lshlrev_b32_e32 v214, 16, v157
	v_and_b32_e32 v215, 0xffff0000, v157
	v_fma_f32 v6, v6, v202, v214
	v_fma_f32 v7, v7, v203, v215
	v_cvt_pk_bf16_f32 v211, v6, v7
	v_lshlrev_b32_e32 v198, 16, v154
	v_and_b32_e32 v199, 0xffff0000, v154
	v_lshlrev_b32_e32 v200, 16, v158
	v_and_b32_e32 v201, 0xffff0000, v158
	v_fma_f32 v0, v0, v198, v200
	v_fma_f32 v1, v1, v199, v201
	v_cvt_pk_bf16_f32 v212, v0, v1
	v_lshlrev_b32_e32 v202, 16, v155
	v_and_b32_e32 v203, 0xffff0000, v155
	v_lshlrev_b32_e32 v214, 16, v159
	v_and_b32_e32 v215, 0xffff0000, v159
	v_fma_f32 v2, v2, v202, v214
	v_fma_f32 v3, v3, v203, v215
	v_cvt_pk_bf16_f32 v213, v2, v3
	global_store_dwordx4 v197, v[210:213], s[12:13]
	s_branch .Lmy_p9_latch

; #define PG8_STAGE(bufoff, gbase, voff) do { _Pragma("unroll") for (int _i = 0; _i < 2; ++_i) \
;         __builtin_amdgcn_global_load_lds((const unsigned*)((const char*)(gbase) + (voff)[_i]), (LAS unsigned*)(lds + (bufoff) + ldsw + _i * 8192), 16, 0, 0); } while (0)
; #define PG8_LDA(dst, b, h) do { _Pragma("unroll") for (int m = 0; m < 4; ++m) _Pragma("unroll") for (int k = 0; k < 2; ++k) dst[m][k] = *(const LAS bf16x8*)(lds + PG8_SA(b, h) + aoff + m * 2048 + k * 1024); } while (0)
; #define PG8_LDB(dst, b, h) do { _Pragma("unroll") for (int n = 0; n < 2; ++n) _Pragma("unroll") for (int k = 0; k < 2; ++k) dst[n][k] = *(const LAS bf16x8*)(lds + PG8_SB(b, h) + boff + n * 2048 + k * 1024); } while (0)
; #define PG8_MMA(ai, bj, At, Bt) do { __builtin_amdgcn_s_setprio(1); _Pragma("unroll") for (int m = 0; m < 4; ++m) _Pragma("unroll") for (int n = 0; n < 2; ++n) _Pragma("unroll") for (int k = 0; k < 2; ++k) \
;         acc[ai][bj][m][n] = __builtin_amdgcn_mfma_f32_16x16x32_bf16(Bt[n][k], At[m][k], acc[ai][bj][m][n], 0, 0, 0); __builtin_amdgcn_s_setprio(0); } while (0)
; #define PG8_WAIT_V(n) asm volatile("s_waitcnt vmcnt(" #n ")" ::: "memory")
; #define PG8_WAIT_L(n) asm volatile("s_waitcnt lgkmcnt(" #n ")" ::: "memory")
; #define PG8_BAR __builtin_amdgcn_s_barrier()
; #define PG8_SCHED __builtin_amdgcn_sched_barrier(0)
; template <class Epi, class Sched>
; __device__ __forceinline__ void gemm_phase(LAS unsigned char* lds, const Gemm g, const Sched& S, const Epi& E) {
;     ...
;             PG8_LDB(B0, 0, 0); PG8_SCHED; PG8_LDA(At, 0, 0); PG8_STAGE(PG8_SA(1, 1), a1 + hstep, voffA);
;             PG8_WAIT_L(8); PG8_BAR; PG8_WAIT_L(0); PG8_MMA(0, 0, At, B0); PG8_BAR; PG8_SCHED;
;             PG8_LDB(B1, 0, 1); PG8_STAGE(PG8_SB(0, 0), b2, voffB);
;             PG8_BAR; PG8_WAIT_L(0); PG8_MMA(0, 1, At, B1); PG8_BAR;
;             PG8_LDA(At, 0, 1); PG8_STAGE(PG8_SA(0, 0), a2, voffA);
;             PG8_BAR; PG8_WAIT_L(0); PG8_MMA(1, 0, At, B0); PG8_BAR; PG8_SCHED;
;             PG8_STAGE(PG8_SB(0, 1), b2 + hstep, voffB);
;             PG8_WAIT_V(6); PG8_BAR; PG8_MMA(1, 1, At, B1); PG8_BAR;
;             PG8_LDB(B0, 1, 0); PG8_SCHED; PG8_LDA(At, 1, 0); PG8_STAGE(PG8_SA(0, 1), a2 + hstep, voffA);
;             PG8_WAIT_L(8); PG8_BAR; PG8_WAIT_L(0); PG8_MMA(0, 0, At, B0); PG8_BAR; PG8_SCHED;
.LBB0_1429:
	ds_read_b128 v[128:131], v185
	ds_read_b128 v[132:135], v185 offset:1024
	ds_read_b128 v[136:139], v185 offset:2048
	ds_read_b128 v[140:143], v185 offset:3072
	s_add_u32 s50, s48, 0x4000
	s_addc_u32 s51, s49, 0
	s_cmp_eq_u32 s73, 28
	s_cselect_b32 s54, s67, s50
	s_cselect_b32 s55, s41, s51
	s_cselect_b32 s50, s68, s69
	s_cselect_b32 s51, s39, s72
	s_add_u32 s52, s54, 0x8000
	s_addc_u32 s53, s55, 0
	v_lshl_add_u64 v[180:181], s[48:49], 0, v[164:165]
	s_add_i32 m0, s47, 0xc000
	ds_read_b128 v[144:147], v186
	ds_read_b128 v[148:151], v186 offset:1024
	ds_read_b128 v[152:155], v186 offset:2048
	ds_read_b128 v[156:159], v186 offset:3072
	ds_read_b128 v[172:175], v186 offset:4096
	ds_read_b128 v[176:179], v186 offset:5120
	ds_read_b128 v[188:191], v186 offset:6144
	ds_read_b128 v[192:195], v186 offset:7168
	global_load_lds_dwordx4 v[180:181], off
	v_lshl_add_u64 v[180:181], s[48:49], 0, v[166:167]
	s_add_i32 m0, s47, 0xe000
	s_nop 0
	global_load_lds_dwordx4 v[180:181], off
	s_waitcnt lgkmcnt(8)
	s_barrier
	s_waitcnt lgkmcnt(0)
	v_mfma_f32_16x16x32_bf16 v[124:127], v[128:131], v[144:147], v[124:127]
	v_mfma_f32_16x16x32_bf16 v[120:123], v[136:139], v[144:147], v[120:123]
	v_mfma_f32_16x16x32_bf16 v[116:119], v[128:131], v[152:155], v[116:119]
	v_mfma_f32_16x16x32_bf16 v[104:107], v[136:139], v[152:155], v[104:107]
	v_mfma_f32_16x16x32_bf16 v[92:95], v[128:131], v[172:175], v[92:95]
	v_mfma_f32_16x16x32_bf16 v[88:91], v[136:139], v[172:175], v[88:91]
	v_mfma_f32_16x16x32_bf16 v[76:79], v[128:131], v[188:191], v[76:79]
	v_mfma_f32_16x16x32_bf16 v[72:75], v[136:139], v[188:191], v[72:75]
	v_mfma_f32_16x16x32_bf16 v[124:127], v[132:135], v[148:151], v[124:127]
	v_mfma_f32_16x16x32_bf16 v[120:123], v[140:143], v[148:151], v[120:123]
	v_mfma_f32_16x16x32_bf16 v[116:119], v[132:135], v[156:159], v[116:119]
	v_mfma_f32_16x16x32_bf16 v[104:107], v[140:143], v[156:159], v[104:107]
	v_mfma_f32_16x16x32_bf16 v[92:95], v[132:135], v[176:179], v[92:95]
	v_mfma_f32_16x16x32_bf16 v[88:91], v[140:143], v[176:179], v[88:91]
	v_mfma_f32_16x16x32_bf16 v[76:79], v[132:135], v[192:195], v[76:79]
	v_mfma_f32_16x16x32_bf16 v[72:75], v[140:143], v[192:195], v[72:75]
	s_barrier
	s_add_i32 s74, s71, s60
	v_lshl_add_u64 v[180:181], s[50:51], 0, v[160:161]
	s_mov_b32 m0, s74
	ds_read_b128 v[196:199], v187
	ds_read_b128 v[200:203], v187 offset:1024
	ds_read_b128 v[206:209], v187 offset:2048
	ds_read_b128 v[210:213], v187 offset:3072
	global_load_lds_dwordx4 v[180:181], off
	v_lshl_add_u64 v[180:181], s[50:51], 0, v[162:163]
	s_add_i32 m0, s74, 0x2000
	s_nop 0
	global_load_lds_dwordx4 v[180:181], off
	s_barrier
	s_waitcnt lgkmcnt(0)
	v_mfma_f32_16x16x32_bf16 v[112:115], v[196:199], v[144:147], v[112:115]
	v_mfma_f32_16x16x32_bf16 v[108:111], v[206:209], v[144:147], v[108:111]
	v_mfma_f32_16x16x32_bf16 v[100:103], v[196:199], v[152:155], v[100:103]
	v_mfma_f32_16x16x32_bf16 v[96:99], v[206:209], v[152:155], v[96:99]
	v_mfma_f32_16x16x32_bf16 v[84:87], v[196:199], v[172:175], v[84:87]
	v_mfma_f32_16x16x32_bf16 v[80:83], v[206:209], v[172:175], v[80:83]
	v_mfma_f32_16x16x32_bf16 v[68:71], v[196:199], v[188:191], v[68:71]
	v_mfma_f32_16x16x32_bf16 v[64:67], v[206:209], v[188:191], v[64:67]
	v_mfma_f32_16x16x32_bf16 v[112:115], v[200:203], v[148:151], v[112:115]
	v_mfma_f32_16x16x32_bf16 v[108:111], v[210:213], v[148:151], v[108:111]
	v_mfma_f32_16x16x32_bf16 v[100:103], v[200:203], v[156:159], v[100:103]
	v_mfma_f32_16x16x32_bf16 v[96:99], v[210:213], v[156:159], v[96:99]
	v_mfma_f32_16x16x32_bf16 v[84:87], v[200:203], v[176:179], v[84:87]
	v_mfma_f32_16x16x32_bf16 v[80:83], v[210:213], v[176:179], v[80:83]
	v_mfma_f32_16x16x32_bf16 v[68:71], v[200:203], v[192:195], v[68:71]
	v_mfma_f32_16x16x32_bf16 v[64:67], v[210:213], v[192:195], v[64:67]
	s_mov_b32 m0, s47
	v_lshl_add_u64 v[180:181], s[54:55], 0, v[160:161]
	s_barrier
	ds_read_b128 v[144:147], v186 offset:16384
	ds_read_b128 v[148:151], v186 offset:17408
	ds_read_b128 v[152:155], v186 offset:18432
	ds_read_b128 v[156:159], v186 offset:19456
	ds_read_b128 v[172:175], v186 offset:20480
	ds_read_b128 v[176:179], v186 offset:21504
	ds_read_b128 v[188:191], v186 offset:22528
	ds_read_b128 v[192:195], v186 offset:23552
	global_load_lds_dwordx4 v[180:181], off
	v_lshl_add_u64 v[180:181], s[54:55], 0, v[162:163]
	s_mov_b32 m0, s61
	s_nop 0
	global_load_lds_dwordx4 v[180:181], off
	s_barrier
	s_waitcnt lgkmcnt(0)
	v_mfma_f32_16x16x32_bf16 v[60:63], v[128:131], v[144:147], v[60:63]
	v_mfma_f32_16x16x32_bf16 v[56:59], v[136:139], v[144:147], v[56:59]
	v_mfma_f32_16x16x32_bf16 v[48:51], v[128:131], v[152:155], v[48:51]
	v_mfma_f32_16x16x32_bf16 v[40:43], v[136:139], v[152:155], v[40:43]
	v_mfma_f32_16x16x32_bf16 v[28:31], v[128:131], v[172:175], v[28:31]
	v_mfma_f32_16x16x32_bf16 v[24:27], v[136:139], v[172:175], v[24:27]
	v_mfma_f32_16x16x32_bf16 v[16:19], v[128:131], v[188:191], v[16:19]
	v_mfma_f32_16x16x32_bf16 v[8:11], v[136:139], v[188:191], v[8:11]
	v_mfma_f32_16x16x32_bf16 v[60:63], v[132:135], v[148:151], v[60:63]
	v_mfma_f32_16x16x32_bf16 v[56:59], v[140:143], v[148:151], v[56:59]
	v_mfma_f32_16x16x32_bf16 v[48:51], v[132:135], v[156:159], v[48:51]
	v_mfma_f32_16x16x32_bf16 v[40:43], v[140:143], v[156:159], v[40:43]
	v_mfma_f32_16x16x32_bf16 v[28:31], v[132:135], v[176:179], v[28:31]
	v_mfma_f32_16x16x32_bf16 v[24:27], v[140:143], v[176:179], v[24:27]
	v_mfma_f32_16x16x32_bf16 v[16:19], v[132:135], v[192:195], v[16:19]
	v_mfma_f32_16x16x32_bf16 v[8:11], v[140:143], v[192:195], v[8:11]
	s_barrier
; #define PG8_STAGE(bufoff, gbase, voff) do { _Pragma("unroll") for (int _i = 0; _i < 2; ++_i) \
;         __builtin_amdgcn_global_load_lds((const unsigned*)((const char*)(gbase) + (voff)[_i]), (LAS unsigned*)(lds + (bufoff) + ldsw + _i * 8192), 16, 0, 0); } while (0)
; #define PG8_LDA(dst, b, h) do { _Pragma("unroll") for (int m = 0; m < 4; ++m) _Pragma("unroll") for (int k = 0; k < 2; ++k) dst[m][k] = *(const LAS bf16x8*)(lds + PG8_SA(b, h) + aoff + m * 2048 + k * 1024); } while (0)
; #define PG8_LDB(dst, b, h) do { _Pragma("unroll") for (int n = 0; n < 2; ++n) _Pragma("unroll") for (int k = 0; k < 2; ++k) dst[n][k] = *(const LAS bf16x8*)(lds + PG8_SB(b, h) + boff + n * 2048 + k * 1024); } while (0)
; #define PG8_MMA(ai, bj, At, Bt) do { __builtin_amdgcn_s_setprio(1); _Pragma("unroll") for (int m = 0; m < 4; ++m) _Pragma("unroll") for (int n = 0; n < 2; ++n) _Pragma("unroll") for (int k = 0; k < 2; ++k) \
;         acc[ai][bj][m][n] = __builtin_amdgcn_mfma_f32_16x16x32_bf16(Bt[n][k], At[m][k], acc[ai][bj][m][n], 0, 0, 0); __builtin_amdgcn_s_setprio(0); } while (0)
; #define PG8_WAIT_V(n) asm volatile("s_waitcnt vmcnt(" #n ")" ::: "memory")
; #define PG8_WAIT_L(n) asm volatile("s_waitcnt lgkmcnt(" #n ")" ::: "memory")
; #define PG8_BAR __builtin_amdgcn_s_barrier()
; #define PG8_SCHED __builtin_amdgcn_sched_barrier(0)
; template <class Epi, class Sched>
; __device__ __forceinline__ void gemm_phase(LAS unsigned char* lds, const Gemm g, const Sched& S, const Epi& E) {
;     ...
;             PG8_BAR; PG8_WAIT_L(0); PG8_MMA(1, 0, At, B0); PG8_BAR; PG8_SCHED;
;             PG8_STAGE(PG8_SB(0, 1), b2 + hstep, voffB);
;             PG8_WAIT_V(6); PG8_BAR; PG8_MMA(1, 1, At, B1); PG8_BAR;
;             PG8_LDB(B0, 1, 0); PG8_SCHED; PG8_LDA(At, 1, 0); PG8_STAGE(PG8_SA(0, 1), a2 + hstep, voffA);
;             PG8_WAIT_L(8); PG8_BAR; PG8_WAIT_L(0); PG8_MMA(0, 0, At, B0); PG8_BAR; PG8_SCHED;
;             PG8_LDB(B1, 1, 1); PG8_STAGE(PG8_SB(1, 0), b3, voffB);
;             PG8_BAR; PG8_WAIT_L(0); PG8_MMA(0, 1, At, B1); PG8_BAR;
;             PG8_LDA(At, 1, 1); PG8_STAGE(PG8_SA(1, 0), a3, voffA);
;             PG8_BAR; PG8_WAIT_L(0); PG8_MMA(1, 0, At, B0); PG8_BAR; PG8_SCHED;
	s_add_u32 s74, s50, 0x4000
	s_addc_u32 s75, s51, 0
	s_add_i32 s76, s66, s60
	v_lshl_add_u64 v[128:129], s[74:75], 0, v[160:161]
	s_mov_b32 m0, s76
	s_nop 0
	global_load_lds_dwordx4 v[128:129], off
	v_lshl_add_u64 v[128:129], s[74:75], 0, v[162:163]
	s_add_i32 m0, s76, 0x2000
	s_nop 0
	global_load_lds_dwordx4 v[128:129], off
	s_waitcnt vmcnt(6)
	s_barrier
	v_mfma_f32_16x16x32_bf16 v[52:55], v[196:199], v[144:147], v[52:55]
	v_mfma_f32_16x16x32_bf16 v[44:47], v[206:209], v[144:147], v[44:47]
	v_mfma_f32_16x16x32_bf16 v[36:39], v[196:199], v[152:155], v[36:39]
	v_mfma_f32_16x16x32_bf16 v[32:35], v[206:209], v[152:155], v[32:35]
	v_mfma_f32_16x16x32_bf16 v[20:23], v[196:199], v[172:175], v[20:23]
	v_mfma_f32_16x16x32_bf16 v[12:15], v[206:209], v[172:175], v[12:15]
	v_mfma_f32_16x16x32_bf16 v[4:7], v[196:199], v[188:191], v[4:7]
	v_mfma_f32_16x16x32_bf16 v[0:3], v[206:209], v[188:191], v[0:3]
	v_mfma_f32_16x16x32_bf16 v[52:55], v[200:203], v[148:151], v[52:55]
	v_mfma_f32_16x16x32_bf16 v[44:47], v[210:213], v[148:151], v[44:47]
	v_mfma_f32_16x16x32_bf16 v[36:39], v[200:203], v[156:159], v[36:39]
	v_mfma_f32_16x16x32_bf16 v[32:35], v[210:213], v[156:159], v[32:35]
	v_mfma_f32_16x16x32_bf16 v[20:23], v[200:203], v[176:179], v[20:23]
	v_mfma_f32_16x16x32_bf16 v[12:15], v[210:213], v[176:179], v[12:15]
	v_mfma_f32_16x16x32_bf16 v[4:7], v[200:203], v[192:195], v[4:7]
	v_mfma_f32_16x16x32_bf16 v[0:3], v[210:213], v[192:195], v[0:3]
	s_add_i32 s74, 0, 0x18000
	v_add_u32_e32 v140, s74, v183
	s_barrier
	ds_read_b128 v[128:131], v140
	ds_read_b128 v[132:135], v140 offset:1024
	ds_read_b128 v[136:139], v140 offset:2048
	ds_read_b128 v[140:143], v140 offset:3072
	s_add_u32 s54, s54, 0x4000
	s_addc_u32 s55, s55, 0
	s_mov_b32 m0, s62
	v_lshl_add_u64 v[180:181], s[54:55], 0, v[160:161]
	ds_read_b128 v[144:147], v186 offset:32768
	ds_read_b128 v[148:151], v186 offset:33792
	ds_read_b128 v[152:155], v186 offset:34816
	ds_read_b128 v[156:159], v186 offset:35840
	ds_read_b128 v[172:175], v186 offset:36864
	ds_read_b128 v[176:179], v186 offset:37888
	ds_read_b128 v[188:191], v186 offset:38912
	ds_read_b128 v[192:195], v186 offset:39936
	global_load_lds_dwordx4 v[180:181], off
	v_lshl_add_u64 v[180:181], s[54:55], 0, v[162:163]
	s_mov_b32 m0, s63
	s_nop 0
	global_load_lds_dwordx4 v[180:181], off
	s_waitcnt lgkmcnt(8)
	s_barrier
	s_waitcnt lgkmcnt(0)
	v_mfma_f32_16x16x32_bf16 v[124:127], v[128:131], v[144:147], v[124:127]
	v_mfma_f32_16x16x32_bf16 v[120:123], v[136:139], v[144:147], v[120:123]
	v_mfma_f32_16x16x32_bf16 v[116:119], v[128:131], v[152:155], v[116:119]
	v_mfma_f32_16x16x32_bf16 v[104:107], v[136:139], v[152:155], v[104:107]
	v_mfma_f32_16x16x32_bf16 v[92:95], v[128:131], v[172:175], v[92:95]
	v_mfma_f32_16x16x32_bf16 v[88:91], v[136:139], v[172:175], v[88:91]
	v_mfma_f32_16x16x32_bf16 v[76:79], v[128:131], v[188:191], v[76:79]
	v_mfma_f32_16x16x32_bf16 v[72:75], v[136:139], v[188:191], v[72:75]
	v_mfma_f32_16x16x32_bf16 v[124:127], v[132:135], v[148:151], v[124:127]
	v_mfma_f32_16x16x32_bf16 v[120:123], v[140:143], v[148:151], v[120:123]
	v_mfma_f32_16x16x32_bf16 v[116:119], v[132:135], v[156:159], v[116:119]
	v_mfma_f32_16x16x32_bf16 v[104:107], v[140:143], v[156:159], v[104:107]
	v_mfma_f32_16x16x32_bf16 v[92:95], v[132:135], v[176:179], v[92:95]
	v_mfma_f32_16x16x32_bf16 v[88:91], v[140:143], v[176:179], v[88:91]
	v_mfma_f32_16x16x32_bf16 v[76:79], v[132:135], v[192:195], v[76:79]
	v_mfma_f32_16x16x32_bf16 v[72:75], v[140:143], v[192:195], v[72:75]
	s_barrier
	s_add_i32 s75, 0, 0x1c000
	s_add_u32 s54, s50, 0x8000
	v_add_u32_e32 v180, s75, v183
	s_addc_u32 s55, s51, 0
	s_add_i32 s74, s74, s60
	ds_read_b128 v[196:199], v180
	ds_read_b128 v[200:203], v180 offset:1024
	ds_read_b128 v[206:209], v180 offset:2048
	ds_read_b128 v[210:213], v180 offset:3072
	v_lshl_add_u64 v[180:181], s[54:55], 0, v[160:161]
	s_mov_b32 m0, s74
	s_nop 0
	global_load_lds_dwordx4 v[180:181], off
	v_lshl_add_u64 v[180:181], s[54:55], 0, v[162:163]
	s_add_i32 m0, s74, 0x2000
	s_nop 0
	global_load_lds_dwordx4 v[180:181], off
	s_barrier
	s_waitcnt lgkmcnt(0)
	v_mfma_f32_16x16x32_bf16 v[112:115], v[196:199], v[144:147], v[112:115]
	v_mfma_f32_16x16x32_bf16 v[108:111], v[206:209], v[144:147], v[108:111]
	v_mfma_f32_16x16x32_bf16 v[100:103], v[196:199], v[152:155], v[100:103]
	v_mfma_f32_16x16x32_bf16 v[96:99], v[206:209], v[152:155], v[96:99]
	v_mfma_f32_16x16x32_bf16 v[84:87], v[196:199], v[172:175], v[84:87]
	v_mfma_f32_16x16x32_bf16 v[80:83], v[206:209], v[172:175], v[80:83]
	v_mfma_f32_16x16x32_bf16 v[68:71], v[196:199], v[188:191], v[68:71]
	v_mfma_f32_16x16x32_bf16 v[64:67], v[206:209], v[188:191], v[64:67]
	v_mfma_f32_16x16x32_bf16 v[112:115], v[200:203], v[148:151], v[112:115]
	v_mfma_f32_16x16x32_bf16 v[108:111], v[210:213], v[148:151], v[108:111]
	v_mfma_f32_16x16x32_bf16 v[100:103], v[200:203], v[156:159], v[100:103]
	v_mfma_f32_16x16x32_bf16 v[96:99], v[210:213], v[156:159], v[96:99]
	v_mfma_f32_16x16x32_bf16 v[84:87], v[200:203], v[176:179], v[84:87]
	v_mfma_f32_16x16x32_bf16 v[80:83], v[210:213], v[176:179], v[80:83]
	v_mfma_f32_16x16x32_bf16 v[68:71], v[200:203], v[192:195], v[68:71]
	v_mfma_f32_16x16x32_bf16 v[64:67], v[210:213], v[192:195], v[64:67]
	s_mov_b32 m0, s15
	v_lshl_add_u64 v[180:181], s[52:53], 0, v[160:161]
	s_barrier
	ds_read_b128 v[144:147], v186 offset:49152
	ds_read_b128 v[148:151], v186 offset:50176
	ds_read_b128 v[152:155], v186 offset:51200
	ds_read_b128 v[156:159], v186 offset:52224
	ds_read_b128 v[172:175], v186 offset:53248
	ds_read_b128 v[176:179], v186 offset:54272
	ds_read_b128 v[188:191], v186 offset:55296
	ds_read_b128 v[192:195], v186 offset:56320
	global_load_lds_dwordx4 v[180:181], off
	v_lshl_add_u64 v[180:181], s[52:53], 0, v[162:163]
	s_mov_b32 m0, s65
	s_nop 0
	global_load_lds_dwordx4 v[180:181], off
	s_barrier
; #define PG8_STAGE(bufoff, gbase, voff) do { _Pragma("unroll") for (int _i = 0; _i < 2; ++_i) \
;         __builtin_amdgcn_global_load_lds((const unsigned*)((const char*)(gbase) + (voff)[_i]), (LAS unsigned*)(lds + (bufoff) + ldsw + _i * 8192), 16, 0, 0); } while (0)
; #define PG8_MMA(ai, bj, At, Bt) do { __builtin_amdgcn_s_setprio(1); _Pragma("unroll") for (int m = 0; m < 4; ++m) _Pragma("unroll") for (int n = 0; n < 2; ++n) _Pragma("unroll") for (int k = 0; k < 2; ++k) \
;         acc[ai][bj][m][n] = __builtin_amdgcn_mfma_f32_16x16x32_bf16(Bt[n][k], At[m][k], acc[ai][bj][m][n], 0, 0, 0); __builtin_amdgcn_s_setprio(0); } while (0)
; #define PG8_BAR __builtin_amdgcn_s_barrier()
; template <class Epi, class Sched>
; __device__ __forceinline__ void gemm_phase(LAS unsigned char* lds, const Gemm g, const Sched& S, const Epi& E) {
;     ...
;             PG8_BAR; PG8_WAIT_L(0); PG8_MMA(1, 0, At, B0); PG8_BAR; PG8_SCHED;
;             PG8_STAGE(PG8_SB(1, 1), b3 + hstep, voffB);
;             PG8_WAIT_V(6); PG8_BAR; PG8_MMA(1, 1, At, B1); PG8_BAR;
;         }
;         E(acc, cur, wr, wc, fr, fq);
;     __device__ __forceinline__ void operator()(const f32x4 (&acc)[2][2][4][2], const Unit& u, int wr, int wc, int fr, int fq) const {
;         const int row0 = u.pm * BM + wr * 64 + fr, col0 = u.pn * BM + wc * 32 + 4 * fq;
;         f32x4 gv[2][2], bv[2][2];
;         if (MODE == 1) {
; #pragma unroll
;             for (int bj = 0; bj < 2; ++bj)
; #pragma unroll
;                 for (int n = 0; n < 2; ++n) { gv[bj][n] = *(const f32x4*)(g + col0 + bj * HALF + n * 16); bv[bj][n] = *(const f32x4*)(b + col0 + bj * HALF + n * 16); }
;         }
; #pragma unroll
;         for (int ai = 0; ai < 2; ++ai)
; #pragma unroll
;             for (int mh = 0; mh < 2; ++mh) {
;                 f32x4 rv[2][2][2]; f32x2 st[2];
; #pragma unroll
;                 for (int mm = 0; mm < 2; ++mm) {
;                     const int r = row0 + ai * HALF + (mh * 2 + mm) * 16;
;                     const float* rp = MODE == 0 ? ((r < 8192 ? x0 + (size_t)r * DM : x1 + (size_t)(r - 8192) * DM) + col0) : (Z + (size_t)r * DM + col0);
;                     if (MODE == 1) st[mm] = stats[r];
; #pragma unroll
;                     for (int bj = 0; bj < 2; ++bj)
; #pragma unroll
;                         for (int n = 0; n < 2; ++n) rv[mm][bj][n] = *(const f32x4*)(rp + bj * HALF + n * 16);
;                 }
	s_waitcnt lgkmcnt(0)
	v_mfma_f32_16x16x32_bf16 v[60:63], v[128:131], v[144:147], v[60:63]
	v_mfma_f32_16x16x32_bf16 v[56:59], v[136:139], v[144:147], v[56:59]
	v_mfma_f32_16x16x32_bf16 v[48:51], v[128:131], v[152:155], v[48:51]
	v_mfma_f32_16x16x32_bf16 v[40:43], v[136:139], v[152:155], v[40:43]
	v_mfma_f32_16x16x32_bf16 v[28:31], v[128:131], v[172:175], v[28:31]
	v_mfma_f32_16x16x32_bf16 v[24:27], v[136:139], v[172:175], v[24:27]
	v_mfma_f32_16x16x32_bf16 v[16:19], v[128:131], v[188:191], v[16:19]
	v_mfma_f32_16x16x32_bf16 v[8:11], v[136:139], v[188:191], v[8:11]
	v_mfma_f32_16x16x32_bf16 v[60:63], v[132:135], v[148:151], v[60:63]
	v_mfma_f32_16x16x32_bf16 v[56:59], v[140:143], v[148:151], v[56:59]
	v_mfma_f32_16x16x32_bf16 v[48:51], v[132:135], v[156:159], v[48:51]
	v_mfma_f32_16x16x32_bf16 v[40:43], v[140:143], v[156:159], v[40:43]
	v_mfma_f32_16x16x32_bf16 v[28:31], v[132:135], v[176:179], v[28:31]
	v_mfma_f32_16x16x32_bf16 v[24:27], v[140:143], v[176:179], v[24:27]
	v_mfma_f32_16x16x32_bf16 v[16:19], v[132:135], v[192:195], v[16:19]
	v_mfma_f32_16x16x32_bf16 v[8:11], v[140:143], v[192:195], v[8:11]
	s_barrier
	s_add_u32 s50, s50, 0xc000
	s_addc_u32 s51, s51, 0
	s_add_i32 s52, s75, s60
	v_lshl_add_u64 v[128:129], s[50:51], 0, v[160:161]
	s_mov_b32 m0, s52
	s_nop 0
	global_load_lds_dwordx4 v[128:129], off
	v_lshl_add_u64 v[128:129], s[50:51], 0, v[162:163]
	s_add_i32 m0, s52, 0x2000
	s_nop 0
	global_load_lds_dwordx4 v[128:129], off
	s_waitcnt vmcnt(6)
	s_barrier
	v_mfma_f32_16x16x32_bf16 v[52:55], v[196:199], v[144:147], v[52:55]
	v_mfma_f32_16x16x32_bf16 v[44:47], v[206:209], v[144:147], v[44:47]
	v_mfma_f32_16x16x32_bf16 v[36:39], v[196:199], v[152:155], v[36:39]
	v_mfma_f32_16x16x32_bf16 v[32:35], v[206:209], v[152:155], v[32:35]
	v_mfma_f32_16x16x32_bf16 v[20:23], v[196:199], v[172:175], v[20:23]
	v_mfma_f32_16x16x32_bf16 v[12:15], v[206:209], v[172:175], v[12:15]
	v_mfma_f32_16x16x32_bf16 v[4:7], v[196:199], v[188:191], v[4:7]
	v_mfma_f32_16x16x32_bf16 v[0:3], v[206:209], v[188:191], v[0:3]
	v_mfma_f32_16x16x32_bf16 v[52:55], v[200:203], v[148:151], v[52:55]
	v_mfma_f32_16x16x32_bf16 v[44:47], v[210:213], v[148:151], v[44:47]
	v_mfma_f32_16x16x32_bf16 v[36:39], v[200:203], v[156:159], v[36:39]
	v_mfma_f32_16x16x32_bf16 v[32:35], v[210:213], v[156:159], v[32:35]
	v_mfma_f32_16x16x32_bf16 v[20:23], v[200:203], v[176:179], v[20:23]
	v_mfma_f32_16x16x32_bf16 v[12:15], v[210:213], v[176:179], v[12:15]
	v_mfma_f32_16x16x32_bf16 v[4:7], v[200:203], v[192:195], v[4:7]
	v_mfma_f32_16x16x32_bf16 v[0:3], v[210:213], v[192:195], v[0:3]
	s_add_i32 s73, s73, 2
	s_add_u32 s48, s48, 0x10000
	s_addc_u32 s49, s49, 0
	s_add_u32 s69, s69, 0x10000
	s_addc_u32 s72, s72, 0
	s_cmp_gt_u32 s73, 29
	s_barrier
	s_cbranch_scc0 .LBB0_1429
	v_lshl_or_b32 v128, s33, 8, v184
	v_ashrrev_i32_e32 v129, 31, v128
	v_lshl_add_u32 v180, s46, 8, v182
	v_lshlrev_b64 v[172:173], 2, v[128:129]
	v_ashrrev_i32_e32 v181, 31, v180
	v_lshl_add_u64 v[174:175], s[12:13], 0, v[172:173]
	v_lshlrev_b64 v[176:177], 13, v[180:181]
	v_or_b32_e32 v130, 16, v180
	v_lshl_add_u64 v[128:129], v[174:175], 0, v[176:177]
	v_lshl_add_u64 v[178:179], v[180:181], 3, s[10:11]
	v_ashrrev_i32_e32 v131, 31, v130
	global_load_dwordx2 v[222:223], v[178:179], off
	global_load_dwordx4 v[188:191], v[128:129], off
	global_load_dwordx4 v[192:195], v[128:129], off offset:64
	global_load_dwordx4 v[196:199], v[128:129], off offset:512
	v_lshlrev_b64 v[224:225], 13, v[130:131]
	global_load_dwordx4 v[200:203], v[128:129], off offset:576
	v_lshl_add_u64 v[128:129], v[130:131], 3, s[10:11]
	v_lshl_add_u64 v[218:219], v[174:175], 0, v[224:225]
	global_load_dwordx2 v[226:227], v[128:129], off
	global_load_dwordx4 v[206:209], v[218:219], off
	v_lshl_add_u64 v[128:129], s[16:17], 0, v[172:173]
	v_lshl_add_u64 v[132:133], s[18:19], 0, v[172:173]
	global_load_dwordx4 v[152:155], v[132:133], off
	global_load_dwordx4 v[156:159], v[128:129], off
	global_load_dwordx4 v[144:147], v[128:129], off offset:64
	global_load_dwordx4 v[148:151], v[132:133], off offset:64
	global_load_dwordx4 v[136:139], v[132:133], off offset:512
	global_load_dwordx4 v[140:143], v[128:129], off offset:512
	s_nop 0
	global_load_dwordx4 v[128:131], v[128:129], off offset:576
	s_nop 0
	global_load_dwordx4 v[132:135], v[132:133], off offset:576
	s_nop 0
	global_load_dwordx4 v[210:213], v[218:219], off offset:64
	global_load_dwordx4 v[214:217], v[218:219], off offset:512
	v_lshl_add_u64 v[220:221], s[12:13], 0, v[176:177]
	v_lshl_add_u64 v[228:229], v[220:221], 0, v[172:173]
	global_load_dwordx4 v[218:221], v[218:219], off offset:576
	v_lshl_add_u64 v[224:225], s[12:13], 0, v[224:225]
	v_lshl_add_u64 v[224:225], v[224:225], 0, v[172:173]
	s_and_b64 vcc, exec, s[8:9]
	s_mov_b32 s33, s38
	s_mov_b32 s46, s40
	s_mov_b64 s[50:51], s[44:45]
	s_mov_b64 s[48:49], s[42:43]
	s_waitcnt vmcnt(0)
;     __device__ __forceinline__ void operator()(const f32x4 (&acc)[2][2][4][2], const Unit& u, int wr, int wc, int fr, int fq) const {
;     ...
; #pragma unroll
;         for (int ai = 0; ai < 2; ++ai)
; #pragma unroll
;             for (int mh = 0; mh < 2; ++mh) {
;                 f32x4 rv[2][2][2]; f32x2 st[2];
; #pragma unroll
;                 for (int mm = 0; mm < 2; ++mm) {
;                     const int r = row0 + ai * HALF + (mh * 2 + mm) * 16;
;                     const float* rp = MODE == 0 ? ((r < 8192 ? x0 + (size_t)r * DM : x1 + (size_t)(r - 8192) * DM) + col0) : (Z + (size_t)r * DM + col0);
;                     if (MODE == 1) st[mm] = stats[r];
; #pragma unroll
;                     for (int bj = 0; bj < 2; ++bj)
; #pragma unroll
;                         for (int n = 0; n < 2; ++n) rv[mm][bj][n] = *(const f32x4*)(rp + bj * HALF + n * 16);
;                 }
; #pragma unroll
;                 for (int mm = 0; mm < 2; ++mm) {
;                     const int m = mh * 2 + mm, r = row0 + ai * HALF + m * 16;
;                     float* zp = Z + (size_t)r * DM + col0;
; #pragma unroll
;                     for (int bj = 0; bj < 2; ++bj)
; #pragma unroll
;                         for (int n = 0; n < 2; ++n) {
;                             f32x4 res = rv[mm][bj][n];
;                             if (MODE == 1) res = (res - st[mm].x) * st[mm].y * gv[bj][n] + bv[bj][n];
;                             *(f32x4*)(zp + bj * HALF + n * 16) = res * ALPHA + acc[ai][bj][m][n] * scale;
;                         }
;                 }
;             }
	v_sub_f32_e32 v189, v189, v222
	v_sub_f32_e32 v188, v188, v222
	v_sub_f32_e32 v191, v191, v222
	v_sub_f32_e32 v190, v190, v222
	v_sub_f32_e32 v201, v201, v222
	v_sub_f32_e32 v200, v200, v222
	v_sub_f32_e32 v203, v203, v222
	v_sub_f32_e32 v202, v202, v222
	v_sub_f32_e32 v193, v193, v222
	v_sub_f32_e32 v192, v192, v222
	v_sub_f32_e32 v195, v195, v222
	v_sub_f32_e32 v194, v194, v222
	v_sub_f32_e32 v197, v197, v222
	v_sub_f32_e32 v196, v196, v222
	v_sub_f32_e32 v199, v199, v222
	v_sub_f32_e32 v198, v198, v222
	v_sub_f32_e32 v207, v207, v226
	v_sub_f32_e32 v206, v206, v226
	v_sub_f32_e32 v209, v209, v226
	v_sub_f32_e32 v208, v208, v226
	v_pk_mul_f32 v[190:191], v[222:223], v[190:191] op_sel:[1,0]
	v_pk_mul_f32 v[188:189], v[222:223], v[188:189] op_sel:[1,0]
	v_pk_mul_f32 v[202:203], v[222:223], v[202:203] op_sel:[1,0]
	v_pk_mul_f32 v[200:201], v[222:223], v[200:201] op_sel:[1,0]
	v_pk_mul_f32 v[194:195], v[222:223], v[194:195] op_sel:[1,0]
	v_pk_mul_f32 v[192:193], v[222:223], v[192:193] op_sel:[1,0]
	v_pk_mul_f32 v[198:199], v[222:223], v[198:199] op_sel:[1,0]
	v_pk_mul_f32 v[196:197], v[222:223], v[196:197] op_sel:[1,0]
	v_pk_mul_f32 v[208:209], v[226:227], v[208:209] op_sel:[1,0]
	v_pk_mul_f32 v[206:207], v[226:227], v[206:207] op_sel:[1,0]
	v_pk_fma_f32 v[188:189], v[156:157], v[188:189], v[152:153]
	v_pk_fma_f32 v[190:191], v[158:159], v[190:191], v[154:155]
	v_pk_fma_f32 v[200:201], v[128:129], v[200:201], v[132:133]
	v_pk_fma_f32 v[202:203], v[130:131], v[202:203], v[134:135]
	v_pk_fma_f32 v[192:193], v[144:145], v[192:193], v[148:149]
	v_pk_fma_f32 v[194:195], v[146:147], v[194:195], v[150:151]
	v_pk_fma_f32 v[196:197], v[140:141], v[196:197], v[136:137]
	v_pk_fma_f32 v[198:199], v[142:143], v[198:199], v[138:139]
	v_pk_fma_f32 v[206:207], v[156:157], v[206:207], v[152:153]
	v_pk_fma_f32 v[208:209], v[158:159], v[208:209], v[154:155]
	v_pk_fma_f32 v[126:127], v[190:191], s[14:15], v[126:127] op_sel_hi:[1,0,1]
	v_pk_fma_f32 v[124:125], v[188:189], s[14:15], v[124:125] op_sel_hi:[1,0,1]
	v_pk_fma_f32 v[110:111], v[202:203], s[14:15], v[110:111] op_sel_hi:[1,0,1]
	v_pk_fma_f32 v[108:109], v[200:201], s[14:15], v[108:109] op_sel_hi:[1,0,1]
	v_pk_fma_f32 v[122:123], v[194:195], s[14:15], v[122:123] op_sel_hi:[1,0,1]
	v_pk_fma_f32 v[120:121], v[192:193], s[14:15], v[120:121] op_sel_hi:[1,0,1]
	v_pk_fma_f32 v[114:115], v[198:199], s[14:15], v[114:115] op_sel_hi:[1,0,1]
	v_pk_fma_f32 v[112:113], v[196:197], s[14:15], v[112:113] op_sel_hi:[1,0,1]
	global_store_dwordx4 v[228:229], v[124:127], off
	global_store_dwordx4 v[228:229], v[120:123], off offset:64
	global_store_dwordx4 v[228:229], v[112:115], off offset:512
	global_store_dwordx4 v[228:229], v[108:111], off offset:576
	s_nop 0
	v_or_b32_e32 v112, 48, v180
	v_pk_fma_f32 v[110:111], v[208:209], s[14:15], v[118:119] op_sel_hi:[1,0,1]
	v_pk_fma_f32 v[108:109], v[206:207], s[14:15], v[116:117] op_sel_hi:[1,0,1]
	global_store_dwordx4 v[224:225], v[108:111], off
	v_ashrrev_i32_e32 v113, 31, v112
	s_nop 0
	v_sub_f32_e32 v109, v211, v226
	v_sub_f32_e32 v108, v210, v226
	v_sub_f32_e32 v111, v213, v226
	v_sub_f32_e32 v110, v212, v226
	v_pk_mul_f32 v[110:111], v[226:227], v[110:111] op_sel:[1,0]
	v_pk_mul_f32 v[108:109], v[226:227], v[108:109] op_sel:[1,0]
	v_pk_fma_f32 v[110:111], v[146:147], v[110:111], v[150:151]
	v_pk_fma_f32 v[108:109], v[144:145], v[108:109], v[148:149]
	v_pk_fma_f32 v[106:107], v[110:111], s[14:15], v[106:107] op_sel_hi:[1,0,1]
	v_pk_fma_f32 v[104:105], v[108:109], s[14:15], v[104:105] op_sel_hi:[1,0,1]
	global_store_dwordx4 v[224:225], v[104:107], off offset:64
	s_nop 1
	v_sub_f32_e32 v105, v215, v226
	v_sub_f32_e32 v104, v214, v226
	v_sub_f32_e32 v107, v217, v226
	v_sub_f32_e32 v106, v216, v226
	v_pk_mul_f32 v[106:107], v[226:227], v[106:107] op_sel:[1,0]
	v_pk_mul_f32 v[104:105], v[226:227], v[104:105] op_sel:[1,0]
	v_pk_fma_f32 v[106:107], v[142:143], v[106:107], v[138:139]
	v_pk_fma_f32 v[104:105], v[140:141], v[104:105], v[136:137]
	v_pk_fma_f32 v[102:103], v[106:107], s[14:15], v[102:103] op_sel_hi:[1,0,1]
	v_pk_fma_f32 v[100:101], v[104:105], s[14:15], v[100:101] op_sel_hi:[1,0,1]
	global_store_dwordx4 v[224:225], v[100:103], off offset:512
	s_nop 1
	v_sub_f32_e32 v101, v219, v226
	v_sub_f32_e32 v100, v218, v226
	v_sub_f32_e32 v103, v221, v226
	v_sub_f32_e32 v102, v220, v226
	v_pk_mul_f32 v[102:103], v[226:227], v[102:103] op_sel:[1,0]
	v_pk_mul_f32 v[100:101], v[226:227], v[100:101] op_sel:[1,0]
	v_pk_fma_f32 v[102:103], v[130:131], v[102:103], v[134:135]
	v_pk_fma_f32 v[100:101], v[128:129], v[100:101], v[132:133]
	v_pk_fma_f32 v[98:99], v[102:103], s[14:15], v[98:99] op_sel_hi:[1,0,1]
	v_pk_fma_f32 v[96:97], v[100:101], s[14:15], v[96:97] op_sel_hi:[1,0,1]
	global_store_dwordx4 v[224:225], v[96:99], off offset:576
	s_nop 1
	v_or_b32_e32 v96, 32, v180
	v_ashrrev_i32_e32 v97, 31, v96
	v_lshlrev_b64 v[124:125], 13, v[96:97]
	v_lshl_add_u64 v[108:109], v[174:175], 0, v[124:125]
	v_lshl_add_u64 v[96:97], v[96:97], 3, s[10:11]
	global_load_dwordx2 v[188:189], v[96:97], off
	s_nop 0
	global_load_dwordx4 v[96:99], v[108:109], off
	global_load_dwordx4 v[100:103], v[108:109], off offset:64
	global_load_dwordx4 v[104:107], v[108:109], off offset:512
	s_nop 0
	global_load_dwordx4 v[108:111], v[108:109], off offset:576
	v_lshlrev_b64 v[180:181], 13, v[112:113]
	v_lshl_add_u64 v[112:113], v[112:113], 3, s[10:11]
	v_lshl_add_u64 v[126:127], v[174:175], 0, v[180:181]
	global_load_dwordx2 v[190:191], v[112:113], off
	s_nop 0
	global_load_dwordx4 v[112:115], v[126:127], off
	global_load_dwordx4 v[116:119], v[126:127], off offset:64
	global_load_dwordx4 v[120:123], v[126:127], off offset:512
	v_lshl_add_u64 v[192:193], s[12:13], 0, v[124:125]
	global_load_dwordx4 v[124:127], v[126:127], off offset:576
	v_lshl_add_u64 v[192:193], v[192:193], 0, v[172:173]
	s_waitcnt vmcnt(0)
;     __device__ __forceinline__ void operator()(const f32x4 (&acc)[2][2][4][2], const Unit& u, int wr, int wc, int fr, int fq) const {
;     ...
; #pragma unroll
;         for (int ai = 0; ai < 2; ++ai)
; #pragma unroll
;             for (int mh = 0; mh < 2; ++mh) {
;                 f32x4 rv[2][2][2]; f32x2 st[2];
; #pragma unroll
;                 for (int mm = 0; mm < 2; ++mm) {
;                     const int r = row0 + ai * HALF + (mh * 2 + mm) * 16;
;                     const float* rp = MODE == 0 ? ((r < 8192 ? x0 + (size_t)r * DM : x1 + (size_t)(r - 8192) * DM) + col0) : (Z + (size_t)r * DM + col0);
;                     if (MODE == 1) st[mm] = stats[r];
; #pragma unroll
;                     for (int bj = 0; bj < 2; ++bj)
; #pragma unroll
;                         for (int n = 0; n < 2; ++n) rv[mm][bj][n] = *(const f32x4*)(rp + bj * HALF + n * 16);
;                 }
; #pragma unroll
;                 for (int mm = 0; mm < 2; ++mm) {
;                     const int m = mh * 2 + mm, r = row0 + ai * HALF + m * 16;
;                     float* zp = Z + (size_t)r * DM + col0;
; #pragma unroll
;                     for (int bj = 0; bj < 2; ++bj)
; #pragma unroll
;                         for (int n = 0; n < 2; ++n) {
;                             f32x4 res = rv[mm][bj][n];
;                             if (MODE == 1) res = (res - st[mm].x) * st[mm].y * gv[bj][n] + bv[bj][n];
;                             *(f32x4*)(zp + bj * HALF + n * 16) = res * ALPHA + acc[ai][bj][m][n] * scale;
;                         }
;                 }
;             }
	v_sub_f32_e32 v97, v97, v188
	v_sub_f32_e32 v96, v96, v188
	v_sub_f32_e32 v99, v99, v188
	v_sub_f32_e32 v98, v98, v188
	v_sub_f32_e32 v101, v101, v188
	v_sub_f32_e32 v100, v100, v188
	v_sub_f32_e32 v103, v103, v188
	v_sub_f32_e32 v102, v102, v188
	v_pk_mul_f32 v[98:99], v[188:189], v[98:99] op_sel:[1,0]
	v_pk_mul_f32 v[96:97], v[188:189], v[96:97] op_sel:[1,0]
	v_pk_mul_f32 v[100:101], v[188:189], v[100:101] op_sel:[1,0]
	v_pk_mul_f32 v[102:103], v[188:189], v[102:103] op_sel:[1,0]
	v_pk_fma_f32 v[96:97], v[156:157], v[96:97], v[152:153]
	v_pk_fma_f32 v[98:99], v[158:159], v[98:99], v[154:155]
	v_pk_fma_f32 v[100:101], v[144:145], v[100:101], v[148:149]
	v_sub_f32_e32 v105, v105, v188
	v_sub_f32_e32 v104, v104, v188
	v_sub_f32_e32 v107, v107, v188
	v_sub_f32_e32 v106, v106, v188
	v_pk_fma_f32 v[102:103], v[146:147], v[102:103], v[150:151]
	v_pk_fma_f32 v[94:95], v[98:99], s[14:15], v[94:95] op_sel_hi:[1,0,1]
	v_pk_fma_f32 v[92:93], v[96:97], s[14:15], v[92:93] op_sel_hi:[1,0,1]
	v_pk_fma_f32 v[88:89], v[100:101], s[14:15], v[88:89] op_sel_hi:[1,0,1]
	v_pk_mul_f32 v[106:107], v[188:189], v[106:107] op_sel:[1,0]
	v_pk_fma_f32 v[90:91], v[102:103], s[14:15], v[90:91] op_sel_hi:[1,0,1]
	global_store_dwordx4 v[192:193], v[92:95], off
	global_store_dwordx4 v[192:193], v[88:91], off offset:64
	v_lshl_add_u64 v[98:99], v[176:177], 0, s[30:31]
	v_lshl_add_u64 v[92:93], v[176:177], 0, s[28:29]
	v_pk_mul_f32 v[88:89], v[188:189], v[104:105] op_sel:[1,0]
	v_pk_fma_f32 v[90:91], v[142:143], v[106:107], v[138:139]
	v_pk_fma_f32 v[88:89], v[140:141], v[88:89], v[136:137]
	v_pk_fma_f32 v[86:87], v[90:91], s[14:15], v[86:87] op_sel_hi:[1,0,1]
	v_pk_fma_f32 v[84:85], v[88:89], s[14:15], v[84:85] op_sel_hi:[1,0,1]
	global_store_dwordx4 v[192:193], v[84:87], off offset:512
	v_lshl_add_u64 v[94:95], v[174:175], 0, v[98:99]
	v_lshl_add_u64 v[102:103], s[12:13], 0, v[92:93]
	v_sub_f32_e32 v85, v109, v188
	v_sub_f32_e32 v84, v108, v188
	v_sub_f32_e32 v87, v111, v188
	v_sub_f32_e32 v86, v110, v188
	v_pk_mul_f32 v[86:87], v[188:189], v[86:87] op_sel:[1,0]
	v_pk_mul_f32 v[84:85], v[188:189], v[84:85] op_sel:[1,0]
	v_pk_fma_f32 v[86:87], v[130:131], v[86:87], v[134:135]
	v_pk_fma_f32 v[84:85], v[128:129], v[84:85], v[132:133]
	v_pk_fma_f32 v[82:83], v[86:87], s[14:15], v[82:83] op_sel_hi:[1,0,1]
	v_pk_fma_f32 v[80:81], v[84:85], s[14:15], v[80:81] op_sel_hi:[1,0,1]
	global_store_dwordx4 v[192:193], v[80:83], off offset:576
	v_sub_f32_e32 v85, v115, v190
	v_sub_f32_e32 v84, v114, v190
	v_sub_f32_e32 v83, v113, v190
	v_sub_f32_e32 v82, v112, v190
	v_pk_mul_f32 v[84:85], v[190:191], v[84:85] op_sel:[1,0]
	v_pk_mul_f32 v[82:83], v[190:191], v[82:83] op_sel:[1,0]
	v_lshl_add_u64 v[80:81], s[12:13], 0, v[180:181]
	v_pk_fma_f32 v[82:83], v[156:157], v[82:83], v[152:153]
	v_pk_fma_f32 v[84:85], v[158:159], v[84:85], v[154:155]
	v_lshl_add_u64 v[80:81], v[80:81], 0, v[172:173]
	v_pk_fma_f32 v[78:79], v[84:85], s[14:15], v[78:79] op_sel_hi:[1,0,1]
	v_pk_fma_f32 v[76:77], v[82:83], s[14:15], v[76:77] op_sel_hi:[1,0,1]
	global_store_dwordx4 v[80:81], v[76:79], off
	v_lshl_add_u64 v[102:103], v[102:103], 0, v[172:173]
	s_nop 0
	v_sub_f32_e32 v77, v117, v190
	v_sub_f32_e32 v76, v116, v190
	v_sub_f32_e32 v79, v119, v190
	v_sub_f32_e32 v78, v118, v190
	v_pk_mul_f32 v[78:79], v[190:191], v[78:79] op_sel:[1,0]
	v_pk_mul_f32 v[76:77], v[190:191], v[76:77] op_sel:[1,0]
	v_pk_fma_f32 v[78:79], v[146:147], v[78:79], v[150:151]
	v_pk_fma_f32 v[76:77], v[144:145], v[76:77], v[148:149]
	v_pk_fma_f32 v[74:75], v[78:79], s[14:15], v[74:75] op_sel_hi:[1,0,1]
	v_pk_fma_f32 v[72:73], v[76:77], s[14:15], v[72:73] op_sel_hi:[1,0,1]
	global_store_dwordx4 v[80:81], v[72:75], off offset:64
	v_lshl_add_u64 v[76:77], v[174:175], 0, v[92:93]
	s_nop 0
	v_sub_f32_e32 v73, v121, v190
	v_sub_f32_e32 v72, v120, v190
	v_sub_f32_e32 v75, v123, v190
	v_sub_f32_e32 v74, v122, v190
	v_pk_mul_f32 v[74:75], v[190:191], v[74:75] op_sel:[1,0]
	v_pk_mul_f32 v[72:73], v[190:191], v[72:73] op_sel:[1,0]
	v_pk_fma_f32 v[74:75], v[142:143], v[74:75], v[138:139]
	v_pk_fma_f32 v[72:73], v[140:141], v[72:73], v[136:137]
	v_pk_fma_f32 v[70:71], v[74:75], s[14:15], v[70:71] op_sel_hi:[1,0,1]
	v_pk_fma_f32 v[68:69], v[72:73], s[14:15], v[68:69] op_sel_hi:[1,0,1]
	global_store_dwordx4 v[80:81], v[68:71], off offset:512
	s_nop 1
	v_sub_f32_e32 v69, v125, v190
	v_sub_f32_e32 v68, v124, v190
	v_sub_f32_e32 v71, v127, v190
	v_sub_f32_e32 v70, v126, v190
	v_pk_mul_f32 v[70:71], v[190:191], v[70:71] op_sel:[1,0]
	v_pk_mul_f32 v[68:69], v[190:191], v[68:69] op_sel:[1,0]
	v_pk_fma_f32 v[70:71], v[130:131], v[70:71], v[134:135]
	v_pk_fma_f32 v[68:69], v[128:129], v[68:69], v[132:133]
	v_pk_fma_f32 v[66:67], v[70:71], s[14:15], v[66:67] op_sel_hi:[1,0,1]
	v_pk_fma_f32 v[64:65], v[68:69], s[14:15], v[64:65] op_sel_hi:[1,0,1]
	global_store_dwordx4 v[80:81], v[64:67], off offset:576
	global_load_dwordx2 v[96:97], v[178:179], off offset:1024
	s_nop 0
	global_load_dwordx4 v[64:67], v[76:77], off
	global_load_dwordx4 v[68:71], v[76:77], off offset:64
	global_load_dwordx4 v[72:75], v[76:77], off offset:512
	s_nop 0
	global_load_dwordx4 v[76:79], v[76:77], off offset:576
	s_nop 0
	global_load_dwordx2 v[100:101], v[178:179], off offset:1152
	global_load_dwordx4 v[80:83], v[94:95], off
	global_load_dwordx4 v[84:87], v[94:95], off offset:64
	global_load_dwordx4 v[88:91], v[94:95], off offset:512
	s_waitcnt vmcnt(0)
;     __device__ __forceinline__ void operator()(const f32x4 (&acc)[2][2][4][2], const Unit& u, int wr, int wc, int fr, int fq) const {
;     ...
; #pragma unroll
;         for (int ai = 0; ai < 2; ++ai)
; #pragma unroll
;             for (int mh = 0; mh < 2; ++mh) {
;                 f32x4 rv[2][2][2]; f32x2 st[2];
; #pragma unroll
;                 for (int mm = 0; mm < 2; ++mm) {
;                     const int r = row0 + ai * HALF + (mh * 2 + mm) * 16;
;                     const float* rp = MODE == 0 ? ((r < 8192 ? x0 + (size_t)r * DM : x1 + (size_t)(r - 8192) * DM) + col0) : (Z + (size_t)r * DM + col0);
;                     if (MODE == 1) st[mm] = stats[r];
; #pragma unroll
;                     for (int bj = 0; bj < 2; ++bj)
; #pragma unroll
;                         for (int n = 0; n < 2; ++n) rv[mm][bj][n] = *(const f32x4*)(rp + bj * HALF + n * 16);
;                 }
; #pragma unroll
;                 for (int mm = 0; mm < 2; ++mm) {
;                     const int m = mh * 2 + mm, r = row0 + ai * HALF + m * 16;
;                     float* zp = Z + (size_t)r * DM + col0;
; #pragma unroll
;                     for (int bj = 0; bj < 2; ++bj)
; #pragma unroll
;                         for (int n = 0; n < 2; ++n) {
;                             f32x4 res = rv[mm][bj][n];
;                             if (MODE == 1) res = (res - st[mm].x) * st[mm].y * gv[bj][n] + bv[bj][n];
;                             *(f32x4*)(zp + bj * HALF + n * 16) = res * ALPHA + acc[ai][bj][m][n] * scale;
;                         }
;                 }
;             }
	v_sub_f32_e32 v65, v65, v96
	global_load_dwordx4 v[92:95], v[94:95], off offset:576
	v_sub_f32_e32 v64, v64, v96
	v_sub_f32_e32 v67, v67, v96
	v_sub_f32_e32 v66, v66, v96
	v_pk_mul_f32 v[66:67], v[96:97], v[66:67] op_sel:[1,0]
	v_pk_mul_f32 v[64:65], v[96:97], v[64:65] op_sel:[1,0]
	v_pk_fma_f32 v[66:67], v[158:159], v[66:67], v[154:155]
	v_pk_fma_f32 v[64:65], v[156:157], v[64:65], v[152:153]
	v_pk_fma_f32 v[62:63], v[66:67], s[14:15], v[62:63] op_sel_hi:[1,0,1]
	v_pk_fma_f32 v[60:61], v[64:65], s[14:15], v[60:61] op_sel_hi:[1,0,1]
	global_store_dwordx4 v[102:103], v[60:63], off
	v_lshl_add_u64 v[64:65], v[176:177], 0, s[34:35]
	s_nop 0
	v_sub_f32_e32 v61, v69, v96
	v_sub_f32_e32 v60, v68, v96
	v_sub_f32_e32 v63, v71, v96
	v_sub_f32_e32 v62, v70, v96
	v_pk_mul_f32 v[62:63], v[96:97], v[62:63] op_sel:[1,0]
	v_pk_mul_f32 v[60:61], v[96:97], v[60:61] op_sel:[1,0]
	v_pk_fma_f32 v[62:63], v[146:147], v[62:63], v[150:151]
	v_pk_fma_f32 v[60:61], v[144:145], v[60:61], v[148:149]
	v_pk_fma_f32 v[58:59], v[62:63], s[14:15], v[58:59] op_sel_hi:[1,0,1]
	v_pk_fma_f32 v[56:57], v[60:61], s[14:15], v[56:57] op_sel_hi:[1,0,1]
	global_store_dwordx4 v[102:103], v[56:59], off offset:64
	v_lshl_add_u64 v[68:69], v[176:177], 0, s[36:37]
	v_lshl_add_u64 v[60:61], v[174:175], 0, v[68:69]
	v_sub_f32_e32 v57, v73, v96
	v_sub_f32_e32 v56, v72, v96
	v_sub_f32_e32 v59, v75, v96
	v_sub_f32_e32 v58, v74, v96
	v_pk_mul_f32 v[58:59], v[96:97], v[58:59] op_sel:[1,0]
	v_pk_mul_f32 v[56:57], v[96:97], v[56:57] op_sel:[1,0]
	v_pk_fma_f32 v[58:59], v[142:143], v[58:59], v[138:139]
	v_pk_fma_f32 v[56:57], v[140:141], v[56:57], v[136:137]
	v_pk_fma_f32 v[54:55], v[58:59], s[14:15], v[54:55] op_sel_hi:[1,0,1]
	v_pk_fma_f32 v[52:53], v[56:57], s[14:15], v[52:53] op_sel_hi:[1,0,1]
	global_store_dwordx4 v[102:103], v[52:55], off offset:512
	s_nop 1
	v_sub_f32_e32 v53, v77, v96
	v_sub_f32_e32 v52, v76, v96
	v_sub_f32_e32 v55, v79, v96
	v_sub_f32_e32 v54, v78, v96
	v_pk_mul_f32 v[54:55], v[96:97], v[54:55] op_sel:[1,0]
	v_pk_mul_f32 v[52:53], v[96:97], v[52:53] op_sel:[1,0]
	v_pk_fma_f32 v[54:55], v[130:131], v[54:55], v[134:135]
	v_pk_fma_f32 v[52:53], v[128:129], v[52:53], v[132:133]
	v_pk_fma_f32 v[46:47], v[54:55], s[14:15], v[46:47] op_sel_hi:[1,0,1]
	v_pk_fma_f32 v[44:45], v[52:53], s[14:15], v[44:45] op_sel_hi:[1,0,1]
	global_store_dwordx4 v[102:103], v[44:47], off offset:576
	s_nop 1
	v_lshl_add_u64 v[44:45], s[12:13], 0, v[98:99]
	v_lshl_add_u64 v[52:53], v[44:45], 0, v[172:173]
	v_sub_f32_e32 v45, v81, v100
	v_sub_f32_e32 v44, v80, v100
	v_sub_f32_e32 v47, v83, v100
	v_sub_f32_e32 v46, v82, v100
	v_pk_mul_f32 v[46:47], v[100:101], v[46:47] op_sel:[1,0]
	v_pk_mul_f32 v[44:45], v[100:101], v[44:45] op_sel:[1,0]
	v_pk_fma_f32 v[46:47], v[158:159], v[46:47], v[154:155]
	v_pk_fma_f32 v[44:45], v[156:157], v[44:45], v[152:153]
	v_pk_fma_f32 v[46:47], v[46:47], s[14:15], v[50:51] op_sel_hi:[1,0,1]
	v_pk_fma_f32 v[44:45], v[44:45], s[14:15], v[48:49] op_sel_hi:[1,0,1]
	global_store_dwordx4 v[52:53], v[44:47], off
	s_nop 1
	v_sub_f32_e32 v45, v85, v100
	v_sub_f32_e32 v44, v84, v100
	v_sub_f32_e32 v47, v87, v100
	v_sub_f32_e32 v46, v86, v100
	v_pk_mul_f32 v[46:47], v[100:101], v[46:47] op_sel:[1,0]
	v_pk_mul_f32 v[44:45], v[100:101], v[44:45] op_sel:[1,0]
	v_pk_fma_f32 v[46:47], v[146:147], v[46:47], v[150:151]
	v_pk_fma_f32 v[44:45], v[144:145], v[44:45], v[148:149]
	v_pk_fma_f32 v[42:43], v[46:47], s[14:15], v[42:43] op_sel_hi:[1,0,1]
	v_pk_fma_f32 v[40:41], v[44:45], s[14:15], v[40:41] op_sel_hi:[1,0,1]
	global_store_dwordx4 v[52:53], v[40:43], off offset:64
	v_lshl_add_u64 v[44:45], v[174:175], 0, v[64:65]
	v_lshl_add_u64 v[64:65], s[12:13], 0, v[64:65]
	v_sub_f32_e32 v41, v89, v100
	v_sub_f32_e32 v40, v88, v100
	v_sub_f32_e32 v43, v91, v100
	v_sub_f32_e32 v42, v90, v100
	v_pk_mul_f32 v[42:43], v[100:101], v[42:43] op_sel:[1,0]
	v_pk_mul_f32 v[40:41], v[100:101], v[40:41] op_sel:[1,0]
	v_pk_fma_f32 v[42:43], v[142:143], v[42:43], v[138:139]
	v_pk_fma_f32 v[40:41], v[140:141], v[40:41], v[136:137]
	v_pk_fma_f32 v[38:39], v[42:43], s[14:15], v[38:39] op_sel_hi:[1,0,1]
	v_pk_fma_f32 v[36:37], v[40:41], s[14:15], v[36:37] op_sel_hi:[1,0,1]
	global_store_dwordx4 v[52:53], v[36:39], off offset:512
	v_lshl_add_u64 v[64:65], v[64:65], 0, v[172:173]
	s_waitcnt vmcnt(0)
	v_sub_f32_e32 v37, v93, v100
	v_sub_f32_e32 v36, v92, v100
	v_sub_f32_e32 v39, v95, v100
	v_sub_f32_e32 v38, v94, v100
	v_pk_mul_f32 v[38:39], v[100:101], v[38:39] op_sel:[1,0]
	v_pk_mul_f32 v[36:37], v[100:101], v[36:37] op_sel:[1,0]
	v_pk_fma_f32 v[38:39], v[130:131], v[38:39], v[134:135]
	v_pk_fma_f32 v[36:37], v[128:129], v[36:37], v[132:133]
	v_pk_fma_f32 v[34:35], v[38:39], s[14:15], v[34:35] op_sel_hi:[1,0,1]
	v_pk_fma_f32 v[32:33], v[36:37], s[14:15], v[32:33] op_sel_hi:[1,0,1]
	global_store_dwordx4 v[52:53], v[32:35], off offset:576
	global_load_dwordx2 v[66:67], v[178:179], off offset:1280
	s_nop 0
	global_load_dwordx4 v[32:35], v[44:45], off
	global_load_dwordx4 v[36:39], v[44:45], off offset:64
	global_load_dwordx4 v[40:43], v[44:45], off offset:512
	s_nop 0
	global_load_dwordx4 v[44:47], v[44:45], off offset:576
	s_nop 0
	global_load_dwordx2 v[70:71], v[178:179], off offset:1408
	global_load_dwordx4 v[48:51], v[60:61], off
	global_load_dwordx4 v[52:55], v[60:61], off offset:64
	global_load_dwordx4 v[56:59], v[60:61], off offset:512
	s_nop 0
	global_load_dwordx4 v[60:63], v[60:61], off offset:576
	s_waitcnt vmcnt(0)
;     __device__ __forceinline__ void operator()(const f32x4 (&acc)[2][2][4][2], const Unit& u, int wr, int wc, int fr, int fq) const {
;     ...
; #pragma unroll
;         for (int ai = 0; ai < 2; ++ai)
; #pragma unroll
;             for (int mh = 0; mh < 2; ++mh) {
;                 f32x4 rv[2][2][2]; f32x2 st[2];
; #pragma unroll
;                 for (int mm = 0; mm < 2; ++mm) {
;                     const int r = row0 + ai * HALF + (mh * 2 + mm) * 16;
;                     const float* rp = MODE == 0 ? ((r < 8192 ? x0 + (size_t)r * DM : x1 + (size_t)(r - 8192) * DM) + col0) : (Z + (size_t)r * DM + col0);
;                     if (MODE == 1) st[mm] = stats[r];
; #pragma unroll
;                     for (int bj = 0; bj < 2; ++bj)
; #pragma unroll
;                         for (int n = 0; n < 2; ++n) rv[mm][bj][n] = *(const f32x4*)(rp + bj * HALF + n * 16);
;                 }
; #pragma unroll
;                 for (int mm = 0; mm < 2; ++mm) {
;                     const int m = mh * 2 + mm, r = row0 + ai * HALF + m * 16;
;                     float* zp = Z + (size_t)r * DM + col0;
; #pragma unroll
;                     for (int bj = 0; bj < 2; ++bj)
; #pragma unroll
;                         for (int n = 0; n < 2; ++n) {
;                             f32x4 res = rv[mm][bj][n];
;                             if (MODE == 1) res = (res - st[mm].x) * st[mm].y * gv[bj][n] + bv[bj][n];
;                             *(f32x4*)(zp + bj * HALF + n * 16) = res * ALPHA + acc[ai][bj][m][n] * scale;
;                         }
;                 }
;             }
	v_sub_f32_e32 v33, v33, v66
	v_sub_f32_e32 v32, v32, v66
	v_sub_f32_e32 v35, v35, v66
	v_sub_f32_e32 v34, v34, v66
	v_pk_mul_f32 v[34:35], v[66:67], v[34:35] op_sel:[1,0]
	v_pk_mul_f32 v[32:33], v[66:67], v[32:33] op_sel:[1,0]
	v_pk_fma_f32 v[34:35], v[158:159], v[34:35], v[154:155]
	v_pk_fma_f32 v[32:33], v[156:157], v[32:33], v[152:153]
	v_pk_fma_f32 v[30:31], v[34:35], s[14:15], v[30:31] op_sel_hi:[1,0,1]
	v_pk_fma_f32 v[28:29], v[32:33], s[14:15], v[28:29] op_sel_hi:[1,0,1]
	global_store_dwordx4 v[64:65], v[28:31], off
	s_nop 1
	v_sub_f32_e32 v29, v37, v66
	v_sub_f32_e32 v28, v36, v66
	v_sub_f32_e32 v31, v39, v66
	v_sub_f32_e32 v30, v38, v66
	v_pk_mul_f32 v[30:31], v[66:67], v[30:31] op_sel:[1,0]
	v_pk_mul_f32 v[28:29], v[66:67], v[28:29] op_sel:[1,0]
	v_pk_fma_f32 v[30:31], v[146:147], v[30:31], v[150:151]
	v_pk_fma_f32 v[28:29], v[144:145], v[28:29], v[148:149]
	v_pk_fma_f32 v[26:27], v[30:31], s[14:15], v[26:27] op_sel_hi:[1,0,1]
	v_pk_fma_f32 v[24:25], v[28:29], s[14:15], v[24:25] op_sel_hi:[1,0,1]
	global_store_dwordx4 v[64:65], v[24:27], off offset:64
	s_nop 1
	v_sub_f32_e32 v25, v41, v66
	v_sub_f32_e32 v24, v40, v66
	v_sub_f32_e32 v27, v43, v66
	v_sub_f32_e32 v26, v42, v66
	v_pk_mul_f32 v[26:27], v[66:67], v[26:27] op_sel:[1,0]
	v_pk_mul_f32 v[24:25], v[66:67], v[24:25] op_sel:[1,0]
	v_pk_fma_f32 v[26:27], v[142:143], v[26:27], v[138:139]
	v_pk_fma_f32 v[24:25], v[140:141], v[24:25], v[136:137]
	v_pk_fma_f32 v[22:23], v[26:27], s[14:15], v[22:23] op_sel_hi:[1,0,1]
	v_pk_fma_f32 v[20:21], v[24:25], s[14:15], v[20:21] op_sel_hi:[1,0,1]
	global_store_dwordx4 v[64:65], v[20:23], off offset:512
	s_nop 1
	v_sub_f32_e32 v21, v45, v66
	v_sub_f32_e32 v20, v44, v66
	v_sub_f32_e32 v23, v47, v66
	v_sub_f32_e32 v22, v46, v66
	v_pk_mul_f32 v[22:23], v[66:67], v[22:23] op_sel:[1,0]
	v_pk_mul_f32 v[20:21], v[66:67], v[20:21] op_sel:[1,0]
	v_pk_fma_f32 v[22:23], v[130:131], v[22:23], v[134:135]
	v_pk_fma_f32 v[20:21], v[128:129], v[20:21], v[132:133]
	v_pk_fma_f32 v[14:15], v[22:23], s[14:15], v[14:15] op_sel_hi:[1,0,1]
	v_pk_fma_f32 v[12:13], v[20:21], s[14:15], v[12:13] op_sel_hi:[1,0,1]
	global_store_dwordx4 v[64:65], v[12:15], off offset:576
	s_nop 1
	v_lshl_add_u64 v[12:13], s[12:13], 0, v[68:69]
	v_lshl_add_u64 v[20:21], v[12:13], 0, v[172:173]
	v_sub_f32_e32 v13, v49, v70
	v_sub_f32_e32 v12, v48, v70
	v_sub_f32_e32 v15, v51, v70
	v_sub_f32_e32 v14, v50, v70
	v_pk_mul_f32 v[14:15], v[70:71], v[14:15] op_sel:[1,0]
	v_pk_mul_f32 v[12:13], v[70:71], v[12:13] op_sel:[1,0]
	v_pk_fma_f32 v[14:15], v[158:159], v[14:15], v[154:155]
	v_pk_fma_f32 v[12:13], v[156:157], v[12:13], v[152:153]
	v_pk_fma_f32 v[14:15], v[14:15], s[14:15], v[18:19] op_sel_hi:[1,0,1]
	v_pk_fma_f32 v[12:13], v[12:13], s[14:15], v[16:17] op_sel_hi:[1,0,1]
	global_store_dwordx4 v[20:21], v[12:15], off
	s_nop 1
	v_sub_f32_e32 v13, v53, v70
	v_sub_f32_e32 v12, v52, v70
	v_sub_f32_e32 v15, v55, v70
	v_sub_f32_e32 v14, v54, v70
	v_pk_mul_f32 v[14:15], v[70:71], v[14:15] op_sel:[1,0]
	v_pk_mul_f32 v[12:13], v[70:71], v[12:13] op_sel:[1,0]
	v_pk_fma_f32 v[14:15], v[146:147], v[14:15], v[150:151]
	v_pk_fma_f32 v[12:13], v[144:145], v[12:13], v[148:149]
	v_pk_fma_f32 v[10:11], v[14:15], s[14:15], v[10:11] op_sel_hi:[1,0,1]
	v_pk_fma_f32 v[8:9], v[12:13], s[14:15], v[8:9] op_sel_hi:[1,0,1]
	global_store_dwordx4 v[20:21], v[8:11], off offset:64
	s_nop 1
	v_sub_f32_e32 v9, v57, v70
	v_sub_f32_e32 v8, v56, v70
	v_sub_f32_e32 v11, v59, v70
	v_sub_f32_e32 v10, v58, v70
	v_pk_mul_f32 v[10:11], v[70:71], v[10:11] op_sel:[1,0]
	v_pk_mul_f32 v[8:9], v[70:71], v[8:9] op_sel:[1,0]
	v_pk_fma_f32 v[10:11], v[142:143], v[10:11], v[138:139]
	v_pk_fma_f32 v[8:9], v[140:141], v[8:9], v[136:137]
	v_pk_fma_f32 v[6:7], v[10:11], s[14:15], v[6:7] op_sel_hi:[1,0,1]
	v_pk_fma_f32 v[4:5], v[8:9], s[14:15], v[4:5] op_sel_hi:[1,0,1]
	global_store_dwordx4 v[20:21], v[4:7], off offset:512
	s_nop 1
	v_sub_f32_e32 v5, v61, v70
	v_sub_f32_e32 v4, v60, v70
	v_sub_f32_e32 v7, v63, v70
	v_sub_f32_e32 v6, v62, v70
	v_pk_mul_f32 v[6:7], v[70:71], v[6:7] op_sel:[1,0]
	v_pk_mul_f32 v[4:5], v[70:71], v[4:5] op_sel:[1,0]
	v_pk_fma_f32 v[6:7], v[130:131], v[6:7], v[134:135]
	v_pk_fma_f32 v[4:5], v[128:129], v[4:5], v[132:133]
	v_pk_fma_f32 v[2:3], v[6:7], s[14:15], v[2:3] op_sel_hi:[1,0,1]
	v_pk_fma_f32 v[0:1], v[4:5], s[14:15], v[0:1] op_sel_hi:[1,0,1]
	global_store_dwordx4 v[20:21], v[0:3], off offset:576
	s_cbranch_vccz .LBB0_1422
	s_waitcnt vmcnt(0)
	s_cmpk_gt_u32 s25, 0xff
	s_cbranch_scc1 .LBB0_1433
	s_barrier

; #define PG8_STAGE(bufoff, gbase, voff) do { _Pragma("unroll") for (int _i = 0; _i < 2; ++_i) \
;         __builtin_amdgcn_global_load_lds((const unsigned*)((const char*)(gbase) + (voff)[_i]), (LAS unsigned*)(lds + (bufoff) + ldsw + _i * 8192), 16, 0, 0); } while (0)
; #define PG8_LDA(dst, b, h) do { _Pragma("unroll") for (int m = 0; m < 4; ++m) _Pragma("unroll") for (int k = 0; k < 2; ++k) dst[m][k] = *(const LAS bf16x8*)(lds + PG8_SA(b, h) + aoff + m * 2048 + k * 1024); } while (0)
; #define PG8_LDB(dst, b, h) do { _Pragma("unroll") for (int n = 0; n < 2; ++n) _Pragma("unroll") for (int k = 0; k < 2; ++k) dst[n][k] = *(const LAS bf16x8*)(lds + PG8_SB(b, h) + boff + n * 2048 + k * 1024); } while (0)
; #define PG8_MMA(ai, bj, At, Bt) do { __builtin_amdgcn_s_setprio(1); _Pragma("unroll") for (int m = 0; m < 4; ++m) _Pragma("unroll") for (int n = 0; n < 2; ++n) _Pragma("unroll") for (int k = 0; k < 2; ++k) \
;         acc[ai][bj][m][n] = __builtin_amdgcn_mfma_f32_16x16x32_bf16(Bt[n][k], At[m][k], acc[ai][bj][m][n], 0, 0, 0); __builtin_amdgcn_s_setprio(0); } while (0)
; #define PG8_WAIT_V(n) asm volatile("s_waitcnt vmcnt(" #n ")" ::: "memory")
; #define PG8_WAIT_L(n) asm volatile("s_waitcnt lgkmcnt(" #n ")" ::: "memory")
; #define PG8_BAR __builtin_amdgcn_s_barrier()
; #define PG8_SCHED __builtin_amdgcn_sched_barrier(0)
; template <class Epi, class Sched>
; __device__ __forceinline__ void gemm_phase(LAS unsigned char* lds, const Gemm g, const Sched& S, const Epi& E) {
;     ...
;             PG8_LDB(B0, 0, 0); PG8_SCHED; PG8_LDA(At, 0, 0); PG8_STAGE(PG8_SA(1, 1), a1 + hstep, voffA);
;             PG8_WAIT_L(8); PG8_BAR; PG8_WAIT_L(0); PG8_MMA(0, 0, At, B0); PG8_BAR; PG8_SCHED;
;             PG8_LDB(B1, 0, 1); PG8_STAGE(PG8_SB(0, 0), b2, voffB);
;             PG8_BAR; PG8_WAIT_L(0); PG8_MMA(0, 1, At, B1); PG8_BAR;
;             PG8_LDA(At, 0, 1); PG8_STAGE(PG8_SA(0, 0), a2, voffA);
;             PG8_BAR; PG8_WAIT_L(0); PG8_MMA(1, 0, At, B0); PG8_BAR; PG8_SCHED;
;             PG8_STAGE(PG8_SB(0, 1), b2 + hstep, voffB);
;             PG8_WAIT_V(6); PG8_BAR; PG8_MMA(1, 1, At, B1); PG8_BAR;
;             PG8_LDB(B0, 1, 0); PG8_SCHED; PG8_LDA(At, 1, 0); PG8_STAGE(PG8_SA(0, 1), a2 + hstep, voffA);
;             PG8_WAIT_L(8); PG8_BAR; PG8_WAIT_L(0); PG8_MMA(0, 0, At, B0); PG8_BAR; PG8_SCHED;
.LBB0_1562:
	ds_read_b128 v[154:157], v150
	ds_read_b128 v[158:161], v150 offset:1024
	ds_read_b128 v[162:165], v150 offset:2048
	ds_read_b128 v[166:169], v150 offset:3072
	s_add_u32 s28, s26, 0x4000
	s_addc_u32 s29, s27, 0
	s_cmp_eq_u32 s57, 28
	s_cselect_b32 s34, s33, s28
	s_cselect_b32 s35, s15, s29
	s_cselect_b32 s28, s54, s55
	s_cselect_b32 s29, s13, s56
	s_add_u32 s30, s34, 0x8000
	s_addc_u32 s31, s35, 0
	v_lshl_add_u64 v[202:203], s[26:27], 0, v[138:139]
	s_add_i32 m0, s43, 0xc000
	ds_read_b128 v[170:173], v151
	ds_read_b128 v[174:177], v151 offset:1024
	ds_read_b128 v[178:181], v151 offset:2048
	ds_read_b128 v[182:185], v151 offset:3072
	ds_read_b128 v[186:189], v151 offset:4096
	ds_read_b128 v[190:193], v151 offset:5120
	ds_read_b128 v[194:197], v151 offset:6144
	ds_read_b128 v[198:201], v151 offset:7168
	global_load_lds_dwordx4 v[202:203], off
	v_lshl_add_u64 v[202:203], s[26:27], 0, v[140:141]
	s_add_i32 m0, s43, 0xe000
	s_nop 0
	global_load_lds_dwordx4 v[202:203], off
	s_waitcnt lgkmcnt(8)
	s_barrier
	s_waitcnt lgkmcnt(0)
	v_mfma_f32_16x16x32_bf16 v[124:127], v[154:157], v[170:173], v[124:127]
	v_mfma_f32_16x16x32_bf16 v[120:123], v[162:165], v[170:173], v[120:123]
	v_mfma_f32_16x16x32_bf16 v[108:111], v[154:157], v[178:181], v[108:111]
	v_mfma_f32_16x16x32_bf16 v[104:107], v[162:165], v[178:181], v[104:107]
	v_mfma_f32_16x16x32_bf16 v[92:95], v[154:157], v[186:189], v[92:95]
	v_mfma_f32_16x16x32_bf16 v[88:91], v[162:165], v[186:189], v[88:91]
	v_mfma_f32_16x16x32_bf16 v[76:79], v[154:157], v[194:197], v[76:79]
	v_mfma_f32_16x16x32_bf16 v[72:75], v[162:165], v[194:197], v[72:75]
	v_mfma_f32_16x16x32_bf16 v[124:127], v[158:161], v[174:177], v[124:127]
	v_mfma_f32_16x16x32_bf16 v[120:123], v[166:169], v[174:177], v[120:123]
	v_mfma_f32_16x16x32_bf16 v[108:111], v[158:161], v[182:185], v[108:111]
	v_mfma_f32_16x16x32_bf16 v[104:107], v[166:169], v[182:185], v[104:107]
	v_mfma_f32_16x16x32_bf16 v[92:95], v[158:161], v[190:193], v[92:95]
	v_mfma_f32_16x16x32_bf16 v[88:91], v[166:169], v[190:193], v[88:91]
	v_mfma_f32_16x16x32_bf16 v[76:79], v[158:161], v[198:201], v[76:79]
	v_mfma_f32_16x16x32_bf16 v[72:75], v[166:169], v[198:201], v[72:75]
	s_barrier
	s_add_i32 s58, s71, s41
	v_lshl_add_u64 v[202:203], s[28:29], 0, v[132:133]
	s_mov_b32 m0, s58
	ds_read_b128 v[206:209], v152
	ds_read_b128 v[210:213], v152 offset:1024
	ds_read_b128 v[214:217], v152 offset:2048
	ds_read_b128 v[218:221], v152 offset:3072
	global_load_lds_dwordx4 v[202:203], off
	v_lshl_add_u64 v[202:203], s[28:29], 0, v[128:129]
	s_add_i32 m0, s58, 0x2000
	s_nop 0
	global_load_lds_dwordx4 v[202:203], off
	s_barrier
	s_waitcnt lgkmcnt(0)
	v_mfma_f32_16x16x32_bf16 v[116:119], v[206:209], v[170:173], v[116:119]
	v_mfma_f32_16x16x32_bf16 v[112:115], v[214:217], v[170:173], v[112:115]
	v_mfma_f32_16x16x32_bf16 v[100:103], v[206:209], v[178:181], v[100:103]
	v_mfma_f32_16x16x32_bf16 v[96:99], v[214:217], v[178:181], v[96:99]
	v_mfma_f32_16x16x32_bf16 v[84:87], v[206:209], v[186:189], v[84:87]
	v_mfma_f32_16x16x32_bf16 v[80:83], v[214:217], v[186:189], v[80:83]
	v_mfma_f32_16x16x32_bf16 v[68:71], v[206:209], v[194:197], v[68:71]
	v_mfma_f32_16x16x32_bf16 v[64:67], v[214:217], v[194:197], v[64:67]
	v_mfma_f32_16x16x32_bf16 v[116:119], v[210:213], v[174:177], v[116:119]
	v_mfma_f32_16x16x32_bf16 v[112:115], v[218:221], v[174:177], v[112:115]
	v_mfma_f32_16x16x32_bf16 v[100:103], v[210:213], v[182:185], v[100:103]
	v_mfma_f32_16x16x32_bf16 v[96:99], v[218:221], v[182:185], v[96:99]
	v_mfma_f32_16x16x32_bf16 v[84:87], v[210:213], v[190:193], v[84:87]
	v_mfma_f32_16x16x32_bf16 v[80:83], v[218:221], v[190:193], v[80:83]
	v_mfma_f32_16x16x32_bf16 v[68:71], v[210:213], v[198:201], v[68:71]
	v_mfma_f32_16x16x32_bf16 v[64:67], v[218:221], v[198:201], v[64:67]
	s_mov_b32 m0, s43
	v_lshl_add_u64 v[202:203], s[34:35], 0, v[134:135]
	s_barrier
	ds_read_b128 v[170:173], v151 offset:16384
	ds_read_b128 v[174:177], v151 offset:17408
	ds_read_b128 v[178:181], v151 offset:18432
	ds_read_b128 v[182:185], v151 offset:19456
	ds_read_b128 v[186:189], v151 offset:20480
	ds_read_b128 v[190:193], v151 offset:21504
	ds_read_b128 v[194:197], v151 offset:22528
	ds_read_b128 v[198:201], v151 offset:23552
	global_load_lds_dwordx4 v[202:203], off
	v_lshl_add_u64 v[202:203], s[34:35], 0, v[130:131]
	s_mov_b32 m0, s44
	s_nop 0
	global_load_lds_dwordx4 v[202:203], off
	s_barrier
	s_waitcnt lgkmcnt(0)
	v_mfma_f32_16x16x32_bf16 v[60:63], v[154:157], v[170:173], v[60:63]
	v_mfma_f32_16x16x32_bf16 v[56:59], v[162:165], v[170:173], v[56:59]
	v_mfma_f32_16x16x32_bf16 v[44:47], v[154:157], v[178:181], v[44:47]
	v_mfma_f32_16x16x32_bf16 v[40:43], v[162:165], v[178:181], v[40:43]
	v_mfma_f32_16x16x32_bf16 v[28:31], v[154:157], v[186:189], v[28:31]
	v_mfma_f32_16x16x32_bf16 v[24:27], v[162:165], v[186:189], v[24:27]
	v_mfma_f32_16x16x32_bf16 v[12:15], v[154:157], v[194:197], v[12:15]
	v_mfma_f32_16x16x32_bf16 v[8:11], v[162:165], v[194:197], v[8:11]
	v_mfma_f32_16x16x32_bf16 v[60:63], v[158:161], v[174:177], v[60:63]
	v_mfma_f32_16x16x32_bf16 v[56:59], v[166:169], v[174:177], v[56:59]
	v_mfma_f32_16x16x32_bf16 v[44:47], v[158:161], v[182:185], v[44:47]
	v_mfma_f32_16x16x32_bf16 v[40:43], v[166:169], v[182:185], v[40:43]
	v_mfma_f32_16x16x32_bf16 v[28:31], v[158:161], v[190:193], v[28:31]
	v_mfma_f32_16x16x32_bf16 v[24:27], v[166:169], v[190:193], v[24:27]
	v_mfma_f32_16x16x32_bf16 v[12:15], v[158:161], v[198:201], v[12:15]
	v_mfma_f32_16x16x32_bf16 v[8:11], v[166:169], v[198:201], v[8:11]
	s_barrier
; #define PG8_STAGE(bufoff, gbase, voff) do { _Pragma("unroll") for (int _i = 0; _i < 2; ++_i) \
;         __builtin_amdgcn_global_load_lds((const unsigned*)((const char*)(gbase) + (voff)[_i]), (LAS unsigned*)(lds + (bufoff) + ldsw + _i * 8192), 16, 0, 0); } while (0)
; #define PG8_LDA(dst, b, h) do { _Pragma("unroll") for (int m = 0; m < 4; ++m) _Pragma("unroll") for (int k = 0; k < 2; ++k) dst[m][k] = *(const LAS bf16x8*)(lds + PG8_SA(b, h) + aoff + m * 2048 + k * 1024); } while (0)
; #define PG8_LDB(dst, b, h) do { _Pragma("unroll") for (int n = 0; n < 2; ++n) _Pragma("unroll") for (int k = 0; k < 2; ++k) dst[n][k] = *(const LAS bf16x8*)(lds + PG8_SB(b, h) + boff + n * 2048 + k * 1024); } while (0)
; #define PG8_MMA(ai, bj, At, Bt) do { __builtin_amdgcn_s_setprio(1); _Pragma("unroll") for (int m = 0; m < 4; ++m) _Pragma("unroll") for (int n = 0; n < 2; ++n) _Pragma("unroll") for (int k = 0; k < 2; ++k) \
;         acc[ai][bj][m][n] = __builtin_amdgcn_mfma_f32_16x16x32_bf16(Bt[n][k], At[m][k], acc[ai][bj][m][n], 0, 0, 0); __builtin_amdgcn_s_setprio(0); } while (0)
; #define PG8_WAIT_V(n) asm volatile("s_waitcnt vmcnt(" #n ")" ::: "memory")
; #define PG8_WAIT_L(n) asm volatile("s_waitcnt lgkmcnt(" #n ")" ::: "memory")
; #define PG8_BAR __builtin_amdgcn_s_barrier()
; #define PG8_SCHED __builtin_amdgcn_sched_barrier(0)
; template <class Epi, class Sched>
; __device__ __forceinline__ void gemm_phase(LAS unsigned char* lds, const Gemm g, const Sched& S, const Epi& E) {
;     ...
;             PG8_BAR; PG8_WAIT_L(0); PG8_MMA(1, 0, At, B0); PG8_BAR; PG8_SCHED;
;             PG8_STAGE(PG8_SB(0, 1), b2 + hstep, voffB);
;             PG8_WAIT_V(6); PG8_BAR; PG8_MMA(1, 1, At, B1); PG8_BAR;
;             PG8_LDB(B0, 1, 0); PG8_SCHED; PG8_LDA(At, 1, 0); PG8_STAGE(PG8_SA(0, 1), a2 + hstep, voffA);
;             PG8_WAIT_L(8); PG8_BAR; PG8_WAIT_L(0); PG8_MMA(0, 0, At, B0); PG8_BAR; PG8_SCHED;
;             PG8_LDB(B1, 1, 1); PG8_STAGE(PG8_SB(1, 0), b3, voffB);
;             PG8_BAR; PG8_WAIT_L(0); PG8_MMA(0, 1, At, B1); PG8_BAR;
;             PG8_LDA(At, 1, 1); PG8_STAGE(PG8_SA(1, 0), a3, voffA);
;             PG8_BAR; PG8_WAIT_L(0); PG8_MMA(1, 0, At, B0); PG8_BAR; PG8_SCHED;
	s_add_u32 s58, s28, 0x4000
	s_addc_u32 s59, s29, 0
	s_add_i32 s60, s52, s41
	v_lshl_add_u64 v[154:155], s[58:59], 0, v[132:133]
	s_mov_b32 m0, s60
	s_nop 0
	global_load_lds_dwordx4 v[154:155], off
	v_lshl_add_u64 v[154:155], s[58:59], 0, v[128:129]
	s_add_i32 m0, s60, 0x2000
	s_nop 0
	global_load_lds_dwordx4 v[154:155], off
	s_waitcnt vmcnt(6)
	s_barrier
	v_mfma_f32_16x16x32_bf16 v[52:55], v[206:209], v[170:173], v[52:55]
	v_mfma_f32_16x16x32_bf16 v[48:51], v[214:217], v[170:173], v[48:51]
	v_mfma_f32_16x16x32_bf16 v[36:39], v[206:209], v[178:181], v[36:39]
	v_mfma_f32_16x16x32_bf16 v[32:35], v[214:217], v[178:181], v[32:35]
	v_mfma_f32_16x16x32_bf16 v[20:23], v[206:209], v[186:189], v[20:23]
	v_mfma_f32_16x16x32_bf16 v[16:19], v[214:217], v[186:189], v[16:19]
	v_mfma_f32_16x16x32_bf16 v[4:7], v[206:209], v[194:197], v[4:7]
	v_mfma_f32_16x16x32_bf16 v[0:3], v[214:217], v[194:197], v[0:3]
	v_mfma_f32_16x16x32_bf16 v[52:55], v[210:213], v[174:177], v[52:55]
	v_mfma_f32_16x16x32_bf16 v[48:51], v[218:221], v[174:177], v[48:51]
	v_mfma_f32_16x16x32_bf16 v[36:39], v[210:213], v[182:185], v[36:39]
	v_mfma_f32_16x16x32_bf16 v[32:35], v[218:221], v[182:185], v[32:35]
	v_mfma_f32_16x16x32_bf16 v[20:23], v[210:213], v[190:193], v[20:23]
	v_mfma_f32_16x16x32_bf16 v[16:19], v[218:221], v[190:193], v[16:19]
	v_mfma_f32_16x16x32_bf16 v[4:7], v[210:213], v[198:201], v[4:7]
	v_mfma_f32_16x16x32_bf16 v[0:3], v[218:221], v[198:201], v[0:3]
	s_add_i32 s58, 0, 0x18000
	v_add_u32_e32 v136, s58, v149
	s_barrier
	ds_read_b128 v[154:157], v136
	ds_read_b128 v[158:161], v136 offset:1024
	ds_read_b128 v[162:165], v136 offset:2048
	ds_read_b128 v[166:169], v136 offset:3072
	s_add_u32 s34, s34, 0x4000
	s_addc_u32 s35, s35, 0
	s_mov_b32 m0, s45
	v_lshl_add_u64 v[202:203], s[34:35], 0, v[134:135]
	ds_read_b128 v[170:173], v151 offset:32768
	ds_read_b128 v[174:177], v151 offset:33792
	ds_read_b128 v[178:181], v151 offset:34816
	ds_read_b128 v[182:185], v151 offset:35840
	ds_read_b128 v[186:189], v151 offset:36864
	ds_read_b128 v[190:193], v151 offset:37888
	ds_read_b128 v[194:197], v151 offset:38912
	ds_read_b128 v[198:201], v151 offset:39936
	global_load_lds_dwordx4 v[202:203], off
	v_lshl_add_u64 v[202:203], s[34:35], 0, v[130:131]
	s_mov_b32 m0, s46
	s_nop 0
	global_load_lds_dwordx4 v[202:203], off
	s_waitcnt lgkmcnt(8)
	s_barrier
	s_waitcnt lgkmcnt(0)
	v_mfma_f32_16x16x32_bf16 v[124:127], v[154:157], v[170:173], v[124:127]
	v_mfma_f32_16x16x32_bf16 v[120:123], v[162:165], v[170:173], v[120:123]
	v_mfma_f32_16x16x32_bf16 v[108:111], v[154:157], v[178:181], v[108:111]
	v_mfma_f32_16x16x32_bf16 v[104:107], v[162:165], v[178:181], v[104:107]
	v_mfma_f32_16x16x32_bf16 v[92:95], v[154:157], v[186:189], v[92:95]
	v_mfma_f32_16x16x32_bf16 v[88:91], v[162:165], v[186:189], v[88:91]
	v_mfma_f32_16x16x32_bf16 v[76:79], v[154:157], v[194:197], v[76:79]
	v_mfma_f32_16x16x32_bf16 v[72:75], v[162:165], v[194:197], v[72:75]
	v_mfma_f32_16x16x32_bf16 v[124:127], v[158:161], v[174:177], v[124:127]
	v_mfma_f32_16x16x32_bf16 v[120:123], v[166:169], v[174:177], v[120:123]
	v_mfma_f32_16x16x32_bf16 v[108:111], v[158:161], v[182:185], v[108:111]
	v_mfma_f32_16x16x32_bf16 v[104:107], v[166:169], v[182:185], v[104:107]
	v_mfma_f32_16x16x32_bf16 v[92:95], v[158:161], v[190:193], v[92:95]
	v_mfma_f32_16x16x32_bf16 v[88:91], v[166:169], v[190:193], v[88:91]
	v_mfma_f32_16x16x32_bf16 v[76:79], v[158:161], v[198:201], v[76:79]
	v_mfma_f32_16x16x32_bf16 v[72:75], v[166:169], v[198:201], v[72:75]
	s_barrier
	s_add_i32 s59, 0, 0x1c000
	s_add_u32 s34, s28, 0x8000
	s_addc_u32 s35, s29, 0
	s_add_i32 s58, s58, s41
	v_add_u32_e32 v136, s59, v149
	v_lshl_add_u64 v[202:203], s[34:35], 0, v[132:133]
	s_mov_b32 m0, s58
	ds_read_b128 v[206:209], v136
	ds_read_b128 v[210:213], v136 offset:1024
	ds_read_b128 v[214:217], v136 offset:2048
	ds_read_b128 v[218:221], v136 offset:3072
	global_load_lds_dwordx4 v[202:203], off
	v_lshl_add_u64 v[202:203], s[34:35], 0, v[128:129]
	s_add_i32 m0, s58, 0x2000
	s_nop 0
	global_load_lds_dwordx4 v[202:203], off
	s_barrier
	s_waitcnt lgkmcnt(0)
	v_mfma_f32_16x16x32_bf16 v[116:119], v[206:209], v[170:173], v[116:119]
	v_mfma_f32_16x16x32_bf16 v[112:115], v[214:217], v[170:173], v[112:115]
	v_mfma_f32_16x16x32_bf16 v[100:103], v[206:209], v[178:181], v[100:103]
	v_mfma_f32_16x16x32_bf16 v[96:99], v[214:217], v[178:181], v[96:99]
	v_mfma_f32_16x16x32_bf16 v[84:87], v[206:209], v[186:189], v[84:87]
	v_mfma_f32_16x16x32_bf16 v[80:83], v[214:217], v[186:189], v[80:83]
	v_mfma_f32_16x16x32_bf16 v[68:71], v[206:209], v[194:197], v[68:71]
	v_mfma_f32_16x16x32_bf16 v[64:67], v[214:217], v[194:197], v[64:67]
	v_mfma_f32_16x16x32_bf16 v[116:119], v[210:213], v[174:177], v[116:119]
	v_mfma_f32_16x16x32_bf16 v[112:115], v[218:221], v[174:177], v[112:115]
	v_mfma_f32_16x16x32_bf16 v[100:103], v[210:213], v[182:185], v[100:103]
	v_mfma_f32_16x16x32_bf16 v[96:99], v[218:221], v[182:185], v[96:99]
	v_mfma_f32_16x16x32_bf16 v[84:87], v[210:213], v[190:193], v[84:87]
	v_mfma_f32_16x16x32_bf16 v[80:83], v[218:221], v[190:193], v[80:83]
	v_mfma_f32_16x16x32_bf16 v[68:71], v[210:213], v[198:201], v[68:71]
	v_mfma_f32_16x16x32_bf16 v[64:67], v[218:221], v[198:201], v[64:67]
	s_mov_b32 m0, s50
	v_lshl_add_u64 v[202:203], s[30:31], 0, v[134:135]
	s_barrier
	ds_read_b128 v[170:173], v151 offset:49152
	ds_read_b128 v[174:177], v151 offset:50176
	ds_read_b128 v[178:181], v151 offset:51200
	ds_read_b128 v[182:185], v151 offset:52224
	ds_read_b128 v[186:189], v151 offset:53248
	ds_read_b128 v[190:193], v151 offset:54272
	ds_read_b128 v[194:197], v151 offset:55296
	ds_read_b128 v[198:201], v151 offset:56320
	global_load_lds_dwordx4 v[202:203], off
	v_lshl_add_u64 v[202:203], s[30:31], 0, v[130:131]
	s_mov_b32 m0, s51
	s_nop 0
	global_load_lds_dwordx4 v[202:203], off
	s_barrier
; __device__ __forceinline__ unsigned cvt_pk_bf16(float lo, float hi) { f32x2 v = {lo, hi}; bf16x2_t b = __builtin_convertvector(v, bf16x2_t); return __builtin_bit_cast(unsigned, b); }
; __device__ __forceinline__ float sigmoid_f(float x) { return __builtin_amdgcn_rcpf(1.0f + __expf(-x)); }
; __device__ __forceinline__ float silu_f(float x) { return x * sigmoid_f(x); }
; __device__ __forceinline__ size_t tl(int r, int c, int K) { return ((size_t)(r >> 8) * (size_t)(K >> 6) + (size_t)(c >> 6)) * 16384 + (size_t)((r & 255) << 6) + (size_t)(c & 63); }
; #define PG8_STAGE(bufoff, gbase, voff) do { _Pragma("unroll") for (int _i = 0; _i < 2; ++_i) \
;         __builtin_amdgcn_global_load_lds((const unsigned*)((const char*)(gbase) + (voff)[_i]), (LAS unsigned*)(lds + (bufoff) + ldsw + _i * 8192), 16, 0, 0); } while (0)
; #define PG8_WAIT_V(n) asm volatile("s_waitcnt vmcnt(" #n ")" ::: "memory")
; #define PG8_WAIT_L(n) asm volatile("s_waitcnt lgkmcnt(" #n ")" ::: "memory")
; #define PG8_BAR __builtin_amdgcn_s_barrier()
; template <class Epi, class Sched>
; __device__ __forceinline__ void gemm_phase(LAS unsigned char* lds, const Gemm g, const Sched& S, const Epi& E) {
;     ...
;             PG8_BAR; PG8_WAIT_L(0); PG8_MMA(1, 0, At, B0); PG8_BAR; PG8_SCHED;
;             PG8_STAGE(PG8_SB(1, 1), b3 + hstep, voffB);
;             PG8_WAIT_V(6); PG8_BAR; PG8_MMA(1, 1, At, B1); PG8_BAR;
;         }
;     __device__ __forceinline__ void operator()(const f32x4 (&acc)[2][2][4][2], const Unit& u, int wr, int wc, int fr, int fq) const {
;         const int row0 = u.pm * BM + wr * 64 + fr, col0 = u.pn * 128 + wc * 32 + 8 * fq;
; #pragma unroll
;         for (int ai = 0; ai < 2; ++ai)
; #pragma unroll
;             for (int m = 0; m < 4; ++m) {
;                 bf16_t* rowp = MODE == 0 ? O + tl(row0 + ai * HALF + m * 16, col0, ldo) : O + (size_t)(row0 + ai * HALF + m * 16) * ldo + col0;
;                 float v[8];
; #pragma unroll
;                 for (int n = 0; n < 2; ++n)
; #pragma unroll
;                     for (int j = 0; j < 4; ++j) { const float a = acc[ai][0][m][n][j], b = acc[ai][1][m][n][j]; v[n * 4 + j] = MODE == 0 ? silu_f(a) * b : a * sigmoid_f(b); }
;                 u32x4 w; w.x = cvt_pk_bf16(v[0], v[1]); w.y = cvt_pk_bf16(v[2], v[3]); w.z = cvt_pk_bf16(v[4], v[5]); w.w = cvt_pk_bf16(v[6], v[7]);
;                 *(u32x4*)rowp = w;
	s_waitcnt lgkmcnt(0)
	v_mfma_f32_16x16x32_bf16 v[60:63], v[154:157], v[170:173], v[60:63]
	v_mfma_f32_16x16x32_bf16 v[56:59], v[162:165], v[170:173], v[56:59]
	v_mfma_f32_16x16x32_bf16 v[44:47], v[154:157], v[178:181], v[44:47]
	v_mfma_f32_16x16x32_bf16 v[40:43], v[162:165], v[178:181], v[40:43]
	v_mfma_f32_16x16x32_bf16 v[28:31], v[154:157], v[186:189], v[28:31]
	v_mfma_f32_16x16x32_bf16 v[24:27], v[162:165], v[186:189], v[24:27]
	v_mfma_f32_16x16x32_bf16 v[12:15], v[154:157], v[194:197], v[12:15]
	v_mfma_f32_16x16x32_bf16 v[8:11], v[162:165], v[194:197], v[8:11]
	v_mfma_f32_16x16x32_bf16 v[60:63], v[158:161], v[174:177], v[60:63]
	v_mfma_f32_16x16x32_bf16 v[56:59], v[166:169], v[174:177], v[56:59]
	v_mfma_f32_16x16x32_bf16 v[44:47], v[158:161], v[182:185], v[44:47]
	v_mfma_f32_16x16x32_bf16 v[40:43], v[166:169], v[182:185], v[40:43]
	v_mfma_f32_16x16x32_bf16 v[28:31], v[158:161], v[190:193], v[28:31]
	v_mfma_f32_16x16x32_bf16 v[24:27], v[166:169], v[190:193], v[24:27]
	v_mfma_f32_16x16x32_bf16 v[12:15], v[158:161], v[198:201], v[12:15]
	v_mfma_f32_16x16x32_bf16 v[8:11], v[166:169], v[198:201], v[8:11]
	s_barrier
	s_add_u32 s28, s28, 0xc000
	s_addc_u32 s29, s29, 0
	s_add_i32 s30, s59, s41
	v_lshl_add_u64 v[154:155], s[28:29], 0, v[132:133]
	s_mov_b32 m0, s30
	s_nop 0
	global_load_lds_dwordx4 v[154:155], off
	v_lshl_add_u64 v[154:155], s[28:29], 0, v[128:129]
	s_add_i32 m0, s30, 0x2000
	s_nop 0
	global_load_lds_dwordx4 v[154:155], off
	s_waitcnt vmcnt(6)
	s_barrier
	v_mfma_f32_16x16x32_bf16 v[52:55], v[206:209], v[170:173], v[52:55]
	v_mfma_f32_16x16x32_bf16 v[48:51], v[214:217], v[170:173], v[48:51]
	v_mfma_f32_16x16x32_bf16 v[36:39], v[206:209], v[178:181], v[36:39]
	v_mfma_f32_16x16x32_bf16 v[32:35], v[214:217], v[178:181], v[32:35]
	v_mfma_f32_16x16x32_bf16 v[20:23], v[206:209], v[186:189], v[20:23]
	v_mfma_f32_16x16x32_bf16 v[16:19], v[214:217], v[186:189], v[16:19]
	v_mfma_f32_16x16x32_bf16 v[4:7], v[206:209], v[194:197], v[4:7]
	v_mfma_f32_16x16x32_bf16 v[0:3], v[214:217], v[194:197], v[0:3]
	v_mfma_f32_16x16x32_bf16 v[52:55], v[210:213], v[174:177], v[52:55]
	v_mfma_f32_16x16x32_bf16 v[48:51], v[218:221], v[174:177], v[48:51]
	v_mfma_f32_16x16x32_bf16 v[36:39], v[210:213], v[182:185], v[36:39]
	v_mfma_f32_16x16x32_bf16 v[32:35], v[218:221], v[182:185], v[32:35]
	v_mfma_f32_16x16x32_bf16 v[20:23], v[210:213], v[190:193], v[20:23]
	v_mfma_f32_16x16x32_bf16 v[16:19], v[218:221], v[190:193], v[16:19]
	v_mfma_f32_16x16x32_bf16 v[4:7], v[210:213], v[198:201], v[4:7]
	v_mfma_f32_16x16x32_bf16 v[0:3], v[218:221], v[198:201], v[0:3]
	s_add_i32 s57, s57, 2
	s_add_u32 s26, s26, 0x10000
	s_addc_u32 s27, s27, 0
	s_add_u32 s55, s55, 0x10000
	s_addc_u32 s56, s56, 0
	s_cmp_gt_u32 s57, 29
	s_barrier
	s_cbranch_scc0 .LBB0_1562
	s_lshl_b32 s13, s24, 8
	s_add_i32 s13, s13, s48
	s_lshl_b32 s15, s25, 7
	v_mul_f32_e32 v136, 0xbfb8aa3b, v124
	v_or_b32_e32 v153, s13, v148
	s_or_b32 s15, s15, s49
	s_ashr_i32 s13, s13, 8
	v_exp_f32_e32 v136, v136
	v_mul_f32_e32 v147, 0xbfb8aa3b, v125
	s_ashr_i32 s24, s15, 6
	s_mulk_i32 s13, 0x56
	v_exp_f32_e32 v147, v147
	s_ashr_i32 s25, s24, 31
	s_ashr_i32 s15, s13, 31
	s_add_u32 s26, s13, s24
	s_addc_u32 s27, s15, s25
	v_add_f32_e32 v136, 1.0, v136
	s_lshl_b64 s[26:27], s[26:27], 15
	v_rcp_f32_e32 v154, v136
	v_add_f32_e32 v136, 1.0, v147
	s_add_u32 s26, s10, s26
	v_rcp_f32_e32 v155, v136
	v_lshlrev_b32_e32 v136, 7, v153
	s_addc_u32 s27, s11, s27
	v_and_b32_e32 v136, 0x6780, v136
	v_lshl_add_u64 v[156:157], s[26:27], 0, v[136:137]
	v_mul_f32_e32 v136, 0xbfb8aa3b, v126
	v_mul_f32_e32 v147, 0xbfb8aa3b, v127
	v_exp_f32_e32 v136, v136
	v_exp_f32_e32 v147, v147
	v_pk_mul_f32 v[124:125], v[124:125], v[154:155]
	s_mov_b64 s[28:29], s[18:19]
	v_pk_mul_f32 v[116:117], v[124:125], v[116:117]
	v_add_f32_e32 v124, 1.0, v136
	v_add_f32_e32 v125, 1.0, v147
	v_mul_f32_e32 v136, 0xbfb8aa3b, v120
	v_rcp_f32_e32 v124, v124
	v_rcp_f32_e32 v125, v125
	v_exp_f32_e32 v136, v136
	v_mul_f32_e32 v147, 0xbfb8aa3b, v121
	v_exp_f32_e32 v147, v147
	v_pk_mul_f32 v[124:125], v[126:127], v[124:125]
	v_add_f32_e32 v126, 1.0, v136
	v_mul_f32_e32 v136, 0xbfb8aa3b, v122
	v_add_f32_e32 v127, 1.0, v147
	v_exp_f32_e32 v136, v136
	v_mul_f32_e32 v147, 0xbfb8aa3b, v123
	v_exp_f32_e32 v147, v147
	v_rcp_f32_e32 v126, v126
	v_add_f32_e32 v136, 1.0, v136
	v_rcp_f32_e32 v127, v127
	v_rcp_f32_e32 v154, v136
	v_add_f32_e32 v136, 1.0, v147
	v_rcp_f32_e32 v155, v136
	v_pk_mul_f32 v[120:121], v[120:121], v[126:127]
	v_pk_mul_f32 v[118:119], v[124:125], v[118:119]
	v_pk_mul_f32 v[120:121], v[120:121], v[112:113]
	v_pk_mul_f32 v[112:113], v[122:123], v[154:155]
	v_mov_b32_e32 v147, v137
	v_pk_mul_f32 v[122:123], v[112:113], v[114:115]
	v_mul_f32_e32 v113, 0xbfb8aa3b, v108
	v_exp_f32_e32 v114, v113
	v_mul_f32_e32 v113, 0xbfb8aa3b, v109
	v_exp_f32_e32 v115, v113
	v_cvt_pk_bf16_f32 v112, v116, v117
	v_add_f32_e32 v114, 1.0, v114
	v_rcp_f32_e32 v116, v114
	v_add_f32_e32 v114, 1.0, v115
	v_lshl_add_u64 v[124:125], v[156:157], 0, v[146:147]
	v_cvt_pk_bf16_f32 v113, v118, v119
	v_rcp_f32_e32 v117, v114
	v_cvt_pk_bf16_f32 v114, v120, v121
	v_cvt_pk_bf16_f32 v115, v122, v123
	global_store_dwordx4 v[124:125], v[112:115], off
	v_pk_mul_f32 v[108:109], v[108:109], v[116:117]
	s_mov_b64 s[26:27], s[16:17]
	v_mul_f32_e32 v112, 0xbfb8aa3b, v110
	v_mul_f32_e32 v113, 0xbfb8aa3b, v111
	v_exp_f32_e32 v112, v112
	v_exp_f32_e32 v113, v113
	v_pk_mul_f32 v[100:101], v[108:109], v[100:101]
	v_add_f32_e32 v108, 1.0, v112
	v_add_f32_e32 v109, 1.0, v113
	v_mul_f32_e32 v112, 0xbfb8aa3b, v104
	v_mul_f32_e32 v113, 0xbfb8aa3b, v105
	v_rcp_f32_e32 v108, v108
	v_rcp_f32_e32 v109, v109
	v_exp_f32_e32 v112, v112
; __device__ __forceinline__ unsigned cvt_pk_bf16(float lo, float hi) { f32x2 v = {lo, hi}; bf16x2_t b = __builtin_convertvector(v, bf16x2_t); return __builtin_bit_cast(unsigned, b); }
; __device__ __forceinline__ float sigmoid_f(float x) { return __builtin_amdgcn_rcpf(1.0f + __expf(-x)); }
; __device__ __forceinline__ float silu_f(float x) { return x * sigmoid_f(x); }
; __device__ __forceinline__ size_t tl(int r, int c, int K) { return ((size_t)(r >> 8) * (size_t)(K >> 6) + (size_t)(c >> 6)) * 16384 + (size_t)((r & 255) << 6) + (size_t)(c & 63); }
;     __device__ __forceinline__ void operator()(const f32x4 (&acc)[2][2][4][2], const Unit& u, int wr, int wc, int fr, int fq) const {
;         const int row0 = u.pm * BM + wr * 64 + fr, col0 = u.pn * 128 + wc * 32 + 8 * fq;
; #pragma unroll
;         for (int ai = 0; ai < 2; ++ai)
; #pragma unroll
;             for (int m = 0; m < 4; ++m) {
;                 bf16_t* rowp = MODE == 0 ? O + tl(row0 + ai * HALF + m * 16, col0, ldo) : O + (size_t)(row0 + ai * HALF + m * 16) * ldo + col0;
;                 float v[8];
; #pragma unroll
;                 for (int n = 0; n < 2; ++n)
; #pragma unroll
;                     for (int j = 0; j < 4; ++j) { const float a = acc[ai][0][m][n][j], b = acc[ai][1][m][n][j]; v[n * 4 + j] = MODE == 0 ? silu_f(a) * b : a * sigmoid_f(b); }
;                 u32x4 w; w.x = cvt_pk_bf16(v[0], v[1]); w.y = cvt_pk_bf16(v[2], v[3]); w.z = cvt_pk_bf16(v[4], v[5]); w.w = cvt_pk_bf16(v[6], v[7]);
;                 *(u32x4*)rowp = w;
;             }
	v_exp_f32_e32 v113, v113
	v_pk_mul_f32 v[108:109], v[110:111], v[108:109]
	v_add_f32_e32 v110, 1.0, v112
	v_add_f32_e32 v111, 1.0, v113
	v_mul_f32_e32 v112, 0xbfb8aa3b, v106
	v_mul_f32_e32 v113, 0xbfb8aa3b, v107
	v_exp_f32_e32 v112, v112
	v_exp_f32_e32 v113, v113
	v_rcp_f32_e32 v110, v110
	v_rcp_f32_e32 v111, v111
	v_add_f32_e32 v112, 1.0, v112
	v_add_f32_e32 v113, 1.0, v113
	v_rcp_f32_e32 v112, v112
	v_rcp_f32_e32 v113, v113
	v_pk_mul_f32 v[104:105], v[104:105], v[110:111]
	v_pk_mul_f32 v[102:103], v[108:109], v[102:103]
	v_pk_mul_f32 v[104:105], v[104:105], v[96:97]
	v_pk_mul_f32 v[96:97], v[106:107], v[112:113]
	s_nop 0
	v_pk_mul_f32 v[106:107], v[96:97], v[98:99]
	v_mul_f32_e32 v97, 0xbfb8aa3b, v92
	v_exp_f32_e32 v98, v97
	v_mul_f32_e32 v97, 0xbfb8aa3b, v93
	v_exp_f32_e32 v99, v97
	v_cvt_pk_bf16_f32 v96, v100, v101
	v_add_f32_e32 v98, 1.0, v98
	v_rcp_f32_e32 v100, v98
	v_add_f32_e32 v98, 1.0, v99
	v_cvt_pk_bf16_f32 v97, v102, v103
	v_rcp_f32_e32 v101, v98
	v_cvt_pk_bf16_f32 v98, v104, v105
	v_cvt_pk_bf16_f32 v99, v106, v107
	global_store_dwordx4 v[124:125], v[96:99], off offset:2048
	v_pk_mul_f32 v[92:93], v[92:93], v[100:101]
	s_nop 0
	v_mul_f32_e32 v96, 0xbfb8aa3b, v94
	v_mul_f32_e32 v97, 0xbfb8aa3b, v95
	v_exp_f32_e32 v96, v96
	v_exp_f32_e32 v97, v97
	v_pk_mul_f32 v[84:85], v[92:93], v[84:85]
	v_add_f32_e32 v92, 1.0, v96
	v_add_f32_e32 v93, 1.0, v97
	v_mul_f32_e32 v96, 0xbfb8aa3b, v88
	v_mul_f32_e32 v97, 0xbfb8aa3b, v89
	v_rcp_f32_e32 v92, v92
	v_rcp_f32_e32 v93, v93
	v_exp_f32_e32 v96, v96
	v_exp_f32_e32 v97, v97
	v_pk_mul_f32 v[92:93], v[94:95], v[92:93]
	v_add_f32_e32 v94, 1.0, v96
	v_add_f32_e32 v95, 1.0, v97
	v_mul_f32_e32 v96, 0xbfb8aa3b, v90
	v_mul_f32_e32 v97, 0xbfb8aa3b, v91
	v_exp_f32_e32 v96, v96
	v_exp_f32_e32 v97, v97
	v_rcp_f32_e32 v94, v94
	v_rcp_f32_e32 v95, v95
	v_add_f32_e32 v96, 1.0, v96
	v_add_f32_e32 v97, 1.0, v97
	v_rcp_f32_e32 v96, v96
	v_rcp_f32_e32 v97, v97
	v_pk_mul_f32 v[88:89], v[88:89], v[94:95]
	v_pk_mul_f32 v[86:87], v[92:93], v[86:87]
	v_pk_mul_f32 v[88:89], v[88:89], v[80:81]
	v_pk_mul_f32 v[80:81], v[90:91], v[96:97]
	s_nop 0
	v_pk_mul_f32 v[90:91], v[80:81], v[82:83]
	v_mul_f32_e32 v83, 0xbfb8aa3b, v76
	v_cvt_pk_bf16_f32 v80, v84, v85
	v_exp_f32_e32 v84, v83
	v_mul_f32_e32 v83, 0xbfb8aa3b, v77
	v_exp_f32_e32 v85, v83
	v_cvt_pk_bf16_f32 v81, v86, v87
	v_add_co_u32_e32 v86, vcc, s53, v124
	v_cvt_pk_bf16_f32 v82, v88, v89
	v_cvt_pk_bf16_f32 v83, v90, v91
	v_add_f32_e32 v84, 1.0, v84
	v_add_f32_e32 v85, 1.0, v85
	v_addc_co_u32_e32 v87, vcc, 0, v125, vcc
	v_rcp_f32_e32 v84, v84
	v_rcp_f32_e32 v85, v85
	global_store_dwordx4 v[86:87], v[80:83], off
	v_pk_mul_f32 v[76:77], v[76:77], v[84:85]
	s_nop 0
	v_mul_f32_e32 v80, 0xbfb8aa3b, v78
	v_mul_f32_e32 v81, 0xbfb8aa3b, v79
	v_exp_f32_e32 v80, v80
	v_exp_f32_e32 v81, v81
	v_pk_mul_f32 v[68:69], v[76:77], v[68:69]
	v_add_f32_e32 v76, 1.0, v80
	v_add_f32_e32 v77, 1.0, v81
	v_mul_f32_e32 v80, 0xbfb8aa3b, v72
	v_mul_f32_e32 v81, 0xbfb8aa3b, v73
	v_rcp_f32_e32 v76, v76
	v_rcp_f32_e32 v77, v77
	v_exp_f32_e32 v80, v80
	v_exp_f32_e32 v81, v81
	v_pk_mul_f32 v[76:77], v[78:79], v[76:77]
	v_add_f32_e32 v78, 1.0, v80
	v_add_f32_e32 v79, 1.0, v81
	v_mul_f32_e32 v80, 0xbfb8aa3b, v74
	v_mul_f32_e32 v81, 0xbfb8aa3b, v75
	v_exp_f32_e32 v80, v80
	v_exp_f32_e32 v81, v81
	v_rcp_f32_e32 v78, v78
	v_rcp_f32_e32 v79, v79
	v_add_f32_e32 v80, 1.0, v80
	v_add_f32_e32 v81, 1.0, v81
	v_rcp_f32_e32 v80, v80
	v_rcp_f32_e32 v81, v81
	v_pk_mul_f32 v[72:73], v[72:73], v[78:79]
	v_pk_mul_f32 v[70:71], v[76:77], v[70:71]
	v_pk_mul_f32 v[72:73], v[72:73], v[64:65]
	v_pk_mul_f32 v[64:65], v[74:75], v[80:81]
	s_nop 0
	v_pk_mul_f32 v[74:75], v[64:65], v[66:67]
	v_cvt_pk_bf16_f32 v64, v68, v69
	v_cvt_pk_bf16_f32 v65, v70, v71
	v_cvt_pk_bf16_f32 v66, v72, v73
	v_cvt_pk_bf16_f32 v67, v74, v75
	global_store_dwordx4 v[86:87], v[64:67], off offset:2048
	v_add_u32_e32 v68, 0x80, v153
	s_nop 0
	v_mul_f32_e32 v66, 0xbfb8aa3b, v60
	v_mul_f32_e32 v67, 0xbfb8aa3b, v61
	v_exp_f32_e32 v66, v66
	v_exp_f32_e32 v67, v67
	v_lshrrev_b32_e32 v64, 8, v68
	v_mul_i32_i24_e32 v64, 0x56, v64
	v_add_f32_e32 v66, 1.0, v66
	v_add_f32_e32 v67, 1.0, v67
	v_rcp_f32_e32 v66, v66
	v_rcp_f32_e32 v67, v67
	v_ashrrev_i32_e32 v65, 31, v64
	v_lshl_add_u64 v[64:65], v[64:65], 0, s[24:25]
	v_lshlrev_b64 v[64:65], 15, v[64:65]
	v_pk_mul_f32 v[60:61], v[60:61], v[66:67]
	v_mul_f32_e32 v66, 0xbfb8aa3b, v62
	v_mul_f32_e32 v67, 0xbfb8aa3b, v63
	v_exp_f32_e32 v66, v66
	v_exp_f32_e32 v67, v67
	v_pk_mul_f32 v[52:53], v[60:61], v[52:53]
	v_lshlrev_b32_e32 v68, 7, v68
	v_add_f32_e32 v60, 1.0, v66
	v_add_f32_e32 v61, 1.0, v67
	v_mul_f32_e32 v66, 0xbfb8aa3b, v56
	v_mul_f32_e32 v67, 0xbfb8aa3b, v57
	v_rcp_f32_e32 v60, v60
	v_rcp_f32_e32 v61, v61
	v_exp_f32_e32 v66, v66
	v_exp_f32_e32 v67, v67
	v_lshl_add_u64 v[64:65], s[10:11], 0, v[64:65]
	v_pk_mul_f32 v[60:61], v[62:63], v[60:61]
	v_add_f32_e32 v62, 1.0, v66
	v_add_f32_e32 v63, 1.0, v67
	v_mul_f32_e32 v66, 0xbfb8aa3b, v58
	v_mul_f32_e32 v67, 0xbfb8aa3b, v59
	v_exp_f32_e32 v66, v66
	v_exp_f32_e32 v67, v67
	v_rcp_f32_e32 v62, v62
	v_rcp_f32_e32 v63, v63
	v_add_f32_e32 v66, 1.0, v66
	v_add_f32_e32 v67, 1.0, v67
; __device__ __forceinline__ unsigned cvt_pk_bf16(float lo, float hi) { f32x2 v = {lo, hi}; bf16x2_t b = __builtin_convertvector(v, bf16x2_t); return __builtin_bit_cast(unsigned, b); }
; __device__ __forceinline__ float sigmoid_f(float x) { return __builtin_amdgcn_rcpf(1.0f + __expf(-x)); }
; __device__ __forceinline__ float silu_f(float x) { return x * sigmoid_f(x); }
; __device__ __forceinline__ size_t tl(int r, int c, int K) { return ((size_t)(r >> 8) * (size_t)(K >> 6) + (size_t)(c >> 6)) * 16384 + (size_t)((r & 255) << 6) + (size_t)(c & 63); }
;     __device__ __forceinline__ void operator()(const f32x4 (&acc)[2][2][4][2], const Unit& u, int wr, int wc, int fr, int fq) const {
;         const int row0 = u.pm * BM + wr * 64 + fr, col0 = u.pn * 128 + wc * 32 + 8 * fq;
; #pragma unroll
;         for (int ai = 0; ai < 2; ++ai)
; #pragma unroll
;             for (int m = 0; m < 4; ++m) {
;                 bf16_t* rowp = MODE == 0 ? O + tl(row0 + ai * HALF + m * 16, col0, ldo) : O + (size_t)(row0 + ai * HALF + m * 16) * ldo + col0;
;                 float v[8];
; #pragma unroll
;                 for (int n = 0; n < 2; ++n)
; #pragma unroll
;                     for (int j = 0; j < 4; ++j) { const float a = acc[ai][0][m][n][j], b = acc[ai][1][m][n][j]; v[n * 4 + j] = MODE == 0 ? silu_f(a) * b : a * sigmoid_f(b); }
;                 u32x4 w; w.x = cvt_pk_bf16(v[0], v[1]); w.y = cvt_pk_bf16(v[2], v[3]); w.z = cvt_pk_bf16(v[4], v[5]); w.w = cvt_pk_bf16(v[6], v[7]);
;                 *(u32x4*)rowp = w;
;             }
	v_rcp_f32_e32 v66, v66
	v_rcp_f32_e32 v67, v67
	v_pk_mul_f32 v[56:57], v[56:57], v[62:63]
	v_and_b32_e32 v136, 0x6780, v68
	v_pk_mul_f32 v[56:57], v[56:57], v[48:49]
	v_pk_mul_f32 v[48:49], v[58:59], v[66:67]
	v_lshl_add_u64 v[64:65], v[64:65], 0, v[136:137]
	v_pk_mul_f32 v[58:59], v[48:49], v[50:51]
	v_mul_f32_e32 v49, 0xbfb8aa3b, v44
	v_exp_f32_e32 v50, v49
	v_mul_f32_e32 v49, 0xbfb8aa3b, v45
	v_exp_f32_e32 v51, v49
	v_pk_mul_f32 v[54:55], v[60:61], v[54:55]
	v_add_f32_e32 v50, 1.0, v50
	v_cvt_pk_bf16_f32 v48, v52, v53
	v_rcp_f32_e32 v52, v50
	v_add_f32_e32 v50, 1.0, v51
	v_lshl_add_u64 v[60:61], v[64:65], 0, v[146:147]
	v_cvt_pk_bf16_f32 v49, v54, v55
	v_rcp_f32_e32 v53, v50
	v_cvt_pk_bf16_f32 v50, v56, v57
	v_cvt_pk_bf16_f32 v51, v58, v59
	global_store_dwordx4 v[60:61], v[48:51], off
	v_pk_mul_f32 v[44:45], v[44:45], v[52:53]
	s_mov_b32 s25, s12
	v_mul_f32_e32 v48, 0xbfb8aa3b, v46
	v_mul_f32_e32 v49, 0xbfb8aa3b, v47
	v_exp_f32_e32 v48, v48
	v_exp_f32_e32 v49, v49
	v_pk_mul_f32 v[36:37], v[44:45], v[36:37]
	s_mov_b32 s24, s14
	v_add_f32_e32 v44, 1.0, v48
	v_add_f32_e32 v45, 1.0, v49
	v_mul_f32_e32 v48, 0xbfb8aa3b, v40
	v_mul_f32_e32 v49, 0xbfb8aa3b, v41
	v_rcp_f32_e32 v44, v44
	v_rcp_f32_e32 v45, v45
	v_exp_f32_e32 v48, v48
	v_exp_f32_e32 v49, v49
	v_pk_mul_f32 v[44:45], v[46:47], v[44:45]
	v_add_f32_e32 v46, 1.0, v48
	v_add_f32_e32 v47, 1.0, v49
	v_mul_f32_e32 v48, 0xbfb8aa3b, v42
	v_mul_f32_e32 v49, 0xbfb8aa3b, v43
	v_exp_f32_e32 v48, v48
	v_exp_f32_e32 v49, v49
	v_rcp_f32_e32 v46, v46
	v_rcp_f32_e32 v47, v47
	v_add_f32_e32 v48, 1.0, v48
	v_add_f32_e32 v49, 1.0, v49
	v_rcp_f32_e32 v48, v48
	v_rcp_f32_e32 v49, v49
	v_pk_mul_f32 v[40:41], v[40:41], v[46:47]
	v_pk_mul_f32 v[38:39], v[44:45], v[38:39]
	v_pk_mul_f32 v[40:41], v[40:41], v[32:33]
	v_pk_mul_f32 v[32:33], v[42:43], v[48:49]
	s_nop 0
	v_pk_mul_f32 v[42:43], v[32:33], v[34:35]
	v_mul_f32_e32 v33, 0xbfb8aa3b, v28
	v_exp_f32_e32 v34, v33
	v_mul_f32_e32 v33, 0xbfb8aa3b, v29
	v_exp_f32_e32 v35, v33
	v_cvt_pk_bf16_f32 v32, v36, v37
	v_add_f32_e32 v34, 1.0, v34
	v_rcp_f32_e32 v36, v34
	v_add_f32_e32 v34, 1.0, v35
	v_cvt_pk_bf16_f32 v33, v38, v39
	v_rcp_f32_e32 v37, v34
	v_cvt_pk_bf16_f32 v34, v40, v41
	v_cvt_pk_bf16_f32 v35, v42, v43
	global_store_dwordx4 v[60:61], v[32:35], off offset:2048
	v_pk_mul_f32 v[28:29], v[28:29], v[36:37]
	s_nop 0
	v_mul_f32_e32 v32, 0xbfb8aa3b, v30
	v_mul_f32_e32 v33, 0xbfb8aa3b, v31
	v_exp_f32_e32 v32, v32
	v_exp_f32_e32 v33, v33
	v_pk_mul_f32 v[20:21], v[28:29], v[20:21]
	v_add_f32_e32 v28, 1.0, v32
	v_add_f32_e32 v29, 1.0, v33
	v_mul_f32_e32 v32, 0xbfb8aa3b, v24
	v_mul_f32_e32 v33, 0xbfb8aa3b, v25
	v_rcp_f32_e32 v28, v28
	v_rcp_f32_e32 v29, v29
	v_exp_f32_e32 v32, v32
	v_exp_f32_e32 v33, v33
	v_pk_mul_f32 v[28:29], v[30:31], v[28:29]
	v_add_f32_e32 v30, 1.0, v32
	v_add_f32_e32 v31, 1.0, v33
	v_mul_f32_e32 v32, 0xbfb8aa3b, v26
	v_mul_f32_e32 v33, 0xbfb8aa3b, v27
	v_exp_f32_e32 v32, v32
	v_exp_f32_e32 v33, v33
	v_rcp_f32_e32 v30, v30
	v_rcp_f32_e32 v31, v31
	v_add_f32_e32 v32, 1.0, v32
	v_add_f32_e32 v33, 1.0, v33
	v_rcp_f32_e32 v32, v32
	v_rcp_f32_e32 v33, v33
	v_pk_mul_f32 v[24:25], v[24:25], v[30:31]
	v_pk_mul_f32 v[22:23], v[28:29], v[22:23]
	v_pk_mul_f32 v[24:25], v[24:25], v[16:17]
	v_pk_mul_f32 v[16:17], v[26:27], v[32:33]
	s_nop 0
	v_pk_mul_f32 v[26:27], v[16:17], v[18:19]
	v_mul_f32_e32 v19, 0xbfb8aa3b, v12
	v_cvt_pk_bf16_f32 v16, v20, v21
	v_exp_f32_e32 v20, v19
	v_mul_f32_e32 v19, 0xbfb8aa3b, v13
	v_exp_f32_e32 v21, v19
	v_cvt_pk_bf16_f32 v17, v22, v23
	v_add_co_u32_e32 v22, vcc, s53, v60
	v_cvt_pk_bf16_f32 v18, v24, v25
	v_cvt_pk_bf16_f32 v19, v26, v27
	v_add_f32_e32 v20, 1.0, v20
	v_add_f32_e32 v21, 1.0, v21
	v_addc_co_u32_e32 v23, vcc, 0, v61, vcc
	v_rcp_f32_e32 v20, v20
	v_rcp_f32_e32 v21, v21
	global_store_dwordx4 v[22:23], v[16:19], off
	s_and_b64 vcc, exec, s[8:9]
	v_pk_mul_f32 v[12:13], v[12:13], v[20:21]
	v_mul_f32_e32 v16, 0xbfb8aa3b, v14
	v_mul_f32_e32 v17, 0xbfb8aa3b, v15
	v_exp_f32_e32 v16, v16
	v_exp_f32_e32 v17, v17
	v_pk_mul_f32 v[4:5], v[12:13], v[4:5]
	v_add_f32_e32 v12, 1.0, v16
	v_add_f32_e32 v13, 1.0, v17
	v_mul_f32_e32 v16, 0xbfb8aa3b, v8
	v_mul_f32_e32 v17, 0xbfb8aa3b, v9
	v_rcp_f32_e32 v12, v12
	v_rcp_f32_e32 v13, v13
	v_exp_f32_e32 v16, v16
	v_exp_f32_e32 v17, v17
	v_pk_mul_f32 v[12:13], v[14:15], v[12:13]
	v_add_f32_e32 v14, 1.0, v16
	v_add_f32_e32 v15, 1.0, v17
	v_mul_f32_e32 v16, 0xbfb8aa3b, v10
	v_mul_f32_e32 v17, 0xbfb8aa3b, v11
	v_exp_f32_e32 v16, v16
	v_exp_f32_e32 v17, v17
	v_rcp_f32_e32 v14, v14
	v_rcp_f32_e32 v15, v15
	v_add_f32_e32 v16, 1.0, v16
	v_add_f32_e32 v17, 1.0, v17
	v_rcp_f32_e32 v16, v16
	v_rcp_f32_e32 v17, v17
	v_pk_mul_f32 v[8:9], v[8:9], v[14:15]
	v_pk_mul_f32 v[6:7], v[12:13], v[6:7]
	v_pk_mul_f32 v[8:9], v[8:9], v[0:1]
	v_pk_mul_f32 v[0:1], v[10:11], v[16:17]
	s_nop 0
	v_pk_mul_f32 v[10:11], v[0:1], v[2:3]
	v_cvt_pk_bf16_f32 v0, v4, v5
	v_cvt_pk_bf16_f32 v1, v6, v7
	v_cvt_pk_bf16_f32 v2, v8, v9
	v_cvt_pk_bf16_f32 v3, v10, v11
	global_store_dwordx4 v[22:23], v[0:3], off offset:2048
	s_cbranch_vccz .LBB0_1559
	s_waitcnt vmcnt(0)
	s_cmpk_gt_u32 s36, 0xff
	s_cbranch_scc1 .LBB0_1566
	s_barrier

; #define PG8_STAGE(bufoff, gbase, voff) do { _Pragma("unroll") for (int _i = 0; _i < 2; ++_i) \
;         __builtin_amdgcn_global_load_lds((const unsigned*)((const char*)(gbase) + (voff)[_i]), (LAS unsigned*)(lds + (bufoff) + ldsw + _i * 8192), 16, 0, 0); } while (0)
; #define PG8_LDA(dst, b, h) do { _Pragma("unroll") for (int m = 0; m < 4; ++m) _Pragma("unroll") for (int k = 0; k < 2; ++k) dst[m][k] = *(const LAS bf16x8*)(lds + PG8_SA(b, h) + aoff + m * 2048 + k * 1024); } while (0)
; #define PG8_LDB(dst, b, h) do { _Pragma("unroll") for (int n = 0; n < 2; ++n) _Pragma("unroll") for (int k = 0; k < 2; ++k) dst[n][k] = *(const LAS bf16x8*)(lds + PG8_SB(b, h) + boff + n * 2048 + k * 1024); } while (0)
; #define PG8_MMA(ai, bj, At, Bt) do { __builtin_amdgcn_s_setprio(1); _Pragma("unroll") for (int m = 0; m < 4; ++m) _Pragma("unroll") for (int n = 0; n < 2; ++n) _Pragma("unroll") for (int k = 0; k < 2; ++k) \
;         acc[ai][bj][m][n] = __builtin_amdgcn_mfma_f32_16x16x32_bf16(Bt[n][k], At[m][k], acc[ai][bj][m][n], 0, 0, 0); __builtin_amdgcn_s_setprio(0); } while (0)
; #define PG8_WAIT_V(n) asm volatile("s_waitcnt vmcnt(" #n ")" ::: "memory")
; #define PG8_WAIT_L(n) asm volatile("s_waitcnt lgkmcnt(" #n ")" ::: "memory")
; #define PG8_BAR __builtin_amdgcn_s_barrier()
; #define PG8_SCHED __builtin_amdgcn_sched_barrier(0)
; template <class Epi, class Sched>
; __device__ __forceinline__ void gemm_phase(LAS unsigned char* lds, const Gemm g, const Sched& S, const Epi& E) {
;     ...
;             PG8_LDB(B0, 0, 0); PG8_SCHED; PG8_LDA(At, 0, 0); PG8_STAGE(PG8_SA(1, 1), a1 + hstep, voffA);
;             PG8_WAIT_L(8); PG8_BAR; PG8_WAIT_L(0); PG8_MMA(0, 0, At, B0); PG8_BAR; PG8_SCHED;
;             PG8_LDB(B1, 0, 1); PG8_STAGE(PG8_SB(0, 0), b2, voffB);
;             PG8_BAR; PG8_WAIT_L(0); PG8_MMA(0, 1, At, B1); PG8_BAR;
;             PG8_LDA(At, 0, 1); PG8_STAGE(PG8_SA(0, 0), a2, voffA);
;             PG8_BAR; PG8_WAIT_L(0); PG8_MMA(1, 0, At, B0); PG8_BAR; PG8_SCHED;
;             PG8_STAGE(PG8_SB(0, 1), b2 + hstep, voffB);
;             PG8_WAIT_V(6); PG8_BAR; PG8_MMA(1, 1, At, B1); PG8_BAR;
;             PG8_LDB(B0, 1, 0); PG8_SCHED; PG8_LDA(At, 1, 0); PG8_STAGE(PG8_SA(0, 1), a2 + hstep, voffA);
;             PG8_WAIT_L(8); PG8_BAR; PG8_WAIT_L(0); PG8_MMA(0, 0, At, B0); PG8_BAR; PG8_SCHED;
.LBB0_1640:
	ds_read_b128 v[128:131], v187
	ds_read_b128 v[132:135], v187 offset:1024
	ds_read_b128 v[136:139], v187 offset:2048
	ds_read_b128 v[140:143], v187 offset:3072
	s_add_u32 s38, s36, 0x4000
	s_addc_u32 s39, s37, 0
	s_cmpk_eq_i32 s62, 0x52
	s_cselect_b32 s42, s8, s38
	s_cselect_b32 s43, s9, s39
	s_cselect_b32 s38, s10, s60
	s_cselect_b32 s39, s11, s61
	s_add_u32 s40, s42, 0x8000
	s_addc_u32 s41, s43, 0
	v_lshl_add_u64 v[194:195], s[36:37], 0, v[164:165]
	s_add_i32 m0, s49, 0xc000
	ds_read_b128 v[144:147], v188
	ds_read_b128 v[148:151], v188 offset:1024
	ds_read_b128 v[152:155], v188 offset:2048
	ds_read_b128 v[156:159], v188 offset:3072
	ds_read_b128 v[172:175], v188 offset:4096
	ds_read_b128 v[176:179], v188 offset:5120
	ds_read_b128 v[180:183], v188 offset:6144
	ds_read_b128 v[190:193], v188 offset:7168
	global_load_lds_dwordx4 v[194:195], off
	v_lshl_add_u64 v[194:195], s[36:37], 0, v[166:167]
	s_add_i32 m0, s49, 0xe000
	s_nop 0
	global_load_lds_dwordx4 v[194:195], off
	s_waitcnt lgkmcnt(8)
	s_barrier
	s_waitcnt lgkmcnt(0)
	v_mfma_f32_16x16x32_bf16 v[124:127], v[128:131], v[144:147], v[124:127]
	v_mfma_f32_16x16x32_bf16 v[120:123], v[136:139], v[144:147], v[120:123]
	v_mfma_f32_16x16x32_bf16 v[112:115], v[128:131], v[152:155], v[112:115]
	v_mfma_f32_16x16x32_bf16 v[104:107], v[136:139], v[152:155], v[104:107]
	v_mfma_f32_16x16x32_bf16 v[92:95], v[128:131], v[172:175], v[92:95]
	v_mfma_f32_16x16x32_bf16 v[88:91], v[136:139], v[172:175], v[88:91]
	v_mfma_f32_16x16x32_bf16 v[76:79], v[128:131], v[180:183], v[76:79]
	v_mfma_f32_16x16x32_bf16 v[72:75], v[136:139], v[180:183], v[72:75]
	v_mfma_f32_16x16x32_bf16 v[124:127], v[132:135], v[148:151], v[124:127]
	v_mfma_f32_16x16x32_bf16 v[120:123], v[140:143], v[148:151], v[120:123]
	v_mfma_f32_16x16x32_bf16 v[112:115], v[132:135], v[156:159], v[112:115]
	v_mfma_f32_16x16x32_bf16 v[104:107], v[140:143], v[156:159], v[104:107]
	v_mfma_f32_16x16x32_bf16 v[92:95], v[132:135], v[176:179], v[92:95]
	v_mfma_f32_16x16x32_bf16 v[88:91], v[140:143], v[176:179], v[88:91]
	v_mfma_f32_16x16x32_bf16 v[76:79], v[132:135], v[190:193], v[76:79]
	v_mfma_f32_16x16x32_bf16 v[72:75], v[140:143], v[190:193], v[72:75]
	s_barrier
	s_add_i32 s63, s71, s48
	v_lshl_add_u64 v[202:203], s[38:39], 0, v[160:161]
	s_mov_b32 m0, s63
	ds_read_b128 v[194:197], v189
	ds_read_b128 v[198:201], v189 offset:1024
	ds_read_b128 v[206:209], v189 offset:2048
	ds_read_b128 v[210:213], v189 offset:3072
	global_load_lds_dwordx4 v[202:203], off
	v_lshl_add_u64 v[202:203], s[38:39], 0, v[162:163]
	s_add_i32 m0, s63, 0x2000
	s_nop 0
	global_load_lds_dwordx4 v[202:203], off
	s_barrier
	s_waitcnt lgkmcnt(0)
	v_mfma_f32_16x16x32_bf16 v[116:119], v[194:197], v[144:147], v[116:119]
	v_mfma_f32_16x16x32_bf16 v[108:111], v[206:209], v[144:147], v[108:111]
	v_mfma_f32_16x16x32_bf16 v[100:103], v[194:197], v[152:155], v[100:103]
	v_mfma_f32_16x16x32_bf16 v[96:99], v[206:209], v[152:155], v[96:99]
	v_mfma_f32_16x16x32_bf16 v[84:87], v[194:197], v[172:175], v[84:87]
	v_mfma_f32_16x16x32_bf16 v[80:83], v[206:209], v[172:175], v[80:83]
	v_mfma_f32_16x16x32_bf16 v[68:71], v[194:197], v[180:183], v[68:71]
	v_mfma_f32_16x16x32_bf16 v[64:67], v[206:209], v[180:183], v[64:67]
	v_mfma_f32_16x16x32_bf16 v[116:119], v[198:201], v[148:151], v[116:119]
	v_mfma_f32_16x16x32_bf16 v[108:111], v[210:213], v[148:151], v[108:111]
	v_mfma_f32_16x16x32_bf16 v[100:103], v[198:201], v[156:159], v[100:103]
	v_mfma_f32_16x16x32_bf16 v[96:99], v[210:213], v[156:159], v[96:99]
	v_mfma_f32_16x16x32_bf16 v[84:87], v[198:201], v[176:179], v[84:87]
	v_mfma_f32_16x16x32_bf16 v[80:83], v[210:213], v[176:179], v[80:83]
	v_mfma_f32_16x16x32_bf16 v[68:71], v[198:201], v[190:193], v[68:71]
	v_mfma_f32_16x16x32_bf16 v[64:67], v[210:213], v[190:193], v[64:67]
	s_mov_b32 m0, s49
	v_lshl_add_u64 v[202:203], s[42:43], 0, v[160:161]
	s_barrier
	ds_read_b128 v[144:147], v188 offset:16384
	ds_read_b128 v[148:151], v188 offset:17408
	ds_read_b128 v[152:155], v188 offset:18432
	ds_read_b128 v[156:159], v188 offset:19456
	ds_read_b128 v[172:175], v188 offset:20480
	ds_read_b128 v[176:179], v188 offset:21504
	ds_read_b128 v[180:183], v188 offset:22528
	ds_read_b128 v[190:193], v188 offset:23552
	global_load_lds_dwordx4 v[202:203], off
	v_lshl_add_u64 v[202:203], s[42:43], 0, v[162:163]
	s_mov_b32 m0, s50
	s_nop 0
	global_load_lds_dwordx4 v[202:203], off
	s_barrier
	s_waitcnt lgkmcnt(0)
	v_mfma_f32_16x16x32_bf16 v[60:63], v[128:131], v[144:147], v[60:63]
	v_mfma_f32_16x16x32_bf16 v[56:59], v[136:139], v[144:147], v[56:59]
	v_mfma_f32_16x16x32_bf16 v[48:51], v[128:131], v[152:155], v[48:51]
	v_mfma_f32_16x16x32_bf16 v[40:43], v[136:139], v[152:155], v[40:43]
	v_mfma_f32_16x16x32_bf16 v[28:31], v[128:131], v[172:175], v[28:31]
	v_mfma_f32_16x16x32_bf16 v[24:27], v[136:139], v[172:175], v[24:27]
	v_mfma_f32_16x16x32_bf16 v[16:19], v[128:131], v[180:183], v[16:19]
	v_mfma_f32_16x16x32_bf16 v[8:11], v[136:139], v[180:183], v[8:11]
	v_mfma_f32_16x16x32_bf16 v[60:63], v[132:135], v[148:151], v[60:63]
	v_mfma_f32_16x16x32_bf16 v[56:59], v[140:143], v[148:151], v[56:59]
	v_mfma_f32_16x16x32_bf16 v[48:51], v[132:135], v[156:159], v[48:51]
	v_mfma_f32_16x16x32_bf16 v[40:43], v[140:143], v[156:159], v[40:43]
	v_mfma_f32_16x16x32_bf16 v[28:31], v[132:135], v[176:179], v[28:31]
	v_mfma_f32_16x16x32_bf16 v[24:27], v[140:143], v[176:179], v[24:27]
	v_mfma_f32_16x16x32_bf16 v[16:19], v[132:135], v[190:193], v[16:19]
	v_mfma_f32_16x16x32_bf16 v[8:11], v[140:143], v[190:193], v[8:11]
	s_barrier
; #define PG8_STAGE(bufoff, gbase, voff) do { _Pragma("unroll") for (int _i = 0; _i < 2; ++_i) \
;         __builtin_amdgcn_global_load_lds((const unsigned*)((const char*)(gbase) + (voff)[_i]), (LAS unsigned*)(lds + (bufoff) + ldsw + _i * 8192), 16, 0, 0); } while (0)
; #define PG8_LDA(dst, b, h) do { _Pragma("unroll") for (int m = 0; m < 4; ++m) _Pragma("unroll") for (int k = 0; k < 2; ++k) dst[m][k] = *(const LAS bf16x8*)(lds + PG8_SA(b, h) + aoff + m * 2048 + k * 1024); } while (0)
; #define PG8_LDB(dst, b, h) do { _Pragma("unroll") for (int n = 0; n < 2; ++n) _Pragma("unroll") for (int k = 0; k < 2; ++k) dst[n][k] = *(const LAS bf16x8*)(lds + PG8_SB(b, h) + boff + n * 2048 + k * 1024); } while (0)
; #define PG8_MMA(ai, bj, At, Bt) do { __builtin_amdgcn_s_setprio(1); _Pragma("unroll") for (int m = 0; m < 4; ++m) _Pragma("unroll") for (int n = 0; n < 2; ++n) _Pragma("unroll") for (int k = 0; k < 2; ++k) \
;         acc[ai][bj][m][n] = __builtin_amdgcn_mfma_f32_16x16x32_bf16(Bt[n][k], At[m][k], acc[ai][bj][m][n], 0, 0, 0); __builtin_amdgcn_s_setprio(0); } while (0)
; #define PG8_WAIT_V(n) asm volatile("s_waitcnt vmcnt(" #n ")" ::: "memory")
; #define PG8_WAIT_L(n) asm volatile("s_waitcnt lgkmcnt(" #n ")" ::: "memory")
; #define PG8_BAR __builtin_amdgcn_s_barrier()
; #define PG8_SCHED __builtin_amdgcn_sched_barrier(0)
; template <class Epi, class Sched>
; __device__ __forceinline__ void gemm_phase(LAS unsigned char* lds, const Gemm g, const Sched& S, const Epi& E) {
;     ...
;             PG8_BAR; PG8_WAIT_L(0); PG8_MMA(1, 0, At, B0); PG8_BAR; PG8_SCHED;
;             PG8_STAGE(PG8_SB(0, 1), b2 + hstep, voffB);
;             PG8_WAIT_V(6); PG8_BAR; PG8_MMA(1, 1, At, B1); PG8_BAR;
;             PG8_LDB(B0, 1, 0); PG8_SCHED; PG8_LDA(At, 1, 0); PG8_STAGE(PG8_SA(0, 1), a2 + hstep, voffA);
;             PG8_WAIT_L(8); PG8_BAR; PG8_WAIT_L(0); PG8_MMA(0, 0, At, B0); PG8_BAR; PG8_SCHED;
;             PG8_LDB(B1, 1, 1); PG8_STAGE(PG8_SB(1, 0), b3, voffB);
;             PG8_BAR; PG8_WAIT_L(0); PG8_MMA(0, 1, At, B1); PG8_BAR;
;             PG8_LDA(At, 1, 1); PG8_STAGE(PG8_SA(1, 0), a3, voffA);
;             PG8_BAR; PG8_WAIT_L(0); PG8_MMA(1, 0, At, B0); PG8_BAR; PG8_SCHED;
	s_add_u32 s64, s38, 0x4000
	s_addc_u32 s65, s39, 0
	s_add_i32 s63, s56, s48
	v_lshl_add_u64 v[128:129], s[64:65], 0, v[160:161]
	s_mov_b32 m0, s63
	s_nop 0
	global_load_lds_dwordx4 v[128:129], off
	v_lshl_add_u64 v[128:129], s[64:65], 0, v[162:163]
	s_add_i32 m0, s63, 0x2000
	s_nop 0
	global_load_lds_dwordx4 v[128:129], off
	s_waitcnt vmcnt(6)
	s_barrier
	v_mfma_f32_16x16x32_bf16 v[52:55], v[194:197], v[144:147], v[52:55]
	v_mfma_f32_16x16x32_bf16 v[44:47], v[206:209], v[144:147], v[44:47]
	v_mfma_f32_16x16x32_bf16 v[36:39], v[194:197], v[152:155], v[36:39]
	v_mfma_f32_16x16x32_bf16 v[32:35], v[206:209], v[152:155], v[32:35]
	v_mfma_f32_16x16x32_bf16 v[20:23], v[194:197], v[172:175], v[20:23]
	v_mfma_f32_16x16x32_bf16 v[12:15], v[206:209], v[172:175], v[12:15]
	v_mfma_f32_16x16x32_bf16 v[4:7], v[194:197], v[180:183], v[4:7]
	v_mfma_f32_16x16x32_bf16 v[0:3], v[206:209], v[180:183], v[0:3]
	v_mfma_f32_16x16x32_bf16 v[52:55], v[198:201], v[148:151], v[52:55]
	v_mfma_f32_16x16x32_bf16 v[44:47], v[210:213], v[148:151], v[44:47]
	v_mfma_f32_16x16x32_bf16 v[36:39], v[198:201], v[156:159], v[36:39]
	v_mfma_f32_16x16x32_bf16 v[32:35], v[210:213], v[156:159], v[32:35]
	v_mfma_f32_16x16x32_bf16 v[20:23], v[198:201], v[176:179], v[20:23]
	v_mfma_f32_16x16x32_bf16 v[12:15], v[210:213], v[176:179], v[12:15]
	v_mfma_f32_16x16x32_bf16 v[4:7], v[198:201], v[190:193], v[4:7]
	v_mfma_f32_16x16x32_bf16 v[0:3], v[210:213], v[190:193], v[0:3]
	s_add_i32 s63, 0, 0x18000
	v_add_u32_e32 v140, s63, v185
	s_barrier
	ds_read_b128 v[128:131], v140
	ds_read_b128 v[132:135], v140 offset:1024
	ds_read_b128 v[136:139], v140 offset:2048
	ds_read_b128 v[140:143], v140 offset:3072
	s_add_u32 s42, s42, 0x4000
	s_addc_u32 s43, s43, 0
	s_mov_b32 m0, s51
	v_lshl_add_u64 v[194:195], s[42:43], 0, v[160:161]
	ds_read_b128 v[144:147], v188 offset:32768
	ds_read_b128 v[148:151], v188 offset:33792
	ds_read_b128 v[152:155], v188 offset:34816
	ds_read_b128 v[156:159], v188 offset:35840
	ds_read_b128 v[172:175], v188 offset:36864
	ds_read_b128 v[176:179], v188 offset:37888
	ds_read_b128 v[180:183], v188 offset:38912
	ds_read_b128 v[190:193], v188 offset:39936
	global_load_lds_dwordx4 v[194:195], off
	v_lshl_add_u64 v[194:195], s[42:43], 0, v[162:163]
	s_mov_b32 m0, s52
	s_nop 0
	global_load_lds_dwordx4 v[194:195], off
	s_waitcnt lgkmcnt(8)
	s_barrier
	s_waitcnt lgkmcnt(0)
	v_mfma_f32_16x16x32_bf16 v[124:127], v[128:131], v[144:147], v[124:127]
	v_mfma_f32_16x16x32_bf16 v[120:123], v[136:139], v[144:147], v[120:123]
	v_mfma_f32_16x16x32_bf16 v[112:115], v[128:131], v[152:155], v[112:115]
	v_mfma_f32_16x16x32_bf16 v[104:107], v[136:139], v[152:155], v[104:107]
	v_mfma_f32_16x16x32_bf16 v[92:95], v[128:131], v[172:175], v[92:95]
	v_mfma_f32_16x16x32_bf16 v[88:91], v[136:139], v[172:175], v[88:91]
	v_mfma_f32_16x16x32_bf16 v[76:79], v[128:131], v[180:183], v[76:79]
	v_mfma_f32_16x16x32_bf16 v[72:75], v[136:139], v[180:183], v[72:75]
	v_mfma_f32_16x16x32_bf16 v[124:127], v[132:135], v[148:151], v[124:127]
	v_mfma_f32_16x16x32_bf16 v[120:123], v[140:143], v[148:151], v[120:123]
	v_mfma_f32_16x16x32_bf16 v[112:115], v[132:135], v[156:159], v[112:115]
	v_mfma_f32_16x16x32_bf16 v[104:107], v[140:143], v[156:159], v[104:107]
	v_mfma_f32_16x16x32_bf16 v[92:95], v[132:135], v[176:179], v[92:95]
	v_mfma_f32_16x16x32_bf16 v[88:91], v[140:143], v[176:179], v[88:91]
	v_mfma_f32_16x16x32_bf16 v[76:79], v[132:135], v[190:193], v[76:79]
	v_mfma_f32_16x16x32_bf16 v[72:75], v[140:143], v[190:193], v[72:75]
	s_barrier
	s_add_i32 s64, 0, 0x1c000
	s_add_u32 s42, s38, 0x8000
	v_add_u32_e32 v202, s64, v185
	s_addc_u32 s43, s39, 0
	s_add_i32 s63, s63, s48
	ds_read_b128 v[194:197], v202
	ds_read_b128 v[198:201], v202 offset:1024
	ds_read_b128 v[206:209], v202 offset:2048
	ds_read_b128 v[210:213], v202 offset:3072
	v_lshl_add_u64 v[202:203], s[42:43], 0, v[160:161]
	s_mov_b32 m0, s63
	s_nop 0
	global_load_lds_dwordx4 v[202:203], off
	v_lshl_add_u64 v[202:203], s[42:43], 0, v[162:163]
	s_add_i32 m0, s63, 0x2000
	s_nop 0
	global_load_lds_dwordx4 v[202:203], off
	s_barrier
	s_waitcnt lgkmcnt(0)
	v_mfma_f32_16x16x32_bf16 v[116:119], v[194:197], v[144:147], v[116:119]
	v_mfma_f32_16x16x32_bf16 v[108:111], v[206:209], v[144:147], v[108:111]
	v_mfma_f32_16x16x32_bf16 v[100:103], v[194:197], v[152:155], v[100:103]
	v_mfma_f32_16x16x32_bf16 v[96:99], v[206:209], v[152:155], v[96:99]
	v_mfma_f32_16x16x32_bf16 v[84:87], v[194:197], v[172:175], v[84:87]
	v_mfma_f32_16x16x32_bf16 v[80:83], v[206:209], v[172:175], v[80:83]
	v_mfma_f32_16x16x32_bf16 v[68:71], v[194:197], v[180:183], v[68:71]
	v_mfma_f32_16x16x32_bf16 v[64:67], v[206:209], v[180:183], v[64:67]
	v_mfma_f32_16x16x32_bf16 v[116:119], v[198:201], v[148:151], v[116:119]
	v_mfma_f32_16x16x32_bf16 v[108:111], v[210:213], v[148:151], v[108:111]
	v_mfma_f32_16x16x32_bf16 v[100:103], v[198:201], v[156:159], v[100:103]
	v_mfma_f32_16x16x32_bf16 v[96:99], v[210:213], v[156:159], v[96:99]
	v_mfma_f32_16x16x32_bf16 v[84:87], v[198:201], v[176:179], v[84:87]
	v_mfma_f32_16x16x32_bf16 v[80:83], v[210:213], v[176:179], v[80:83]
	v_mfma_f32_16x16x32_bf16 v[68:71], v[198:201], v[190:193], v[68:71]
	v_mfma_f32_16x16x32_bf16 v[64:67], v[210:213], v[190:193], v[64:67]
	s_mov_b32 m0, s54
	v_lshl_add_u64 v[202:203], s[40:41], 0, v[160:161]
	s_barrier
	ds_read_b128 v[144:147], v188 offset:49152
	ds_read_b128 v[148:151], v188 offset:50176
	ds_read_b128 v[152:155], v188 offset:51200
	ds_read_b128 v[156:159], v188 offset:52224
	ds_read_b128 v[172:175], v188 offset:53248
	ds_read_b128 v[176:179], v188 offset:54272
	ds_read_b128 v[180:183], v188 offset:55296
	ds_read_b128 v[190:193], v188 offset:56320
	global_load_lds_dwordx4 v[202:203], off
	v_lshl_add_u64 v[202:203], s[40:41], 0, v[162:163]
	s_mov_b32 m0, s55
	s_nop 0
	global_load_lds_dwordx4 v[202:203], off
	s_barrier
; #define PG8_STAGE(bufoff, gbase, voff) do { _Pragma("unroll") for (int _i = 0; _i < 2; ++_i) \
;         __builtin_amdgcn_global_load_lds((const unsigned*)((const char*)(gbase) + (voff)[_i]), (LAS unsigned*)(lds + (bufoff) + ldsw + _i * 8192), 16, 0, 0); } while (0)
; #define PG8_MMA(ai, bj, At, Bt) do { __builtin_amdgcn_s_setprio(1); _Pragma("unroll") for (int m = 0; m < 4; ++m) _Pragma("unroll") for (int n = 0; n < 2; ++n) _Pragma("unroll") for (int k = 0; k < 2; ++k) \
;         acc[ai][bj][m][n] = __builtin_amdgcn_mfma_f32_16x16x32_bf16(Bt[n][k], At[m][k], acc[ai][bj][m][n], 0, 0, 0); __builtin_amdgcn_s_setprio(0); } while (0)
; #define PG8_BAR __builtin_amdgcn_s_barrier()
; template <class Epi, class Sched>
; __device__ __forceinline__ void gemm_phase(LAS unsigned char* lds, const Gemm g, const Sched& S, const Epi& E) {
;     ...
;             PG8_BAR; PG8_WAIT_L(0); PG8_MMA(1, 0, At, B0); PG8_BAR; PG8_SCHED;
;             PG8_STAGE(PG8_SB(1, 1), b3 + hstep, voffB);
;             PG8_WAIT_V(6); PG8_BAR; PG8_MMA(1, 1, At, B1); PG8_BAR;
;         }
;         E(acc, cur, wr, wc, fr, fq);
;     __device__ __forceinline__ void operator()(const f32x4 (&acc)[2][2][4][2], const Unit& u, int wr, int wc, int fr, int fq) const {
;         const int row0 = u.pm * BM + wr * 64 + fr, col0 = u.pn * BM + wc * 32 + 4 * fq;
;         f32x4 gv[2][2], bv[2][2];
;         if (MODE == 1) {
; #pragma unroll
;             for (int bj = 0; bj < 2; ++bj)
; #pragma unroll
;                 for (int n = 0; n < 2; ++n) { gv[bj][n] = *(const f32x4*)(g + col0 + bj * HALF + n * 16); bv[bj][n] = *(const f32x4*)(b + col0 + bj * HALF + n * 16); }
;         }
; #pragma unroll
;         for (int ai = 0; ai < 2; ++ai)
; #pragma unroll
;             for (int mh = 0; mh < 2; ++mh) {
;                 f32x4 rv[2][2][2]; f32x2 st[2];
; #pragma unroll
;                 for (int mm = 0; mm < 2; ++mm) {
;                     const int r = row0 + ai * HALF + (mh * 2 + mm) * 16;
;                     const float* rp = MODE == 0 ? ((r < 8192 ? x0 + (size_t)r * DM : x1 + (size_t)(r - 8192) * DM) + col0) : (Z + (size_t)r * DM + col0);
;                     if (MODE == 1) st[mm] = stats[r];
; #pragma unroll
;                     for (int bj = 0; bj < 2; ++bj)
; #pragma unroll
;                         for (int n = 0; n < 2; ++n) rv[mm][bj][n] = *(const f32x4*)(rp + bj * HALF + n * 16);
;                 }
	s_waitcnt lgkmcnt(0)
	v_mfma_f32_16x16x32_bf16 v[60:63], v[128:131], v[144:147], v[60:63]
	v_mfma_f32_16x16x32_bf16 v[56:59], v[136:139], v[144:147], v[56:59]
	v_mfma_f32_16x16x32_bf16 v[48:51], v[128:131], v[152:155], v[48:51]
	v_mfma_f32_16x16x32_bf16 v[40:43], v[136:139], v[152:155], v[40:43]
	v_mfma_f32_16x16x32_bf16 v[28:31], v[128:131], v[172:175], v[28:31]
	v_mfma_f32_16x16x32_bf16 v[24:27], v[136:139], v[172:175], v[24:27]
	v_mfma_f32_16x16x32_bf16 v[16:19], v[128:131], v[180:183], v[16:19]
	v_mfma_f32_16x16x32_bf16 v[8:11], v[136:139], v[180:183], v[8:11]
	v_mfma_f32_16x16x32_bf16 v[60:63], v[132:135], v[148:151], v[60:63]
	v_mfma_f32_16x16x32_bf16 v[56:59], v[140:143], v[148:151], v[56:59]
	v_mfma_f32_16x16x32_bf16 v[48:51], v[132:135], v[156:159], v[48:51]
	v_mfma_f32_16x16x32_bf16 v[40:43], v[140:143], v[156:159], v[40:43]
	v_mfma_f32_16x16x32_bf16 v[28:31], v[132:135], v[176:179], v[28:31]
	v_mfma_f32_16x16x32_bf16 v[24:27], v[140:143], v[176:179], v[24:27]
	v_mfma_f32_16x16x32_bf16 v[16:19], v[132:135], v[190:193], v[16:19]
	v_mfma_f32_16x16x32_bf16 v[8:11], v[140:143], v[190:193], v[8:11]
	s_barrier
	s_add_u32 s38, s38, 0xc000
	s_addc_u32 s39, s39, 0
	s_add_i32 s40, s64, s48
	v_lshl_add_u64 v[128:129], s[38:39], 0, v[160:161]
	s_mov_b32 m0, s40
	s_nop 0
	global_load_lds_dwordx4 v[128:129], off
	v_lshl_add_u64 v[128:129], s[38:39], 0, v[162:163]
	s_add_i32 m0, s40, 0x2000
	s_nop 0
	global_load_lds_dwordx4 v[128:129], off
	s_waitcnt vmcnt(6)
	s_barrier
	v_mfma_f32_16x16x32_bf16 v[52:55], v[194:197], v[144:147], v[52:55]
	v_mfma_f32_16x16x32_bf16 v[44:47], v[206:209], v[144:147], v[44:47]
	v_mfma_f32_16x16x32_bf16 v[36:39], v[194:197], v[152:155], v[36:39]
	v_mfma_f32_16x16x32_bf16 v[32:35], v[206:209], v[152:155], v[32:35]
	v_mfma_f32_16x16x32_bf16 v[20:23], v[194:197], v[172:175], v[20:23]
	v_mfma_f32_16x16x32_bf16 v[12:15], v[206:209], v[172:175], v[12:15]
	v_mfma_f32_16x16x32_bf16 v[4:7], v[194:197], v[180:183], v[4:7]
	v_mfma_f32_16x16x32_bf16 v[0:3], v[206:209], v[180:183], v[0:3]
	v_mfma_f32_16x16x32_bf16 v[52:55], v[198:201], v[148:151], v[52:55]
	v_mfma_f32_16x16x32_bf16 v[44:47], v[210:213], v[148:151], v[44:47]
	v_mfma_f32_16x16x32_bf16 v[36:39], v[198:201], v[156:159], v[36:39]
	v_mfma_f32_16x16x32_bf16 v[32:35], v[210:213], v[156:159], v[32:35]
	v_mfma_f32_16x16x32_bf16 v[20:23], v[198:201], v[176:179], v[20:23]
	v_mfma_f32_16x16x32_bf16 v[12:15], v[210:213], v[176:179], v[12:15]
	v_mfma_f32_16x16x32_bf16 v[4:7], v[198:201], v[190:193], v[4:7]
	v_mfma_f32_16x16x32_bf16 v[0:3], v[210:213], v[190:193], v[0:3]
	s_add_i32 s62, s62, 2
	s_add_u32 s36, s36, 0x10000
	s_addc_u32 s37, s37, 0
	s_add_u32 s60, s60, 0x10000
	s_addc_u32 s61, s61, 0
	s_cmpk_gt_u32 s62, 0x53
	s_barrier
	s_cbranch_scc0 .LBB0_1640
	v_lshl_or_b32 v128, s59, 8, v186
	v_ashrrev_i32_e32 v129, 31, v128
	v_lshl_add_u32 v180, s33, 8, v184
	v_lshlrev_b64 v[172:173], 2, v[128:129]
	v_ashrrev_i32_e32 v181, 31, v180
	v_lshl_add_u64 v[174:175], s[12:13], 0, v[172:173]
	v_lshlrev_b64 v[176:177], 13, v[180:181]
	v_lshl_add_u64 v[128:129], v[174:175], 0, v[176:177]
	v_lshl_add_u64 v[178:179], v[180:181], 3, s[14:15]
	v_or_b32_e32 v130, 16, v180
	global_load_dwordx2 v[202:203], v[178:179], off
	global_load_dwordx4 v[190:193], v[128:129], off
	global_load_dwordx4 v[194:197], v[128:129], off offset:64
	global_load_dwordx4 v[198:201], v[128:129], off offset:512
	v_ashrrev_i32_e32 v131, 31, v130
	global_load_dwordx4 v[206:209], v[128:129], off offset:576
	v_lshlrev_b64 v[218:219], 13, v[130:131]
	v_lshl_add_u64 v[128:129], v[130:131], 3, s[14:15]
	v_lshl_add_u64 v[222:223], v[174:175], 0, v[218:219]
	global_load_dwordx2 v[182:183], v[128:129], off
	global_load_dwordx4 v[210:213], v[222:223], off
	v_lshl_add_u64 v[128:129], s[16:17], 0, v[172:173]
	v_lshl_add_u64 v[132:133], s[18:19], 0, v[172:173]
	global_load_dwordx4 v[152:155], v[132:133], off
	global_load_dwordx4 v[156:159], v[128:129], off
	global_load_dwordx4 v[144:147], v[128:129], off offset:64
	global_load_dwordx4 v[148:151], v[132:133], off offset:64
	global_load_dwordx4 v[136:139], v[132:133], off offset:512
	global_load_dwordx4 v[140:143], v[128:129], off offset:512
	s_nop 0
	global_load_dwordx4 v[128:131], v[128:129], off offset:576
	s_nop 0
	global_load_dwordx4 v[132:135], v[132:133], off offset:576
	s_nop 0
	global_load_dwordx4 v[214:217], v[222:223], off offset:64
	v_lshl_add_u64 v[220:221], s[12:13], 0, v[176:177]
	v_lshl_add_u64 v[226:227], v[220:221], 0, v[172:173]
	v_lshl_add_u64 v[228:229], s[12:13], 0, v[218:219]
	global_load_dwordx4 v[218:221], v[222:223], off offset:512
	s_nop 0
	global_load_dwordx4 v[222:225], v[222:223], off offset:576
	v_lshl_add_u64 v[228:229], v[228:229], 0, v[172:173]
	s_and_b64 vcc, exec, s[6:7]
	s_mov_b32 s59, s57
	s_mov_b32 s33, s58
	s_mov_b64 s[38:39], s[10:11]
	s_mov_b64 s[36:37], s[8:9]
	s_waitcnt vmcnt(0)
;     __device__ __forceinline__ void operator()(const f32x4 (&acc)[2][2][4][2], const Unit& u, int wr, int wc, int fr, int fq) const {
;     ...
;         for (int ai = 0; ai < 2; ++ai)
; #pragma unroll
;             for (int mh = 0; mh < 2; ++mh) {
;                 f32x4 rv[2][2][2]; f32x2 st[2];
; #pragma unroll
;                 for (int mm = 0; mm < 2; ++mm) {
;                     const int r = row0 + ai * HALF + (mh * 2 + mm) * 16;
;                     const float* rp = MODE == 0 ? ((r < 8192 ? x0 + (size_t)r * DM : x1 + (size_t)(r - 8192) * DM) + col0) : (Z + (size_t)r * DM + col0);
;                     if (MODE == 1) st[mm] = stats[r];
; #pragma unroll
;                     for (int bj = 0; bj < 2; ++bj)
; #pragma unroll
;                         for (int n = 0; n < 2; ++n) rv[mm][bj][n] = *(const f32x4*)(rp + bj * HALF + n * 16);
;                 }
; #pragma unroll
;                 for (int mm = 0; mm < 2; ++mm) {
;                     const int m = mh * 2 + mm, r = row0 + ai * HALF + m * 16;
;                     float* zp = Z + (size_t)r * DM + col0;
; #pragma unroll
;                     for (int bj = 0; bj < 2; ++bj)
; #pragma unroll
;                         for (int n = 0; n < 2; ++n) {
;                             f32x4 res = rv[mm][bj][n];
;                             if (MODE == 1) res = (res - st[mm].x) * st[mm].y * gv[bj][n] + bv[bj][n];
;                             *(f32x4*)(zp + bj * HALF + n * 16) = res * ALPHA + acc[ai][bj][m][n] * scale;
;                         }
;                 }
	v_sub_f32_e32 v193, v193, v202
	v_sub_f32_e32 v192, v192, v202
	v_sub_f32_e32 v191, v191, v202
	v_sub_f32_e32 v190, v190, v202
	v_sub_f32_e32 v207, v207, v202
	v_sub_f32_e32 v206, v206, v202
	v_sub_f32_e32 v197, v197, v202
	v_sub_f32_e32 v196, v196, v202
	v_sub_f32_e32 v195, v195, v202
	v_sub_f32_e32 v194, v194, v202
	v_sub_f32_e32 v201, v201, v202
	v_sub_f32_e32 v200, v200, v202
	v_sub_f32_e32 v199, v199, v202
	v_sub_f32_e32 v198, v198, v202
	v_sub_f32_e32 v209, v209, v202
	v_sub_f32_e32 v208, v208, v202
	v_pk_mul_f32 v[190:191], v[202:203], v[190:191] op_sel:[1,0]
	v_pk_mul_f32 v[192:193], v[202:203], v[192:193] op_sel:[1,0]
	v_pk_mul_f32 v[206:207], v[202:203], v[206:207] op_sel:[1,0]
	v_pk_mul_f32 v[194:195], v[202:203], v[194:195] op_sel:[1,0]
	v_pk_mul_f32 v[196:197], v[202:203], v[196:197] op_sel:[1,0]
	v_pk_mul_f32 v[198:199], v[202:203], v[198:199] op_sel:[1,0]
	v_pk_mul_f32 v[200:201], v[202:203], v[200:201] op_sel:[1,0]
	v_pk_mul_f32 v[202:203], v[202:203], v[208:209] op_sel:[1,0]
	v_pk_fma_f32 v[192:193], v[158:159], v[192:193], v[154:155]
	v_pk_fma_f32 v[190:191], v[156:157], v[190:191], v[152:153]
	v_pk_fma_f32 v[206:207], v[128:129], v[206:207], v[132:133]
	v_pk_fma_f32 v[196:197], v[146:147], v[196:197], v[150:151]
	v_pk_fma_f32 v[194:195], v[144:145], v[194:195], v[148:149]
	v_pk_fma_f32 v[200:201], v[142:143], v[200:201], v[138:139]
	v_pk_fma_f32 v[198:199], v[140:141], v[198:199], v[136:137]
	v_pk_fma_f32 v[202:203], v[130:131], v[202:203], v[134:135]
	v_pk_mul_f32 v[190:191], v[190:191], s[24:25] op_sel_hi:[1,0]
	v_pk_mul_f32 v[192:193], v[192:193], s[24:25] op_sel_hi:[1,0]
	v_pk_mul_f32 v[206:207], v[206:207], s[24:25] op_sel_hi:[1,0]
	v_pk_mul_f32 v[194:195], v[194:195], s[24:25] op_sel_hi:[1,0]
	v_pk_mul_f32 v[196:197], v[196:197], s[24:25] op_sel_hi:[1,0]
	v_pk_mul_f32 v[198:199], v[198:199], s[24:25] op_sel_hi:[1,0]
	v_pk_mul_f32 v[200:201], v[200:201], s[24:25] op_sel_hi:[1,0]
	v_pk_mul_f32 v[202:203], v[202:203], s[24:25] op_sel_hi:[1,0]
	v_pk_fma_f32 v[126:127], v[126:127], 0.5, v[192:193] op_sel_hi:[1,0,1]
	v_pk_fma_f32 v[124:125], v[124:125], 0.5, v[190:191] op_sel_hi:[1,0,1]
	v_pk_fma_f32 v[108:109], v[108:109], 0.5, v[206:207] op_sel_hi:[1,0,1]
	v_sub_f32_e32 v213, v213, v182
	v_pk_fma_f32 v[122:123], v[122:123], 0.5, v[196:197] op_sel_hi:[1,0,1]
	v_pk_fma_f32 v[120:121], v[120:121], 0.5, v[194:195] op_sel_hi:[1,0,1]
	v_pk_fma_f32 v[118:119], v[118:119], 0.5, v[200:201] op_sel_hi:[1,0,1]
	v_pk_fma_f32 v[116:117], v[116:117], 0.5, v[198:199] op_sel_hi:[1,0,1]
	v_pk_fma_f32 v[110:111], v[110:111], 0.5, v[202:203] op_sel_hi:[1,0,1]
	global_store_dwordx4 v[226:227], v[124:127], off
	global_store_dwordx4 v[226:227], v[120:123], off offset:64
	global_store_dwordx4 v[226:227], v[116:119], off offset:512
	global_store_dwordx4 v[226:227], v[108:111], off offset:576
	v_sub_f32_e32 v212, v212, v182
	s_nop 0
	v_sub_f32_e32 v109, v211, v182
	v_sub_f32_e32 v108, v210, v182
	v_pk_mul_f32 v[108:109], v[182:183], v[108:109] op_sel:[1,0]
	v_pk_mul_f32 v[110:111], v[182:183], v[212:213] op_sel:[1,0]
	v_pk_fma_f32 v[108:109], v[156:157], v[108:109], v[152:153]
	v_pk_fma_f32 v[110:111], v[158:159], v[110:111], v[154:155]
	v_pk_mul_f32 v[108:109], v[108:109], s[24:25] op_sel_hi:[1,0]
	v_pk_mul_f32 v[110:111], v[110:111], s[24:25] op_sel_hi:[1,0]
	v_pk_fma_f32 v[108:109], v[112:113], 0.5, v[108:109] op_sel_hi:[1,0,1]
	v_pk_fma_f32 v[110:111], v[114:115], 0.5, v[110:111] op_sel_hi:[1,0,1]
	global_store_dwordx4 v[228:229], v[108:111], off
	v_or_b32_e32 v112, 48, v180
	v_ashrrev_i32_e32 v113, 31, v112
	v_sub_f32_e32 v109, v217, v182
	v_sub_f32_e32 v108, v216, v182
	v_sub_f32_e32 v111, v215, v182
	v_sub_f32_e32 v110, v214, v182
	v_pk_mul_f32 v[110:111], v[182:183], v[110:111] op_sel:[1,0]
	v_pk_mul_f32 v[108:109], v[182:183], v[108:109] op_sel:[1,0]
	v_pk_fma_f32 v[110:111], v[144:145], v[110:111], v[148:149]
	v_pk_fma_f32 v[108:109], v[146:147], v[108:109], v[150:151]
	v_pk_mul_f32 v[110:111], v[110:111], s[24:25] op_sel_hi:[1,0]
	v_pk_mul_f32 v[108:109], v[108:109], s[24:25] op_sel_hi:[1,0]
	v_pk_fma_f32 v[104:105], v[104:105], 0.5, v[110:111] op_sel_hi:[1,0,1]
	v_pk_fma_f32 v[106:107], v[106:107], 0.5, v[108:109] op_sel_hi:[1,0,1]
	global_store_dwordx4 v[228:229], v[104:107], off offset:64
	s_nop 1
	v_sub_f32_e32 v105, v221, v182
	v_sub_f32_e32 v104, v220, v182
	v_sub_f32_e32 v107, v219, v182
	v_sub_f32_e32 v106, v218, v182
	v_pk_mul_f32 v[106:107], v[182:183], v[106:107] op_sel:[1,0]
	v_pk_mul_f32 v[104:105], v[182:183], v[104:105] op_sel:[1,0]
	v_pk_fma_f32 v[106:107], v[140:141], v[106:107], v[136:137]
	v_pk_fma_f32 v[104:105], v[142:143], v[104:105], v[138:139]
	v_pk_mul_f32 v[106:107], v[106:107], s[24:25] op_sel_hi:[1,0]
	v_pk_mul_f32 v[104:105], v[104:105], s[24:25] op_sel_hi:[1,0]
	v_pk_fma_f32 v[100:101], v[100:101], 0.5, v[106:107] op_sel_hi:[1,0,1]
	v_pk_fma_f32 v[102:103], v[102:103], 0.5, v[104:105] op_sel_hi:[1,0,1]
	global_store_dwordx4 v[228:229], v[100:103], off offset:512
	s_nop 1
	v_sub_f32_e32 v101, v225, v182
	v_sub_f32_e32 v100, v224, v182
	v_sub_f32_e32 v103, v223, v182
	v_sub_f32_e32 v102, v222, v182
	v_pk_mul_f32 v[102:103], v[182:183], v[102:103] op_sel:[1,0]
	v_pk_mul_f32 v[100:101], v[182:183], v[100:101] op_sel:[1,0]
	v_pk_fma_f32 v[102:103], v[128:129], v[102:103], v[132:133]
	v_pk_fma_f32 v[100:101], v[130:131], v[100:101], v[134:135]
	v_pk_mul_f32 v[102:103], v[102:103], s[24:25] op_sel_hi:[1,0]
	v_pk_mul_f32 v[100:101], v[100:101], s[24:25] op_sel_hi:[1,0]
	v_pk_fma_f32 v[96:97], v[96:97], 0.5, v[102:103] op_sel_hi:[1,0,1]
	v_pk_fma_f32 v[98:99], v[98:99], 0.5, v[100:101] op_sel_hi:[1,0,1]
	global_store_dwordx4 v[228:229], v[96:99], off offset:576
	s_nop 1
	v_or_b32_e32 v96, 32, v180
	v_ashrrev_i32_e32 v97, 31, v96
	v_lshlrev_b64 v[120:121], 13, v[96:97]
	v_lshl_add_u64 v[108:109], v[174:175], 0, v[120:121]
	v_lshl_add_u64 v[96:97], v[96:97], 3, s[14:15]
	global_load_dwordx2 v[182:183], v[96:97], off
	s_nop 0
	global_load_dwordx4 v[96:99], v[108:109], off
	global_load_dwordx4 v[100:103], v[108:109], off offset:64
	global_load_dwordx4 v[104:107], v[108:109], off offset:512
	s_nop 0
	global_load_dwordx4 v[108:111], v[108:109], off offset:576
	v_lshlrev_b64 v[180:181], 13, v[112:113]
	v_lshl_add_u64 v[112:113], v[112:113], 3, s[14:15]
	v_lshl_add_u64 v[124:125], v[174:175], 0, v[180:181]
	global_load_dwordx2 v[190:191], v[112:113], off
	s_nop 0
	global_load_dwordx4 v[112:115], v[124:125], off
	global_load_dwordx4 v[116:119], v[124:125], off offset:64
	v_lshl_add_u64 v[192:193], s[12:13], 0, v[120:121]
	global_load_dwordx4 v[120:123], v[124:125], off offset:512
	s_nop 0
	global_load_dwordx4 v[124:127], v[124:125], off offset:576
	v_lshl_add_u64 v[192:193], v[192:193], 0, v[172:173]
	s_waitcnt vmcnt(0)
;     __device__ __forceinline__ void operator()(const f32x4 (&acc)[2][2][4][2], const Unit& u, int wr, int wc, int fr, int fq) const {
;     ...
;         for (int ai = 0; ai < 2; ++ai)
; #pragma unroll
;             for (int mh = 0; mh < 2; ++mh) {
;                 f32x4 rv[2][2][2]; f32x2 st[2];
; #pragma unroll
;                 for (int mm = 0; mm < 2; ++mm) {
;                     const int r = row0 + ai * HALF + (mh * 2 + mm) * 16;
;                     const float* rp = MODE == 0 ? ((r < 8192 ? x0 + (size_t)r * DM : x1 + (size_t)(r - 8192) * DM) + col0) : (Z + (size_t)r * DM + col0);
;                     if (MODE == 1) st[mm] = stats[r];
; #pragma unroll
;                     for (int bj = 0; bj < 2; ++bj)
; #pragma unroll
;                         for (int n = 0; n < 2; ++n) rv[mm][bj][n] = *(const f32x4*)(rp + bj * HALF + n * 16);
;                 }
; #pragma unroll
;                 for (int mm = 0; mm < 2; ++mm) {
;                     const int m = mh * 2 + mm, r = row0 + ai * HALF + m * 16;
;                     float* zp = Z + (size_t)r * DM + col0;
; #pragma unroll
;                     for (int bj = 0; bj < 2; ++bj)
; #pragma unroll
;                         for (int n = 0; n < 2; ++n) {
;                             f32x4 res = rv[mm][bj][n];
;                             if (MODE == 1) res = (res - st[mm].x) * st[mm].y * gv[bj][n] + bv[bj][n];
;                             *(f32x4*)(zp + bj * HALF + n * 16) = res * ALPHA + acc[ai][bj][m][n] * scale;
;                         }
;                 }
	v_sub_f32_e32 v99, v99, v182
	v_sub_f32_e32 v98, v98, v182
	v_sub_f32_e32 v97, v97, v182
	v_sub_f32_e32 v96, v96, v182
	v_pk_mul_f32 v[96:97], v[182:183], v[96:97] op_sel:[1,0]
	v_pk_mul_f32 v[98:99], v[182:183], v[98:99] op_sel:[1,0]
	v_pk_fma_f32 v[96:97], v[156:157], v[96:97], v[152:153]
	v_pk_fma_f32 v[98:99], v[158:159], v[98:99], v[154:155]
	v_pk_mul_f32 v[96:97], v[96:97], s[24:25] op_sel_hi:[1,0]
	v_pk_mul_f32 v[98:99], v[98:99], s[24:25] op_sel_hi:[1,0]
	v_pk_fma_f32 v[92:93], v[92:93], 0.5, v[96:97] op_sel_hi:[1,0,1]
	v_pk_fma_f32 v[94:95], v[94:95], 0.5, v[98:99] op_sel_hi:[1,0,1]
	global_store_dwordx4 v[192:193], v[92:95], off
	v_lshl_add_u64 v[96:97], v[176:177], 0, s[26:27]
	s_nop 0
	v_sub_f32_e32 v93, v103, v182
	v_sub_f32_e32 v92, v102, v182
	v_sub_f32_e32 v95, v101, v182
	v_sub_f32_e32 v94, v100, v182
	v_pk_mul_f32 v[94:95], v[182:183], v[94:95] op_sel:[1,0]
	v_pk_mul_f32 v[92:93], v[182:183], v[92:93] op_sel:[1,0]
	v_pk_fma_f32 v[94:95], v[144:145], v[94:95], v[148:149]
	v_pk_fma_f32 v[92:93], v[146:147], v[92:93], v[150:151]
	v_pk_mul_f32 v[94:95], v[94:95], s[24:25] op_sel_hi:[1,0]
	v_pk_mul_f32 v[92:93], v[92:93], s[24:25] op_sel_hi:[1,0]
	v_pk_fma_f32 v[88:89], v[88:89], 0.5, v[94:95] op_sel_hi:[1,0,1]
	v_pk_fma_f32 v[90:91], v[90:91], 0.5, v[92:93] op_sel_hi:[1,0,1]
	global_store_dwordx4 v[192:193], v[88:91], off offset:64
	v_lshl_add_u64 v[100:101], v[176:177], 0, s[28:29]
	v_lshl_add_u64 v[92:93], v[174:175], 0, v[100:101]
	v_sub_f32_e32 v89, v107, v182
	v_sub_f32_e32 v88, v106, v182
	v_sub_f32_e32 v91, v105, v182
	v_sub_f32_e32 v90, v104, v182
	v_pk_mul_f32 v[90:91], v[182:183], v[90:91] op_sel:[1,0]
	v_pk_mul_f32 v[88:89], v[182:183], v[88:89] op_sel:[1,0]
	v_pk_fma_f32 v[90:91], v[140:141], v[90:91], v[136:137]
	v_pk_fma_f32 v[88:89], v[142:143], v[88:89], v[138:139]
	v_pk_mul_f32 v[90:91], v[90:91], s[24:25] op_sel_hi:[1,0]
	v_pk_mul_f32 v[88:89], v[88:89], s[24:25] op_sel_hi:[1,0]
	v_pk_fma_f32 v[84:85], v[84:85], 0.5, v[90:91] op_sel_hi:[1,0,1]
	v_pk_fma_f32 v[86:87], v[86:87], 0.5, v[88:89] op_sel_hi:[1,0,1]
	global_store_dwordx4 v[192:193], v[84:87], off offset:512
	s_nop 1
	v_sub_f32_e32 v85, v111, v182
	v_sub_f32_e32 v84, v110, v182
	v_sub_f32_e32 v87, v109, v182
	v_sub_f32_e32 v86, v108, v182
	v_pk_mul_f32 v[86:87], v[182:183], v[86:87] op_sel:[1,0]
	v_pk_mul_f32 v[84:85], v[182:183], v[84:85] op_sel:[1,0]
	v_pk_fma_f32 v[86:87], v[128:129], v[86:87], v[132:133]
	v_pk_fma_f32 v[84:85], v[130:131], v[84:85], v[134:135]
	v_pk_mul_f32 v[86:87], v[86:87], s[24:25] op_sel_hi:[1,0]
	v_pk_mul_f32 v[84:85], v[84:85], s[24:25] op_sel_hi:[1,0]
	v_pk_fma_f32 v[80:81], v[80:81], 0.5, v[86:87] op_sel_hi:[1,0,1]
	v_pk_fma_f32 v[82:83], v[82:83], 0.5, v[84:85] op_sel_hi:[1,0,1]
	global_store_dwordx4 v[192:193], v[80:83], off offset:576
	v_sub_f32_e32 v85, v113, v190
	v_sub_f32_e32 v84, v112, v190
	v_sub_f32_e32 v83, v115, v190
	v_sub_f32_e32 v82, v114, v190
	v_pk_mul_f32 v[84:85], v[190:191], v[84:85] op_sel:[1,0]
	v_pk_mul_f32 v[82:83], v[190:191], v[82:83] op_sel:[1,0]
	v_pk_fma_f32 v[84:85], v[156:157], v[84:85], v[152:153]
	v_pk_fma_f32 v[82:83], v[158:159], v[82:83], v[154:155]
	v_lshl_add_u64 v[80:81], s[12:13], 0, v[180:181]
	v_pk_mul_f32 v[84:85], v[84:85], s[24:25] op_sel_hi:[1,0]
	v_pk_mul_f32 v[82:83], v[82:83], s[24:25] op_sel_hi:[1,0]
	v_lshl_add_u64 v[80:81], v[80:81], 0, v[172:173]
	v_pk_fma_f32 v[78:79], v[78:79], 0.5, v[82:83] op_sel_hi:[1,0,1]
	v_pk_fma_f32 v[76:77], v[76:77], 0.5, v[84:85] op_sel_hi:[1,0,1]
	global_store_dwordx4 v[80:81], v[76:79], off
	s_nop 1
	v_sub_f32_e32 v77, v119, v190
	v_sub_f32_e32 v76, v118, v190
	v_sub_f32_e32 v79, v117, v190
	v_sub_f32_e32 v78, v116, v190
	v_pk_mul_f32 v[78:79], v[190:191], v[78:79] op_sel:[1,0]
	v_pk_mul_f32 v[76:77], v[190:191], v[76:77] op_sel:[1,0]
	v_pk_fma_f32 v[78:79], v[144:145], v[78:79], v[148:149]
	v_pk_fma_f32 v[76:77], v[146:147], v[76:77], v[150:151]
	v_pk_mul_f32 v[78:79], v[78:79], s[24:25] op_sel_hi:[1,0]
	v_pk_mul_f32 v[76:77], v[76:77], s[24:25] op_sel_hi:[1,0]
	v_pk_fma_f32 v[72:73], v[72:73], 0.5, v[78:79] op_sel_hi:[1,0,1]
	v_pk_fma_f32 v[74:75], v[74:75], 0.5, v[76:77] op_sel_hi:[1,0,1]
	global_store_dwordx4 v[80:81], v[72:75], off offset:64
	v_lshl_add_u64 v[76:77], v[174:175], 0, v[96:97]
	v_lshl_add_u64 v[96:97], s[12:13], 0, v[96:97]
	v_sub_f32_e32 v73, v123, v190
	v_sub_f32_e32 v72, v122, v190
	v_sub_f32_e32 v75, v121, v190
	v_sub_f32_e32 v74, v120, v190
	v_pk_mul_f32 v[74:75], v[190:191], v[74:75] op_sel:[1,0]
	v_pk_mul_f32 v[72:73], v[190:191], v[72:73] op_sel:[1,0]
	v_pk_fma_f32 v[74:75], v[140:141], v[74:75], v[136:137]
	v_pk_fma_f32 v[72:73], v[142:143], v[72:73], v[138:139]
	v_pk_mul_f32 v[74:75], v[74:75], s[24:25] op_sel_hi:[1,0]
	v_pk_mul_f32 v[72:73], v[72:73], s[24:25] op_sel_hi:[1,0]
	v_pk_fma_f32 v[68:69], v[68:69], 0.5, v[74:75] op_sel_hi:[1,0,1]
	v_pk_fma_f32 v[70:71], v[70:71], 0.5, v[72:73] op_sel_hi:[1,0,1]
	global_store_dwordx4 v[80:81], v[68:71], off offset:512
	v_lshl_add_u64 v[96:97], v[96:97], 0, v[172:173]
	s_nop 0
	v_sub_f32_e32 v69, v127, v190
	v_sub_f32_e32 v68, v126, v190
	v_sub_f32_e32 v71, v125, v190
	v_sub_f32_e32 v70, v124, v190
	v_pk_mul_f32 v[70:71], v[190:191], v[70:71] op_sel:[1,0]
	v_pk_mul_f32 v[68:69], v[190:191], v[68:69] op_sel:[1,0]
	v_pk_fma_f32 v[70:71], v[128:129], v[70:71], v[132:133]
	v_pk_fma_f32 v[68:69], v[130:131], v[68:69], v[134:135]
	v_pk_mul_f32 v[70:71], v[70:71], s[24:25] op_sel_hi:[1,0]
	v_pk_mul_f32 v[68:69], v[68:69], s[24:25] op_sel_hi:[1,0]
	v_pk_fma_f32 v[64:65], v[64:65], 0.5, v[70:71] op_sel_hi:[1,0,1]
	v_pk_fma_f32 v[66:67], v[66:67], 0.5, v[68:69] op_sel_hi:[1,0,1]
	global_store_dwordx4 v[80:81], v[64:67], off offset:576
	global_load_dwordx2 v[98:99], v[178:179], off offset:1024
	s_nop 0
	global_load_dwordx4 v[64:67], v[76:77], off
	global_load_dwordx4 v[68:71], v[76:77], off offset:64
	global_load_dwordx4 v[72:75], v[76:77], off offset:512
	s_nop 0
	global_load_dwordx4 v[76:79], v[76:77], off offset:576
	s_nop 0
	global_load_dwordx2 v[102:103], v[178:179], off offset:1152
	global_load_dwordx4 v[80:83], v[92:93], off
	global_load_dwordx4 v[84:87], v[92:93], off offset:64
	global_load_dwordx4 v[88:91], v[92:93], off offset:512
	s_nop 0
	global_load_dwordx4 v[92:95], v[92:93], off offset:576
	s_waitcnt vmcnt(0)
;     __device__ __forceinline__ void operator()(const f32x4 (&acc)[2][2][4][2], const Unit& u, int wr, int wc, int fr, int fq) const {
;     ...
;         for (int ai = 0; ai < 2; ++ai)
; #pragma unroll
;             for (int mh = 0; mh < 2; ++mh) {
;                 f32x4 rv[2][2][2]; f32x2 st[2];
; #pragma unroll
;                 for (int mm = 0; mm < 2; ++mm) {
;                     const int r = row0 + ai * HALF + (mh * 2 + mm) * 16;
;                     const float* rp = MODE == 0 ? ((r < 8192 ? x0 + (size_t)r * DM : x1 + (size_t)(r - 8192) * DM) + col0) : (Z + (size_t)r * DM + col0);
;                     if (MODE == 1) st[mm] = stats[r];
; #pragma unroll
;                     for (int bj = 0; bj < 2; ++bj)
; #pragma unroll
;                         for (int n = 0; n < 2; ++n) rv[mm][bj][n] = *(const f32x4*)(rp + bj * HALF + n * 16);
;                 }
; #pragma unroll
;                 for (int mm = 0; mm < 2; ++mm) {
;                     const int m = mh * 2 + mm, r = row0 + ai * HALF + m * 16;
;                     float* zp = Z + (size_t)r * DM + col0;
; #pragma unroll
;                     for (int bj = 0; bj < 2; ++bj)
; #pragma unroll
;                         for (int n = 0; n < 2; ++n) {
;                             f32x4 res = rv[mm][bj][n];
;                             if (MODE == 1) res = (res - st[mm].x) * st[mm].y * gv[bj][n] + bv[bj][n];
;                             *(f32x4*)(zp + bj * HALF + n * 16) = res * ALPHA + acc[ai][bj][m][n] * scale;
;                         }
;                 }
	v_sub_f32_e32 v67, v67, v98
	v_sub_f32_e32 v66, v66, v98
	v_sub_f32_e32 v65, v65, v98
	v_sub_f32_e32 v64, v64, v98
	v_pk_mul_f32 v[64:65], v[98:99], v[64:65] op_sel:[1,0]
	v_pk_mul_f32 v[66:67], v[98:99], v[66:67] op_sel:[1,0]
	v_pk_fma_f32 v[64:65], v[156:157], v[64:65], v[152:153]
	v_pk_fma_f32 v[66:67], v[158:159], v[66:67], v[154:155]
	v_pk_mul_f32 v[64:65], v[64:65], s[24:25] op_sel_hi:[1,0]
	v_pk_mul_f32 v[66:67], v[66:67], s[24:25] op_sel_hi:[1,0]
	v_pk_fma_f32 v[60:61], v[60:61], 0.5, v[64:65] op_sel_hi:[1,0,1]
	v_pk_fma_f32 v[62:63], v[62:63], 0.5, v[66:67] op_sel_hi:[1,0,1]
	global_store_dwordx4 v[96:97], v[60:63], off
	v_lshl_add_u64 v[64:65], v[176:177], 0, s[30:31]
	s_nop 0
	v_sub_f32_e32 v61, v71, v98
	v_sub_f32_e32 v60, v70, v98
	v_sub_f32_e32 v63, v69, v98
	v_sub_f32_e32 v62, v68, v98
	v_pk_mul_f32 v[62:63], v[98:99], v[62:63] op_sel:[1,0]
	v_pk_mul_f32 v[60:61], v[98:99], v[60:61] op_sel:[1,0]
	v_pk_fma_f32 v[62:63], v[144:145], v[62:63], v[148:149]
	v_pk_fma_f32 v[60:61], v[146:147], v[60:61], v[150:151]
	v_pk_mul_f32 v[62:63], v[62:63], s[24:25] op_sel_hi:[1,0]
	v_pk_mul_f32 v[60:61], v[60:61], s[24:25] op_sel_hi:[1,0]
	v_pk_fma_f32 v[56:57], v[56:57], 0.5, v[62:63] op_sel_hi:[1,0,1]
	v_pk_fma_f32 v[58:59], v[58:59], 0.5, v[60:61] op_sel_hi:[1,0,1]
	global_store_dwordx4 v[96:97], v[56:59], off offset:64
	v_lshl_add_u64 v[68:69], v[176:177], 0, s[34:35]
	v_lshl_add_u64 v[60:61], v[174:175], 0, v[68:69]
	v_sub_f32_e32 v57, v75, v98
	v_sub_f32_e32 v56, v74, v98
	v_sub_f32_e32 v59, v73, v98
	v_sub_f32_e32 v58, v72, v98
	v_pk_mul_f32 v[58:59], v[98:99], v[58:59] op_sel:[1,0]
	v_pk_mul_f32 v[56:57], v[98:99], v[56:57] op_sel:[1,0]
	v_pk_fma_f32 v[58:59], v[140:141], v[58:59], v[136:137]
	v_pk_fma_f32 v[56:57], v[142:143], v[56:57], v[138:139]
	v_pk_mul_f32 v[58:59], v[58:59], s[24:25] op_sel_hi:[1,0]
	v_pk_mul_f32 v[56:57], v[56:57], s[24:25] op_sel_hi:[1,0]
	v_pk_fma_f32 v[52:53], v[52:53], 0.5, v[58:59] op_sel_hi:[1,0,1]
	v_pk_fma_f32 v[54:55], v[54:55], 0.5, v[56:57] op_sel_hi:[1,0,1]
	global_store_dwordx4 v[96:97], v[52:55], off offset:512
	s_nop 1
	v_sub_f32_e32 v53, v79, v98
	v_sub_f32_e32 v52, v78, v98
	v_sub_f32_e32 v55, v77, v98
	v_sub_f32_e32 v54, v76, v98
	v_pk_mul_f32 v[54:55], v[98:99], v[54:55] op_sel:[1,0]
	v_pk_mul_f32 v[52:53], v[98:99], v[52:53] op_sel:[1,0]
	v_pk_fma_f32 v[54:55], v[128:129], v[54:55], v[132:133]
	v_pk_fma_f32 v[52:53], v[130:131], v[52:53], v[134:135]
	v_pk_mul_f32 v[54:55], v[54:55], s[24:25] op_sel_hi:[1,0]
	v_pk_mul_f32 v[52:53], v[52:53], s[24:25] op_sel_hi:[1,0]
	v_pk_fma_f32 v[44:45], v[44:45], 0.5, v[54:55] op_sel_hi:[1,0,1]
	v_pk_fma_f32 v[46:47], v[46:47], 0.5, v[52:53] op_sel_hi:[1,0,1]
	global_store_dwordx4 v[96:97], v[44:47], off offset:576
	s_nop 1
	v_lshl_add_u64 v[44:45], s[12:13], 0, v[100:101]
	v_lshl_add_u64 v[52:53], v[44:45], 0, v[172:173]
	v_sub_f32_e32 v45, v83, v102
	v_sub_f32_e32 v44, v82, v102
	v_sub_f32_e32 v47, v81, v102
	v_sub_f32_e32 v46, v80, v102
	v_pk_mul_f32 v[46:47], v[102:103], v[46:47] op_sel:[1,0]
	v_pk_mul_f32 v[44:45], v[102:103], v[44:45] op_sel:[1,0]
	v_pk_fma_f32 v[46:47], v[156:157], v[46:47], v[152:153]
	v_pk_fma_f32 v[44:45], v[158:159], v[44:45], v[154:155]
	v_pk_mul_f32 v[54:55], v[46:47], s[24:25] op_sel_hi:[1,0]
	v_pk_mul_f32 v[44:45], v[44:45], s[24:25] op_sel_hi:[1,0]
	s_nop 0
	v_pk_fma_f32 v[46:47], v[50:51], 0.5, v[44:45] op_sel_hi:[1,0,1]
	v_pk_fma_f32 v[44:45], v[48:49], 0.5, v[54:55] op_sel_hi:[1,0,1]
	global_store_dwordx4 v[52:53], v[44:47], off
	s_nop 1
	v_sub_f32_e32 v45, v87, v102
	v_sub_f32_e32 v44, v86, v102
	v_sub_f32_e32 v47, v85, v102
	v_sub_f32_e32 v46, v84, v102
	v_pk_mul_f32 v[46:47], v[102:103], v[46:47] op_sel:[1,0]
	v_pk_mul_f32 v[44:45], v[102:103], v[44:45] op_sel:[1,0]
	v_pk_fma_f32 v[46:47], v[144:145], v[46:47], v[148:149]
	v_pk_fma_f32 v[44:45], v[146:147], v[44:45], v[150:151]
	v_pk_mul_f32 v[46:47], v[46:47], s[24:25] op_sel_hi:[1,0]
	v_pk_mul_f32 v[44:45], v[44:45], s[24:25] op_sel_hi:[1,0]
	v_pk_fma_f32 v[40:41], v[40:41], 0.5, v[46:47] op_sel_hi:[1,0,1]
	v_pk_fma_f32 v[42:43], v[42:43], 0.5, v[44:45] op_sel_hi:[1,0,1]
	global_store_dwordx4 v[52:53], v[40:43], off offset:64
	v_lshl_add_u64 v[44:45], v[174:175], 0, v[64:65]
	v_lshl_add_u64 v[64:65], s[12:13], 0, v[64:65]
	v_sub_f32_e32 v41, v91, v102
	v_sub_f32_e32 v40, v90, v102
	v_sub_f32_e32 v43, v89, v102
	v_sub_f32_e32 v42, v88, v102
	v_pk_mul_f32 v[42:43], v[102:103], v[42:43] op_sel:[1,0]
	v_pk_mul_f32 v[40:41], v[102:103], v[40:41] op_sel:[1,0]
	v_pk_fma_f32 v[42:43], v[140:141], v[42:43], v[136:137]
	v_pk_fma_f32 v[40:41], v[142:143], v[40:41], v[138:139]
	v_pk_mul_f32 v[42:43], v[42:43], s[24:25] op_sel_hi:[1,0]
	v_pk_mul_f32 v[40:41], v[40:41], s[24:25] op_sel_hi:[1,0]
	v_pk_fma_f32 v[36:37], v[36:37], 0.5, v[42:43] op_sel_hi:[1,0,1]
	v_pk_fma_f32 v[38:39], v[38:39], 0.5, v[40:41] op_sel_hi:[1,0,1]
	global_store_dwordx4 v[52:53], v[36:39], off offset:512
	v_lshl_add_u64 v[64:65], v[64:65], 0, v[172:173]
	s_nop 0
	v_sub_f32_e32 v37, v95, v102
	v_sub_f32_e32 v36, v94, v102
	v_sub_f32_e32 v39, v93, v102
	v_sub_f32_e32 v38, v92, v102
	v_pk_mul_f32 v[38:39], v[102:103], v[38:39] op_sel:[1,0]
	v_pk_mul_f32 v[36:37], v[102:103], v[36:37] op_sel:[1,0]
	v_pk_fma_f32 v[38:39], v[128:129], v[38:39], v[132:133]
	v_pk_fma_f32 v[36:37], v[130:131], v[36:37], v[134:135]
	v_pk_mul_f32 v[38:39], v[38:39], s[24:25] op_sel_hi:[1,0]
	v_pk_mul_f32 v[36:37], v[36:37], s[24:25] op_sel_hi:[1,0]
	v_pk_fma_f32 v[32:33], v[32:33], 0.5, v[38:39] op_sel_hi:[1,0,1]
	v_pk_fma_f32 v[34:35], v[34:35], 0.5, v[36:37] op_sel_hi:[1,0,1]
	global_store_dwordx4 v[52:53], v[32:35], off offset:576
	global_load_dwordx2 v[66:67], v[178:179], off offset:1280
	s_nop 0
	global_load_dwordx4 v[32:35], v[44:45], off
	global_load_dwordx4 v[36:39], v[44:45], off offset:64
	global_load_dwordx4 v[40:43], v[44:45], off offset:512
	s_nop 0
	global_load_dwordx4 v[44:47], v[44:45], off offset:576
	s_nop 0
	global_load_dwordx2 v[70:71], v[178:179], off offset:1408
	global_load_dwordx4 v[48:51], v[60:61], off
	global_load_dwordx4 v[52:55], v[60:61], off offset:64
	global_load_dwordx4 v[56:59], v[60:61], off offset:512
	s_nop 0
	global_load_dwordx4 v[60:63], v[60:61], off offset:576
	s_waitcnt vmcnt(0)
; #define PG8_WAIT_V(n) asm volatile("s_waitcnt vmcnt(" #n ")" ::: "memory")
; #define PG8_BAR __builtin_amdgcn_s_barrier()
; template <class Epi, class Sched>
; __device__ __forceinline__ void gemm_phase(LAS unsigned char* lds, const Gemm g, const Sched& S, const Epi& E) {
;     ...
;     PG8_WAIT_V(0);
;     if (wr == 0) PG8_BAR;
;     PG8_BAR;
;     __device__ __forceinline__ void operator()(const f32x4 (&acc)[2][2][4][2], const Unit& u, int wr, int wc, int fr, int fq) const {
;     ...
;                 for (int mm = 0; mm < 2; ++mm) {
;                     const int m = mh * 2 + mm, r = row0 + ai * HALF + m * 16;
;                     float* zp = Z + (size_t)r * DM + col0;
; #pragma unroll
;                     for (int bj = 0; bj < 2; ++bj)
; #pragma unroll
;                         for (int n = 0; n < 2; ++n) {
;                             f32x4 res = rv[mm][bj][n];
;                             if (MODE == 1) res = (res - st[mm].x) * st[mm].y * gv[bj][n] + bv[bj][n];
;                             *(f32x4*)(zp + bj * HALF + n * 16) = res * ALPHA + acc[ai][bj][m][n] * scale;
;                         }
;                 }
	v_sub_f32_e32 v35, v35, v66
	v_sub_f32_e32 v34, v34, v66
	v_sub_f32_e32 v33, v33, v66
	v_sub_f32_e32 v32, v32, v66
	v_pk_mul_f32 v[32:33], v[66:67], v[32:33] op_sel:[1,0]
	v_pk_mul_f32 v[34:35], v[66:67], v[34:35] op_sel:[1,0]
	v_pk_fma_f32 v[32:33], v[156:157], v[32:33], v[152:153]
	v_pk_fma_f32 v[34:35], v[158:159], v[34:35], v[154:155]
	v_pk_mul_f32 v[32:33], v[32:33], s[24:25] op_sel_hi:[1,0]
	v_pk_mul_f32 v[34:35], v[34:35], s[24:25] op_sel_hi:[1,0]
	v_pk_fma_f32 v[28:29], v[28:29], 0.5, v[32:33] op_sel_hi:[1,0,1]
	v_pk_fma_f32 v[30:31], v[30:31], 0.5, v[34:35] op_sel_hi:[1,0,1]
	global_store_dwordx4 v[64:65], v[28:31], off
	s_nop 1
	v_sub_f32_e32 v29, v39, v66
	v_sub_f32_e32 v28, v38, v66
	v_sub_f32_e32 v31, v37, v66
	v_sub_f32_e32 v30, v36, v66
	v_pk_mul_f32 v[30:31], v[66:67], v[30:31] op_sel:[1,0]
	v_pk_mul_f32 v[28:29], v[66:67], v[28:29] op_sel:[1,0]
	v_pk_fma_f32 v[30:31], v[144:145], v[30:31], v[148:149]
	v_pk_fma_f32 v[28:29], v[146:147], v[28:29], v[150:151]
	v_pk_mul_f32 v[30:31], v[30:31], s[24:25] op_sel_hi:[1,0]
	v_pk_mul_f32 v[28:29], v[28:29], s[24:25] op_sel_hi:[1,0]
	v_pk_fma_f32 v[24:25], v[24:25], 0.5, v[30:31] op_sel_hi:[1,0,1]
	v_pk_fma_f32 v[26:27], v[26:27], 0.5, v[28:29] op_sel_hi:[1,0,1]
	global_store_dwordx4 v[64:65], v[24:27], off offset:64
	s_nop 1
	v_sub_f32_e32 v25, v43, v66
	v_sub_f32_e32 v24, v42, v66
	v_sub_f32_e32 v27, v41, v66
	v_sub_f32_e32 v26, v40, v66
	v_pk_mul_f32 v[26:27], v[66:67], v[26:27] op_sel:[1,0]
	v_pk_mul_f32 v[24:25], v[66:67], v[24:25] op_sel:[1,0]
	v_pk_fma_f32 v[26:27], v[140:141], v[26:27], v[136:137]
	v_pk_fma_f32 v[24:25], v[142:143], v[24:25], v[138:139]
	v_pk_mul_f32 v[26:27], v[26:27], s[24:25] op_sel_hi:[1,0]
	v_pk_mul_f32 v[24:25], v[24:25], s[24:25] op_sel_hi:[1,0]
	v_pk_fma_f32 v[20:21], v[20:21], 0.5, v[26:27] op_sel_hi:[1,0,1]
	v_pk_fma_f32 v[22:23], v[22:23], 0.5, v[24:25] op_sel_hi:[1,0,1]
	global_store_dwordx4 v[64:65], v[20:23], off offset:512
	s_nop 1
	v_sub_f32_e32 v21, v47, v66
	v_sub_f32_e32 v20, v46, v66
	v_sub_f32_e32 v23, v45, v66
	v_sub_f32_e32 v22, v44, v66
	v_pk_mul_f32 v[22:23], v[66:67], v[22:23] op_sel:[1,0]
	v_pk_mul_f32 v[20:21], v[66:67], v[20:21] op_sel:[1,0]
	v_pk_fma_f32 v[22:23], v[128:129], v[22:23], v[132:133]
	v_pk_fma_f32 v[20:21], v[130:131], v[20:21], v[134:135]
	v_pk_mul_f32 v[22:23], v[22:23], s[24:25] op_sel_hi:[1,0]
	v_pk_mul_f32 v[20:21], v[20:21], s[24:25] op_sel_hi:[1,0]
	v_pk_fma_f32 v[12:13], v[12:13], 0.5, v[22:23] op_sel_hi:[1,0,1]
	v_pk_fma_f32 v[14:15], v[14:15], 0.5, v[20:21] op_sel_hi:[1,0,1]
	global_store_dwordx4 v[64:65], v[12:15], off offset:576
	s_nop 1
	v_lshl_add_u64 v[12:13], s[12:13], 0, v[68:69]
	v_lshl_add_u64 v[20:21], v[12:13], 0, v[172:173]
	v_sub_f32_e32 v13, v51, v70
	v_sub_f32_e32 v12, v50, v70
	v_sub_f32_e32 v15, v49, v70
	v_sub_f32_e32 v14, v48, v70
	v_pk_mul_f32 v[14:15], v[70:71], v[14:15] op_sel:[1,0]
	v_pk_mul_f32 v[12:13], v[70:71], v[12:13] op_sel:[1,0]
	v_pk_fma_f32 v[14:15], v[156:157], v[14:15], v[152:153]
	v_pk_fma_f32 v[12:13], v[158:159], v[12:13], v[154:155]
	v_pk_mul_f32 v[22:23], v[14:15], s[24:25] op_sel_hi:[1,0]
	v_pk_mul_f32 v[12:13], v[12:13], s[24:25] op_sel_hi:[1,0]
	s_nop 0
	v_pk_fma_f32 v[14:15], v[18:19], 0.5, v[12:13] op_sel_hi:[1,0,1]
	v_pk_fma_f32 v[12:13], v[16:17], 0.5, v[22:23] op_sel_hi:[1,0,1]
	global_store_dwordx4 v[20:21], v[12:15], off
	s_nop 1
	v_sub_f32_e32 v13, v55, v70
	v_sub_f32_e32 v12, v54, v70
	v_sub_f32_e32 v15, v53, v70
	v_sub_f32_e32 v14, v52, v70
	v_pk_mul_f32 v[14:15], v[70:71], v[14:15] op_sel:[1,0]
	v_pk_mul_f32 v[12:13], v[70:71], v[12:13] op_sel:[1,0]
	v_pk_fma_f32 v[14:15], v[144:145], v[14:15], v[148:149]
	v_pk_fma_f32 v[12:13], v[146:147], v[12:13], v[150:151]
	v_pk_mul_f32 v[14:15], v[14:15], s[24:25] op_sel_hi:[1,0]
	v_pk_mul_f32 v[12:13], v[12:13], s[24:25] op_sel_hi:[1,0]
	v_pk_fma_f32 v[8:9], v[8:9], 0.5, v[14:15] op_sel_hi:[1,0,1]
	v_pk_fma_f32 v[10:11], v[10:11], 0.5, v[12:13] op_sel_hi:[1,0,1]
	global_store_dwordx4 v[20:21], v[8:11], off offset:64
	s_nop 1
	v_sub_f32_e32 v9, v59, v70
	v_sub_f32_e32 v8, v58, v70
	v_sub_f32_e32 v11, v57, v70
	v_sub_f32_e32 v10, v56, v70
	v_pk_mul_f32 v[10:11], v[70:71], v[10:11] op_sel:[1,0]
	v_pk_mul_f32 v[8:9], v[70:71], v[8:9] op_sel:[1,0]
	v_pk_fma_f32 v[10:11], v[140:141], v[10:11], v[136:137]
	v_pk_fma_f32 v[8:9], v[142:143], v[8:9], v[138:139]
	v_pk_mul_f32 v[10:11], v[10:11], s[24:25] op_sel_hi:[1,0]
	v_pk_mul_f32 v[8:9], v[8:9], s[24:25] op_sel_hi:[1,0]
	v_pk_fma_f32 v[4:5], v[4:5], 0.5, v[10:11] op_sel_hi:[1,0,1]
	v_pk_fma_f32 v[6:7], v[6:7], 0.5, v[8:9] op_sel_hi:[1,0,1]
	global_store_dwordx4 v[20:21], v[4:7], off offset:512
	s_nop 1
	v_sub_f32_e32 v5, v63, v70
	v_sub_f32_e32 v4, v62, v70
	v_sub_f32_e32 v7, v61, v70
	v_sub_f32_e32 v6, v60, v70
	v_pk_mul_f32 v[6:7], v[70:71], v[6:7] op_sel:[1,0]
	v_pk_mul_f32 v[4:5], v[70:71], v[4:5] op_sel:[1,0]
	v_pk_fma_f32 v[6:7], v[128:129], v[6:7], v[132:133]
	v_pk_fma_f32 v[4:5], v[130:131], v[4:5], v[134:135]
	v_pk_mul_f32 v[6:7], v[6:7], s[24:25] op_sel_hi:[1,0]
	v_pk_mul_f32 v[4:5], v[4:5], s[24:25] op_sel_hi:[1,0]
	v_pk_fma_f32 v[0:1], v[0:1], 0.5, v[6:7] op_sel_hi:[1,0,1]
	v_pk_fma_f32 v[2:3], v[2:3], 0.5, v[4:5] op_sel_hi:[1,0,1]
	global_store_dwordx4 v[20:21], v[0:3], off offset:576
	s_cbranch_vccz .LBB0_1629
	s_waitcnt vmcnt(0)
	s_cmpk_gt_u32 s25, 0xff
	s_cbranch_scc1 .LBB0_1644
	s_barrier
